# v37 + GEMM K-loop MFMAs re-ordered within each run of 8 so consecutive MFMAs share NO operand register (same per-accumulator k order)
# baseline (speedup 1.0000x reference)
.LBB0_274:
	ds_read_b128 v[146:149], v153
	ds_read_b128 v[156:159], v153 offset:1024
	ds_read_b128 v[160:163], v153 offset:2048
	ds_read_b128 v[164:167], v153 offset:3072
	ds_read_b128 v[168:171], v154
	ds_read_b128 v[172:175], v154 offset:1024
	ds_read_b128 v[176:179], v154 offset:2048
	ds_read_b128 v[180:183], v154 offset:3072
	s_add_u32 s34, s76, 0xfff80080
	s_addc_u32 s35, s77, -1
	s_cmp_eq_u32 s85, 28
	s_cselect_b32 s79, s0, s35
	s_cselect_b32 s78, s1, s34
	s_cselect_b32 s35, s67, s84
	s_cselect_b32 s34, s69, s83
	v_lshl_add_u64 v[218:219], s[76:77], 0, v[138:139]
	s_add_i32 m0, s54, 0xc000
	ds_read_b128 v[184:187], v155
	ds_read_b128 v[188:191], v155 offset:1024
	ds_read_b128 v[192:195], v155 offset:2048
	ds_read_b128 v[196:199], v155 offset:3072
	ds_read_b128 v[200:203], v155 offset:4096
	ds_read_b128 v[204:207], v155 offset:5120
	ds_read_b128 v[208:211], v155 offset:6144
	ds_read_b128 v[212:215], v155 offset:7168
	global_load_lds_dwordx4 v[218:219], off
	v_lshl_add_u64 v[218:219], s[76:77], 0, v[140:141]
	s_add_i32 m0, s54, 0xe000
	s_nop 0
	global_load_lds_dwordx4 v[218:219], off
	s_waitcnt vmcnt(8)
	s_waitcnt lgkmcnt(0)
	s_barrier
	s_setprio 1
	s_waitcnt lgkmcnt(0)
	v_mfma_f32_16x16x32_bf16 v[126:129], v[146:149], v[184:187], v[126:129]
	v_mfma_f32_16x16x32_bf16 v[102:105], v[160:163], v[192:195], v[102:105]
	v_mfma_f32_16x16x32_bf16 v[94:97], v[146:149], v[200:203], v[94:97]
	v_mfma_f32_16x16x32_bf16 v[70:73], v[160:163], v[208:211], v[70:73]
	v_mfma_f32_16x16x32_bf16 v[110:113], v[146:149], v[192:195], v[110:113]
	v_mfma_f32_16x16x32_bf16 v[118:121], v[160:163], v[184:187], v[118:121]
	v_mfma_f32_16x16x32_bf16 v[78:81], v[146:149], v[208:211], v[78:81]
	v_mfma_f32_16x16x32_bf16 v[86:89], v[160:163], v[200:203], v[86:89]
	v_mfma_f32_16x16x32_bf16 v[126:129], v[156:159], v[188:191], v[126:129]
	v_mfma_f32_16x16x32_bf16 v[102:105], v[164:167], v[196:199], v[102:105]
	v_mfma_f32_16x16x32_bf16 v[94:97], v[156:159], v[204:207], v[94:97]
	v_mfma_f32_16x16x32_bf16 v[70:73], v[164:167], v[212:215], v[70:73]
	v_mfma_f32_16x16x32_bf16 v[110:113], v[156:159], v[196:199], v[110:113]
	v_mfma_f32_16x16x32_bf16 v[118:121], v[164:167], v[188:191], v[118:121]
	v_mfma_f32_16x16x32_bf16 v[78:81], v[156:159], v[212:215], v[78:81]
	v_mfma_f32_16x16x32_bf16 v[86:89], v[164:167], v[204:207], v[86:89]
	s_setprio 0
	s_setprio 1
	v_mfma_f32_16x16x32_bf16 v[122:125], v[168:171], v[184:187], v[122:125]
	v_mfma_f32_16x16x32_bf16 v[98:101], v[176:179], v[192:195], v[98:101]
	v_mfma_f32_16x16x32_bf16 v[90:93], v[168:171], v[200:203], v[90:93]
	v_mfma_f32_16x16x32_bf16 v[66:69], v[176:179], v[208:211], v[66:69]
	v_mfma_f32_16x16x32_bf16 v[106:109], v[168:171], v[192:195], v[106:109]
	v_mfma_f32_16x16x32_bf16 v[114:117], v[176:179], v[184:187], v[114:117]
	v_mfma_f32_16x16x32_bf16 v[74:77], v[168:171], v[208:211], v[74:77]
	v_mfma_f32_16x16x32_bf16 v[82:85], v[176:179], v[200:203], v[82:85]
	v_mfma_f32_16x16x32_bf16 v[122:125], v[172:175], v[188:191], v[122:125]
	v_mfma_f32_16x16x32_bf16 v[98:101], v[180:183], v[196:199], v[98:101]
	v_mfma_f32_16x16x32_bf16 v[90:93], v[172:175], v[204:207], v[90:93]
	v_mfma_f32_16x16x32_bf16 v[66:69], v[180:183], v[212:215], v[66:69]
	v_mfma_f32_16x16x32_bf16 v[106:109], v[172:175], v[196:199], v[106:109]
	v_mfma_f32_16x16x32_bf16 v[114:117], v[180:183], v[188:191], v[114:117]
	v_mfma_f32_16x16x32_bf16 v[74:77], v[172:175], v[212:215], v[74:77]
	v_mfma_f32_16x16x32_bf16 v[82:85], v[180:183], v[204:207], v[82:85]
	s_setprio 0
	s_barrier
	s_add_i32 s62, s75, s33
	v_lshl_add_u64 v[218:219], s[34:35], 0, v[134:135]
	s_mov_b32 m0, s62
	ds_read_b128 v[184:187], v155 offset:16384
	ds_read_b128 v[188:191], v155 offset:17408
	ds_read_b128 v[192:195], v155 offset:18432
	ds_read_b128 v[196:199], v155 offset:19456
	ds_read_b128 v[200:203], v155 offset:20480
	ds_read_b128 v[204:207], v155 offset:21504
	ds_read_b128 v[208:211], v155 offset:22528
	ds_read_b128 v[212:215], v155 offset:23552
	global_load_lds_dwordx4 v[218:219], off
	s_add_i32 m0, s62, 0x2000
	s_add_u32 s62, s34, 0x80000
	v_lshl_add_u64 v[220:221], s[34:35], 0, v[130:131]
	s_addc_u32 s63, s35, 0
	s_add_i32 s86, s80, s33
	global_load_lds_dwordx4 v[220:221], off
	v_lshl_add_u64 v[222:223], s[62:63], 0, v[134:135]
	s_mov_b32 m0, s86
	v_lshl_add_u64 v[224:225], s[78:79], 0, v[132:133]
	global_load_lds_dwordx4 v[222:223], off
	v_lshl_add_u64 v[222:223], s[62:63], 0, v[130:131]
	s_add_i32 m0, s86, 0x2000
	s_nop 0
	global_load_lds_dwordx4 v[222:223], off
	v_lshl_add_u64 v[222:223], s[78:79], 0, v[136:137]
	s_mov_b32 m0, s54
	s_nop 0
	global_load_lds_dwordx4 v[222:223], off
	s_mov_b32 m0, s55
	s_nop 0
	global_load_lds_dwordx4 v[224:225], off
	s_waitcnt vmcnt(8)
	s_waitcnt lgkmcnt(0)
	s_barrier
	s_setprio 1
	s_waitcnt lgkmcnt(0)
	v_mfma_f32_16x16x32_bf16 v[62:65], v[146:149], v[184:187], v[62:65]
	v_mfma_f32_16x16x32_bf16 v[38:41], v[160:163], v[192:195], v[38:41]
	v_mfma_f32_16x16x32_bf16 v[30:33], v[146:149], v[200:203], v[30:33]
	v_mfma_f32_16x16x32_bf16 v[6:9], v[160:163], v[208:211], v[6:9]
	v_mfma_f32_16x16x32_bf16 v[46:49], v[146:149], v[192:195], v[46:49]
	v_mfma_f32_16x16x32_bf16 v[54:57], v[160:163], v[184:187], v[54:57]
	v_mfma_f32_16x16x32_bf16 v[14:17], v[146:149], v[208:211], v[14:17]
	v_mfma_f32_16x16x32_bf16 v[22:25], v[160:163], v[200:203], v[22:25]
	v_mfma_f32_16x16x32_bf16 v[62:65], v[156:159], v[188:191], v[62:65]
	v_mfma_f32_16x16x32_bf16 v[38:41], v[164:167], v[196:199], v[38:41]
	v_mfma_f32_16x16x32_bf16 v[30:33], v[156:159], v[204:207], v[30:33]
	v_mfma_f32_16x16x32_bf16 v[6:9], v[164:167], v[212:215], v[6:9]
	v_mfma_f32_16x16x32_bf16 v[46:49], v[156:159], v[196:199], v[46:49]
	v_mfma_f32_16x16x32_bf16 v[54:57], v[164:167], v[188:191], v[54:57]
	v_mfma_f32_16x16x32_bf16 v[14:17], v[156:159], v[212:215], v[14:17]
	v_mfma_f32_16x16x32_bf16 v[22:25], v[164:167], v[204:207], v[22:25]
	s_setprio 0
	s_setprio 1
	v_mfma_f32_16x16x32_bf16 v[58:61], v[168:171], v[184:187], v[58:61]
	v_mfma_f32_16x16x32_bf16 v[34:37], v[176:179], v[192:195], v[34:37]
	v_mfma_f32_16x16x32_bf16 v[26:29], v[168:171], v[200:203], v[26:29]
	v_mfma_f32_16x16x32_bf16 v[2:5], v[176:179], v[208:211], v[2:5]
	v_mfma_f32_16x16x32_bf16 v[42:45], v[168:171], v[192:195], v[42:45]
	v_mfma_f32_16x16x32_bf16 v[50:53], v[176:179], v[184:187], v[50:53]
	v_mfma_f32_16x16x32_bf16 v[10:13], v[168:171], v[208:211], v[10:13]
	v_mfma_f32_16x16x32_bf16 v[18:21], v[176:179], v[200:203], v[18:21]
	v_mfma_f32_16x16x32_bf16 v[58:61], v[172:175], v[188:191], v[58:61]
	v_mfma_f32_16x16x32_bf16 v[34:37], v[180:183], v[196:199], v[34:37]
	v_mfma_f32_16x16x32_bf16 v[26:29], v[172:175], v[204:207], v[26:29]
	v_mfma_f32_16x16x32_bf16 v[2:5], v[180:183], v[212:215], v[2:5]
	v_mfma_f32_16x16x32_bf16 v[42:45], v[172:175], v[196:199], v[42:45]
	v_mfma_f32_16x16x32_bf16 v[50:53], v[180:183], v[188:191], v[50:53]
	v_mfma_f32_16x16x32_bf16 v[10:13], v[172:175], v[212:215], v[10:13]
	v_mfma_f32_16x16x32_bf16 v[18:21], v[180:183], v[204:207], v[18:21]
	s_setprio 0
	s_barrier
	s_add_i32 s86, 0, 0x18000
	s_add_i32 s87, 0, 0x1c000
	v_add_u32_e32 v164, s86, v151
	v_add_u32_e32 v180, s87, v151
	ds_read_b128 v[146:149], v164
	ds_read_b128 v[156:159], v164 offset:1024
	ds_read_b128 v[160:163], v164 offset:2048
	ds_read_b128 v[164:167], v164 offset:3072
	ds_read_b128 v[168:171], v180
	ds_read_b128 v[172:175], v180 offset:1024
	ds_read_b128 v[176:179], v180 offset:2048
	ds_read_b128 v[180:183], v180 offset:3072
	s_add_u32 s62, s78, 0x80000
	s_addc_u32 s63, s79, 0
	s_mov_b32 m0, s56
	v_lshl_add_u64 v[226:227], s[62:63], 0, v[136:137]
	ds_read_b128 v[184:187], v155 offset:32768
	ds_read_b128 v[188:191], v155 offset:33792
	ds_read_b128 v[192:195], v155 offset:34816
	ds_read_b128 v[196:199], v155 offset:35840
	ds_read_b128 v[200:203], v155 offset:36864
	ds_read_b128 v[204:207], v155 offset:37888
	ds_read_b128 v[208:211], v155 offset:38912
	ds_read_b128 v[212:215], v155 offset:39936
	global_load_lds_dwordx4 v[226:227], off
	v_lshl_add_u64 v[226:227], s[62:63], 0, v[132:133]
	s_mov_b32 m0, s57
	s_nop 0
	global_load_lds_dwordx4 v[226:227], off
	s_waitcnt vmcnt(8)
	s_waitcnt lgkmcnt(0)
	s_barrier
	s_setprio 1
	s_waitcnt lgkmcnt(0)
	v_mfma_f32_16x16x32_bf16 v[126:129], v[146:149], v[184:187], v[126:129]
	v_mfma_f32_16x16x32_bf16 v[102:105], v[160:163], v[192:195], v[102:105]
	v_mfma_f32_16x16x32_bf16 v[94:97], v[146:149], v[200:203], v[94:97]
	v_mfma_f32_16x16x32_bf16 v[70:73], v[160:163], v[208:211], v[70:73]
	v_mfma_f32_16x16x32_bf16 v[110:113], v[146:149], v[192:195], v[110:113]
	v_mfma_f32_16x16x32_bf16 v[118:121], v[160:163], v[184:187], v[118:121]
	v_mfma_f32_16x16x32_bf16 v[78:81], v[146:149], v[208:211], v[78:81]
	v_mfma_f32_16x16x32_bf16 v[86:89], v[160:163], v[200:203], v[86:89]
	v_mfma_f32_16x16x32_bf16 v[126:129], v[156:159], v[188:191], v[126:129]
	v_mfma_f32_16x16x32_bf16 v[102:105], v[164:167], v[196:199], v[102:105]
	v_mfma_f32_16x16x32_bf16 v[94:97], v[156:159], v[204:207], v[94:97]
	v_mfma_f32_16x16x32_bf16 v[70:73], v[164:167], v[212:215], v[70:73]
	v_mfma_f32_16x16x32_bf16 v[110:113], v[156:159], v[196:199], v[110:113]
	v_mfma_f32_16x16x32_bf16 v[118:121], v[164:167], v[188:191], v[118:121]
	v_mfma_f32_16x16x32_bf16 v[78:81], v[156:159], v[212:215], v[78:81]
	v_mfma_f32_16x16x32_bf16 v[86:89], v[164:167], v[204:207], v[86:89]
	s_setprio 0
	s_setprio 1
	v_mfma_f32_16x16x32_bf16 v[122:125], v[168:171], v[184:187], v[122:125]
	v_mfma_f32_16x16x32_bf16 v[98:101], v[176:179], v[192:195], v[98:101]
	v_mfma_f32_16x16x32_bf16 v[90:93], v[168:171], v[200:203], v[90:93]
	v_mfma_f32_16x16x32_bf16 v[66:69], v[176:179], v[208:211], v[66:69]
	v_mfma_f32_16x16x32_bf16 v[106:109], v[168:171], v[192:195], v[106:109]
	v_mfma_f32_16x16x32_bf16 v[114:117], v[176:179], v[184:187], v[114:117]
	v_mfma_f32_16x16x32_bf16 v[74:77], v[168:171], v[208:211], v[74:77]
	v_mfma_f32_16x16x32_bf16 v[82:85], v[176:179], v[200:203], v[82:85]
	v_mfma_f32_16x16x32_bf16 v[122:125], v[172:175], v[188:191], v[122:125]
	v_mfma_f32_16x16x32_bf16 v[98:101], v[180:183], v[196:199], v[98:101]
	v_mfma_f32_16x16x32_bf16 v[90:93], v[172:175], v[204:207], v[90:93]
	v_mfma_f32_16x16x32_bf16 v[66:69], v[180:183], v[212:215], v[66:69]
	v_mfma_f32_16x16x32_bf16 v[106:109], v[172:175], v[196:199], v[106:109]
	v_mfma_f32_16x16x32_bf16 v[114:117], v[180:183], v[188:191], v[114:117]
	v_mfma_f32_16x16x32_bf16 v[74:77], v[172:175], v[212:215], v[74:77]
	v_mfma_f32_16x16x32_bf16 v[82:85], v[180:183], v[204:207], v[82:85]
	s_setprio 0
	s_barrier
	s_add_i32 s62, s86, s33
	v_lshl_add_u64 v[218:219], v[218:219], 0, s[8:9]
	s_mov_b32 m0, s62
	ds_read_b128 v[184:187], v155 offset:49152
	ds_read_b128 v[188:191], v155 offset:50176
	ds_read_b128 v[192:195], v155 offset:51200
	ds_read_b128 v[196:199], v155 offset:52224
	ds_read_b128 v[200:203], v155 offset:53248
	ds_read_b128 v[204:207], v155 offset:54272
	ds_read_b128 v[208:211], v155 offset:55296
	ds_read_b128 v[212:215], v155 offset:56320
	global_load_lds_dwordx4 v[218:219], off
	s_add_i32 m0, s62, 0x2000
	s_add_u32 s34, s34, 0x80080
	v_lshl_add_u64 v[218:219], v[220:221], 0, s[8:9]
	s_addc_u32 s35, s35, 0
	s_add_i32 s62, s87, s33
	global_load_lds_dwordx4 v[218:219], off
	v_lshl_add_u64 v[218:219], s[34:35], 0, v[134:135]
	s_mov_b32 m0, s62
	s_nop 0
	global_load_lds_dwordx4 v[218:219], off
	v_lshl_add_u64 v[218:219], s[34:35], 0, v[130:131]
	s_add_i32 m0, s62, 0x2000
	s_nop 0
	global_load_lds_dwordx4 v[218:219], off
	v_lshl_add_u64 v[218:219], v[222:223], 0, s[8:9]
	s_mov_b32 m0, s59
	s_nop 0
	global_load_lds_dwordx4 v[218:219], off
	v_lshl_add_u64 v[218:219], v[224:225], 0, s[8:9]
	s_mov_b32 m0, s60
	s_nop 0
	global_load_lds_dwordx4 v[218:219], off
	s_waitcnt vmcnt(8)
	s_waitcnt lgkmcnt(0)
	s_barrier
	s_setprio 1
	s_waitcnt lgkmcnt(0)
	v_mfma_f32_16x16x32_bf16 v[62:65], v[146:149], v[184:187], v[62:65]
	v_mfma_f32_16x16x32_bf16 v[38:41], v[160:163], v[192:195], v[38:41]
	v_mfma_f32_16x16x32_bf16 v[30:33], v[146:149], v[200:203], v[30:33]
	v_mfma_f32_16x16x32_bf16 v[6:9], v[160:163], v[208:211], v[6:9]
	v_mfma_f32_16x16x32_bf16 v[46:49], v[146:149], v[192:195], v[46:49]
	v_mfma_f32_16x16x32_bf16 v[54:57], v[160:163], v[184:187], v[54:57]
	v_mfma_f32_16x16x32_bf16 v[14:17], v[146:149], v[208:211], v[14:17]
	v_mfma_f32_16x16x32_bf16 v[22:25], v[160:163], v[200:203], v[22:25]
	v_mfma_f32_16x16x32_bf16 v[62:65], v[156:159], v[188:191], v[62:65]
	v_mfma_f32_16x16x32_bf16 v[38:41], v[164:167], v[196:199], v[38:41]
	v_mfma_f32_16x16x32_bf16 v[30:33], v[156:159], v[204:207], v[30:33]
	v_mfma_f32_16x16x32_bf16 v[6:9], v[164:167], v[212:215], v[6:9]
	v_mfma_f32_16x16x32_bf16 v[46:49], v[156:159], v[196:199], v[46:49]
	v_mfma_f32_16x16x32_bf16 v[54:57], v[164:167], v[188:191], v[54:57]
	v_mfma_f32_16x16x32_bf16 v[14:17], v[156:159], v[212:215], v[14:17]
	v_mfma_f32_16x16x32_bf16 v[22:25], v[164:167], v[204:207], v[22:25]
	s_setprio 0
	s_setprio 1
	v_mfma_f32_16x16x32_bf16 v[58:61], v[168:171], v[184:187], v[58:61]
	v_mfma_f32_16x16x32_bf16 v[34:37], v[176:179], v[192:195], v[34:37]
	v_mfma_f32_16x16x32_bf16 v[26:29], v[168:171], v[200:203], v[26:29]
	v_mfma_f32_16x16x32_bf16 v[2:5], v[176:179], v[208:211], v[2:5]
	v_mfma_f32_16x16x32_bf16 v[42:45], v[168:171], v[192:195], v[42:45]
	v_mfma_f32_16x16x32_bf16 v[50:53], v[176:179], v[184:187], v[50:53]
	v_mfma_f32_16x16x32_bf16 v[10:13], v[168:171], v[208:211], v[10:13]
	v_mfma_f32_16x16x32_bf16 v[18:21], v[176:179], v[200:203], v[18:21]
	v_mfma_f32_16x16x32_bf16 v[58:61], v[172:175], v[188:191], v[58:61]
	v_mfma_f32_16x16x32_bf16 v[34:37], v[180:183], v[196:199], v[34:37]
	v_mfma_f32_16x16x32_bf16 v[26:29], v[172:175], v[204:207], v[26:29]
	v_mfma_f32_16x16x32_bf16 v[2:5], v[180:183], v[212:215], v[2:5]
	v_mfma_f32_16x16x32_bf16 v[42:45], v[172:175], v[196:199], v[42:45]
	v_mfma_f32_16x16x32_bf16 v[50:53], v[180:183], v[188:191], v[50:53]
	v_mfma_f32_16x16x32_bf16 v[10:13], v[172:175], v[212:215], v[10:13]
	v_mfma_f32_16x16x32_bf16 v[18:21], v[180:183], v[204:207], v[18:21]
	s_setprio 0
	s_barrier
	s_add_i32 s85, s85, 2
	s_add_u32 s76, s76, 0x100
	s_addc_u32 s77, s77, 0
	s_add_u32 s83, s83, 0x100
	s_addc_u32 s84, s84, 0
	s_cmp_gt_u32 s85, 29
	s_cbranch_scc0 .LBB0_274
	v_mov_b32_e32 v160, 0xbfb8aa3b
	s_and_b64 vcc, exec, s[64:65]
	s_cbranch_vccz .LBB0_277
	s_barrier

.LBB0_387:
	ds_read_b128 v[146:149], v154
	ds_read_b128 v[158:161], v154 offset:1024
	ds_read_b128 v[162:165], v154 offset:2048
	ds_read_b128 v[166:169], v154 offset:3072
	ds_read_b128 v[170:173], v155
	ds_read_b128 v[174:177], v155 offset:1024
	ds_read_b128 v[178:181], v155 offset:2048
	ds_read_b128 v[182:185], v155 offset:3072
	s_add_u32 s34, s72, 0xffea0080
	s_addc_u32 s35, s73, -1
	s_cmpk_eq_i32 s81, 0x54
	s_cselect_b32 s75, s5, s35
	s_cselect_b32 s74, s4, s34
	s_cselect_b32 s35, s71, s1
	s_cselect_b32 s34, s70, s0
	v_lshl_add_u64 v[150:151], s[72:73], 0, v[138:139]
	s_add_i32 m0, s53, 0xc000
	ds_read_b128 v[186:189], v156
	ds_read_b128 v[190:193], v156 offset:1024
	ds_read_b128 v[194:197], v156 offset:2048
	ds_read_b128 v[198:201], v156 offset:3072
	ds_read_b128 v[202:205], v156 offset:4096
	ds_read_b128 v[206:209], v156 offset:5120
	ds_read_b128 v[210:213], v156 offset:6144
	ds_read_b128 v[218:221], v156 offset:7168
	global_load_lds_dwordx4 v[150:151], off
	v_lshl_add_u64 v[150:151], s[72:73], 0, v[140:141]
	s_add_i32 m0, s53, 0xe000
	s_nop 0
	global_load_lds_dwordx4 v[150:151], off
	s_waitcnt vmcnt(8)
	s_waitcnt lgkmcnt(0)
	s_barrier
	s_setprio 1
	s_waitcnt lgkmcnt(0)
	v_mfma_f32_16x16x32_bf16 v[126:129], v[146:149], v[186:189], v[126:129]
	v_mfma_f32_16x16x32_bf16 v[114:117], v[162:165], v[194:197], v[114:117]
	v_mfma_f32_16x16x32_bf16 v[94:97], v[146:149], v[202:205], v[94:97]
	v_mfma_f32_16x16x32_bf16 v[82:85], v[162:165], v[210:213], v[82:85]
	v_mfma_f32_16x16x32_bf16 v[118:121], v[146:149], v[194:197], v[118:121]
	v_mfma_f32_16x16x32_bf16 v[122:125], v[162:165], v[186:189], v[122:125]
	v_mfma_f32_16x16x32_bf16 v[86:89], v[146:149], v[210:213], v[86:89]
	v_mfma_f32_16x16x32_bf16 v[90:93], v[162:165], v[202:205], v[90:93]
	v_mfma_f32_16x16x32_bf16 v[126:129], v[158:161], v[190:193], v[126:129]
	v_mfma_f32_16x16x32_bf16 v[114:117], v[166:169], v[198:201], v[114:117]
	v_mfma_f32_16x16x32_bf16 v[94:97], v[158:161], v[206:209], v[94:97]
	v_mfma_f32_16x16x32_bf16 v[82:85], v[166:169], v[218:221], v[82:85]
	v_mfma_f32_16x16x32_bf16 v[118:121], v[158:161], v[198:201], v[118:121]
	v_mfma_f32_16x16x32_bf16 v[122:125], v[166:169], v[190:193], v[122:125]
	v_mfma_f32_16x16x32_bf16 v[86:89], v[158:161], v[218:221], v[86:89]
	v_mfma_f32_16x16x32_bf16 v[90:93], v[166:169], v[206:209], v[90:93]
	s_setprio 0
	s_setprio 1
	v_mfma_f32_16x16x32_bf16 v[110:113], v[170:173], v[186:189], v[110:113]
	v_mfma_f32_16x16x32_bf16 v[98:101], v[178:181], v[194:197], v[98:101]
	v_mfma_f32_16x16x32_bf16 v[78:81], v[170:173], v[202:205], v[78:81]
	v_mfma_f32_16x16x32_bf16 v[66:69], v[178:181], v[210:213], v[66:69]
	v_mfma_f32_16x16x32_bf16 v[102:105], v[170:173], v[194:197], v[102:105]
	v_mfma_f32_16x16x32_bf16 v[106:109], v[178:181], v[186:189], v[106:109]
	v_mfma_f32_16x16x32_bf16 v[70:73], v[170:173], v[210:213], v[70:73]
	v_mfma_f32_16x16x32_bf16 v[74:77], v[178:181], v[202:205], v[74:77]
	v_mfma_f32_16x16x32_bf16 v[110:113], v[174:177], v[190:193], v[110:113]
	v_mfma_f32_16x16x32_bf16 v[98:101], v[182:185], v[198:201], v[98:101]
	v_mfma_f32_16x16x32_bf16 v[78:81], v[174:177], v[206:209], v[78:81]
	v_mfma_f32_16x16x32_bf16 v[66:69], v[182:185], v[218:221], v[66:69]
	v_mfma_f32_16x16x32_bf16 v[102:105], v[174:177], v[198:201], v[102:105]
	v_mfma_f32_16x16x32_bf16 v[106:109], v[182:185], v[190:193], v[106:109]
	v_mfma_f32_16x16x32_bf16 v[70:73], v[174:177], v[218:221], v[70:73]
	v_mfma_f32_16x16x32_bf16 v[74:77], v[182:185], v[206:209], v[74:77]
	s_setprio 0
	s_barrier
	s_add_i32 s62, s61, s52
	v_lshl_add_u64 v[150:151], s[34:35], 0, v[132:133]
	s_mov_b32 m0, s62
	ds_read_b128 v[186:189], v156 offset:16384
	ds_read_b128 v[190:193], v156 offset:17408
	ds_read_b128 v[194:197], v156 offset:18432
	ds_read_b128 v[198:201], v156 offset:19456
	ds_read_b128 v[202:205], v156 offset:20480
	ds_read_b128 v[206:209], v156 offset:21504
	ds_read_b128 v[210:213], v156 offset:22528
	ds_read_b128 v[218:221], v156 offset:23552
	global_load_lds_dwordx4 v[150:151], off
	s_add_i32 m0, s62, 0x2000
	s_add_u32 s62, s34, 0x160000
	v_lshl_add_u64 v[214:215], s[34:35], 0, v[136:137]
	s_addc_u32 s63, s35, 0
	s_add_i32 s82, s76, s52
	global_load_lds_dwordx4 v[214:215], off
	v_lshl_add_u64 v[222:223], s[62:63], 0, v[132:133]
	s_mov_b32 m0, s82
	v_lshl_add_u64 v[224:225], s[74:75], 0, v[134:135]
	global_load_lds_dwordx4 v[222:223], off
	v_lshl_add_u64 v[222:223], s[62:63], 0, v[136:137]
	s_add_i32 m0, s82, 0x2000
	s_nop 0
	global_load_lds_dwordx4 v[222:223], off
	v_lshl_add_u64 v[222:223], s[74:75], 0, v[130:131]
	s_mov_b32 m0, s53
	s_nop 0
	global_load_lds_dwordx4 v[222:223], off
	s_mov_b32 m0, s54
	s_nop 0
	global_load_lds_dwordx4 v[224:225], off
	s_waitcnt vmcnt(8)
	s_waitcnt lgkmcnt(0)
	s_barrier
	s_setprio 1
	s_waitcnt lgkmcnt(0)
	v_mfma_f32_16x16x32_bf16 v[62:65], v[146:149], v[186:189], v[62:65]
	v_mfma_f32_16x16x32_bf16 v[50:53], v[162:165], v[194:197], v[50:53]
	v_mfma_f32_16x16x32_bf16 v[30:33], v[146:149], v[202:205], v[30:33]
	v_mfma_f32_16x16x32_bf16 v[18:21], v[162:165], v[210:213], v[18:21]
	v_mfma_f32_16x16x32_bf16 v[54:57], v[146:149], v[194:197], v[54:57]
	v_mfma_f32_16x16x32_bf16 v[58:61], v[162:165], v[186:189], v[58:61]
	v_mfma_f32_16x16x32_bf16 v[22:25], v[146:149], v[210:213], v[22:25]
	v_mfma_f32_16x16x32_bf16 v[26:29], v[162:165], v[202:205], v[26:29]
	v_mfma_f32_16x16x32_bf16 v[62:65], v[158:161], v[190:193], v[62:65]
	v_mfma_f32_16x16x32_bf16 v[50:53], v[166:169], v[198:201], v[50:53]
	v_mfma_f32_16x16x32_bf16 v[30:33], v[158:161], v[206:209], v[30:33]
	v_mfma_f32_16x16x32_bf16 v[18:21], v[166:169], v[218:221], v[18:21]
	v_mfma_f32_16x16x32_bf16 v[54:57], v[158:161], v[198:201], v[54:57]
	v_mfma_f32_16x16x32_bf16 v[58:61], v[166:169], v[190:193], v[58:61]
	v_mfma_f32_16x16x32_bf16 v[22:25], v[158:161], v[218:221], v[22:25]
	v_mfma_f32_16x16x32_bf16 v[26:29], v[166:169], v[206:209], v[26:29]
	s_setprio 0
	s_setprio 1
	v_mfma_f32_16x16x32_bf16 v[46:49], v[170:173], v[186:189], v[46:49]
	v_mfma_f32_16x16x32_bf16 v[34:37], v[178:181], v[194:197], v[34:37]
	v_mfma_f32_16x16x32_bf16 v[14:17], v[170:173], v[202:205], v[14:17]
	v_mfma_f32_16x16x32_bf16 v[2:5], v[178:181], v[210:213], v[2:5]
	v_mfma_f32_16x16x32_bf16 v[38:41], v[170:173], v[194:197], v[38:41]
	v_mfma_f32_16x16x32_bf16 v[42:45], v[178:181], v[186:189], v[42:45]
	v_mfma_f32_16x16x32_bf16 v[6:9], v[170:173], v[210:213], v[6:9]
	v_mfma_f32_16x16x32_bf16 v[10:13], v[178:181], v[202:205], v[10:13]
	v_mfma_f32_16x16x32_bf16 v[46:49], v[174:177], v[190:193], v[46:49]
	v_mfma_f32_16x16x32_bf16 v[34:37], v[182:185], v[198:201], v[34:37]
	v_mfma_f32_16x16x32_bf16 v[14:17], v[174:177], v[206:209], v[14:17]
	v_mfma_f32_16x16x32_bf16 v[2:5], v[182:185], v[218:221], v[2:5]
	v_mfma_f32_16x16x32_bf16 v[38:41], v[174:177], v[198:201], v[38:41]
	v_mfma_f32_16x16x32_bf16 v[42:45], v[182:185], v[190:193], v[42:45]
	v_mfma_f32_16x16x32_bf16 v[6:9], v[174:177], v[218:221], v[6:9]
	v_mfma_f32_16x16x32_bf16 v[10:13], v[182:185], v[206:209], v[10:13]
	s_setprio 0
	s_barrier
	s_add_i32 s82, 0, 0x18000
	v_add_u32_e32 v157, s82, v152
	s_add_i32 s83, 0, 0x1c000
	ds_read_b128 v[146:149], v157
	ds_read_b128 v[158:161], v157 offset:1024
	ds_read_b128 v[162:165], v157 offset:2048
	ds_read_b128 v[166:169], v157 offset:3072
	v_add_u32_e32 v157, s83, v152
	ds_read_b128 v[170:173], v157
	ds_read_b128 v[174:177], v157 offset:1024
	ds_read_b128 v[178:181], v157 offset:2048
	ds_read_b128 v[182:185], v157 offset:3072
	s_add_u32 s62, s74, 0x160000
	s_addc_u32 s63, s75, 0
	s_mov_b32 m0, s55
	v_lshl_add_u64 v[226:227], s[62:63], 0, v[130:131]
	ds_read_b128 v[186:189], v156 offset:32768
	ds_read_b128 v[190:193], v156 offset:33792
	ds_read_b128 v[194:197], v156 offset:34816
	ds_read_b128 v[198:201], v156 offset:35840
	ds_read_b128 v[202:205], v156 offset:36864
	ds_read_b128 v[206:209], v156 offset:37888
	ds_read_b128 v[210:213], v156 offset:38912
	ds_read_b128 v[218:221], v156 offset:39936
	global_load_lds_dwordx4 v[226:227], off
	v_lshl_add_u64 v[226:227], s[62:63], 0, v[134:135]
	s_mov_b32 m0, s56
	s_nop 0
	global_load_lds_dwordx4 v[226:227], off
	s_waitcnt vmcnt(8)
	s_waitcnt lgkmcnt(0)
	s_barrier
	s_setprio 1
	s_waitcnt lgkmcnt(0)
	v_mfma_f32_16x16x32_bf16 v[126:129], v[146:149], v[186:189], v[126:129]
	v_mfma_f32_16x16x32_bf16 v[114:117], v[162:165], v[194:197], v[114:117]
	v_mfma_f32_16x16x32_bf16 v[94:97], v[146:149], v[202:205], v[94:97]
	v_mfma_f32_16x16x32_bf16 v[82:85], v[162:165], v[210:213], v[82:85]
	v_mfma_f32_16x16x32_bf16 v[118:121], v[146:149], v[194:197], v[118:121]
	v_mfma_f32_16x16x32_bf16 v[122:125], v[162:165], v[186:189], v[122:125]
	v_mfma_f32_16x16x32_bf16 v[86:89], v[146:149], v[210:213], v[86:89]
	v_mfma_f32_16x16x32_bf16 v[90:93], v[162:165], v[202:205], v[90:93]
	v_mfma_f32_16x16x32_bf16 v[126:129], v[158:161], v[190:193], v[126:129]
	v_mfma_f32_16x16x32_bf16 v[114:117], v[166:169], v[198:201], v[114:117]
	v_mfma_f32_16x16x32_bf16 v[94:97], v[158:161], v[206:209], v[94:97]
	v_mfma_f32_16x16x32_bf16 v[82:85], v[166:169], v[218:221], v[82:85]
	v_mfma_f32_16x16x32_bf16 v[118:121], v[158:161], v[198:201], v[118:121]
	v_mfma_f32_16x16x32_bf16 v[122:125], v[166:169], v[190:193], v[122:125]
	v_mfma_f32_16x16x32_bf16 v[86:89], v[158:161], v[218:221], v[86:89]
	v_mfma_f32_16x16x32_bf16 v[90:93], v[166:169], v[206:209], v[90:93]
	s_setprio 0
	s_setprio 1
	v_mfma_f32_16x16x32_bf16 v[110:113], v[170:173], v[186:189], v[110:113]
	v_mfma_f32_16x16x32_bf16 v[98:101], v[178:181], v[194:197], v[98:101]
	v_mfma_f32_16x16x32_bf16 v[78:81], v[170:173], v[202:205], v[78:81]
	v_mfma_f32_16x16x32_bf16 v[66:69], v[178:181], v[210:213], v[66:69]
	v_mfma_f32_16x16x32_bf16 v[102:105], v[170:173], v[194:197], v[102:105]
	v_mfma_f32_16x16x32_bf16 v[106:109], v[178:181], v[186:189], v[106:109]
	v_mfma_f32_16x16x32_bf16 v[70:73], v[170:173], v[210:213], v[70:73]
	v_mfma_f32_16x16x32_bf16 v[74:77], v[178:181], v[202:205], v[74:77]
	v_mfma_f32_16x16x32_bf16 v[110:113], v[174:177], v[190:193], v[110:113]
	v_mfma_f32_16x16x32_bf16 v[98:101], v[182:185], v[198:201], v[98:101]
	v_mfma_f32_16x16x32_bf16 v[78:81], v[174:177], v[206:209], v[78:81]
	v_mfma_f32_16x16x32_bf16 v[66:69], v[182:185], v[218:221], v[66:69]
	v_mfma_f32_16x16x32_bf16 v[102:105], v[174:177], v[198:201], v[102:105]
	v_mfma_f32_16x16x32_bf16 v[106:109], v[182:185], v[190:193], v[106:109]
	v_mfma_f32_16x16x32_bf16 v[70:73], v[174:177], v[218:221], v[70:73]
	v_mfma_f32_16x16x32_bf16 v[74:77], v[182:185], v[206:209], v[74:77]
	s_setprio 0
	s_barrier
	s_add_i32 s62, s82, s52
	v_lshl_add_u64 v[150:151], v[150:151], 0, s[66:67]
	s_mov_b32 m0, s62
	ds_read_b128 v[186:189], v156 offset:49152
	ds_read_b128 v[190:193], v156 offset:50176
	ds_read_b128 v[194:197], v156 offset:51200
	ds_read_b128 v[198:201], v156 offset:52224
	ds_read_b128 v[202:205], v156 offset:53248
	ds_read_b128 v[206:209], v156 offset:54272
	ds_read_b128 v[210:213], v156 offset:55296
	ds_read_b128 v[218:221], v156 offset:56320
	global_load_lds_dwordx4 v[150:151], off
	s_add_i32 m0, s62, 0x2000
	s_add_u32 s34, s34, 0x160080
	v_lshl_add_u64 v[150:151], v[214:215], 0, s[66:67]
	s_addc_u32 s35, s35, 0
	s_add_i32 s62, s83, s52
	global_load_lds_dwordx4 v[150:151], off
	v_lshl_add_u64 v[150:151], s[34:35], 0, v[132:133]
	s_mov_b32 m0, s62
	s_nop 0
	global_load_lds_dwordx4 v[150:151], off
	v_lshl_add_u64 v[150:151], s[34:35], 0, v[136:137]
	s_add_i32 m0, s62, 0x2000
	s_nop 0
	global_load_lds_dwordx4 v[150:151], off
	v_lshl_add_u64 v[150:151], v[222:223], 0, s[66:67]
	s_mov_b32 m0, s58
	s_nop 0
	global_load_lds_dwordx4 v[150:151], off
	v_lshl_add_u64 v[150:151], v[224:225], 0, s[66:67]
	s_mov_b32 m0, s59
	s_nop 0
	global_load_lds_dwordx4 v[150:151], off
	s_waitcnt vmcnt(8)
	s_waitcnt lgkmcnt(0)
	s_barrier
	s_setprio 1
	s_waitcnt lgkmcnt(0)
	v_mfma_f32_16x16x32_bf16 v[62:65], v[146:149], v[186:189], v[62:65]
	v_mfma_f32_16x16x32_bf16 v[50:53], v[162:165], v[194:197], v[50:53]
	v_mfma_f32_16x16x32_bf16 v[30:33], v[146:149], v[202:205], v[30:33]
	v_mfma_f32_16x16x32_bf16 v[18:21], v[162:165], v[210:213], v[18:21]
	v_mfma_f32_16x16x32_bf16 v[54:57], v[146:149], v[194:197], v[54:57]
	v_mfma_f32_16x16x32_bf16 v[58:61], v[162:165], v[186:189], v[58:61]
	v_mfma_f32_16x16x32_bf16 v[22:25], v[146:149], v[210:213], v[22:25]
	v_mfma_f32_16x16x32_bf16 v[26:29], v[162:165], v[202:205], v[26:29]
	v_mfma_f32_16x16x32_bf16 v[62:65], v[158:161], v[190:193], v[62:65]
	v_mfma_f32_16x16x32_bf16 v[50:53], v[166:169], v[198:201], v[50:53]
	v_mfma_f32_16x16x32_bf16 v[30:33], v[158:161], v[206:209], v[30:33]
	v_mfma_f32_16x16x32_bf16 v[18:21], v[166:169], v[218:221], v[18:21]
	v_mfma_f32_16x16x32_bf16 v[54:57], v[158:161], v[198:201], v[54:57]
	v_mfma_f32_16x16x32_bf16 v[58:61], v[166:169], v[190:193], v[58:61]
	v_mfma_f32_16x16x32_bf16 v[22:25], v[158:161], v[218:221], v[22:25]
	v_mfma_f32_16x16x32_bf16 v[26:29], v[166:169], v[206:209], v[26:29]
	s_setprio 0
	s_setprio 1
	v_mfma_f32_16x16x32_bf16 v[46:49], v[170:173], v[186:189], v[46:49]
	v_mfma_f32_16x16x32_bf16 v[34:37], v[178:181], v[194:197], v[34:37]
	v_mfma_f32_16x16x32_bf16 v[14:17], v[170:173], v[202:205], v[14:17]
	v_mfma_f32_16x16x32_bf16 v[2:5], v[178:181], v[210:213], v[2:5]
	v_mfma_f32_16x16x32_bf16 v[38:41], v[170:173], v[194:197], v[38:41]
	v_mfma_f32_16x16x32_bf16 v[42:45], v[178:181], v[186:189], v[42:45]
	v_mfma_f32_16x16x32_bf16 v[6:9], v[170:173], v[210:213], v[6:9]
	v_mfma_f32_16x16x32_bf16 v[10:13], v[178:181], v[202:205], v[10:13]
	v_mfma_f32_16x16x32_bf16 v[46:49], v[174:177], v[190:193], v[46:49]
	v_mfma_f32_16x16x32_bf16 v[34:37], v[182:185], v[198:201], v[34:37]
	v_mfma_f32_16x16x32_bf16 v[14:17], v[174:177], v[206:209], v[14:17]
	v_mfma_f32_16x16x32_bf16 v[2:5], v[182:185], v[218:221], v[2:5]
	v_mfma_f32_16x16x32_bf16 v[38:41], v[174:177], v[198:201], v[38:41]
	v_mfma_f32_16x16x32_bf16 v[42:45], v[182:185], v[190:193], v[42:45]
	v_mfma_f32_16x16x32_bf16 v[6:9], v[174:177], v[218:221], v[6:9]
	v_mfma_f32_16x16x32_bf16 v[10:13], v[182:185], v[206:209], v[10:13]
	s_setprio 0
	s_barrier
	s_add_i32 s81, s81, 2
	s_add_u32 s72, s72, 0x100
	s_addc_u32 s73, s73, 0
	s_add_u32 s0, s0, 0x100
	s_addc_u32 s1, s1, 0
	s_cmpk_gt_u32 s81, 0x55
	s_cbranch_scc0 .LBB0_387
	s_and_b64 vcc, exec, s[68:69]
	s_cbranch_vccz .LBB0_390
	s_barrier

.LBB0_518:
	ds_read_b128 v[160:163], v155
	ds_read_b128 v[164:167], v155 offset:1024
	ds_read_b128 v[168:171], v155 offset:2048
	ds_read_b128 v[172:175], v155 offset:3072
	ds_read_b128 v[176:179], v156
	ds_read_b128 v[180:183], v156 offset:1024
	ds_read_b128 v[184:187], v156 offset:2048
	ds_read_b128 v[188:191], v156 offset:3072
	s_add_u32 s34, s90, 0xfff80080
	s_addc_u32 s35, s91, -1
	s_cmp_eq_u32 s83, 28
	s_cselect_b32 s93, s0, s35
	s_cselect_b32 s92, s1, s34
	s_cselect_b32 s35, s7, s68
	s_cselect_b32 s34, s9, s52
	v_lshl_add_u64 v[152:153], s[90:91], 0, v[144:145]
	s_add_i32 m0, s56, 0xc000
	ds_read_b128 v[192:195], v157
	ds_read_b128 v[196:199], v157 offset:1024
	ds_read_b128 v[200:203], v157 offset:2048
	ds_read_b128 v[204:207], v157 offset:3072
	ds_read_b128 v[208:211], v157 offset:4096
	ds_read_b128 v[212:215], v157 offset:5120
	ds_read_b128 v[218:221], v157 offset:6144
	ds_read_b128 v[222:225], v157 offset:7168
	global_load_lds_dwordx4 v[152:153], off
	v_lshl_add_u64 v[152:153], s[90:91], 0, v[146:147]
	s_add_i32 m0, s56, 0xe000
	s_nop 0
	global_load_lds_dwordx4 v[152:153], off
	s_waitcnt vmcnt(8)
	s_waitcnt lgkmcnt(0)
	s_barrier
	s_setprio 1
	s_waitcnt lgkmcnt(0)
	v_mfma_f32_16x16x32_bf16 v[126:129], v[160:163], v[192:195], v[126:129]
	v_mfma_f32_16x16x32_bf16 v[106:109], v[168:171], v[200:203], v[106:109]
	v_mfma_f32_16x16x32_bf16 v[94:97], v[160:163], v[208:211], v[94:97]
	v_mfma_f32_16x16x32_bf16 v[74:77], v[168:171], v[218:221], v[74:77]
	v_mfma_f32_16x16x32_bf16 v[110:113], v[160:163], v[200:203], v[110:113]
	v_mfma_f32_16x16x32_bf16 v[122:125], v[168:171], v[192:195], v[122:125]
	v_mfma_f32_16x16x32_bf16 v[78:81], v[160:163], v[218:221], v[78:81]
	v_mfma_f32_16x16x32_bf16 v[90:93], v[168:171], v[208:211], v[90:93]
	v_mfma_f32_16x16x32_bf16 v[126:129], v[164:167], v[196:199], v[126:129]
	v_mfma_f32_16x16x32_bf16 v[106:109], v[172:175], v[204:207], v[106:109]
	v_mfma_f32_16x16x32_bf16 v[94:97], v[164:167], v[212:215], v[94:97]
	v_mfma_f32_16x16x32_bf16 v[74:77], v[172:175], v[222:225], v[74:77]
	v_mfma_f32_16x16x32_bf16 v[110:113], v[164:167], v[204:207], v[110:113]
	v_mfma_f32_16x16x32_bf16 v[122:125], v[172:175], v[196:199], v[122:125]
	v_mfma_f32_16x16x32_bf16 v[78:81], v[164:167], v[222:225], v[78:81]
	v_mfma_f32_16x16x32_bf16 v[90:93], v[172:175], v[212:215], v[90:93]
	s_setprio 0
	s_setprio 1
	v_mfma_f32_16x16x32_bf16 v[118:121], v[176:179], v[192:195], v[118:121]
	v_mfma_f32_16x16x32_bf16 v[98:101], v[184:187], v[200:203], v[98:101]
	v_mfma_f32_16x16x32_bf16 v[86:89], v[176:179], v[208:211], v[86:89]
	v_mfma_f32_16x16x32_bf16 v[66:69], v[184:187], v[218:221], v[66:69]
	v_mfma_f32_16x16x32_bf16 v[102:105], v[176:179], v[200:203], v[102:105]
	v_mfma_f32_16x16x32_bf16 v[114:117], v[184:187], v[192:195], v[114:117]
	v_mfma_f32_16x16x32_bf16 v[70:73], v[176:179], v[218:221], v[70:73]
	v_mfma_f32_16x16x32_bf16 v[82:85], v[184:187], v[208:211], v[82:85]
	v_mfma_f32_16x16x32_bf16 v[118:121], v[180:183], v[196:199], v[118:121]
	v_mfma_f32_16x16x32_bf16 v[98:101], v[188:191], v[204:207], v[98:101]
	v_mfma_f32_16x16x32_bf16 v[86:89], v[180:183], v[212:215], v[86:89]
	v_mfma_f32_16x16x32_bf16 v[66:69], v[188:191], v[222:225], v[66:69]
	v_mfma_f32_16x16x32_bf16 v[102:105], v[180:183], v[204:207], v[102:105]
	v_mfma_f32_16x16x32_bf16 v[114:117], v[188:191], v[196:199], v[114:117]
	v_mfma_f32_16x16x32_bf16 v[70:73], v[180:183], v[222:225], v[70:73]
	v_mfma_f32_16x16x32_bf16 v[82:85], v[188:191], v[212:215], v[82:85]
	s_setprio 0
	s_barrier
	s_add_i32 s53, s75, s30
	v_lshl_add_u64 v[152:153], s[34:35], 0, v[132:133]
	s_mov_b32 m0, s53
	ds_read_b128 v[192:195], v157 offset:16384
	ds_read_b128 v[196:199], v157 offset:17408
	ds_read_b128 v[200:203], v157 offset:18432
	ds_read_b128 v[204:207], v157 offset:19456
	ds_read_b128 v[208:211], v157 offset:20480
	ds_read_b128 v[212:215], v157 offset:21504
	ds_read_b128 v[218:221], v157 offset:22528
	ds_read_b128 v[222:225], v157 offset:23552
	global_load_lds_dwordx4 v[152:153], off
	s_add_i32 m0, s53, 0x2000
	s_add_u32 s54, s34, 0x80000
	v_lshl_add_u64 v[226:227], s[34:35], 0, v[136:137]
	s_addc_u32 s55, s35, 0
	s_add_i32 s53, s94, s30
	global_load_lds_dwordx4 v[226:227], off
	v_lshl_add_u64 v[228:229], s[54:55], 0, v[132:133]
	s_mov_b32 m0, s53
	v_lshl_add_u64 v[230:231], s[92:93], 0, v[134:135]
	global_load_lds_dwordx4 v[228:229], off
	v_lshl_add_u64 v[228:229], s[54:55], 0, v[136:137]
	s_add_i32 m0, s53, 0x2000
	s_nop 0
	global_load_lds_dwordx4 v[228:229], off
	v_lshl_add_u64 v[228:229], s[92:93], 0, v[130:131]
	s_mov_b32 m0, s56
	s_nop 0
	global_load_lds_dwordx4 v[228:229], off
	s_mov_b32 m0, s57
	s_nop 0
	global_load_lds_dwordx4 v[230:231], off
	s_waitcnt vmcnt(8)
	s_waitcnt lgkmcnt(0)
	s_barrier
	s_setprio 1
	s_waitcnt lgkmcnt(0)
	v_mfma_f32_16x16x32_bf16 v[62:65], v[160:163], v[192:195], v[62:65]
	v_mfma_f32_16x16x32_bf16 v[42:45], v[168:171], v[200:203], v[42:45]
	v_mfma_f32_16x16x32_bf16 v[30:33], v[160:163], v[208:211], v[30:33]
	v_mfma_f32_16x16x32_bf16 v[10:13], v[168:171], v[218:221], v[10:13]
	v_mfma_f32_16x16x32_bf16 v[46:49], v[160:163], v[200:203], v[46:49]
	v_mfma_f32_16x16x32_bf16 v[58:61], v[168:171], v[192:195], v[58:61]
	v_mfma_f32_16x16x32_bf16 v[14:17], v[160:163], v[218:221], v[14:17]
	v_mfma_f32_16x16x32_bf16 v[26:29], v[168:171], v[208:211], v[26:29]
	v_mfma_f32_16x16x32_bf16 v[62:65], v[164:167], v[196:199], v[62:65]
	v_mfma_f32_16x16x32_bf16 v[42:45], v[172:175], v[204:207], v[42:45]
	v_mfma_f32_16x16x32_bf16 v[30:33], v[164:167], v[212:215], v[30:33]
	v_mfma_f32_16x16x32_bf16 v[10:13], v[172:175], v[222:225], v[10:13]
	v_mfma_f32_16x16x32_bf16 v[46:49], v[164:167], v[204:207], v[46:49]
	v_mfma_f32_16x16x32_bf16 v[58:61], v[172:175], v[196:199], v[58:61]
	v_mfma_f32_16x16x32_bf16 v[14:17], v[164:167], v[222:225], v[14:17]
	v_mfma_f32_16x16x32_bf16 v[26:29], v[172:175], v[212:215], v[26:29]
	s_setprio 0
	s_setprio 1
	v_mfma_f32_16x16x32_bf16 v[54:57], v[176:179], v[192:195], v[54:57]
	v_mfma_f32_16x16x32_bf16 v[34:37], v[184:187], v[200:203], v[34:37]
	v_mfma_f32_16x16x32_bf16 v[22:25], v[176:179], v[208:211], v[22:25]
	v_mfma_f32_16x16x32_bf16 v[2:5], v[184:187], v[218:221], v[2:5]
	v_mfma_f32_16x16x32_bf16 v[38:41], v[176:179], v[200:203], v[38:41]
	v_mfma_f32_16x16x32_bf16 v[50:53], v[184:187], v[192:195], v[50:53]
	v_mfma_f32_16x16x32_bf16 v[6:9], v[176:179], v[218:221], v[6:9]
	v_mfma_f32_16x16x32_bf16 v[18:21], v[184:187], v[208:211], v[18:21]
	v_mfma_f32_16x16x32_bf16 v[54:57], v[180:183], v[196:199], v[54:57]
	v_mfma_f32_16x16x32_bf16 v[34:37], v[188:191], v[204:207], v[34:37]
	v_mfma_f32_16x16x32_bf16 v[22:25], v[180:183], v[212:215], v[22:25]
	v_mfma_f32_16x16x32_bf16 v[2:5], v[188:191], v[222:225], v[2:5]
	v_mfma_f32_16x16x32_bf16 v[38:41], v[180:183], v[204:207], v[38:41]
	v_mfma_f32_16x16x32_bf16 v[50:53], v[188:191], v[196:199], v[50:53]
	v_mfma_f32_16x16x32_bf16 v[6:9], v[180:183], v[222:225], v[6:9]
	v_mfma_f32_16x16x32_bf16 v[18:21], v[188:191], v[212:215], v[18:21]
	s_setprio 0
	s_barrier
	s_add_i32 s53, 0, 0x18000
	v_add_u32_e32 v138, s53, v154
	s_add_i32 s62, 0, 0x1c000
	ds_read_b128 v[160:163], v138
	ds_read_b128 v[164:167], v138 offset:1024
	ds_read_b128 v[168:171], v138 offset:2048
	ds_read_b128 v[172:175], v138 offset:3072
	v_add_u32_e32 v138, s62, v154
	ds_read_b128 v[176:179], v138
	ds_read_b128 v[180:183], v138 offset:1024
	ds_read_b128 v[184:187], v138 offset:2048
	ds_read_b128 v[188:191], v138 offset:3072
	s_add_u32 s54, s92, 0x80000
	s_addc_u32 s55, s93, 0
	s_mov_b32 m0, s58
	v_lshl_add_u64 v[232:233], s[54:55], 0, v[130:131]
	ds_read_b128 v[192:195], v157 offset:32768
	ds_read_b128 v[196:199], v157 offset:33792
	ds_read_b128 v[200:203], v157 offset:34816
	ds_read_b128 v[204:207], v157 offset:35840
	ds_read_b128 v[208:211], v157 offset:36864
	ds_read_b128 v[212:215], v157 offset:37888
	ds_read_b128 v[218:221], v157 offset:38912
	ds_read_b128 v[222:225], v157 offset:39936
	global_load_lds_dwordx4 v[232:233], off
	v_lshl_add_u64 v[232:233], s[54:55], 0, v[134:135]
	s_mov_b32 m0, s59
	s_nop 0
	global_load_lds_dwordx4 v[232:233], off
	s_waitcnt vmcnt(8)
	s_waitcnt lgkmcnt(0)
	s_barrier
	s_setprio 1
	s_waitcnt lgkmcnt(0)
	v_mfma_f32_16x16x32_bf16 v[126:129], v[160:163], v[192:195], v[126:129]
	v_mfma_f32_16x16x32_bf16 v[106:109], v[168:171], v[200:203], v[106:109]
	v_mfma_f32_16x16x32_bf16 v[94:97], v[160:163], v[208:211], v[94:97]
	v_mfma_f32_16x16x32_bf16 v[74:77], v[168:171], v[218:221], v[74:77]
	v_mfma_f32_16x16x32_bf16 v[110:113], v[160:163], v[200:203], v[110:113]
	v_mfma_f32_16x16x32_bf16 v[122:125], v[168:171], v[192:195], v[122:125]
	v_mfma_f32_16x16x32_bf16 v[78:81], v[160:163], v[218:221], v[78:81]
	v_mfma_f32_16x16x32_bf16 v[90:93], v[168:171], v[208:211], v[90:93]
	v_mfma_f32_16x16x32_bf16 v[126:129], v[164:167], v[196:199], v[126:129]
	v_mfma_f32_16x16x32_bf16 v[106:109], v[172:175], v[204:207], v[106:109]
	v_mfma_f32_16x16x32_bf16 v[94:97], v[164:167], v[212:215], v[94:97]
	v_mfma_f32_16x16x32_bf16 v[74:77], v[172:175], v[222:225], v[74:77]
	v_mfma_f32_16x16x32_bf16 v[110:113], v[164:167], v[204:207], v[110:113]
	v_mfma_f32_16x16x32_bf16 v[122:125], v[172:175], v[196:199], v[122:125]
	v_mfma_f32_16x16x32_bf16 v[78:81], v[164:167], v[222:225], v[78:81]
	v_mfma_f32_16x16x32_bf16 v[90:93], v[172:175], v[212:215], v[90:93]
	s_setprio 0
	s_setprio 1
	v_mfma_f32_16x16x32_bf16 v[118:121], v[176:179], v[192:195], v[118:121]
	v_mfma_f32_16x16x32_bf16 v[98:101], v[184:187], v[200:203], v[98:101]
	v_mfma_f32_16x16x32_bf16 v[86:89], v[176:179], v[208:211], v[86:89]
	v_mfma_f32_16x16x32_bf16 v[66:69], v[184:187], v[218:221], v[66:69]
	v_mfma_f32_16x16x32_bf16 v[102:105], v[176:179], v[200:203], v[102:105]
	v_mfma_f32_16x16x32_bf16 v[114:117], v[184:187], v[192:195], v[114:117]
	v_mfma_f32_16x16x32_bf16 v[70:73], v[176:179], v[218:221], v[70:73]
	v_mfma_f32_16x16x32_bf16 v[82:85], v[184:187], v[208:211], v[82:85]
	v_mfma_f32_16x16x32_bf16 v[118:121], v[180:183], v[196:199], v[118:121]
	v_mfma_f32_16x16x32_bf16 v[98:101], v[188:191], v[204:207], v[98:101]
	v_mfma_f32_16x16x32_bf16 v[86:89], v[180:183], v[212:215], v[86:89]
	v_mfma_f32_16x16x32_bf16 v[66:69], v[188:191], v[222:225], v[66:69]
	v_mfma_f32_16x16x32_bf16 v[102:105], v[180:183], v[204:207], v[102:105]
	v_mfma_f32_16x16x32_bf16 v[114:117], v[188:191], v[196:199], v[114:117]
	v_mfma_f32_16x16x32_bf16 v[70:73], v[180:183], v[222:225], v[70:73]
	v_mfma_f32_16x16x32_bf16 v[82:85], v[188:191], v[212:215], v[82:85]
	s_setprio 0
	s_barrier
	s_add_i32 s53, s53, s30
	v_lshl_add_u64 v[152:153], v[152:153], 0, s[76:77]
	s_mov_b32 m0, s53
	ds_read_b128 v[192:195], v157 offset:49152
	ds_read_b128 v[196:199], v157 offset:50176
	ds_read_b128 v[200:203], v157 offset:51200
	ds_read_b128 v[204:207], v157 offset:52224
	ds_read_b128 v[208:211], v157 offset:53248
	ds_read_b128 v[212:215], v157 offset:54272
	ds_read_b128 v[218:221], v157 offset:55296
	ds_read_b128 v[222:225], v157 offset:56320
	global_load_lds_dwordx4 v[152:153], off
	s_add_i32 m0, s53, 0x2000
	s_add_u32 s34, s34, 0x80080
	v_lshl_add_u64 v[152:153], v[226:227], 0, s[76:77]
	s_addc_u32 s35, s35, 0
	s_add_i32 s53, s62, s30
	global_load_lds_dwordx4 v[152:153], off
	v_lshl_add_u64 v[152:153], s[34:35], 0, v[132:133]
	s_mov_b32 m0, s53
	s_nop 0
	global_load_lds_dwordx4 v[152:153], off
	v_lshl_add_u64 v[152:153], s[34:35], 0, v[136:137]
	s_add_i32 m0, s53, 0x2000
	s_nop 0
	global_load_lds_dwordx4 v[152:153], off
	v_lshl_add_u64 v[152:153], v[228:229], 0, s[76:77]
	s_mov_b32 m0, s61
	s_nop 0
	global_load_lds_dwordx4 v[152:153], off
	v_lshl_add_u64 v[152:153], v[230:231], 0, s[76:77]
	s_mov_b32 m0, s72
	s_nop 0
	global_load_lds_dwordx4 v[152:153], off
	s_waitcnt vmcnt(8)
	s_waitcnt lgkmcnt(0)
	s_barrier
	s_setprio 1
	s_waitcnt lgkmcnt(0)
	v_mfma_f32_16x16x32_bf16 v[62:65], v[160:163], v[192:195], v[62:65]
	v_mfma_f32_16x16x32_bf16 v[42:45], v[168:171], v[200:203], v[42:45]
	v_mfma_f32_16x16x32_bf16 v[30:33], v[160:163], v[208:211], v[30:33]
	v_mfma_f32_16x16x32_bf16 v[10:13], v[168:171], v[218:221], v[10:13]
	v_mfma_f32_16x16x32_bf16 v[46:49], v[160:163], v[200:203], v[46:49]
	v_mfma_f32_16x16x32_bf16 v[58:61], v[168:171], v[192:195], v[58:61]
	v_mfma_f32_16x16x32_bf16 v[14:17], v[160:163], v[218:221], v[14:17]
	v_mfma_f32_16x16x32_bf16 v[26:29], v[168:171], v[208:211], v[26:29]
	v_mfma_f32_16x16x32_bf16 v[62:65], v[164:167], v[196:199], v[62:65]
	v_mfma_f32_16x16x32_bf16 v[42:45], v[172:175], v[204:207], v[42:45]
	v_mfma_f32_16x16x32_bf16 v[30:33], v[164:167], v[212:215], v[30:33]
	v_mfma_f32_16x16x32_bf16 v[10:13], v[172:175], v[222:225], v[10:13]
	v_mfma_f32_16x16x32_bf16 v[46:49], v[164:167], v[204:207], v[46:49]
	v_mfma_f32_16x16x32_bf16 v[58:61], v[172:175], v[196:199], v[58:61]
	v_mfma_f32_16x16x32_bf16 v[14:17], v[164:167], v[222:225], v[14:17]
	v_mfma_f32_16x16x32_bf16 v[26:29], v[172:175], v[212:215], v[26:29]
	s_setprio 0
	s_setprio 1
	v_mfma_f32_16x16x32_bf16 v[54:57], v[176:179], v[192:195], v[54:57]
	v_mfma_f32_16x16x32_bf16 v[34:37], v[184:187], v[200:203], v[34:37]
	v_mfma_f32_16x16x32_bf16 v[22:25], v[176:179], v[208:211], v[22:25]
	v_mfma_f32_16x16x32_bf16 v[2:5], v[184:187], v[218:221], v[2:5]
	v_mfma_f32_16x16x32_bf16 v[38:41], v[176:179], v[200:203], v[38:41]
	v_mfma_f32_16x16x32_bf16 v[50:53], v[184:187], v[192:195], v[50:53]
	v_mfma_f32_16x16x32_bf16 v[6:9], v[176:179], v[218:221], v[6:9]
	v_mfma_f32_16x16x32_bf16 v[18:21], v[184:187], v[208:211], v[18:21]
	v_mfma_f32_16x16x32_bf16 v[54:57], v[180:183], v[196:199], v[54:57]
	v_mfma_f32_16x16x32_bf16 v[34:37], v[188:191], v[204:207], v[34:37]
	v_mfma_f32_16x16x32_bf16 v[22:25], v[180:183], v[212:215], v[22:25]
	v_mfma_f32_16x16x32_bf16 v[2:5], v[188:191], v[222:225], v[2:5]
	v_mfma_f32_16x16x32_bf16 v[38:41], v[180:183], v[204:207], v[38:41]
	v_mfma_f32_16x16x32_bf16 v[50:53], v[188:191], v[196:199], v[50:53]
	v_mfma_f32_16x16x32_bf16 v[6:9], v[180:183], v[222:225], v[6:9]
	v_mfma_f32_16x16x32_bf16 v[18:21], v[188:191], v[212:215], v[18:21]
	s_setprio 0
	s_barrier
	s_add_i32 s83, s83, 2
	s_add_u32 s90, s90, 0x100
	s_addc_u32 s91, s91, 0
	s_add_u32 s52, s52, 0x100
	s_addc_u32 s68, s68, 0
	s_cmp_gt_u32 s83, 29
	s_cbranch_scc0 .LBB0_518
	s_and_b64 vcc, exec, s[78:79]
	s_cbranch_vccz .LBB0_521
	s_barrier

.LBB0_685:
	ds_read_b128 v[146:149], v165
	ds_read_b128 v[150:153], v165 offset:1024
	ds_read_b128 v[168:171], v165 offset:2048
	ds_read_b128 v[172:175], v165 offset:3072
	ds_read_b128 v[176:179], v166
	ds_read_b128 v[180:183], v166 offset:1024
	ds_read_b128 v[184:187], v166 offset:2048
	ds_read_b128 v[188:191], v166 offset:3072
	s_add_u32 s34, s84, 0xfffe0080
	s_addc_u32 s35, s85, -1
	s_cmp_eq_u32 s89, 4
	s_cselect_b32 s87, s0, s35
	s_cselect_b32 s86, s1, s34
	s_cselect_b32 s35, s52, s88
	s_cselect_b32 s34, s71, s77
	v_lshl_add_u64 v[226:227], s[84:85], 0, v[138:139]
	s_add_i32 m0, s33, 0xc000
	ds_read_b128 v[192:195], v167
	ds_read_b128 v[196:199], v167 offset:1024
	ds_read_b128 v[200:203], v167 offset:2048
	ds_read_b128 v[204:207], v167 offset:3072
	ds_read_b128 v[208:211], v167 offset:4096
	ds_read_b128 v[212:215], v167 offset:5120
	ds_read_b128 v[218:221], v167 offset:6144
	ds_read_b128 v[222:225], v167 offset:7168
	global_load_lds_dwordx4 v[226:227], off
	v_lshl_add_u64 v[226:227], s[84:85], 0, v[140:141]
	s_add_i32 m0, s33, 0xe000
	s_nop 0
	global_load_lds_dwordx4 v[226:227], off
	s_waitcnt vmcnt(8)
	s_waitcnt lgkmcnt(0)
	s_barrier
	s_setprio 1
	s_waitcnt lgkmcnt(0)
	v_mfma_f32_16x16x32_bf16 v[126:129], v[146:149], v[192:195], v[126:129]
	v_mfma_f32_16x16x32_bf16 v[106:109], v[168:171], v[200:203], v[106:109]
	v_mfma_f32_16x16x32_bf16 v[98:101], v[146:149], v[208:211], v[98:101]
	v_mfma_f32_16x16x32_bf16 v[74:77], v[168:171], v[218:221], v[74:77]
	v_mfma_f32_16x16x32_bf16 v[114:117], v[146:149], v[200:203], v[114:117]
	v_mfma_f32_16x16x32_bf16 v[122:125], v[168:171], v[192:195], v[122:125]
	v_mfma_f32_16x16x32_bf16 v[82:85], v[146:149], v[218:221], v[82:85]
	v_mfma_f32_16x16x32_bf16 v[90:93], v[168:171], v[208:211], v[90:93]
	v_mfma_f32_16x16x32_bf16 v[126:129], v[150:153], v[196:199], v[126:129]
	v_mfma_f32_16x16x32_bf16 v[106:109], v[172:175], v[204:207], v[106:109]
	v_mfma_f32_16x16x32_bf16 v[98:101], v[150:153], v[212:215], v[98:101]
	v_mfma_f32_16x16x32_bf16 v[74:77], v[172:175], v[222:225], v[74:77]
	v_mfma_f32_16x16x32_bf16 v[114:117], v[150:153], v[204:207], v[114:117]
	v_mfma_f32_16x16x32_bf16 v[122:125], v[172:175], v[196:199], v[122:125]
	v_mfma_f32_16x16x32_bf16 v[82:85], v[150:153], v[222:225], v[82:85]
	v_mfma_f32_16x16x32_bf16 v[90:93], v[172:175], v[212:215], v[90:93]
	s_setprio 0
	s_setprio 1
	v_mfma_f32_16x16x32_bf16 v[118:121], v[176:179], v[192:195], v[118:121]
	v_mfma_f32_16x16x32_bf16 v[94:97], v[184:187], v[200:203], v[94:97]
	v_mfma_f32_16x16x32_bf16 v[86:89], v[176:179], v[208:211], v[86:89]
	v_mfma_f32_16x16x32_bf16 v[66:69], v[184:187], v[218:221], v[66:69]
	v_mfma_f32_16x16x32_bf16 v[102:105], v[176:179], v[200:203], v[102:105]
	v_mfma_f32_16x16x32_bf16 v[110:113], v[184:187], v[192:195], v[110:113]
	v_mfma_f32_16x16x32_bf16 v[70:73], v[176:179], v[218:221], v[70:73]
	v_mfma_f32_16x16x32_bf16 v[78:81], v[184:187], v[208:211], v[78:81]
	v_mfma_f32_16x16x32_bf16 v[118:121], v[180:183], v[196:199], v[118:121]
	v_mfma_f32_16x16x32_bf16 v[94:97], v[188:191], v[204:207], v[94:97]
	v_mfma_f32_16x16x32_bf16 v[86:89], v[180:183], v[212:215], v[86:89]
	v_mfma_f32_16x16x32_bf16 v[66:69], v[188:191], v[222:225], v[66:69]
	v_mfma_f32_16x16x32_bf16 v[102:105], v[180:183], v[204:207], v[102:105]
	v_mfma_f32_16x16x32_bf16 v[110:113], v[188:191], v[196:199], v[110:113]
	v_mfma_f32_16x16x32_bf16 v[70:73], v[180:183], v[222:225], v[70:73]
	v_mfma_f32_16x16x32_bf16 v[78:81], v[188:191], v[212:215], v[78:81]
	s_setprio 0
	s_barrier
	s_add_i32 s53, s73, s12
	v_lshl_add_u64 v[226:227], s[34:35], 0, v[132:133]
	s_mov_b32 m0, s53
	ds_read_b128 v[192:195], v167 offset:16384
	ds_read_b128 v[196:199], v167 offset:17408
	ds_read_b128 v[200:203], v167 offset:18432
	ds_read_b128 v[204:207], v167 offset:19456
	ds_read_b128 v[208:211], v167 offset:20480
	ds_read_b128 v[212:215], v167 offset:21504
	ds_read_b128 v[218:221], v167 offset:22528
	ds_read_b128 v[222:225], v167 offset:23552
	global_load_lds_dwordx4 v[226:227], off
	s_add_i32 m0, s53, 0x2000
	s_add_u32 s54, s34, 0x20000
	v_lshl_add_u64 v[228:229], s[34:35], 0, v[136:137]
	s_addc_u32 s55, s35, 0
	s_add_i32 s53, s74, s12
	global_load_lds_dwordx4 v[228:229], off
	v_lshl_add_u64 v[230:231], s[54:55], 0, v[132:133]
	s_mov_b32 m0, s53
	v_lshl_add_u64 v[232:233], s[86:87], 0, v[134:135]
	global_load_lds_dwordx4 v[230:231], off
	v_lshl_add_u64 v[230:231], s[54:55], 0, v[136:137]
	s_add_i32 m0, s53, 0x2000
	s_nop 0
	global_load_lds_dwordx4 v[230:231], off
	v_lshl_add_u64 v[230:231], s[86:87], 0, v[130:131]
	s_mov_b32 m0, s33
	s_nop 0
	global_load_lds_dwordx4 v[230:231], off
	s_mov_b32 m0, s56
	s_nop 0
	global_load_lds_dwordx4 v[232:233], off
	s_waitcnt vmcnt(8)
	s_waitcnt lgkmcnt(0)
	s_barrier
	s_setprio 1
	s_waitcnt lgkmcnt(0)
	v_mfma_f32_16x16x32_bf16 v[62:65], v[146:149], v[192:195], v[62:65]
	v_mfma_f32_16x16x32_bf16 v[42:45], v[168:171], v[200:203], v[42:45]
	v_mfma_f32_16x16x32_bf16 v[34:37], v[146:149], v[208:211], v[34:37]
	v_mfma_f32_16x16x32_bf16 v[10:13], v[168:171], v[218:221], v[10:13]
	v_mfma_f32_16x16x32_bf16 v[50:53], v[146:149], v[200:203], v[50:53]
	v_mfma_f32_16x16x32_bf16 v[58:61], v[168:171], v[192:195], v[58:61]
	v_mfma_f32_16x16x32_bf16 v[18:21], v[146:149], v[218:221], v[18:21]
	v_mfma_f32_16x16x32_bf16 v[26:29], v[168:171], v[208:211], v[26:29]
	v_mfma_f32_16x16x32_bf16 v[62:65], v[150:153], v[196:199], v[62:65]
	v_mfma_f32_16x16x32_bf16 v[42:45], v[172:175], v[204:207], v[42:45]
	v_mfma_f32_16x16x32_bf16 v[34:37], v[150:153], v[212:215], v[34:37]
	v_mfma_f32_16x16x32_bf16 v[10:13], v[172:175], v[222:225], v[10:13]
	v_mfma_f32_16x16x32_bf16 v[50:53], v[150:153], v[204:207], v[50:53]
	v_mfma_f32_16x16x32_bf16 v[58:61], v[172:175], v[196:199], v[58:61]
	v_mfma_f32_16x16x32_bf16 v[18:21], v[150:153], v[222:225], v[18:21]
	v_mfma_f32_16x16x32_bf16 v[26:29], v[172:175], v[212:215], v[26:29]
	s_setprio 0
	s_setprio 1
	v_mfma_f32_16x16x32_bf16 v[54:57], v[176:179], v[192:195], v[54:57]
	v_mfma_f32_16x16x32_bf16 v[30:33], v[184:187], v[200:203], v[30:33]
	v_mfma_f32_16x16x32_bf16 v[22:25], v[176:179], v[208:211], v[22:25]
	v_mfma_f32_16x16x32_bf16 v[2:5], v[184:187], v[218:221], v[2:5]
	v_mfma_f32_16x16x32_bf16 v[38:41], v[176:179], v[200:203], v[38:41]
	v_mfma_f32_16x16x32_bf16 v[46:49], v[184:187], v[192:195], v[46:49]
	v_mfma_f32_16x16x32_bf16 v[6:9], v[176:179], v[218:221], v[6:9]
	v_mfma_f32_16x16x32_bf16 v[14:17], v[184:187], v[208:211], v[14:17]
	v_mfma_f32_16x16x32_bf16 v[54:57], v[180:183], v[196:199], v[54:57]
	v_mfma_f32_16x16x32_bf16 v[30:33], v[188:191], v[204:207], v[30:33]
	v_mfma_f32_16x16x32_bf16 v[22:25], v[180:183], v[212:215], v[22:25]
	v_mfma_f32_16x16x32_bf16 v[2:5], v[188:191], v[222:225], v[2:5]
	v_mfma_f32_16x16x32_bf16 v[38:41], v[180:183], v[204:207], v[38:41]
	v_mfma_f32_16x16x32_bf16 v[46:49], v[188:191], v[196:199], v[46:49]
	v_mfma_f32_16x16x32_bf16 v[6:9], v[180:183], v[222:225], v[6:9]
	v_mfma_f32_16x16x32_bf16 v[14:17], v[188:191], v[212:215], v[14:17]
	s_setprio 0
	s_barrier
	s_add_i32 s53, 0, 0x18000
	s_add_i32 s62, 0, 0x1c000
	v_add_u32_e32 v172, s53, v162
	v_add_u32_e32 v188, s62, v162
	ds_read_b128 v[146:149], v172
	ds_read_b128 v[150:153], v172 offset:1024
	ds_read_b128 v[168:171], v172 offset:2048
	ds_read_b128 v[172:175], v172 offset:3072
	ds_read_b128 v[176:179], v188
	ds_read_b128 v[180:183], v188 offset:1024
	ds_read_b128 v[184:187], v188 offset:2048
	ds_read_b128 v[188:191], v188 offset:3072
	s_add_u32 s54, s86, 0x20000
	s_addc_u32 s55, s87, 0
	s_mov_b32 m0, s57
	v_lshl_add_u64 v[234:235], s[54:55], 0, v[130:131]
	ds_read_b128 v[192:195], v167 offset:32768
	ds_read_b128 v[196:199], v167 offset:33792
	ds_read_b128 v[200:203], v167 offset:34816
	ds_read_b128 v[204:207], v167 offset:35840
	ds_read_b128 v[208:211], v167 offset:36864
	ds_read_b128 v[212:215], v167 offset:37888
	ds_read_b128 v[218:221], v167 offset:38912
	ds_read_b128 v[222:225], v167 offset:39936
	global_load_lds_dwordx4 v[234:235], off
	v_lshl_add_u64 v[234:235], s[54:55], 0, v[134:135]
	s_mov_b32 m0, s58
	s_nop 0
	global_load_lds_dwordx4 v[234:235], off
	s_waitcnt vmcnt(8)
	s_waitcnt lgkmcnt(0)
	s_barrier
	s_setprio 1
	s_waitcnt lgkmcnt(0)
	v_mfma_f32_16x16x32_bf16 v[126:129], v[146:149], v[192:195], v[126:129]
	v_mfma_f32_16x16x32_bf16 v[106:109], v[168:171], v[200:203], v[106:109]
	v_mfma_f32_16x16x32_bf16 v[98:101], v[146:149], v[208:211], v[98:101]
	v_mfma_f32_16x16x32_bf16 v[74:77], v[168:171], v[218:221], v[74:77]
	v_mfma_f32_16x16x32_bf16 v[114:117], v[146:149], v[200:203], v[114:117]
	v_mfma_f32_16x16x32_bf16 v[122:125], v[168:171], v[192:195], v[122:125]
	v_mfma_f32_16x16x32_bf16 v[82:85], v[146:149], v[218:221], v[82:85]
	v_mfma_f32_16x16x32_bf16 v[90:93], v[168:171], v[208:211], v[90:93]
	v_mfma_f32_16x16x32_bf16 v[126:129], v[150:153], v[196:199], v[126:129]
	v_mfma_f32_16x16x32_bf16 v[106:109], v[172:175], v[204:207], v[106:109]
	v_mfma_f32_16x16x32_bf16 v[98:101], v[150:153], v[212:215], v[98:101]
	v_mfma_f32_16x16x32_bf16 v[74:77], v[172:175], v[222:225], v[74:77]
	v_mfma_f32_16x16x32_bf16 v[114:117], v[150:153], v[204:207], v[114:117]
	v_mfma_f32_16x16x32_bf16 v[122:125], v[172:175], v[196:199], v[122:125]
	v_mfma_f32_16x16x32_bf16 v[82:85], v[150:153], v[222:225], v[82:85]
	v_mfma_f32_16x16x32_bf16 v[90:93], v[172:175], v[212:215], v[90:93]
	s_setprio 0
	s_setprio 1
	v_mfma_f32_16x16x32_bf16 v[118:121], v[176:179], v[192:195], v[118:121]
	v_mfma_f32_16x16x32_bf16 v[94:97], v[184:187], v[200:203], v[94:97]
	v_mfma_f32_16x16x32_bf16 v[86:89], v[176:179], v[208:211], v[86:89]
	v_mfma_f32_16x16x32_bf16 v[66:69], v[184:187], v[218:221], v[66:69]
	v_mfma_f32_16x16x32_bf16 v[102:105], v[176:179], v[200:203], v[102:105]
	v_mfma_f32_16x16x32_bf16 v[110:113], v[184:187], v[192:195], v[110:113]
	v_mfma_f32_16x16x32_bf16 v[70:73], v[176:179], v[218:221], v[70:73]
	v_mfma_f32_16x16x32_bf16 v[78:81], v[184:187], v[208:211], v[78:81]
	v_mfma_f32_16x16x32_bf16 v[118:121], v[180:183], v[196:199], v[118:121]
	v_mfma_f32_16x16x32_bf16 v[94:97], v[188:191], v[204:207], v[94:97]
	v_mfma_f32_16x16x32_bf16 v[86:89], v[180:183], v[212:215], v[86:89]
	v_mfma_f32_16x16x32_bf16 v[66:69], v[188:191], v[222:225], v[66:69]
	v_mfma_f32_16x16x32_bf16 v[102:105], v[180:183], v[204:207], v[102:105]
	v_mfma_f32_16x16x32_bf16 v[110:113], v[188:191], v[196:199], v[110:113]
	v_mfma_f32_16x16x32_bf16 v[70:73], v[180:183], v[222:225], v[70:73]
	v_mfma_f32_16x16x32_bf16 v[78:81], v[188:191], v[212:215], v[78:81]
	s_setprio 0
	s_barrier
	s_add_i32 s53, s53, s12
	v_lshl_add_u64 v[226:227], v[226:227], 0, s[8:9]
	s_mov_b32 m0, s53
	ds_read_b128 v[192:195], v167 offset:49152
	ds_read_b128 v[196:199], v167 offset:50176
	ds_read_b128 v[200:203], v167 offset:51200
	ds_read_b128 v[204:207], v167 offset:52224
	ds_read_b128 v[208:211], v167 offset:53248
	ds_read_b128 v[212:215], v167 offset:54272
	ds_read_b128 v[218:221], v167 offset:55296
	ds_read_b128 v[222:225], v167 offset:56320
	global_load_lds_dwordx4 v[226:227], off
	s_add_i32 m0, s53, 0x2000
	s_add_u32 s34, s34, 0x20080
	v_lshl_add_u64 v[226:227], v[228:229], 0, s[8:9]
	s_addc_u32 s35, s35, 0
	s_add_i32 s53, s62, s12
	global_load_lds_dwordx4 v[226:227], off
	v_lshl_add_u64 v[226:227], s[34:35], 0, v[132:133]
	s_mov_b32 m0, s53
	s_nop 0
	global_load_lds_dwordx4 v[226:227], off
	v_lshl_add_u64 v[226:227], s[34:35], 0, v[136:137]
	s_add_i32 m0, s53, 0x2000
	s_nop 0
	global_load_lds_dwordx4 v[226:227], off
	v_lshl_add_u64 v[226:227], v[230:231], 0, s[8:9]
	s_mov_b32 m0, s60
	s_nop 0
	global_load_lds_dwordx4 v[226:227], off
	v_lshl_add_u64 v[226:227], v[232:233], 0, s[8:9]
	s_mov_b32 m0, s61
	s_nop 0
	global_load_lds_dwordx4 v[226:227], off
	s_waitcnt vmcnt(8)
	s_waitcnt lgkmcnt(0)
	s_barrier
	s_setprio 1
	s_waitcnt lgkmcnt(0)
	v_mfma_f32_16x16x32_bf16 v[62:65], v[146:149], v[192:195], v[62:65]
	v_mfma_f32_16x16x32_bf16 v[42:45], v[168:171], v[200:203], v[42:45]
	v_mfma_f32_16x16x32_bf16 v[34:37], v[146:149], v[208:211], v[34:37]
	v_mfma_f32_16x16x32_bf16 v[10:13], v[168:171], v[218:221], v[10:13]
	v_mfma_f32_16x16x32_bf16 v[50:53], v[146:149], v[200:203], v[50:53]
	v_mfma_f32_16x16x32_bf16 v[58:61], v[168:171], v[192:195], v[58:61]
	v_mfma_f32_16x16x32_bf16 v[18:21], v[146:149], v[218:221], v[18:21]
	v_mfma_f32_16x16x32_bf16 v[26:29], v[168:171], v[208:211], v[26:29]
	v_mfma_f32_16x16x32_bf16 v[62:65], v[150:153], v[196:199], v[62:65]
	v_mfma_f32_16x16x32_bf16 v[42:45], v[172:175], v[204:207], v[42:45]
	v_mfma_f32_16x16x32_bf16 v[34:37], v[150:153], v[212:215], v[34:37]
	v_mfma_f32_16x16x32_bf16 v[10:13], v[172:175], v[222:225], v[10:13]
	v_mfma_f32_16x16x32_bf16 v[50:53], v[150:153], v[204:207], v[50:53]
	v_mfma_f32_16x16x32_bf16 v[58:61], v[172:175], v[196:199], v[58:61]
	v_mfma_f32_16x16x32_bf16 v[18:21], v[150:153], v[222:225], v[18:21]
	v_mfma_f32_16x16x32_bf16 v[26:29], v[172:175], v[212:215], v[26:29]
	s_setprio 0
	s_setprio 1
	v_mfma_f32_16x16x32_bf16 v[54:57], v[176:179], v[192:195], v[54:57]
	v_mfma_f32_16x16x32_bf16 v[30:33], v[184:187], v[200:203], v[30:33]
	v_mfma_f32_16x16x32_bf16 v[22:25], v[176:179], v[208:211], v[22:25]
	v_mfma_f32_16x16x32_bf16 v[2:5], v[184:187], v[218:221], v[2:5]
	v_mfma_f32_16x16x32_bf16 v[38:41], v[176:179], v[200:203], v[38:41]
	v_mfma_f32_16x16x32_bf16 v[46:49], v[184:187], v[192:195], v[46:49]
	v_mfma_f32_16x16x32_bf16 v[6:9], v[176:179], v[218:221], v[6:9]
	v_mfma_f32_16x16x32_bf16 v[14:17], v[184:187], v[208:211], v[14:17]
	v_mfma_f32_16x16x32_bf16 v[54:57], v[180:183], v[196:199], v[54:57]
	v_mfma_f32_16x16x32_bf16 v[30:33], v[188:191], v[204:207], v[30:33]
	v_mfma_f32_16x16x32_bf16 v[22:25], v[180:183], v[212:215], v[22:25]
	v_mfma_f32_16x16x32_bf16 v[2:5], v[188:191], v[222:225], v[2:5]
	v_mfma_f32_16x16x32_bf16 v[38:41], v[180:183], v[204:207], v[38:41]
	v_mfma_f32_16x16x32_bf16 v[46:49], v[188:191], v[196:199], v[46:49]
	v_mfma_f32_16x16x32_bf16 v[6:9], v[180:183], v[222:225], v[6:9]
	v_mfma_f32_16x16x32_bf16 v[14:17], v[188:191], v[212:215], v[14:17]
	s_setprio 0
	s_barrier
	s_add_i32 s89, s89, 2
	s_add_u32 s84, s84, 0x100
	s_addc_u32 s85, s85, 0
	s_add_u32 s77, s77, 0x100
	s_addc_u32 s88, s88, 0
	s_cmp_gt_u32 s89, 5
	s_cbranch_scc0 .LBB0_685
	s_and_b64 vcc, exec, s[66:67]
	s_cbranch_vccz .LBB0_688
	s_barrier

.LBB0_715:
	ds_read_b128 v[146:149], v1
	ds_read_b128 v[160:163], v1 offset:1024
	ds_read_b128 v[164:167], v1 offset:2048
	ds_read_b128 v[168:171], v1 offset:3072
	ds_read_b128 v[172:175], v154
	ds_read_b128 v[176:179], v154 offset:1024
	ds_read_b128 v[180:183], v154 offset:2048
	ds_read_b128 v[184:187], v154 offset:3072
	s_add_u32 s34, s84, 0xfffe0080
	s_addc_u32 s35, s85, -1
	s_cmp_eq_u32 s88, 4
	s_cselect_b32 s87, s0, s35
	s_cselect_b32 s86, s1, s34
	s_cselect_b32 s35, s52, s83
	s_cselect_b32 s34, s71, s77
	v_lshl_add_u64 v[150:151], s[84:85], 0, v[138:139]
	s_add_i32 m0, s33, 0xc000
	ds_read_b128 v[188:191], v155
	ds_read_b128 v[192:195], v155 offset:1024
	ds_read_b128 v[196:199], v155 offset:2048
	ds_read_b128 v[200:203], v155 offset:3072
	ds_read_b128 v[204:207], v155 offset:4096
	ds_read_b128 v[208:211], v155 offset:5120
	ds_read_b128 v[212:215], v155 offset:6144
	ds_read_b128 v[218:221], v155 offset:7168
	global_load_lds_dwordx4 v[150:151], off
	v_lshl_add_u64 v[150:151], s[84:85], 0, v[140:141]
	s_add_i32 m0, s33, 0xe000
	s_nop 0
	global_load_lds_dwordx4 v[150:151], off
	s_waitcnt vmcnt(8)
	s_waitcnt lgkmcnt(0)
	s_barrier
	s_setprio 1
	s_waitcnt lgkmcnt(0)
	v_mfma_f32_16x16x32_bf16 v[126:129], v[146:149], v[188:191], v[126:129]
	v_mfma_f32_16x16x32_bf16 v[106:109], v[164:167], v[196:199], v[106:109]
	v_mfma_f32_16x16x32_bf16 v[94:97], v[146:149], v[204:207], v[94:97]
	v_mfma_f32_16x16x32_bf16 v[74:77], v[164:167], v[212:215], v[74:77]
	v_mfma_f32_16x16x32_bf16 v[110:113], v[146:149], v[196:199], v[110:113]
	v_mfma_f32_16x16x32_bf16 v[122:125], v[164:167], v[188:191], v[122:125]
	v_mfma_f32_16x16x32_bf16 v[78:81], v[146:149], v[212:215], v[78:81]
	v_mfma_f32_16x16x32_bf16 v[90:93], v[164:167], v[204:207], v[90:93]
	v_mfma_f32_16x16x32_bf16 v[126:129], v[160:163], v[192:195], v[126:129]
	v_mfma_f32_16x16x32_bf16 v[106:109], v[168:171], v[200:203], v[106:109]
	v_mfma_f32_16x16x32_bf16 v[94:97], v[160:163], v[208:211], v[94:97]
	v_mfma_f32_16x16x32_bf16 v[74:77], v[168:171], v[218:221], v[74:77]
	v_mfma_f32_16x16x32_bf16 v[110:113], v[160:163], v[200:203], v[110:113]
	v_mfma_f32_16x16x32_bf16 v[122:125], v[168:171], v[192:195], v[122:125]
	v_mfma_f32_16x16x32_bf16 v[78:81], v[160:163], v[218:221], v[78:81]
	v_mfma_f32_16x16x32_bf16 v[90:93], v[168:171], v[208:211], v[90:93]
	s_setprio 0
	s_setprio 1
	v_mfma_f32_16x16x32_bf16 v[118:121], v[172:175], v[188:191], v[118:121]
	v_mfma_f32_16x16x32_bf16 v[98:101], v[180:183], v[196:199], v[98:101]
	v_mfma_f32_16x16x32_bf16 v[86:89], v[172:175], v[204:207], v[86:89]
	v_mfma_f32_16x16x32_bf16 v[66:69], v[180:183], v[212:215], v[66:69]
	v_mfma_f32_16x16x32_bf16 v[102:105], v[172:175], v[196:199], v[102:105]
	v_mfma_f32_16x16x32_bf16 v[114:117], v[180:183], v[188:191], v[114:117]
	v_mfma_f32_16x16x32_bf16 v[70:73], v[172:175], v[212:215], v[70:73]
	v_mfma_f32_16x16x32_bf16 v[82:85], v[180:183], v[204:207], v[82:85]
	v_mfma_f32_16x16x32_bf16 v[118:121], v[176:179], v[192:195], v[118:121]
	v_mfma_f32_16x16x32_bf16 v[98:101], v[184:187], v[200:203], v[98:101]
	v_mfma_f32_16x16x32_bf16 v[86:89], v[176:179], v[208:211], v[86:89]
	v_mfma_f32_16x16x32_bf16 v[66:69], v[184:187], v[218:221], v[66:69]
	v_mfma_f32_16x16x32_bf16 v[102:105], v[176:179], v[200:203], v[102:105]
	v_mfma_f32_16x16x32_bf16 v[114:117], v[184:187], v[192:195], v[114:117]
	v_mfma_f32_16x16x32_bf16 v[70:73], v[176:179], v[218:221], v[70:73]
	v_mfma_f32_16x16x32_bf16 v[82:85], v[184:187], v[208:211], v[82:85]
	s_setprio 0
	s_barrier
	s_add_i32 s53, s73, s13
	v_lshl_add_u64 v[150:151], s[34:35], 0, v[132:133]
	s_mov_b32 m0, s53
	ds_read_b128 v[188:191], v155 offset:16384
	ds_read_b128 v[192:195], v155 offset:17408
	ds_read_b128 v[196:199], v155 offset:18432
	ds_read_b128 v[200:203], v155 offset:19456
	ds_read_b128 v[204:207], v155 offset:20480
	ds_read_b128 v[208:211], v155 offset:21504
	ds_read_b128 v[212:215], v155 offset:22528
	ds_read_b128 v[218:221], v155 offset:23552
	global_load_lds_dwordx4 v[150:151], off
	s_add_i32 m0, s53, 0x2000
	s_add_u32 s54, s34, 0x20000
	v_lshl_add_u64 v[222:223], s[34:35], 0, v[136:137]
	s_addc_u32 s55, s35, 0
	s_add_i32 s53, s74, s13
	global_load_lds_dwordx4 v[222:223], off
	v_lshl_add_u64 v[224:225], s[54:55], 0, v[132:133]
	s_mov_b32 m0, s53
	v_lshl_add_u64 v[226:227], s[86:87], 0, v[134:135]
	global_load_lds_dwordx4 v[224:225], off
	v_lshl_add_u64 v[224:225], s[54:55], 0, v[136:137]
	s_add_i32 m0, s53, 0x2000
	s_nop 0
	global_load_lds_dwordx4 v[224:225], off
	v_lshl_add_u64 v[224:225], s[86:87], 0, v[130:131]
	s_mov_b32 m0, s33
	s_nop 0
	global_load_lds_dwordx4 v[224:225], off
	s_mov_b32 m0, s56
	s_nop 0
	global_load_lds_dwordx4 v[226:227], off
	s_waitcnt vmcnt(8)
	s_waitcnt lgkmcnt(0)
	s_barrier
	s_setprio 1
	s_waitcnt lgkmcnt(0)
	v_mfma_f32_16x16x32_bf16 v[62:65], v[146:149], v[188:191], v[62:65]
	v_mfma_f32_16x16x32_bf16 v[42:45], v[164:167], v[196:199], v[42:45]
	v_mfma_f32_16x16x32_bf16 v[34:37], v[146:149], v[204:207], v[34:37]
	v_mfma_f32_16x16x32_bf16 v[10:13], v[164:167], v[212:215], v[10:13]
	v_mfma_f32_16x16x32_bf16 v[50:53], v[146:149], v[196:199], v[50:53]
	v_mfma_f32_16x16x32_bf16 v[58:61], v[164:167], v[188:191], v[58:61]
	v_mfma_f32_16x16x32_bf16 v[18:21], v[146:149], v[212:215], v[18:21]
	v_mfma_f32_16x16x32_bf16 v[26:29], v[164:167], v[204:207], v[26:29]
	v_mfma_f32_16x16x32_bf16 v[62:65], v[160:163], v[192:195], v[62:65]
	v_mfma_f32_16x16x32_bf16 v[42:45], v[168:171], v[200:203], v[42:45]
	v_mfma_f32_16x16x32_bf16 v[34:37], v[160:163], v[208:211], v[34:37]
	v_mfma_f32_16x16x32_bf16 v[10:13], v[168:171], v[218:221], v[10:13]
	v_mfma_f32_16x16x32_bf16 v[50:53], v[160:163], v[200:203], v[50:53]
	v_mfma_f32_16x16x32_bf16 v[58:61], v[168:171], v[192:195], v[58:61]
	v_mfma_f32_16x16x32_bf16 v[18:21], v[160:163], v[218:221], v[18:21]
	v_mfma_f32_16x16x32_bf16 v[26:29], v[168:171], v[208:211], v[26:29]
	s_setprio 0
	s_setprio 1
	v_mfma_f32_16x16x32_bf16 v[54:57], v[172:175], v[188:191], v[54:57]
	v_mfma_f32_16x16x32_bf16 v[30:33], v[180:183], v[196:199], v[30:33]
	v_mfma_f32_16x16x32_bf16 v[22:25], v[172:175], v[204:207], v[22:25]
	v_mfma_f32_16x16x32_bf16 v[2:5], v[180:183], v[212:215], v[2:5]
	v_mfma_f32_16x16x32_bf16 v[38:41], v[172:175], v[196:199], v[38:41]
	v_mfma_f32_16x16x32_bf16 v[46:49], v[180:183], v[188:191], v[46:49]
	v_mfma_f32_16x16x32_bf16 v[6:9], v[172:175], v[212:215], v[6:9]
	v_mfma_f32_16x16x32_bf16 v[14:17], v[180:183], v[204:207], v[14:17]
	v_mfma_f32_16x16x32_bf16 v[54:57], v[176:179], v[192:195], v[54:57]
	v_mfma_f32_16x16x32_bf16 v[30:33], v[184:187], v[200:203], v[30:33]
	v_mfma_f32_16x16x32_bf16 v[22:25], v[176:179], v[208:211], v[22:25]
	v_mfma_f32_16x16x32_bf16 v[2:5], v[184:187], v[218:221], v[2:5]
	v_mfma_f32_16x16x32_bf16 v[38:41], v[176:179], v[200:203], v[38:41]
	v_mfma_f32_16x16x32_bf16 v[46:49], v[184:187], v[192:195], v[46:49]
	v_mfma_f32_16x16x32_bf16 v[6:9], v[176:179], v[218:221], v[6:9]
	v_mfma_f32_16x16x32_bf16 v[14:17], v[184:187], v[208:211], v[14:17]
	s_setprio 0
	s_barrier
	s_add_i32 s53, 0, 0x18000
	v_add_u32_e32 v156, s53, v153
	s_add_i32 s62, 0, 0x1c000
	ds_read_b128 v[146:149], v156
	ds_read_b128 v[160:163], v156 offset:1024
	ds_read_b128 v[164:167], v156 offset:2048
	ds_read_b128 v[168:171], v156 offset:3072
	v_add_u32_e32 v156, s62, v153
	ds_read_b128 v[172:175], v156
	ds_read_b128 v[176:179], v156 offset:1024
	ds_read_b128 v[180:183], v156 offset:2048
	ds_read_b128 v[184:187], v156 offset:3072
	s_add_u32 s54, s86, 0x20000
	s_addc_u32 s55, s87, 0
	s_mov_b32 m0, s57
	v_lshl_add_u64 v[228:229], s[54:55], 0, v[130:131]
	ds_read_b128 v[188:191], v155 offset:32768
	ds_read_b128 v[192:195], v155 offset:33792
	ds_read_b128 v[196:199], v155 offset:34816
	ds_read_b128 v[200:203], v155 offset:35840
	ds_read_b128 v[204:207], v155 offset:36864
	ds_read_b128 v[208:211], v155 offset:37888
	ds_read_b128 v[212:215], v155 offset:38912
	ds_read_b128 v[218:221], v155 offset:39936
	global_load_lds_dwordx4 v[228:229], off
	v_lshl_add_u64 v[228:229], s[54:55], 0, v[134:135]
	s_mov_b32 m0, s58
	s_nop 0
	global_load_lds_dwordx4 v[228:229], off
	s_waitcnt vmcnt(8)
	s_waitcnt lgkmcnt(0)
	s_barrier
	s_setprio 1
	s_waitcnt lgkmcnt(0)
	v_mfma_f32_16x16x32_bf16 v[126:129], v[146:149], v[188:191], v[126:129]
	v_mfma_f32_16x16x32_bf16 v[106:109], v[164:167], v[196:199], v[106:109]
	v_mfma_f32_16x16x32_bf16 v[94:97], v[146:149], v[204:207], v[94:97]
	v_mfma_f32_16x16x32_bf16 v[74:77], v[164:167], v[212:215], v[74:77]
	v_mfma_f32_16x16x32_bf16 v[110:113], v[146:149], v[196:199], v[110:113]
	v_mfma_f32_16x16x32_bf16 v[122:125], v[164:167], v[188:191], v[122:125]
	v_mfma_f32_16x16x32_bf16 v[78:81], v[146:149], v[212:215], v[78:81]
	v_mfma_f32_16x16x32_bf16 v[90:93], v[164:167], v[204:207], v[90:93]
	v_mfma_f32_16x16x32_bf16 v[126:129], v[160:163], v[192:195], v[126:129]
	v_mfma_f32_16x16x32_bf16 v[106:109], v[168:171], v[200:203], v[106:109]
	v_mfma_f32_16x16x32_bf16 v[94:97], v[160:163], v[208:211], v[94:97]
	v_mfma_f32_16x16x32_bf16 v[74:77], v[168:171], v[218:221], v[74:77]
	v_mfma_f32_16x16x32_bf16 v[110:113], v[160:163], v[200:203], v[110:113]
	v_mfma_f32_16x16x32_bf16 v[122:125], v[168:171], v[192:195], v[122:125]
	v_mfma_f32_16x16x32_bf16 v[78:81], v[160:163], v[218:221], v[78:81]
	v_mfma_f32_16x16x32_bf16 v[90:93], v[168:171], v[208:211], v[90:93]
	s_setprio 0
	s_setprio 1
	v_mfma_f32_16x16x32_bf16 v[118:121], v[172:175], v[188:191], v[118:121]
	v_mfma_f32_16x16x32_bf16 v[98:101], v[180:183], v[196:199], v[98:101]
	v_mfma_f32_16x16x32_bf16 v[86:89], v[172:175], v[204:207], v[86:89]
	v_mfma_f32_16x16x32_bf16 v[66:69], v[180:183], v[212:215], v[66:69]
	v_mfma_f32_16x16x32_bf16 v[102:105], v[172:175], v[196:199], v[102:105]
	v_mfma_f32_16x16x32_bf16 v[114:117], v[180:183], v[188:191], v[114:117]
	v_mfma_f32_16x16x32_bf16 v[70:73], v[172:175], v[212:215], v[70:73]
	v_mfma_f32_16x16x32_bf16 v[82:85], v[180:183], v[204:207], v[82:85]
	v_mfma_f32_16x16x32_bf16 v[118:121], v[176:179], v[192:195], v[118:121]
	v_mfma_f32_16x16x32_bf16 v[98:101], v[184:187], v[200:203], v[98:101]
	v_mfma_f32_16x16x32_bf16 v[86:89], v[176:179], v[208:211], v[86:89]
	v_mfma_f32_16x16x32_bf16 v[66:69], v[184:187], v[218:221], v[66:69]
	v_mfma_f32_16x16x32_bf16 v[102:105], v[176:179], v[200:203], v[102:105]
	v_mfma_f32_16x16x32_bf16 v[114:117], v[184:187], v[192:195], v[114:117]
	v_mfma_f32_16x16x32_bf16 v[70:73], v[176:179], v[218:221], v[70:73]
	v_mfma_f32_16x16x32_bf16 v[82:85], v[184:187], v[208:211], v[82:85]
	s_setprio 0
	s_barrier
	s_add_i32 s53, s53, s13
	v_lshl_add_u64 v[150:151], v[150:151], 0, s[8:9]
	s_mov_b32 m0, s53
	ds_read_b128 v[188:191], v155 offset:49152
	ds_read_b128 v[192:195], v155 offset:50176
	ds_read_b128 v[196:199], v155 offset:51200
	ds_read_b128 v[200:203], v155 offset:52224
	ds_read_b128 v[204:207], v155 offset:53248
	ds_read_b128 v[208:211], v155 offset:54272
	ds_read_b128 v[212:215], v155 offset:55296
	ds_read_b128 v[218:221], v155 offset:56320
	global_load_lds_dwordx4 v[150:151], off
	s_add_i32 m0, s53, 0x2000
	s_add_u32 s34, s34, 0x20080
	v_lshl_add_u64 v[150:151], v[222:223], 0, s[8:9]
	s_addc_u32 s35, s35, 0
	s_add_i32 s53, s62, s13
	global_load_lds_dwordx4 v[150:151], off
	v_lshl_add_u64 v[150:151], s[34:35], 0, v[132:133]
	s_mov_b32 m0, s53
	s_nop 0
	global_load_lds_dwordx4 v[150:151], off
	v_lshl_add_u64 v[150:151], s[34:35], 0, v[136:137]
	s_add_i32 m0, s53, 0x2000
	s_nop 0
	global_load_lds_dwordx4 v[150:151], off
	v_lshl_add_u64 v[150:151], v[224:225], 0, s[8:9]
	s_mov_b32 m0, s60
	s_nop 0
	global_load_lds_dwordx4 v[150:151], off
	v_lshl_add_u64 v[150:151], v[226:227], 0, s[8:9]
	s_mov_b32 m0, s61
	s_nop 0
	global_load_lds_dwordx4 v[150:151], off
	s_waitcnt vmcnt(8)
	s_waitcnt lgkmcnt(0)
	s_barrier
	s_setprio 1
	s_waitcnt lgkmcnt(0)
	v_mfma_f32_16x16x32_bf16 v[62:65], v[146:149], v[188:191], v[62:65]
	v_mfma_f32_16x16x32_bf16 v[42:45], v[164:167], v[196:199], v[42:45]
	v_mfma_f32_16x16x32_bf16 v[34:37], v[146:149], v[204:207], v[34:37]
	v_mfma_f32_16x16x32_bf16 v[10:13], v[164:167], v[212:215], v[10:13]
	v_mfma_f32_16x16x32_bf16 v[50:53], v[146:149], v[196:199], v[50:53]
	v_mfma_f32_16x16x32_bf16 v[58:61], v[164:167], v[188:191], v[58:61]
	v_mfma_f32_16x16x32_bf16 v[18:21], v[146:149], v[212:215], v[18:21]
	v_mfma_f32_16x16x32_bf16 v[26:29], v[164:167], v[204:207], v[26:29]
	v_mfma_f32_16x16x32_bf16 v[62:65], v[160:163], v[192:195], v[62:65]
	v_mfma_f32_16x16x32_bf16 v[42:45], v[168:171], v[200:203], v[42:45]
	v_mfma_f32_16x16x32_bf16 v[34:37], v[160:163], v[208:211], v[34:37]
	v_mfma_f32_16x16x32_bf16 v[10:13], v[168:171], v[218:221], v[10:13]
	v_mfma_f32_16x16x32_bf16 v[50:53], v[160:163], v[200:203], v[50:53]
	v_mfma_f32_16x16x32_bf16 v[58:61], v[168:171], v[192:195], v[58:61]
	v_mfma_f32_16x16x32_bf16 v[18:21], v[160:163], v[218:221], v[18:21]
	v_mfma_f32_16x16x32_bf16 v[26:29], v[168:171], v[208:211], v[26:29]
	s_setprio 0
	s_setprio 1
	v_mfma_f32_16x16x32_bf16 v[54:57], v[172:175], v[188:191], v[54:57]
	v_mfma_f32_16x16x32_bf16 v[30:33], v[180:183], v[196:199], v[30:33]
	v_mfma_f32_16x16x32_bf16 v[22:25], v[172:175], v[204:207], v[22:25]
	v_mfma_f32_16x16x32_bf16 v[2:5], v[180:183], v[212:215], v[2:5]
	v_mfma_f32_16x16x32_bf16 v[38:41], v[172:175], v[196:199], v[38:41]
	v_mfma_f32_16x16x32_bf16 v[46:49], v[180:183], v[188:191], v[46:49]
	v_mfma_f32_16x16x32_bf16 v[6:9], v[172:175], v[212:215], v[6:9]
	v_mfma_f32_16x16x32_bf16 v[14:17], v[180:183], v[204:207], v[14:17]
	v_mfma_f32_16x16x32_bf16 v[54:57], v[176:179], v[192:195], v[54:57]
	v_mfma_f32_16x16x32_bf16 v[30:33], v[184:187], v[200:203], v[30:33]
	v_mfma_f32_16x16x32_bf16 v[22:25], v[176:179], v[208:211], v[22:25]
	v_mfma_f32_16x16x32_bf16 v[2:5], v[184:187], v[218:221], v[2:5]
	v_mfma_f32_16x16x32_bf16 v[38:41], v[176:179], v[200:203], v[38:41]
	v_mfma_f32_16x16x32_bf16 v[46:49], v[184:187], v[192:195], v[46:49]
	v_mfma_f32_16x16x32_bf16 v[6:9], v[176:179], v[218:221], v[6:9]
	v_mfma_f32_16x16x32_bf16 v[14:17], v[184:187], v[208:211], v[14:17]
	s_setprio 0
	s_barrier
	s_add_i32 s88, s88, 2
	s_add_u32 s84, s84, 0x100
	s_addc_u32 s85, s85, 0
	s_add_u32 s77, s77, 0x100
	s_addc_u32 s83, s83, 0
	s_cmp_gt_u32 s88, 5
	s_cbranch_scc0 .LBB0_715
	s_and_b64 vcc, exec, s[66:67]
	s_cbranch_vccz .LBB0_718
	s_barrier

.LBB0_995:
	ds_read_b128 v[146:149], v164
	ds_read_b128 v[150:153], v164 offset:1024
	ds_read_b128 v[154:157], v164 offset:2048
	ds_read_b128 v[158:161], v164 offset:3072
	ds_read_b128 v[168:171], v165
	ds_read_b128 v[172:175], v165 offset:1024
	ds_read_b128 v[176:179], v165 offset:2048
	ds_read_b128 v[180:183], v165 offset:3072
	s_add_u32 s34, s88, 0xfff80080
	s_addc_u32 s35, s89, -1
	s_cmp_eq_u32 s81, 28
	s_cselect_b32 s91, s0, s35
	s_cselect_b32 s90, s1, s34
	s_cselect_b32 s35, s52, s77
	s_cselect_b32 s34, s74, s75
	v_lshl_add_u64 v[218:219], s[88:89], 0, v[138:139]
	s_add_i32 m0, s33, 0xc000
	ds_read_b128 v[184:187], v166
	ds_read_b128 v[188:191], v166 offset:1024
	ds_read_b128 v[192:195], v166 offset:2048
	ds_read_b128 v[196:199], v166 offset:3072
	ds_read_b128 v[200:203], v166 offset:4096
	ds_read_b128 v[204:207], v166 offset:5120
	ds_read_b128 v[208:211], v166 offset:6144
	ds_read_b128 v[212:215], v166 offset:7168
	global_load_lds_dwordx4 v[218:219], off
	v_lshl_add_u64 v[218:219], s[88:89], 0, v[140:141]
	s_add_i32 m0, s33, 0xe000
	s_nop 0
	global_load_lds_dwordx4 v[218:219], off
	s_waitcnt vmcnt(8)
	s_waitcnt lgkmcnt(0)
	s_barrier
	s_setprio 1
	s_waitcnt lgkmcnt(0)
	v_mfma_f32_16x16x32_bf16 v[126:129], v[146:149], v[184:187], v[126:129]
	v_mfma_f32_16x16x32_bf16 v[106:109], v[154:157], v[192:195], v[106:109]
	v_mfma_f32_16x16x32_bf16 v[94:97], v[146:149], v[200:203], v[94:97]
	v_mfma_f32_16x16x32_bf16 v[74:77], v[154:157], v[208:211], v[74:77]
	v_mfma_f32_16x16x32_bf16 v[110:113], v[146:149], v[192:195], v[110:113]
	v_mfma_f32_16x16x32_bf16 v[122:125], v[154:157], v[184:187], v[122:125]
	v_mfma_f32_16x16x32_bf16 v[78:81], v[146:149], v[208:211], v[78:81]
	v_mfma_f32_16x16x32_bf16 v[90:93], v[154:157], v[200:203], v[90:93]
	v_mfma_f32_16x16x32_bf16 v[126:129], v[150:153], v[188:191], v[126:129]
	v_mfma_f32_16x16x32_bf16 v[106:109], v[158:161], v[196:199], v[106:109]
	v_mfma_f32_16x16x32_bf16 v[94:97], v[150:153], v[204:207], v[94:97]
	v_mfma_f32_16x16x32_bf16 v[74:77], v[158:161], v[212:215], v[74:77]
	v_mfma_f32_16x16x32_bf16 v[110:113], v[150:153], v[196:199], v[110:113]
	v_mfma_f32_16x16x32_bf16 v[122:125], v[158:161], v[188:191], v[122:125]
	v_mfma_f32_16x16x32_bf16 v[78:81], v[150:153], v[212:215], v[78:81]
	v_mfma_f32_16x16x32_bf16 v[90:93], v[158:161], v[204:207], v[90:93]
	s_setprio 0
	s_setprio 1
	v_mfma_f32_16x16x32_bf16 v[118:121], v[168:171], v[184:187], v[118:121]
	v_mfma_f32_16x16x32_bf16 v[98:101], v[176:179], v[192:195], v[98:101]
	v_mfma_f32_16x16x32_bf16 v[86:89], v[168:171], v[200:203], v[86:89]
	v_mfma_f32_16x16x32_bf16 v[66:69], v[176:179], v[208:211], v[66:69]
	v_mfma_f32_16x16x32_bf16 v[102:105], v[168:171], v[192:195], v[102:105]
	v_mfma_f32_16x16x32_bf16 v[114:117], v[176:179], v[184:187], v[114:117]
	v_mfma_f32_16x16x32_bf16 v[70:73], v[168:171], v[208:211], v[70:73]
	v_mfma_f32_16x16x32_bf16 v[82:85], v[176:179], v[200:203], v[82:85]
	v_mfma_f32_16x16x32_bf16 v[118:121], v[172:175], v[188:191], v[118:121]
	v_mfma_f32_16x16x32_bf16 v[98:101], v[180:183], v[196:199], v[98:101]
	v_mfma_f32_16x16x32_bf16 v[86:89], v[172:175], v[204:207], v[86:89]
	v_mfma_f32_16x16x32_bf16 v[66:69], v[180:183], v[212:215], v[66:69]
	v_mfma_f32_16x16x32_bf16 v[102:105], v[172:175], v[196:199], v[102:105]
	v_mfma_f32_16x16x32_bf16 v[114:117], v[180:183], v[188:191], v[114:117]
	v_mfma_f32_16x16x32_bf16 v[70:73], v[172:175], v[212:215], v[70:73]
	v_mfma_f32_16x16x32_bf16 v[82:85], v[180:183], v[204:207], v[82:85]
	s_setprio 0
	s_barrier
	s_add_i32 s53, s71, s31
	v_lshl_add_u64 v[218:219], s[34:35], 0, v[132:133]
	s_mov_b32 m0, s53
	ds_read_b128 v[184:187], v166 offset:16384
	ds_read_b128 v[188:191], v166 offset:17408
	ds_read_b128 v[192:195], v166 offset:18432
	ds_read_b128 v[196:199], v166 offset:19456
	ds_read_b128 v[200:203], v166 offset:20480
	ds_read_b128 v[204:207], v166 offset:21504
	ds_read_b128 v[208:211], v166 offset:22528
	ds_read_b128 v[212:215], v166 offset:23552
	global_load_lds_dwordx4 v[218:219], off
	s_add_i32 m0, s53, 0x2000
	s_add_u32 s54, s34, 0x80000
	v_lshl_add_u64 v[220:221], s[34:35], 0, v[136:137]
	s_addc_u32 s55, s35, 0
	s_add_i32 s53, s72, s31
	global_load_lds_dwordx4 v[220:221], off
	v_lshl_add_u64 v[222:223], s[54:55], 0, v[132:133]
	s_mov_b32 m0, s53
	v_lshl_add_u64 v[224:225], s[90:91], 0, v[134:135]
	global_load_lds_dwordx4 v[222:223], off
	v_lshl_add_u64 v[222:223], s[54:55], 0, v[136:137]
	s_add_i32 m0, s53, 0x2000
	s_nop 0
	global_load_lds_dwordx4 v[222:223], off
	v_lshl_add_u64 v[222:223], s[90:91], 0, v[130:131]
	s_mov_b32 m0, s33
	s_nop 0
	global_load_lds_dwordx4 v[222:223], off
	s_mov_b32 m0, s56
	s_nop 0
	global_load_lds_dwordx4 v[224:225], off
	s_waitcnt vmcnt(8)
	s_waitcnt lgkmcnt(0)
	s_barrier
	s_setprio 1
	s_waitcnt lgkmcnt(0)
	v_mfma_f32_16x16x32_bf16 v[62:65], v[146:149], v[184:187], v[62:65]
	v_mfma_f32_16x16x32_bf16 v[42:45], v[154:157], v[192:195], v[42:45]
	v_mfma_f32_16x16x32_bf16 v[30:33], v[146:149], v[200:203], v[30:33]
	v_mfma_f32_16x16x32_bf16 v[10:13], v[154:157], v[208:211], v[10:13]
	v_mfma_f32_16x16x32_bf16 v[46:49], v[146:149], v[192:195], v[46:49]
	v_mfma_f32_16x16x32_bf16 v[58:61], v[154:157], v[184:187], v[58:61]
	v_mfma_f32_16x16x32_bf16 v[14:17], v[146:149], v[208:211], v[14:17]
	v_mfma_f32_16x16x32_bf16 v[26:29], v[154:157], v[200:203], v[26:29]
	v_mfma_f32_16x16x32_bf16 v[62:65], v[150:153], v[188:191], v[62:65]
	v_mfma_f32_16x16x32_bf16 v[42:45], v[158:161], v[196:199], v[42:45]
	v_mfma_f32_16x16x32_bf16 v[30:33], v[150:153], v[204:207], v[30:33]
	v_mfma_f32_16x16x32_bf16 v[10:13], v[158:161], v[212:215], v[10:13]
	v_mfma_f32_16x16x32_bf16 v[46:49], v[150:153], v[196:199], v[46:49]
	v_mfma_f32_16x16x32_bf16 v[58:61], v[158:161], v[188:191], v[58:61]
	v_mfma_f32_16x16x32_bf16 v[14:17], v[150:153], v[212:215], v[14:17]
	v_mfma_f32_16x16x32_bf16 v[26:29], v[158:161], v[204:207], v[26:29]
	s_setprio 0
	s_setprio 1
	v_mfma_f32_16x16x32_bf16 v[54:57], v[168:171], v[184:187], v[54:57]
	v_mfma_f32_16x16x32_bf16 v[34:37], v[176:179], v[192:195], v[34:37]
	v_mfma_f32_16x16x32_bf16 v[22:25], v[168:171], v[200:203], v[22:25]
	v_mfma_f32_16x16x32_bf16 v[2:5], v[176:179], v[208:211], v[2:5]
	v_mfma_f32_16x16x32_bf16 v[38:41], v[168:171], v[192:195], v[38:41]
	v_mfma_f32_16x16x32_bf16 v[50:53], v[176:179], v[184:187], v[50:53]
	v_mfma_f32_16x16x32_bf16 v[6:9], v[168:171], v[208:211], v[6:9]
	v_mfma_f32_16x16x32_bf16 v[18:21], v[176:179], v[200:203], v[18:21]
	v_mfma_f32_16x16x32_bf16 v[54:57], v[172:175], v[188:191], v[54:57]
	v_mfma_f32_16x16x32_bf16 v[34:37], v[180:183], v[196:199], v[34:37]
	v_mfma_f32_16x16x32_bf16 v[22:25], v[172:175], v[204:207], v[22:25]
	v_mfma_f32_16x16x32_bf16 v[2:5], v[180:183], v[212:215], v[2:5]
	v_mfma_f32_16x16x32_bf16 v[38:41], v[172:175], v[196:199], v[38:41]
	v_mfma_f32_16x16x32_bf16 v[50:53], v[180:183], v[188:191], v[50:53]
	v_mfma_f32_16x16x32_bf16 v[6:9], v[172:175], v[212:215], v[6:9]
	v_mfma_f32_16x16x32_bf16 v[18:21], v[180:183], v[204:207], v[18:21]
	s_setprio 0
	s_barrier
	s_add_i32 s53, 0, 0x18000
	s_add_i32 s62, 0, 0x1c000
	v_add_u32_e32 v158, s53, v162
	v_add_u32_e32 v167, s62, v162
	ds_read_b128 v[146:149], v158
	ds_read_b128 v[150:153], v158 offset:1024
	ds_read_b128 v[154:157], v158 offset:2048
	ds_read_b128 v[158:161], v158 offset:3072
	ds_read_b128 v[168:171], v167
	ds_read_b128 v[172:175], v167 offset:1024
	ds_read_b128 v[176:179], v167 offset:2048
	ds_read_b128 v[180:183], v167 offset:3072
	s_add_u32 s54, s90, 0x80000
	s_addc_u32 s55, s91, 0
	s_mov_b32 m0, s57
	v_lshl_add_u64 v[226:227], s[54:55], 0, v[130:131]
	ds_read_b128 v[184:187], v166 offset:32768
	ds_read_b128 v[188:191], v166 offset:33792
	ds_read_b128 v[192:195], v166 offset:34816
	ds_read_b128 v[196:199], v166 offset:35840
	ds_read_b128 v[200:203], v166 offset:36864
	ds_read_b128 v[204:207], v166 offset:37888
	ds_read_b128 v[208:211], v166 offset:38912
	ds_read_b128 v[212:215], v166 offset:39936
	global_load_lds_dwordx4 v[226:227], off
	v_lshl_add_u64 v[226:227], s[54:55], 0, v[134:135]
	s_mov_b32 m0, s58
	s_nop 0
	global_load_lds_dwordx4 v[226:227], off
	s_waitcnt vmcnt(8)
	s_waitcnt lgkmcnt(0)
	s_barrier
	s_setprio 1
	s_waitcnt lgkmcnt(0)
	v_mfma_f32_16x16x32_bf16 v[126:129], v[146:149], v[184:187], v[126:129]
	v_mfma_f32_16x16x32_bf16 v[106:109], v[154:157], v[192:195], v[106:109]
	v_mfma_f32_16x16x32_bf16 v[94:97], v[146:149], v[200:203], v[94:97]
	v_mfma_f32_16x16x32_bf16 v[74:77], v[154:157], v[208:211], v[74:77]
	v_mfma_f32_16x16x32_bf16 v[110:113], v[146:149], v[192:195], v[110:113]
	v_mfma_f32_16x16x32_bf16 v[122:125], v[154:157], v[184:187], v[122:125]
	v_mfma_f32_16x16x32_bf16 v[78:81], v[146:149], v[208:211], v[78:81]
	v_mfma_f32_16x16x32_bf16 v[90:93], v[154:157], v[200:203], v[90:93]
	v_mfma_f32_16x16x32_bf16 v[126:129], v[150:153], v[188:191], v[126:129]
	v_mfma_f32_16x16x32_bf16 v[106:109], v[158:161], v[196:199], v[106:109]
	v_mfma_f32_16x16x32_bf16 v[94:97], v[150:153], v[204:207], v[94:97]
	v_mfma_f32_16x16x32_bf16 v[74:77], v[158:161], v[212:215], v[74:77]
	v_mfma_f32_16x16x32_bf16 v[110:113], v[150:153], v[196:199], v[110:113]
	v_mfma_f32_16x16x32_bf16 v[122:125], v[158:161], v[188:191], v[122:125]
	v_mfma_f32_16x16x32_bf16 v[78:81], v[150:153], v[212:215], v[78:81]
	v_mfma_f32_16x16x32_bf16 v[90:93], v[158:161], v[204:207], v[90:93]
	s_setprio 0
	s_setprio 1
	v_mfma_f32_16x16x32_bf16 v[118:121], v[168:171], v[184:187], v[118:121]
	v_mfma_f32_16x16x32_bf16 v[98:101], v[176:179], v[192:195], v[98:101]
	v_mfma_f32_16x16x32_bf16 v[86:89], v[168:171], v[200:203], v[86:89]
	v_mfma_f32_16x16x32_bf16 v[66:69], v[176:179], v[208:211], v[66:69]
	v_mfma_f32_16x16x32_bf16 v[102:105], v[168:171], v[192:195], v[102:105]
	v_mfma_f32_16x16x32_bf16 v[114:117], v[176:179], v[184:187], v[114:117]
	v_mfma_f32_16x16x32_bf16 v[70:73], v[168:171], v[208:211], v[70:73]
	v_mfma_f32_16x16x32_bf16 v[82:85], v[176:179], v[200:203], v[82:85]
	v_mfma_f32_16x16x32_bf16 v[118:121], v[172:175], v[188:191], v[118:121]
	v_mfma_f32_16x16x32_bf16 v[98:101], v[180:183], v[196:199], v[98:101]
	v_mfma_f32_16x16x32_bf16 v[86:89], v[172:175], v[204:207], v[86:89]
	v_mfma_f32_16x16x32_bf16 v[66:69], v[180:183], v[212:215], v[66:69]
	v_mfma_f32_16x16x32_bf16 v[102:105], v[172:175], v[196:199], v[102:105]
	v_mfma_f32_16x16x32_bf16 v[114:117], v[180:183], v[188:191], v[114:117]
	v_mfma_f32_16x16x32_bf16 v[70:73], v[172:175], v[212:215], v[70:73]
	v_mfma_f32_16x16x32_bf16 v[82:85], v[180:183], v[204:207], v[82:85]
	s_setprio 0
	s_barrier
	s_add_i32 s53, s53, s31
	v_lshl_add_u64 v[218:219], v[218:219], 0, s[8:9]
	s_mov_b32 m0, s53
	ds_read_b128 v[184:187], v166 offset:49152
	ds_read_b128 v[188:191], v166 offset:50176
	ds_read_b128 v[192:195], v166 offset:51200
	ds_read_b128 v[196:199], v166 offset:52224
	ds_read_b128 v[200:203], v166 offset:53248
	ds_read_b128 v[204:207], v166 offset:54272
	ds_read_b128 v[208:211], v166 offset:55296
	ds_read_b128 v[212:215], v166 offset:56320
	global_load_lds_dwordx4 v[218:219], off
	s_add_i32 m0, s53, 0x2000
	s_add_u32 s34, s34, 0x80080
	v_lshl_add_u64 v[218:219], v[220:221], 0, s[8:9]
	s_addc_u32 s35, s35, 0
	s_add_i32 s53, s62, s31
	global_load_lds_dwordx4 v[218:219], off
	v_lshl_add_u64 v[218:219], s[34:35], 0, v[132:133]
	s_mov_b32 m0, s53
	s_nop 0
	global_load_lds_dwordx4 v[218:219], off
	v_lshl_add_u64 v[218:219], s[34:35], 0, v[136:137]
	s_add_i32 m0, s53, 0x2000
	s_nop 0
	global_load_lds_dwordx4 v[218:219], off
	v_lshl_add_u64 v[218:219], v[222:223], 0, s[8:9]
	s_mov_b32 m0, s60
	s_nop 0
	global_load_lds_dwordx4 v[218:219], off
	v_lshl_add_u64 v[218:219], v[224:225], 0, s[8:9]
	s_mov_b32 m0, s61
	s_nop 0
	global_load_lds_dwordx4 v[218:219], off
	s_waitcnt vmcnt(8)
	s_waitcnt lgkmcnt(0)
	s_barrier
	s_setprio 1
	s_waitcnt lgkmcnt(0)
	v_mfma_f32_16x16x32_bf16 v[62:65], v[146:149], v[184:187], v[62:65]
	v_mfma_f32_16x16x32_bf16 v[42:45], v[154:157], v[192:195], v[42:45]
	v_mfma_f32_16x16x32_bf16 v[30:33], v[146:149], v[200:203], v[30:33]
	v_mfma_f32_16x16x32_bf16 v[10:13], v[154:157], v[208:211], v[10:13]
	v_mfma_f32_16x16x32_bf16 v[46:49], v[146:149], v[192:195], v[46:49]
	v_mfma_f32_16x16x32_bf16 v[58:61], v[154:157], v[184:187], v[58:61]
	v_mfma_f32_16x16x32_bf16 v[14:17], v[146:149], v[208:211], v[14:17]
	v_mfma_f32_16x16x32_bf16 v[26:29], v[154:157], v[200:203], v[26:29]
	v_mfma_f32_16x16x32_bf16 v[62:65], v[150:153], v[188:191], v[62:65]
	v_mfma_f32_16x16x32_bf16 v[42:45], v[158:161], v[196:199], v[42:45]
	v_mfma_f32_16x16x32_bf16 v[30:33], v[150:153], v[204:207], v[30:33]
	v_mfma_f32_16x16x32_bf16 v[10:13], v[158:161], v[212:215], v[10:13]
	v_mfma_f32_16x16x32_bf16 v[46:49], v[150:153], v[196:199], v[46:49]
	v_mfma_f32_16x16x32_bf16 v[58:61], v[158:161], v[188:191], v[58:61]
	v_mfma_f32_16x16x32_bf16 v[14:17], v[150:153], v[212:215], v[14:17]
	v_mfma_f32_16x16x32_bf16 v[26:29], v[158:161], v[204:207], v[26:29]
	s_setprio 0
	s_setprio 1
	v_mfma_f32_16x16x32_bf16 v[54:57], v[168:171], v[184:187], v[54:57]
	v_mfma_f32_16x16x32_bf16 v[34:37], v[176:179], v[192:195], v[34:37]
	v_mfma_f32_16x16x32_bf16 v[22:25], v[168:171], v[200:203], v[22:25]
	v_mfma_f32_16x16x32_bf16 v[2:5], v[176:179], v[208:211], v[2:5]
	v_mfma_f32_16x16x32_bf16 v[38:41], v[168:171], v[192:195], v[38:41]
	v_mfma_f32_16x16x32_bf16 v[50:53], v[176:179], v[184:187], v[50:53]
	v_mfma_f32_16x16x32_bf16 v[6:9], v[168:171], v[208:211], v[6:9]
	v_mfma_f32_16x16x32_bf16 v[18:21], v[176:179], v[200:203], v[18:21]
	v_mfma_f32_16x16x32_bf16 v[54:57], v[172:175], v[188:191], v[54:57]
	v_mfma_f32_16x16x32_bf16 v[34:37], v[180:183], v[196:199], v[34:37]
	v_mfma_f32_16x16x32_bf16 v[22:25], v[172:175], v[204:207], v[22:25]
	v_mfma_f32_16x16x32_bf16 v[2:5], v[180:183], v[212:215], v[2:5]
	v_mfma_f32_16x16x32_bf16 v[38:41], v[172:175], v[196:199], v[38:41]
	v_mfma_f32_16x16x32_bf16 v[50:53], v[180:183], v[188:191], v[50:53]
	v_mfma_f32_16x16x32_bf16 v[6:9], v[172:175], v[212:215], v[6:9]
	v_mfma_f32_16x16x32_bf16 v[18:21], v[180:183], v[204:207], v[18:21]
	s_setprio 0
	s_barrier
	s_add_i32 s81, s81, 2
	s_add_u32 s88, s88, 0x100
	s_addc_u32 s89, s89, 0
	s_add_u32 s75, s75, 0x100
	s_addc_u32 s77, s77, 0
	s_cmp_gt_u32 s81, 29
	s_cbranch_scc0 .LBB0_995
	s_and_b64 vcc, exec, s[78:79]
	s_cbranch_vccz .LBB0_998
	s_barrier

.LBB0_1124:
	ds_read_b128 v[146:149], v153
	ds_read_b128 v[156:159], v153 offset:1024
	ds_read_b128 v[160:163], v153 offset:2048
	ds_read_b128 v[164:167], v153 offset:3072
	ds_read_b128 v[168:171], v154
	ds_read_b128 v[172:175], v154 offset:1024
	ds_read_b128 v[176:179], v154 offset:2048
	ds_read_b128 v[180:183], v154 offset:3072
	s_add_u32 s34, s88, 0xfff80080
	s_addc_u32 s35, s89, -1
	s_cmp_eq_u32 s92, 28
	s_cselect_b32 s91, s0, s35
	s_cselect_b32 s90, s1, s34
	s_cselect_b32 s35, s52, s83
	s_cselect_b32 s34, s77, s81
	v_lshl_add_u64 v[218:219], s[88:89], 0, v[138:139]
	s_add_i32 m0, s56, 0xc000
	ds_read_b128 v[184:187], v155
	ds_read_b128 v[188:191], v155 offset:1024
	ds_read_b128 v[192:195], v155 offset:2048
	ds_read_b128 v[196:199], v155 offset:3072
	ds_read_b128 v[200:203], v155 offset:4096
	ds_read_b128 v[204:207], v155 offset:5120
	ds_read_b128 v[208:211], v155 offset:6144
	ds_read_b128 v[212:215], v155 offset:7168
	global_load_lds_dwordx4 v[218:219], off
	v_lshl_add_u64 v[218:219], s[88:89], 0, v[140:141]
	s_add_i32 m0, s56, 0xe000
	s_nop 0
	global_load_lds_dwordx4 v[218:219], off
	s_waitcnt vmcnt(8)
	s_waitcnt lgkmcnt(0)
	s_barrier
	s_setprio 1
	s_waitcnt lgkmcnt(0)
	v_mfma_f32_16x16x32_bf16 v[126:129], v[146:149], v[184:187], v[126:129]
	v_mfma_f32_16x16x32_bf16 v[102:105], v[160:163], v[192:195], v[102:105]
	v_mfma_f32_16x16x32_bf16 v[94:97], v[146:149], v[200:203], v[94:97]
	v_mfma_f32_16x16x32_bf16 v[70:73], v[160:163], v[208:211], v[70:73]
	v_mfma_f32_16x16x32_bf16 v[110:113], v[146:149], v[192:195], v[110:113]
	v_mfma_f32_16x16x32_bf16 v[118:121], v[160:163], v[184:187], v[118:121]
	v_mfma_f32_16x16x32_bf16 v[78:81], v[146:149], v[208:211], v[78:81]
	v_mfma_f32_16x16x32_bf16 v[86:89], v[160:163], v[200:203], v[86:89]
	v_mfma_f32_16x16x32_bf16 v[126:129], v[156:159], v[188:191], v[126:129]
	v_mfma_f32_16x16x32_bf16 v[102:105], v[164:167], v[196:199], v[102:105]
	v_mfma_f32_16x16x32_bf16 v[94:97], v[156:159], v[204:207], v[94:97]
	v_mfma_f32_16x16x32_bf16 v[70:73], v[164:167], v[212:215], v[70:73]
	v_mfma_f32_16x16x32_bf16 v[110:113], v[156:159], v[196:199], v[110:113]
	v_mfma_f32_16x16x32_bf16 v[118:121], v[164:167], v[188:191], v[118:121]
	v_mfma_f32_16x16x32_bf16 v[78:81], v[156:159], v[212:215], v[78:81]
	v_mfma_f32_16x16x32_bf16 v[86:89], v[164:167], v[204:207], v[86:89]
	s_setprio 0
	s_setprio 1
	v_mfma_f32_16x16x32_bf16 v[122:125], v[168:171], v[184:187], v[122:125]
	v_mfma_f32_16x16x32_bf16 v[98:101], v[176:179], v[192:195], v[98:101]
	v_mfma_f32_16x16x32_bf16 v[90:93], v[168:171], v[200:203], v[90:93]
	v_mfma_f32_16x16x32_bf16 v[66:69], v[176:179], v[208:211], v[66:69]
	v_mfma_f32_16x16x32_bf16 v[106:109], v[168:171], v[192:195], v[106:109]
	v_mfma_f32_16x16x32_bf16 v[114:117], v[176:179], v[184:187], v[114:117]
	v_mfma_f32_16x16x32_bf16 v[74:77], v[168:171], v[208:211], v[74:77]
	v_mfma_f32_16x16x32_bf16 v[82:85], v[176:179], v[200:203], v[82:85]
	v_mfma_f32_16x16x32_bf16 v[122:125], v[172:175], v[188:191], v[122:125]
	v_mfma_f32_16x16x32_bf16 v[98:101], v[180:183], v[196:199], v[98:101]
	v_mfma_f32_16x16x32_bf16 v[90:93], v[172:175], v[204:207], v[90:93]
	v_mfma_f32_16x16x32_bf16 v[66:69], v[180:183], v[212:215], v[66:69]
	v_mfma_f32_16x16x32_bf16 v[106:109], v[172:175], v[196:199], v[106:109]
	v_mfma_f32_16x16x32_bf16 v[114:117], v[180:183], v[188:191], v[114:117]
	v_mfma_f32_16x16x32_bf16 v[74:77], v[172:175], v[212:215], v[74:77]
	v_mfma_f32_16x16x32_bf16 v[82:85], v[180:183], v[204:207], v[82:85]
	s_setprio 0
	s_barrier
	s_add_i32 s53, s72, s30
	v_lshl_add_u64 v[218:219], s[34:35], 0, v[134:135]
	s_mov_b32 m0, s53
	ds_read_b128 v[184:187], v155 offset:16384
	ds_read_b128 v[188:191], v155 offset:17408
	ds_read_b128 v[192:195], v155 offset:18432
	ds_read_b128 v[196:199], v155 offset:19456
	ds_read_b128 v[200:203], v155 offset:20480
	ds_read_b128 v[204:207], v155 offset:21504
	ds_read_b128 v[208:211], v155 offset:22528
	ds_read_b128 v[212:215], v155 offset:23552
	global_load_lds_dwordx4 v[218:219], off
	s_add_i32 m0, s53, 0x2000
	s_add_u32 s54, s34, 0x80000
	v_lshl_add_u64 v[220:221], s[34:35], 0, v[130:131]
	s_addc_u32 s55, s35, 0
	s_add_i32 s53, s73, s30
	global_load_lds_dwordx4 v[220:221], off
	v_lshl_add_u64 v[222:223], s[54:55], 0, v[134:135]
	s_mov_b32 m0, s53
	v_lshl_add_u64 v[224:225], s[90:91], 0, v[132:133]
	global_load_lds_dwordx4 v[222:223], off
	v_lshl_add_u64 v[222:223], s[54:55], 0, v[130:131]
	s_add_i32 m0, s53, 0x2000
	s_nop 0
	global_load_lds_dwordx4 v[222:223], off
	v_lshl_add_u64 v[222:223], s[90:91], 0, v[136:137]
	s_mov_b32 m0, s56
	s_nop 0
	global_load_lds_dwordx4 v[222:223], off
	s_mov_b32 m0, s57
	s_nop 0
	global_load_lds_dwordx4 v[224:225], off
	s_waitcnt vmcnt(8)
	s_waitcnt lgkmcnt(0)
	s_barrier
	s_setprio 1
	s_waitcnt lgkmcnt(0)
	v_mfma_f32_16x16x32_bf16 v[62:65], v[146:149], v[184:187], v[62:65]
	v_mfma_f32_16x16x32_bf16 v[38:41], v[160:163], v[192:195], v[38:41]
	v_mfma_f32_16x16x32_bf16 v[30:33], v[146:149], v[200:203], v[30:33]
	v_mfma_f32_16x16x32_bf16 v[6:9], v[160:163], v[208:211], v[6:9]
	v_mfma_f32_16x16x32_bf16 v[46:49], v[146:149], v[192:195], v[46:49]
	v_mfma_f32_16x16x32_bf16 v[54:57], v[160:163], v[184:187], v[54:57]
	v_mfma_f32_16x16x32_bf16 v[14:17], v[146:149], v[208:211], v[14:17]
	v_mfma_f32_16x16x32_bf16 v[22:25], v[160:163], v[200:203], v[22:25]
	v_mfma_f32_16x16x32_bf16 v[62:65], v[156:159], v[188:191], v[62:65]
	v_mfma_f32_16x16x32_bf16 v[38:41], v[164:167], v[196:199], v[38:41]
	v_mfma_f32_16x16x32_bf16 v[30:33], v[156:159], v[204:207], v[30:33]
	v_mfma_f32_16x16x32_bf16 v[6:9], v[164:167], v[212:215], v[6:9]
	v_mfma_f32_16x16x32_bf16 v[46:49], v[156:159], v[196:199], v[46:49]
	v_mfma_f32_16x16x32_bf16 v[54:57], v[164:167], v[188:191], v[54:57]
	v_mfma_f32_16x16x32_bf16 v[14:17], v[156:159], v[212:215], v[14:17]
	v_mfma_f32_16x16x32_bf16 v[22:25], v[164:167], v[204:207], v[22:25]
	s_setprio 0
	s_setprio 1
	v_mfma_f32_16x16x32_bf16 v[58:61], v[168:171], v[184:187], v[58:61]
	v_mfma_f32_16x16x32_bf16 v[34:37], v[176:179], v[192:195], v[34:37]
	v_mfma_f32_16x16x32_bf16 v[26:29], v[168:171], v[200:203], v[26:29]
	v_mfma_f32_16x16x32_bf16 v[2:5], v[176:179], v[208:211], v[2:5]
	v_mfma_f32_16x16x32_bf16 v[42:45], v[168:171], v[192:195], v[42:45]
	v_mfma_f32_16x16x32_bf16 v[50:53], v[176:179], v[184:187], v[50:53]
	v_mfma_f32_16x16x32_bf16 v[10:13], v[168:171], v[208:211], v[10:13]
	v_mfma_f32_16x16x32_bf16 v[18:21], v[176:179], v[200:203], v[18:21]
	v_mfma_f32_16x16x32_bf16 v[58:61], v[172:175], v[188:191], v[58:61]
	v_mfma_f32_16x16x32_bf16 v[34:37], v[180:183], v[196:199], v[34:37]
	v_mfma_f32_16x16x32_bf16 v[26:29], v[172:175], v[204:207], v[26:29]
	v_mfma_f32_16x16x32_bf16 v[2:5], v[180:183], v[212:215], v[2:5]
	v_mfma_f32_16x16x32_bf16 v[42:45], v[172:175], v[196:199], v[42:45]
	v_mfma_f32_16x16x32_bf16 v[50:53], v[180:183], v[188:191], v[50:53]
	v_mfma_f32_16x16x32_bf16 v[10:13], v[172:175], v[212:215], v[10:13]
	v_mfma_f32_16x16x32_bf16 v[18:21], v[180:183], v[204:207], v[18:21]
	s_setprio 0
	s_barrier
	s_add_i32 s53, 0, 0x18000
	s_add_i32 s62, 0, 0x1c000
	v_add_u32_e32 v164, s53, v151
	v_add_u32_e32 v180, s62, v151
	ds_read_b128 v[146:149], v164
	ds_read_b128 v[156:159], v164 offset:1024
	ds_read_b128 v[160:163], v164 offset:2048
	ds_read_b128 v[164:167], v164 offset:3072
	ds_read_b128 v[168:171], v180
	ds_read_b128 v[172:175], v180 offset:1024
	ds_read_b128 v[176:179], v180 offset:2048
	ds_read_b128 v[180:183], v180 offset:3072
	s_add_u32 s54, s90, 0x80000
	s_addc_u32 s55, s91, 0
	s_mov_b32 m0, s58
	v_lshl_add_u64 v[226:227], s[54:55], 0, v[136:137]
	ds_read_b128 v[184:187], v155 offset:32768
	ds_read_b128 v[188:191], v155 offset:33792
	ds_read_b128 v[192:195], v155 offset:34816
	ds_read_b128 v[196:199], v155 offset:35840
	ds_read_b128 v[200:203], v155 offset:36864
	ds_read_b128 v[204:207], v155 offset:37888
	ds_read_b128 v[208:211], v155 offset:38912
	ds_read_b128 v[212:215], v155 offset:39936
	global_load_lds_dwordx4 v[226:227], off
	v_lshl_add_u64 v[226:227], s[54:55], 0, v[132:133]
	s_mov_b32 m0, s59
	s_nop 0
	global_load_lds_dwordx4 v[226:227], off
	s_waitcnt vmcnt(8)
	s_waitcnt lgkmcnt(0)
	s_barrier
	s_setprio 1
	s_waitcnt lgkmcnt(0)
	v_mfma_f32_16x16x32_bf16 v[126:129], v[146:149], v[184:187], v[126:129]
	v_mfma_f32_16x16x32_bf16 v[102:105], v[160:163], v[192:195], v[102:105]
	v_mfma_f32_16x16x32_bf16 v[94:97], v[146:149], v[200:203], v[94:97]
	v_mfma_f32_16x16x32_bf16 v[70:73], v[160:163], v[208:211], v[70:73]
	v_mfma_f32_16x16x32_bf16 v[110:113], v[146:149], v[192:195], v[110:113]
	v_mfma_f32_16x16x32_bf16 v[118:121], v[160:163], v[184:187], v[118:121]
	v_mfma_f32_16x16x32_bf16 v[78:81], v[146:149], v[208:211], v[78:81]
	v_mfma_f32_16x16x32_bf16 v[86:89], v[160:163], v[200:203], v[86:89]
	v_mfma_f32_16x16x32_bf16 v[126:129], v[156:159], v[188:191], v[126:129]
	v_mfma_f32_16x16x32_bf16 v[102:105], v[164:167], v[196:199], v[102:105]
	v_mfma_f32_16x16x32_bf16 v[94:97], v[156:159], v[204:207], v[94:97]
	v_mfma_f32_16x16x32_bf16 v[70:73], v[164:167], v[212:215], v[70:73]
	v_mfma_f32_16x16x32_bf16 v[110:113], v[156:159], v[196:199], v[110:113]
	v_mfma_f32_16x16x32_bf16 v[118:121], v[164:167], v[188:191], v[118:121]
	v_mfma_f32_16x16x32_bf16 v[78:81], v[156:159], v[212:215], v[78:81]
	v_mfma_f32_16x16x32_bf16 v[86:89], v[164:167], v[204:207], v[86:89]
	s_setprio 0
	s_setprio 1
	v_mfma_f32_16x16x32_bf16 v[122:125], v[168:171], v[184:187], v[122:125]
	v_mfma_f32_16x16x32_bf16 v[98:101], v[176:179], v[192:195], v[98:101]
	v_mfma_f32_16x16x32_bf16 v[90:93], v[168:171], v[200:203], v[90:93]
	v_mfma_f32_16x16x32_bf16 v[66:69], v[176:179], v[208:211], v[66:69]
	v_mfma_f32_16x16x32_bf16 v[106:109], v[168:171], v[192:195], v[106:109]
	v_mfma_f32_16x16x32_bf16 v[114:117], v[176:179], v[184:187], v[114:117]
	v_mfma_f32_16x16x32_bf16 v[74:77], v[168:171], v[208:211], v[74:77]
	v_mfma_f32_16x16x32_bf16 v[82:85], v[176:179], v[200:203], v[82:85]
	v_mfma_f32_16x16x32_bf16 v[122:125], v[172:175], v[188:191], v[122:125]
	v_mfma_f32_16x16x32_bf16 v[98:101], v[180:183], v[196:199], v[98:101]
	v_mfma_f32_16x16x32_bf16 v[90:93], v[172:175], v[204:207], v[90:93]
	v_mfma_f32_16x16x32_bf16 v[66:69], v[180:183], v[212:215], v[66:69]
	v_mfma_f32_16x16x32_bf16 v[106:109], v[172:175], v[196:199], v[106:109]
	v_mfma_f32_16x16x32_bf16 v[114:117], v[180:183], v[188:191], v[114:117]
	v_mfma_f32_16x16x32_bf16 v[74:77], v[172:175], v[212:215], v[74:77]
	v_mfma_f32_16x16x32_bf16 v[82:85], v[180:183], v[204:207], v[82:85]
	s_setprio 0
	s_barrier
	s_add_i32 s53, s53, s30
	v_lshl_add_u64 v[218:219], v[218:219], 0, s[8:9]
	s_mov_b32 m0, s53
	ds_read_b128 v[184:187], v155 offset:49152
	ds_read_b128 v[188:191], v155 offset:50176
	ds_read_b128 v[192:195], v155 offset:51200
	ds_read_b128 v[196:199], v155 offset:52224
	ds_read_b128 v[200:203], v155 offset:53248
	ds_read_b128 v[204:207], v155 offset:54272
	ds_read_b128 v[208:211], v155 offset:55296
	ds_read_b128 v[212:215], v155 offset:56320
	global_load_lds_dwordx4 v[218:219], off
	s_add_i32 m0, s53, 0x2000
	s_add_u32 s34, s34, 0x80080
	v_lshl_add_u64 v[218:219], v[220:221], 0, s[8:9]
	s_addc_u32 s35, s35, 0
	s_add_i32 s53, s62, s30
	global_load_lds_dwordx4 v[218:219], off
	v_lshl_add_u64 v[218:219], s[34:35], 0, v[134:135]
	s_mov_b32 m0, s53
	s_nop 0
	global_load_lds_dwordx4 v[218:219], off
	v_lshl_add_u64 v[218:219], s[34:35], 0, v[130:131]
	s_add_i32 m0, s53, 0x2000
	s_nop 0
	global_load_lds_dwordx4 v[218:219], off
	v_lshl_add_u64 v[218:219], v[222:223], 0, s[8:9]
	s_mov_b32 m0, s61
	s_nop 0
	global_load_lds_dwordx4 v[218:219], off
	v_lshl_add_u64 v[218:219], v[224:225], 0, s[8:9]
	s_mov_b32 m0, s70
	s_nop 0
	global_load_lds_dwordx4 v[218:219], off
	s_waitcnt vmcnt(8)
	s_waitcnt lgkmcnt(0)
	s_barrier
	s_setprio 1
	s_waitcnt lgkmcnt(0)
	v_mfma_f32_16x16x32_bf16 v[62:65], v[146:149], v[184:187], v[62:65]
	v_mfma_f32_16x16x32_bf16 v[38:41], v[160:163], v[192:195], v[38:41]
	v_mfma_f32_16x16x32_bf16 v[30:33], v[146:149], v[200:203], v[30:33]
	v_mfma_f32_16x16x32_bf16 v[6:9], v[160:163], v[208:211], v[6:9]
	v_mfma_f32_16x16x32_bf16 v[46:49], v[146:149], v[192:195], v[46:49]
	v_mfma_f32_16x16x32_bf16 v[54:57], v[160:163], v[184:187], v[54:57]
	v_mfma_f32_16x16x32_bf16 v[14:17], v[146:149], v[208:211], v[14:17]
	v_mfma_f32_16x16x32_bf16 v[22:25], v[160:163], v[200:203], v[22:25]
	v_mfma_f32_16x16x32_bf16 v[62:65], v[156:159], v[188:191], v[62:65]
	v_mfma_f32_16x16x32_bf16 v[38:41], v[164:167], v[196:199], v[38:41]
	v_mfma_f32_16x16x32_bf16 v[30:33], v[156:159], v[204:207], v[30:33]
	v_mfma_f32_16x16x32_bf16 v[6:9], v[164:167], v[212:215], v[6:9]
	v_mfma_f32_16x16x32_bf16 v[46:49], v[156:159], v[196:199], v[46:49]
	v_mfma_f32_16x16x32_bf16 v[54:57], v[164:167], v[188:191], v[54:57]
	v_mfma_f32_16x16x32_bf16 v[14:17], v[156:159], v[212:215], v[14:17]
	v_mfma_f32_16x16x32_bf16 v[22:25], v[164:167], v[204:207], v[22:25]
	s_setprio 0
	s_setprio 1
	v_mfma_f32_16x16x32_bf16 v[58:61], v[168:171], v[184:187], v[58:61]
	v_mfma_f32_16x16x32_bf16 v[34:37], v[176:179], v[192:195], v[34:37]
	v_mfma_f32_16x16x32_bf16 v[26:29], v[168:171], v[200:203], v[26:29]
	v_mfma_f32_16x16x32_bf16 v[2:5], v[176:179], v[208:211], v[2:5]
	v_mfma_f32_16x16x32_bf16 v[42:45], v[168:171], v[192:195], v[42:45]
	v_mfma_f32_16x16x32_bf16 v[50:53], v[176:179], v[184:187], v[50:53]
	v_mfma_f32_16x16x32_bf16 v[10:13], v[168:171], v[208:211], v[10:13]
	v_mfma_f32_16x16x32_bf16 v[18:21], v[176:179], v[200:203], v[18:21]
	v_mfma_f32_16x16x32_bf16 v[58:61], v[172:175], v[188:191], v[58:61]
	v_mfma_f32_16x16x32_bf16 v[34:37], v[180:183], v[196:199], v[34:37]
	v_mfma_f32_16x16x32_bf16 v[26:29], v[172:175], v[204:207], v[26:29]
	v_mfma_f32_16x16x32_bf16 v[2:5], v[180:183], v[212:215], v[2:5]
	v_mfma_f32_16x16x32_bf16 v[42:45], v[172:175], v[196:199], v[42:45]
	v_mfma_f32_16x16x32_bf16 v[50:53], v[180:183], v[188:191], v[50:53]
	v_mfma_f32_16x16x32_bf16 v[10:13], v[172:175], v[212:215], v[10:13]
	v_mfma_f32_16x16x32_bf16 v[18:21], v[180:183], v[204:207], v[18:21]
	s_setprio 0
	s_barrier
	s_add_i32 s92, s92, 2
	s_add_u32 s88, s88, 0x100
	s_addc_u32 s89, s89, 0
	s_add_u32 s81, s81, 0x100
	s_addc_u32 s83, s83, 0
	s_cmp_gt_u32 s92, 29
	s_cbranch_scc0 .LBB0_1124
	v_mov_b32_e32 v157, 0xbfb8aa3b
	s_and_b64 vcc, exec, s[78:79]
	s_cbranch_vccz .LBB0_1127
	s_barrier

.LBB0_1237:
	ds_read_b128 v[146:149], v164
	ds_read_b128 v[150:153], v164 offset:1024
	ds_read_b128 v[154:157], v164 offset:2048
	ds_read_b128 v[158:161], v164 offset:3072
	ds_read_b128 v[168:171], v165
	ds_read_b128 v[172:175], v165 offset:1024
	ds_read_b128 v[176:179], v165 offset:2048
	ds_read_b128 v[180:183], v165 offset:3072
	s_add_u32 s34, s76, 0xffea0080
	s_addc_u32 s35, s77, -1
	s_cmpk_eq_i32 s52, 0x54
	s_cselect_b32 s85, s5, s35
	s_cselect_b32 s84, s4, s34
	s_cselect_b32 s35, s83, s1
	s_cselect_b32 s34, s82, s0
	v_lshl_add_u64 v[218:219], s[76:77], 0, v[138:139]
	s_add_i32 m0, s33, 0xc000
	ds_read_b128 v[184:187], v166
	ds_read_b128 v[188:191], v166 offset:1024
	ds_read_b128 v[192:195], v166 offset:2048
	ds_read_b128 v[196:199], v166 offset:3072
	ds_read_b128 v[200:203], v166 offset:4096
	ds_read_b128 v[204:207], v166 offset:5120
	ds_read_b128 v[208:211], v166 offset:6144
	ds_read_b128 v[212:215], v166 offset:7168
	global_load_lds_dwordx4 v[218:219], off
	v_lshl_add_u64 v[218:219], s[76:77], 0, v[140:141]
	s_add_i32 m0, s33, 0xe000
	s_nop 0
	global_load_lds_dwordx4 v[218:219], off
	s_waitcnt vmcnt(8)
	s_waitcnt lgkmcnt(0)
	s_barrier
	s_setprio 1
	s_waitcnt lgkmcnt(0)
	v_mfma_f32_16x16x32_bf16 v[126:129], v[146:149], v[184:187], v[126:129]
	v_mfma_f32_16x16x32_bf16 v[106:109], v[154:157], v[192:195], v[106:109]
	v_mfma_f32_16x16x32_bf16 v[94:97], v[146:149], v[200:203], v[94:97]
	v_mfma_f32_16x16x32_bf16 v[74:77], v[154:157], v[208:211], v[74:77]
	v_mfma_f32_16x16x32_bf16 v[110:113], v[146:149], v[192:195], v[110:113]
	v_mfma_f32_16x16x32_bf16 v[122:125], v[154:157], v[184:187], v[122:125]
	v_mfma_f32_16x16x32_bf16 v[78:81], v[146:149], v[208:211], v[78:81]
	v_mfma_f32_16x16x32_bf16 v[90:93], v[154:157], v[200:203], v[90:93]
	v_mfma_f32_16x16x32_bf16 v[126:129], v[150:153], v[188:191], v[126:129]
	v_mfma_f32_16x16x32_bf16 v[106:109], v[158:161], v[196:199], v[106:109]
	v_mfma_f32_16x16x32_bf16 v[94:97], v[150:153], v[204:207], v[94:97]
	v_mfma_f32_16x16x32_bf16 v[74:77], v[158:161], v[212:215], v[74:77]
	v_mfma_f32_16x16x32_bf16 v[110:113], v[150:153], v[196:199], v[110:113]
	v_mfma_f32_16x16x32_bf16 v[122:125], v[158:161], v[188:191], v[122:125]
	v_mfma_f32_16x16x32_bf16 v[78:81], v[150:153], v[212:215], v[78:81]
	v_mfma_f32_16x16x32_bf16 v[90:93], v[158:161], v[204:207], v[90:93]
	s_setprio 0
	s_setprio 1
	v_mfma_f32_16x16x32_bf16 v[118:121], v[168:171], v[184:187], v[118:121]
	v_mfma_f32_16x16x32_bf16 v[98:101], v[176:179], v[192:195], v[98:101]
	v_mfma_f32_16x16x32_bf16 v[86:89], v[168:171], v[200:203], v[86:89]
	v_mfma_f32_16x16x32_bf16 v[66:69], v[176:179], v[208:211], v[66:69]
	v_mfma_f32_16x16x32_bf16 v[102:105], v[168:171], v[192:195], v[102:105]
	v_mfma_f32_16x16x32_bf16 v[114:117], v[176:179], v[184:187], v[114:117]
	v_mfma_f32_16x16x32_bf16 v[70:73], v[168:171], v[208:211], v[70:73]
	v_mfma_f32_16x16x32_bf16 v[82:85], v[176:179], v[200:203], v[82:85]
	v_mfma_f32_16x16x32_bf16 v[118:121], v[172:175], v[188:191], v[118:121]
	v_mfma_f32_16x16x32_bf16 v[98:101], v[180:183], v[196:199], v[98:101]
	v_mfma_f32_16x16x32_bf16 v[86:89], v[172:175], v[204:207], v[86:89]
	v_mfma_f32_16x16x32_bf16 v[66:69], v[180:183], v[212:215], v[66:69]
	v_mfma_f32_16x16x32_bf16 v[102:105], v[172:175], v[196:199], v[102:105]
	v_mfma_f32_16x16x32_bf16 v[114:117], v[180:183], v[188:191], v[114:117]
	v_mfma_f32_16x16x32_bf16 v[70:73], v[172:175], v[212:215], v[70:73]
	v_mfma_f32_16x16x32_bf16 v[82:85], v[180:183], v[204:207], v[82:85]
	s_setprio 0
	s_barrier
	s_add_i32 s53, s71, s31
	v_lshl_add_u64 v[218:219], s[34:35], 0, v[132:133]
	s_mov_b32 m0, s53
	ds_read_b128 v[184:187], v166 offset:16384
	ds_read_b128 v[188:191], v166 offset:17408
	ds_read_b128 v[192:195], v166 offset:18432
	ds_read_b128 v[196:199], v166 offset:19456
	ds_read_b128 v[200:203], v166 offset:20480
	ds_read_b128 v[204:207], v166 offset:21504
	ds_read_b128 v[208:211], v166 offset:22528
	ds_read_b128 v[212:215], v166 offset:23552
	global_load_lds_dwordx4 v[218:219], off
	s_add_i32 m0, s53, 0x2000
	s_add_u32 s54, s34, 0x160000
	v_lshl_add_u64 v[220:221], s[34:35], 0, v[136:137]
	s_addc_u32 s55, s35, 0
	s_add_i32 s53, s72, s31
	global_load_lds_dwordx4 v[220:221], off
	v_lshl_add_u64 v[222:223], s[54:55], 0, v[132:133]
	s_mov_b32 m0, s53
	v_lshl_add_u64 v[224:225], s[84:85], 0, v[134:135]
	global_load_lds_dwordx4 v[222:223], off
	v_lshl_add_u64 v[222:223], s[54:55], 0, v[136:137]
	s_add_i32 m0, s53, 0x2000
	s_nop 0
	global_load_lds_dwordx4 v[222:223], off
	v_lshl_add_u64 v[222:223], s[84:85], 0, v[130:131]
	s_mov_b32 m0, s33
	s_nop 0
	global_load_lds_dwordx4 v[222:223], off
	s_mov_b32 m0, s56
	s_nop 0
	global_load_lds_dwordx4 v[224:225], off
	s_waitcnt vmcnt(8)
	s_waitcnt lgkmcnt(0)
	s_barrier
	s_setprio 1
	s_waitcnt lgkmcnt(0)
	v_mfma_f32_16x16x32_bf16 v[62:65], v[146:149], v[184:187], v[62:65]
	v_mfma_f32_16x16x32_bf16 v[42:45], v[154:157], v[192:195], v[42:45]
	v_mfma_f32_16x16x32_bf16 v[30:33], v[146:149], v[200:203], v[30:33]
	v_mfma_f32_16x16x32_bf16 v[10:13], v[154:157], v[208:211], v[10:13]
	v_mfma_f32_16x16x32_bf16 v[46:49], v[146:149], v[192:195], v[46:49]
	v_mfma_f32_16x16x32_bf16 v[58:61], v[154:157], v[184:187], v[58:61]
	v_mfma_f32_16x16x32_bf16 v[14:17], v[146:149], v[208:211], v[14:17]
	v_mfma_f32_16x16x32_bf16 v[26:29], v[154:157], v[200:203], v[26:29]
	v_mfma_f32_16x16x32_bf16 v[62:65], v[150:153], v[188:191], v[62:65]
	v_mfma_f32_16x16x32_bf16 v[42:45], v[158:161], v[196:199], v[42:45]
	v_mfma_f32_16x16x32_bf16 v[30:33], v[150:153], v[204:207], v[30:33]
	v_mfma_f32_16x16x32_bf16 v[10:13], v[158:161], v[212:215], v[10:13]
	v_mfma_f32_16x16x32_bf16 v[46:49], v[150:153], v[196:199], v[46:49]
	v_mfma_f32_16x16x32_bf16 v[58:61], v[158:161], v[188:191], v[58:61]
	v_mfma_f32_16x16x32_bf16 v[14:17], v[150:153], v[212:215], v[14:17]
	v_mfma_f32_16x16x32_bf16 v[26:29], v[158:161], v[204:207], v[26:29]
	s_setprio 0
	s_setprio 1
	v_mfma_f32_16x16x32_bf16 v[54:57], v[168:171], v[184:187], v[54:57]
	v_mfma_f32_16x16x32_bf16 v[34:37], v[176:179], v[192:195], v[34:37]
	v_mfma_f32_16x16x32_bf16 v[22:25], v[168:171], v[200:203], v[22:25]
	v_mfma_f32_16x16x32_bf16 v[2:5], v[176:179], v[208:211], v[2:5]
	v_mfma_f32_16x16x32_bf16 v[38:41], v[168:171], v[192:195], v[38:41]
	v_mfma_f32_16x16x32_bf16 v[50:53], v[176:179], v[184:187], v[50:53]
	v_mfma_f32_16x16x32_bf16 v[6:9], v[168:171], v[208:211], v[6:9]
	v_mfma_f32_16x16x32_bf16 v[18:21], v[176:179], v[200:203], v[18:21]
	v_mfma_f32_16x16x32_bf16 v[54:57], v[172:175], v[188:191], v[54:57]
	v_mfma_f32_16x16x32_bf16 v[34:37], v[180:183], v[196:199], v[34:37]
	v_mfma_f32_16x16x32_bf16 v[22:25], v[172:175], v[204:207], v[22:25]
	v_mfma_f32_16x16x32_bf16 v[2:5], v[180:183], v[212:215], v[2:5]
	v_mfma_f32_16x16x32_bf16 v[38:41], v[172:175], v[196:199], v[38:41]
	v_mfma_f32_16x16x32_bf16 v[50:53], v[180:183], v[188:191], v[50:53]
	v_mfma_f32_16x16x32_bf16 v[6:9], v[172:175], v[212:215], v[6:9]
	v_mfma_f32_16x16x32_bf16 v[18:21], v[180:183], v[204:207], v[18:21]
	s_setprio 0
	s_barrier
	s_add_i32 s53, 0, 0x18000
	s_add_i32 s62, 0, 0x1c000
	v_add_u32_e32 v158, s53, v162
	v_add_u32_e32 v167, s62, v162
	ds_read_b128 v[146:149], v158
	ds_read_b128 v[150:153], v158 offset:1024
	ds_read_b128 v[154:157], v158 offset:2048
	ds_read_b128 v[158:161], v158 offset:3072
	ds_read_b128 v[168:171], v167
	ds_read_b128 v[172:175], v167 offset:1024
	ds_read_b128 v[176:179], v167 offset:2048
	ds_read_b128 v[180:183], v167 offset:3072
	s_add_u32 s54, s84, 0x160000
	s_addc_u32 s55, s85, 0
	s_mov_b32 m0, s57
	v_lshl_add_u64 v[226:227], s[54:55], 0, v[130:131]
	ds_read_b128 v[184:187], v166 offset:32768
	ds_read_b128 v[188:191], v166 offset:33792
	ds_read_b128 v[192:195], v166 offset:34816
	ds_read_b128 v[196:199], v166 offset:35840
	ds_read_b128 v[200:203], v166 offset:36864
	ds_read_b128 v[204:207], v166 offset:37888
	ds_read_b128 v[208:211], v166 offset:38912
	ds_read_b128 v[212:215], v166 offset:39936
	global_load_lds_dwordx4 v[226:227], off
	v_lshl_add_u64 v[226:227], s[54:55], 0, v[134:135]
	s_mov_b32 m0, s58
	s_nop 0
	global_load_lds_dwordx4 v[226:227], off
	s_waitcnt vmcnt(8)
	s_waitcnt lgkmcnt(0)
	s_barrier
	s_setprio 1
	s_waitcnt lgkmcnt(0)
	v_mfma_f32_16x16x32_bf16 v[126:129], v[146:149], v[184:187], v[126:129]
	v_mfma_f32_16x16x32_bf16 v[106:109], v[154:157], v[192:195], v[106:109]
	v_mfma_f32_16x16x32_bf16 v[94:97], v[146:149], v[200:203], v[94:97]
	v_mfma_f32_16x16x32_bf16 v[74:77], v[154:157], v[208:211], v[74:77]
	v_mfma_f32_16x16x32_bf16 v[110:113], v[146:149], v[192:195], v[110:113]
	v_mfma_f32_16x16x32_bf16 v[122:125], v[154:157], v[184:187], v[122:125]
	v_mfma_f32_16x16x32_bf16 v[78:81], v[146:149], v[208:211], v[78:81]
	v_mfma_f32_16x16x32_bf16 v[90:93], v[154:157], v[200:203], v[90:93]
	v_mfma_f32_16x16x32_bf16 v[126:129], v[150:153], v[188:191], v[126:129]
	v_mfma_f32_16x16x32_bf16 v[106:109], v[158:161], v[196:199], v[106:109]
	v_mfma_f32_16x16x32_bf16 v[94:97], v[150:153], v[204:207], v[94:97]
	v_mfma_f32_16x16x32_bf16 v[74:77], v[158:161], v[212:215], v[74:77]
	v_mfma_f32_16x16x32_bf16 v[110:113], v[150:153], v[196:199], v[110:113]
	v_mfma_f32_16x16x32_bf16 v[122:125], v[158:161], v[188:191], v[122:125]
	v_mfma_f32_16x16x32_bf16 v[78:81], v[150:153], v[212:215], v[78:81]
	v_mfma_f32_16x16x32_bf16 v[90:93], v[158:161], v[204:207], v[90:93]
	s_setprio 0
	s_setprio 1
	v_mfma_f32_16x16x32_bf16 v[118:121], v[168:171], v[184:187], v[118:121]
	v_mfma_f32_16x16x32_bf16 v[98:101], v[176:179], v[192:195], v[98:101]
	v_mfma_f32_16x16x32_bf16 v[86:89], v[168:171], v[200:203], v[86:89]
	v_mfma_f32_16x16x32_bf16 v[66:69], v[176:179], v[208:211], v[66:69]
	v_mfma_f32_16x16x32_bf16 v[102:105], v[168:171], v[192:195], v[102:105]
	v_mfma_f32_16x16x32_bf16 v[114:117], v[176:179], v[184:187], v[114:117]
	v_mfma_f32_16x16x32_bf16 v[70:73], v[168:171], v[208:211], v[70:73]
	v_mfma_f32_16x16x32_bf16 v[82:85], v[176:179], v[200:203], v[82:85]
	v_mfma_f32_16x16x32_bf16 v[118:121], v[172:175], v[188:191], v[118:121]
	v_mfma_f32_16x16x32_bf16 v[98:101], v[180:183], v[196:199], v[98:101]
	v_mfma_f32_16x16x32_bf16 v[86:89], v[172:175], v[204:207], v[86:89]
	v_mfma_f32_16x16x32_bf16 v[66:69], v[180:183], v[212:215], v[66:69]
	v_mfma_f32_16x16x32_bf16 v[102:105], v[172:175], v[196:199], v[102:105]
	v_mfma_f32_16x16x32_bf16 v[114:117], v[180:183], v[188:191], v[114:117]
	v_mfma_f32_16x16x32_bf16 v[70:73], v[172:175], v[212:215], v[70:73]
	v_mfma_f32_16x16x32_bf16 v[82:85], v[180:183], v[204:207], v[82:85]
	s_setprio 0
	s_barrier
	s_add_i32 s53, s53, s31
	v_lshl_add_u64 v[218:219], v[218:219], 0, s[78:79]
	s_mov_b32 m0, s53
	ds_read_b128 v[184:187], v166 offset:49152
	ds_read_b128 v[188:191], v166 offset:50176
	ds_read_b128 v[192:195], v166 offset:51200
	ds_read_b128 v[196:199], v166 offset:52224
	ds_read_b128 v[200:203], v166 offset:53248
	ds_read_b128 v[204:207], v166 offset:54272
	ds_read_b128 v[208:211], v166 offset:55296
	ds_read_b128 v[212:215], v166 offset:56320
	global_load_lds_dwordx4 v[218:219], off
	s_add_i32 m0, s53, 0x2000
	s_add_u32 s34, s34, 0x160080
	v_lshl_add_u64 v[218:219], v[220:221], 0, s[78:79]
	s_addc_u32 s35, s35, 0
	s_add_i32 s53, s62, s31
	global_load_lds_dwordx4 v[218:219], off
	v_lshl_add_u64 v[218:219], s[34:35], 0, v[132:133]
	s_mov_b32 m0, s53
	s_nop 0
	global_load_lds_dwordx4 v[218:219], off
	v_lshl_add_u64 v[218:219], s[34:35], 0, v[136:137]
	s_add_i32 m0, s53, 0x2000
	s_nop 0
	global_load_lds_dwordx4 v[218:219], off
	v_lshl_add_u64 v[218:219], v[222:223], 0, s[78:79]
	s_mov_b32 m0, s60
	s_nop 0
	global_load_lds_dwordx4 v[218:219], off
	v_lshl_add_u64 v[218:219], v[224:225], 0, s[78:79]
	s_mov_b32 m0, s61
	s_nop 0
	global_load_lds_dwordx4 v[218:219], off
	s_waitcnt vmcnt(8)
	s_waitcnt lgkmcnt(0)
	s_barrier
	s_setprio 1
	s_waitcnt lgkmcnt(0)
	v_mfma_f32_16x16x32_bf16 v[62:65], v[146:149], v[184:187], v[62:65]
	v_mfma_f32_16x16x32_bf16 v[42:45], v[154:157], v[192:195], v[42:45]
	v_mfma_f32_16x16x32_bf16 v[30:33], v[146:149], v[200:203], v[30:33]
	v_mfma_f32_16x16x32_bf16 v[10:13], v[154:157], v[208:211], v[10:13]
	v_mfma_f32_16x16x32_bf16 v[46:49], v[146:149], v[192:195], v[46:49]
	v_mfma_f32_16x16x32_bf16 v[58:61], v[154:157], v[184:187], v[58:61]
	v_mfma_f32_16x16x32_bf16 v[14:17], v[146:149], v[208:211], v[14:17]
	v_mfma_f32_16x16x32_bf16 v[26:29], v[154:157], v[200:203], v[26:29]
	v_mfma_f32_16x16x32_bf16 v[62:65], v[150:153], v[188:191], v[62:65]
	v_mfma_f32_16x16x32_bf16 v[42:45], v[158:161], v[196:199], v[42:45]
	v_mfma_f32_16x16x32_bf16 v[30:33], v[150:153], v[204:207], v[30:33]
	v_mfma_f32_16x16x32_bf16 v[10:13], v[158:161], v[212:215], v[10:13]
	v_mfma_f32_16x16x32_bf16 v[46:49], v[150:153], v[196:199], v[46:49]
	v_mfma_f32_16x16x32_bf16 v[58:61], v[158:161], v[188:191], v[58:61]
	v_mfma_f32_16x16x32_bf16 v[14:17], v[150:153], v[212:215], v[14:17]
	v_mfma_f32_16x16x32_bf16 v[26:29], v[158:161], v[204:207], v[26:29]
	s_setprio 0
	s_setprio 1
	v_mfma_f32_16x16x32_bf16 v[54:57], v[168:171], v[184:187], v[54:57]
	v_mfma_f32_16x16x32_bf16 v[34:37], v[176:179], v[192:195], v[34:37]
	v_mfma_f32_16x16x32_bf16 v[22:25], v[168:171], v[200:203], v[22:25]
	v_mfma_f32_16x16x32_bf16 v[2:5], v[176:179], v[208:211], v[2:5]
	v_mfma_f32_16x16x32_bf16 v[38:41], v[168:171], v[192:195], v[38:41]
	v_mfma_f32_16x16x32_bf16 v[50:53], v[176:179], v[184:187], v[50:53]
	v_mfma_f32_16x16x32_bf16 v[6:9], v[168:171], v[208:211], v[6:9]
	v_mfma_f32_16x16x32_bf16 v[18:21], v[176:179], v[200:203], v[18:21]
	v_mfma_f32_16x16x32_bf16 v[54:57], v[172:175], v[188:191], v[54:57]
	v_mfma_f32_16x16x32_bf16 v[34:37], v[180:183], v[196:199], v[34:37]
	v_mfma_f32_16x16x32_bf16 v[22:25], v[172:175], v[204:207], v[22:25]
	v_mfma_f32_16x16x32_bf16 v[2:5], v[180:183], v[212:215], v[2:5]
	v_mfma_f32_16x16x32_bf16 v[38:41], v[172:175], v[196:199], v[38:41]
	v_mfma_f32_16x16x32_bf16 v[50:53], v[180:183], v[188:191], v[50:53]
	v_mfma_f32_16x16x32_bf16 v[6:9], v[172:175], v[212:215], v[6:9]
	v_mfma_f32_16x16x32_bf16 v[18:21], v[180:183], v[204:207], v[18:21]
	s_setprio 0
	s_barrier
	s_add_i32 s52, s52, 2
	s_add_u32 s76, s76, 0x100
	s_addc_u32 s77, s77, 0
	s_add_u32 s0, s0, 0x100
	s_addc_u32 s1, s1, 0
	s_cmpk_gt_u32 s52, 0x55
	s_cbranch_scc0 .LBB0_1237
	s_and_b64 vcc, exec, s[80:81]
	s_cbranch_vccz .LBB0_1240
	s_barrier

.LBB0_1624:
	ds_read_b128 v[154:157], v151
	ds_read_b128 v[158:161], v151 offset:1024
	ds_read_b128 v[162:165], v151 offset:2048
	ds_read_b128 v[166:169], v151 offset:3072
	ds_read_b128 v[170:173], v152
	ds_read_b128 v[174:177], v152 offset:1024
	ds_read_b128 v[178:181], v152 offset:2048
	ds_read_b128 v[182:185], v152 offset:3072
	s_add_u32 s34, s88, 0xfff80080
	s_addc_u32 s35, s89, -1
	s_cmp_eq_u32 s83, 28
	s_cselect_b32 s91, s0, s35
	s_cselect_b32 s90, s1, s34
	s_cselect_b32 s35, s52, s81
	s_cselect_b32 s34, s75, s77
	v_lshl_add_u64 v[146:147], s[88:89], 0, v[138:139]
	s_add_i32 m0, s33, 0xc000
	ds_read_b128 v[186:189], v153
	ds_read_b128 v[190:193], v153 offset:1024
	ds_read_b128 v[194:197], v153 offset:2048
	ds_read_b128 v[198:201], v153 offset:3072
	ds_read_b128 v[202:205], v153 offset:4096
	ds_read_b128 v[206:209], v153 offset:5120
	ds_read_b128 v[210:213], v153 offset:6144
	ds_read_b128 v[218:221], v153 offset:7168
	global_load_lds_dwordx4 v[146:147], off
	v_lshl_add_u64 v[146:147], s[88:89], 0, v[140:141]
	s_add_i32 m0, s33, 0xe000
	s_nop 0
	global_load_lds_dwordx4 v[146:147], off
	s_waitcnt vmcnt(8)
	s_waitcnt lgkmcnt(0)
	s_barrier
	s_setprio 1
	s_waitcnt lgkmcnt(0)
	v_mfma_f32_16x16x32_bf16 v[126:129], v[154:157], v[186:189], v[126:129]
	v_mfma_f32_16x16x32_bf16 v[106:109], v[162:165], v[194:197], v[106:109]
	v_mfma_f32_16x16x32_bf16 v[98:101], v[154:157], v[202:205], v[98:101]
	v_mfma_f32_16x16x32_bf16 v[74:77], v[162:165], v[210:213], v[74:77]
	v_mfma_f32_16x16x32_bf16 v[114:117], v[154:157], v[194:197], v[114:117]
	v_mfma_f32_16x16x32_bf16 v[122:125], v[162:165], v[186:189], v[122:125]
	v_mfma_f32_16x16x32_bf16 v[82:85], v[154:157], v[210:213], v[82:85]
	v_mfma_f32_16x16x32_bf16 v[90:93], v[162:165], v[202:205], v[90:93]
	v_mfma_f32_16x16x32_bf16 v[126:129], v[158:161], v[190:193], v[126:129]
	v_mfma_f32_16x16x32_bf16 v[106:109], v[166:169], v[198:201], v[106:109]
	v_mfma_f32_16x16x32_bf16 v[98:101], v[158:161], v[206:209], v[98:101]
	v_mfma_f32_16x16x32_bf16 v[74:77], v[166:169], v[218:221], v[74:77]
	v_mfma_f32_16x16x32_bf16 v[114:117], v[158:161], v[198:201], v[114:117]
	v_mfma_f32_16x16x32_bf16 v[122:125], v[166:169], v[190:193], v[122:125]
	v_mfma_f32_16x16x32_bf16 v[82:85], v[158:161], v[218:221], v[82:85]
	v_mfma_f32_16x16x32_bf16 v[90:93], v[166:169], v[206:209], v[90:93]
	s_setprio 0
	s_setprio 1
	v_mfma_f32_16x16x32_bf16 v[118:121], v[170:173], v[186:189], v[118:121]
	v_mfma_f32_16x16x32_bf16 v[94:97], v[178:181], v[194:197], v[94:97]
	v_mfma_f32_16x16x32_bf16 v[86:89], v[170:173], v[202:205], v[86:89]
	v_mfma_f32_16x16x32_bf16 v[66:69], v[178:181], v[210:213], v[66:69]
	v_mfma_f32_16x16x32_bf16 v[102:105], v[170:173], v[194:197], v[102:105]
	v_mfma_f32_16x16x32_bf16 v[110:113], v[178:181], v[186:189], v[110:113]
	v_mfma_f32_16x16x32_bf16 v[70:73], v[170:173], v[210:213], v[70:73]
	v_mfma_f32_16x16x32_bf16 v[78:81], v[178:181], v[202:205], v[78:81]
	v_mfma_f32_16x16x32_bf16 v[118:121], v[174:177], v[190:193], v[118:121]
	v_mfma_f32_16x16x32_bf16 v[94:97], v[182:185], v[198:201], v[94:97]
	v_mfma_f32_16x16x32_bf16 v[86:89], v[174:177], v[206:209], v[86:89]
	v_mfma_f32_16x16x32_bf16 v[66:69], v[182:185], v[218:221], v[66:69]
	v_mfma_f32_16x16x32_bf16 v[102:105], v[174:177], v[198:201], v[102:105]
	v_mfma_f32_16x16x32_bf16 v[110:113], v[182:185], v[190:193], v[110:113]
	v_mfma_f32_16x16x32_bf16 v[70:73], v[174:177], v[218:221], v[70:73]
	v_mfma_f32_16x16x32_bf16 v[78:81], v[182:185], v[206:209], v[78:81]
	s_setprio 0
	s_barrier
	s_add_i32 s53, s71, s12
	v_lshl_add_u64 v[146:147], s[34:35], 0, v[134:135]
	s_mov_b32 m0, s53
	ds_read_b128 v[186:189], v153 offset:16384
	ds_read_b128 v[190:193], v153 offset:17408
	ds_read_b128 v[194:197], v153 offset:18432
	ds_read_b128 v[198:201], v153 offset:19456
	ds_read_b128 v[202:205], v153 offset:20480
	ds_read_b128 v[206:209], v153 offset:21504
	ds_read_b128 v[210:213], v153 offset:22528
	ds_read_b128 v[218:221], v153 offset:23552
	global_load_lds_dwordx4 v[146:147], off
	s_add_i32 m0, s53, 0x2000
	s_add_u32 s54, s34, 0x80000
	v_lshl_add_u64 v[214:215], s[34:35], 0, v[130:131]
	s_addc_u32 s55, s35, 0
	s_add_i32 s53, s72, s12
	global_load_lds_dwordx4 v[214:215], off
	v_lshl_add_u64 v[222:223], s[54:55], 0, v[134:135]
	s_mov_b32 m0, s53
	v_lshl_add_u64 v[224:225], s[90:91], 0, v[132:133]
	global_load_lds_dwordx4 v[222:223], off
	v_lshl_add_u64 v[222:223], s[54:55], 0, v[130:131]
	s_add_i32 m0, s53, 0x2000
	s_nop 0
	global_load_lds_dwordx4 v[222:223], off
	v_lshl_add_u64 v[222:223], s[90:91], 0, v[136:137]
	s_mov_b32 m0, s33
	s_nop 0
	global_load_lds_dwordx4 v[222:223], off
	s_mov_b32 m0, s56
	s_nop 0
	global_load_lds_dwordx4 v[224:225], off
	s_waitcnt vmcnt(8)
	s_waitcnt lgkmcnt(0)
	s_barrier
	s_setprio 1
	s_waitcnt lgkmcnt(0)
	v_mfma_f32_16x16x32_bf16 v[62:65], v[154:157], v[186:189], v[62:65]
	v_mfma_f32_16x16x32_bf16 v[42:45], v[162:165], v[194:197], v[42:45]
	v_mfma_f32_16x16x32_bf16 v[34:37], v[154:157], v[202:205], v[34:37]
	v_mfma_f32_16x16x32_bf16 v[10:13], v[162:165], v[210:213], v[10:13]
	v_mfma_f32_16x16x32_bf16 v[50:53], v[154:157], v[194:197], v[50:53]
	v_mfma_f32_16x16x32_bf16 v[58:61], v[162:165], v[186:189], v[58:61]
	v_mfma_f32_16x16x32_bf16 v[18:21], v[154:157], v[210:213], v[18:21]
	v_mfma_f32_16x16x32_bf16 v[26:29], v[162:165], v[202:205], v[26:29]
	v_mfma_f32_16x16x32_bf16 v[62:65], v[158:161], v[190:193], v[62:65]
	v_mfma_f32_16x16x32_bf16 v[42:45], v[166:169], v[198:201], v[42:45]
	v_mfma_f32_16x16x32_bf16 v[34:37], v[158:161], v[206:209], v[34:37]
	v_mfma_f32_16x16x32_bf16 v[10:13], v[166:169], v[218:221], v[10:13]
	v_mfma_f32_16x16x32_bf16 v[50:53], v[158:161], v[198:201], v[50:53]
	v_mfma_f32_16x16x32_bf16 v[58:61], v[166:169], v[190:193], v[58:61]
	v_mfma_f32_16x16x32_bf16 v[18:21], v[158:161], v[218:221], v[18:21]
	v_mfma_f32_16x16x32_bf16 v[26:29], v[166:169], v[206:209], v[26:29]
	s_setprio 0
	s_setprio 1
	v_mfma_f32_16x16x32_bf16 v[54:57], v[170:173], v[186:189], v[54:57]
	v_mfma_f32_16x16x32_bf16 v[30:33], v[178:181], v[194:197], v[30:33]
	v_mfma_f32_16x16x32_bf16 v[22:25], v[170:173], v[202:205], v[22:25]
	v_mfma_f32_16x16x32_bf16 v[2:5], v[178:181], v[210:213], v[2:5]
	v_mfma_f32_16x16x32_bf16 v[38:41], v[170:173], v[194:197], v[38:41]
	v_mfma_f32_16x16x32_bf16 v[46:49], v[178:181], v[186:189], v[46:49]
	v_mfma_f32_16x16x32_bf16 v[6:9], v[170:173], v[210:213], v[6:9]
	v_mfma_f32_16x16x32_bf16 v[14:17], v[178:181], v[202:205], v[14:17]
	v_mfma_f32_16x16x32_bf16 v[54:57], v[174:177], v[190:193], v[54:57]
	v_mfma_f32_16x16x32_bf16 v[30:33], v[182:185], v[198:201], v[30:33]
	v_mfma_f32_16x16x32_bf16 v[22:25], v[174:177], v[206:209], v[22:25]
	v_mfma_f32_16x16x32_bf16 v[2:5], v[182:185], v[218:221], v[2:5]
	v_mfma_f32_16x16x32_bf16 v[38:41], v[174:177], v[198:201], v[38:41]
	v_mfma_f32_16x16x32_bf16 v[46:49], v[182:185], v[190:193], v[46:49]
	v_mfma_f32_16x16x32_bf16 v[6:9], v[174:177], v[218:221], v[6:9]
	v_mfma_f32_16x16x32_bf16 v[14:17], v[182:185], v[206:209], v[14:17]
	s_setprio 0
	s_barrier
	s_add_i32 s53, 0, 0x18000
	s_add_i32 s62, 0, 0x1c000
	v_add_u32_e32 v166, s53, v149
	v_add_u32_e32 v182, s62, v149
	ds_read_b128 v[154:157], v166
	ds_read_b128 v[158:161], v166 offset:1024
	ds_read_b128 v[162:165], v166 offset:2048
	ds_read_b128 v[166:169], v166 offset:3072
	ds_read_b128 v[170:173], v182
	ds_read_b128 v[174:177], v182 offset:1024
	ds_read_b128 v[178:181], v182 offset:2048
	ds_read_b128 v[182:185], v182 offset:3072
	s_add_u32 s54, s90, 0x80000
	s_addc_u32 s55, s91, 0
	s_mov_b32 m0, s57
	v_lshl_add_u64 v[226:227], s[54:55], 0, v[136:137]
	ds_read_b128 v[186:189], v153 offset:32768
	ds_read_b128 v[190:193], v153 offset:33792
	ds_read_b128 v[194:197], v153 offset:34816
	ds_read_b128 v[198:201], v153 offset:35840
	ds_read_b128 v[202:205], v153 offset:36864
	ds_read_b128 v[206:209], v153 offset:37888
	ds_read_b128 v[210:213], v153 offset:38912
	ds_read_b128 v[218:221], v153 offset:39936
	global_load_lds_dwordx4 v[226:227], off
	v_lshl_add_u64 v[226:227], s[54:55], 0, v[132:133]
	s_mov_b32 m0, s58
	s_nop 0
	global_load_lds_dwordx4 v[226:227], off
	s_waitcnt vmcnt(8)
	s_waitcnt lgkmcnt(0)
	s_barrier
	s_setprio 1
	s_waitcnt lgkmcnt(0)
	v_mfma_f32_16x16x32_bf16 v[126:129], v[154:157], v[186:189], v[126:129]
	v_mfma_f32_16x16x32_bf16 v[106:109], v[162:165], v[194:197], v[106:109]
	v_mfma_f32_16x16x32_bf16 v[98:101], v[154:157], v[202:205], v[98:101]
	v_mfma_f32_16x16x32_bf16 v[74:77], v[162:165], v[210:213], v[74:77]
	v_mfma_f32_16x16x32_bf16 v[114:117], v[154:157], v[194:197], v[114:117]
	v_mfma_f32_16x16x32_bf16 v[122:125], v[162:165], v[186:189], v[122:125]
	v_mfma_f32_16x16x32_bf16 v[82:85], v[154:157], v[210:213], v[82:85]
	v_mfma_f32_16x16x32_bf16 v[90:93], v[162:165], v[202:205], v[90:93]
	v_mfma_f32_16x16x32_bf16 v[126:129], v[158:161], v[190:193], v[126:129]
	v_mfma_f32_16x16x32_bf16 v[106:109], v[166:169], v[198:201], v[106:109]
	v_mfma_f32_16x16x32_bf16 v[98:101], v[158:161], v[206:209], v[98:101]
	v_mfma_f32_16x16x32_bf16 v[74:77], v[166:169], v[218:221], v[74:77]
	v_mfma_f32_16x16x32_bf16 v[114:117], v[158:161], v[198:201], v[114:117]
	v_mfma_f32_16x16x32_bf16 v[122:125], v[166:169], v[190:193], v[122:125]
	v_mfma_f32_16x16x32_bf16 v[82:85], v[158:161], v[218:221], v[82:85]
	v_mfma_f32_16x16x32_bf16 v[90:93], v[166:169], v[206:209], v[90:93]
	s_setprio 0
	s_setprio 1
	v_mfma_f32_16x16x32_bf16 v[118:121], v[170:173], v[186:189], v[118:121]
	v_mfma_f32_16x16x32_bf16 v[94:97], v[178:181], v[194:197], v[94:97]
	v_mfma_f32_16x16x32_bf16 v[86:89], v[170:173], v[202:205], v[86:89]
	v_mfma_f32_16x16x32_bf16 v[66:69], v[178:181], v[210:213], v[66:69]
	v_mfma_f32_16x16x32_bf16 v[102:105], v[170:173], v[194:197], v[102:105]
	v_mfma_f32_16x16x32_bf16 v[110:113], v[178:181], v[186:189], v[110:113]
	v_mfma_f32_16x16x32_bf16 v[70:73], v[170:173], v[210:213], v[70:73]
	v_mfma_f32_16x16x32_bf16 v[78:81], v[178:181], v[202:205], v[78:81]
	v_mfma_f32_16x16x32_bf16 v[118:121], v[174:177], v[190:193], v[118:121]
	v_mfma_f32_16x16x32_bf16 v[94:97], v[182:185], v[198:201], v[94:97]
	v_mfma_f32_16x16x32_bf16 v[86:89], v[174:177], v[206:209], v[86:89]
	v_mfma_f32_16x16x32_bf16 v[66:69], v[182:185], v[218:221], v[66:69]
	v_mfma_f32_16x16x32_bf16 v[102:105], v[174:177], v[198:201], v[102:105]
	v_mfma_f32_16x16x32_bf16 v[110:113], v[182:185], v[190:193], v[110:113]
	v_mfma_f32_16x16x32_bf16 v[70:73], v[174:177], v[218:221], v[70:73]
	v_mfma_f32_16x16x32_bf16 v[78:81], v[182:185], v[206:209], v[78:81]
	s_setprio 0
	s_barrier
	s_add_i32 s53, s53, s12
	v_lshl_add_u64 v[146:147], v[146:147], 0, s[8:9]
	s_mov_b32 m0, s53
	ds_read_b128 v[186:189], v153 offset:49152
	ds_read_b128 v[190:193], v153 offset:50176
	ds_read_b128 v[194:197], v153 offset:51200
	ds_read_b128 v[198:201], v153 offset:52224
	ds_read_b128 v[202:205], v153 offset:53248
	ds_read_b128 v[206:209], v153 offset:54272
	ds_read_b128 v[210:213], v153 offset:55296
	ds_read_b128 v[218:221], v153 offset:56320
	global_load_lds_dwordx4 v[146:147], off
	s_add_i32 m0, s53, 0x2000
	s_add_u32 s34, s34, 0x80080
	v_lshl_add_u64 v[146:147], v[214:215], 0, s[8:9]
	s_addc_u32 s35, s35, 0
	s_add_i32 s53, s62, s12
	global_load_lds_dwordx4 v[146:147], off
	v_lshl_add_u64 v[146:147], s[34:35], 0, v[134:135]
	s_mov_b32 m0, s53
	s_nop 0
	global_load_lds_dwordx4 v[146:147], off
	v_lshl_add_u64 v[146:147], s[34:35], 0, v[130:131]
	s_add_i32 m0, s53, 0x2000
	s_nop 0
	global_load_lds_dwordx4 v[146:147], off
	v_lshl_add_u64 v[146:147], v[222:223], 0, s[8:9]
	s_mov_b32 m0, s60
	s_nop 0
	global_load_lds_dwordx4 v[146:147], off
	v_lshl_add_u64 v[146:147], v[224:225], 0, s[8:9]
	s_mov_b32 m0, s61
	s_nop 0
	global_load_lds_dwordx4 v[146:147], off
	s_waitcnt vmcnt(8)
	s_waitcnt lgkmcnt(0)
	s_barrier
	s_setprio 1
	s_waitcnt lgkmcnt(0)
	v_mfma_f32_16x16x32_bf16 v[62:65], v[154:157], v[186:189], v[62:65]
	v_mfma_f32_16x16x32_bf16 v[42:45], v[162:165], v[194:197], v[42:45]
	v_mfma_f32_16x16x32_bf16 v[34:37], v[154:157], v[202:205], v[34:37]
	v_mfma_f32_16x16x32_bf16 v[10:13], v[162:165], v[210:213], v[10:13]
	v_mfma_f32_16x16x32_bf16 v[50:53], v[154:157], v[194:197], v[50:53]
	v_mfma_f32_16x16x32_bf16 v[58:61], v[162:165], v[186:189], v[58:61]
	v_mfma_f32_16x16x32_bf16 v[18:21], v[154:157], v[210:213], v[18:21]
	v_mfma_f32_16x16x32_bf16 v[26:29], v[162:165], v[202:205], v[26:29]
	v_mfma_f32_16x16x32_bf16 v[62:65], v[158:161], v[190:193], v[62:65]
	v_mfma_f32_16x16x32_bf16 v[42:45], v[166:169], v[198:201], v[42:45]
	v_mfma_f32_16x16x32_bf16 v[34:37], v[158:161], v[206:209], v[34:37]
	v_mfma_f32_16x16x32_bf16 v[10:13], v[166:169], v[218:221], v[10:13]
	v_mfma_f32_16x16x32_bf16 v[50:53], v[158:161], v[198:201], v[50:53]
	v_mfma_f32_16x16x32_bf16 v[58:61], v[166:169], v[190:193], v[58:61]
	v_mfma_f32_16x16x32_bf16 v[18:21], v[158:161], v[218:221], v[18:21]
	v_mfma_f32_16x16x32_bf16 v[26:29], v[166:169], v[206:209], v[26:29]
	s_setprio 0
	s_setprio 1
	v_mfma_f32_16x16x32_bf16 v[54:57], v[170:173], v[186:189], v[54:57]
	v_mfma_f32_16x16x32_bf16 v[30:33], v[178:181], v[194:197], v[30:33]
	v_mfma_f32_16x16x32_bf16 v[22:25], v[170:173], v[202:205], v[22:25]
	v_mfma_f32_16x16x32_bf16 v[2:5], v[178:181], v[210:213], v[2:5]
	v_mfma_f32_16x16x32_bf16 v[38:41], v[170:173], v[194:197], v[38:41]
	v_mfma_f32_16x16x32_bf16 v[46:49], v[178:181], v[186:189], v[46:49]
	v_mfma_f32_16x16x32_bf16 v[6:9], v[170:173], v[210:213], v[6:9]
	v_mfma_f32_16x16x32_bf16 v[14:17], v[178:181], v[202:205], v[14:17]
	v_mfma_f32_16x16x32_bf16 v[54:57], v[174:177], v[190:193], v[54:57]
	v_mfma_f32_16x16x32_bf16 v[30:33], v[182:185], v[198:201], v[30:33]
	v_mfma_f32_16x16x32_bf16 v[22:25], v[174:177], v[206:209], v[22:25]
	v_mfma_f32_16x16x32_bf16 v[2:5], v[182:185], v[218:221], v[2:5]
	v_mfma_f32_16x16x32_bf16 v[38:41], v[174:177], v[198:201], v[38:41]
	v_mfma_f32_16x16x32_bf16 v[46:49], v[182:185], v[190:193], v[46:49]
	v_mfma_f32_16x16x32_bf16 v[6:9], v[174:177], v[218:221], v[6:9]
	v_mfma_f32_16x16x32_bf16 v[14:17], v[182:185], v[206:209], v[14:17]
	s_setprio 0
	s_barrier
	s_add_i32 s83, s83, 2
	s_add_u32 s88, s88, 0x100
	s_addc_u32 s89, s89, 0
	s_add_u32 s77, s77, 0x100
	s_addc_u32 s81, s81, 0
	s_cmp_gt_u32 s83, 29
	s_cbranch_scc0 .LBB0_1624
	s_and_b64 vcc, exec, s[78:79]
	s_cbranch_vccz .LBB0_1627
	s_barrier

.LBB0_2089:
	ds_read_b128 v[130:133], v178
	ds_read_b128 v[134:137], v178 offset:1024
	ds_read_b128 v[138:141], v178 offset:2048
	ds_read_b128 v[142:145], v178 offset:3072
	ds_read_b128 v[162:165], v179
	ds_read_b128 v[166:169], v179 offset:1024
	ds_read_b128 v[170:173], v179 offset:2048
	ds_read_b128 v[182:185], v179 offset:3072
	s_add_u32 s34, s38, 0xffea0080
	s_addc_u32 s35, s39, -1
	s_cmpk_eq_i32 s52, 0x54
	s_cselect_b32 s41, s5, s35
	s_cselect_b32 s40, s4, s34
	s_cselect_b32 s35, s37, s1
	s_cselect_b32 s34, s36, s0
	v_lshl_add_u64 v[174:175], s[38:39], 0, v[154:155]
	s_add_i32 m0, s33, 0xc000
	ds_read_b128 v[186:189], v180
	ds_read_b128 v[190:193], v180 offset:1024
	ds_read_b128 v[194:197], v180 offset:2048
	ds_read_b128 v[198:201], v180 offset:3072
	ds_read_b128 v[202:205], v180 offset:4096
	ds_read_b128 v[206:209], v180 offset:5120
	ds_read_b128 v[210:213], v180 offset:6144
	ds_read_b128 v[218:221], v180 offset:7168
	global_load_lds_dwordx4 v[174:175], off
	v_lshl_add_u64 v[174:175], s[38:39], 0, v[156:157]
	s_add_i32 m0, s33, 0xe000
	s_nop 0
	global_load_lds_dwordx4 v[174:175], off
	s_waitcnt vmcnt(8)
	s_waitcnt lgkmcnt(0)
	s_barrier
	s_setprio 1
	s_waitcnt lgkmcnt(0)
	v_mfma_f32_16x16x32_bf16 v[126:129], v[130:133], v[186:189], v[126:129]
	v_mfma_f32_16x16x32_bf16 v[106:109], v[138:141], v[194:197], v[106:109]
	v_mfma_f32_16x16x32_bf16 v[94:97], v[130:133], v[202:205], v[94:97]
	v_mfma_f32_16x16x32_bf16 v[74:77], v[138:141], v[210:213], v[74:77]
	v_mfma_f32_16x16x32_bf16 v[110:113], v[130:133], v[194:197], v[110:113]
	v_mfma_f32_16x16x32_bf16 v[122:125], v[138:141], v[186:189], v[122:125]
	v_mfma_f32_16x16x32_bf16 v[78:81], v[130:133], v[210:213], v[78:81]
	v_mfma_f32_16x16x32_bf16 v[90:93], v[138:141], v[202:205], v[90:93]
	v_mfma_f32_16x16x32_bf16 v[126:129], v[134:137], v[190:193], v[126:129]
	v_mfma_f32_16x16x32_bf16 v[106:109], v[142:145], v[198:201], v[106:109]
	v_mfma_f32_16x16x32_bf16 v[94:97], v[134:137], v[206:209], v[94:97]
	v_mfma_f32_16x16x32_bf16 v[74:77], v[142:145], v[218:221], v[74:77]
	v_mfma_f32_16x16x32_bf16 v[110:113], v[134:137], v[198:201], v[110:113]
	v_mfma_f32_16x16x32_bf16 v[122:125], v[142:145], v[190:193], v[122:125]
	v_mfma_f32_16x16x32_bf16 v[78:81], v[134:137], v[218:221], v[78:81]
	v_mfma_f32_16x16x32_bf16 v[90:93], v[142:145], v[206:209], v[90:93]
	s_setprio 0
	s_setprio 1
	v_mfma_f32_16x16x32_bf16 v[118:121], v[162:165], v[186:189], v[118:121]
	v_mfma_f32_16x16x32_bf16 v[98:101], v[170:173], v[194:197], v[98:101]
	v_mfma_f32_16x16x32_bf16 v[86:89], v[162:165], v[202:205], v[86:89]
	v_mfma_f32_16x16x32_bf16 v[66:69], v[170:173], v[210:213], v[66:69]
	v_mfma_f32_16x16x32_bf16 v[102:105], v[162:165], v[194:197], v[102:105]
	v_mfma_f32_16x16x32_bf16 v[114:117], v[170:173], v[186:189], v[114:117]
	v_mfma_f32_16x16x32_bf16 v[70:73], v[162:165], v[210:213], v[70:73]
	v_mfma_f32_16x16x32_bf16 v[82:85], v[170:173], v[202:205], v[82:85]
	v_mfma_f32_16x16x32_bf16 v[118:121], v[166:169], v[190:193], v[118:121]
	v_mfma_f32_16x16x32_bf16 v[98:101], v[182:185], v[198:201], v[98:101]
	v_mfma_f32_16x16x32_bf16 v[86:89], v[166:169], v[206:209], v[86:89]
	v_mfma_f32_16x16x32_bf16 v[66:69], v[182:185], v[218:221], v[66:69]
	v_mfma_f32_16x16x32_bf16 v[102:105], v[166:169], v[198:201], v[102:105]
	v_mfma_f32_16x16x32_bf16 v[114:117], v[182:185], v[190:193], v[114:117]
	v_mfma_f32_16x16x32_bf16 v[70:73], v[166:169], v[218:221], v[70:73]
	v_mfma_f32_16x16x32_bf16 v[82:85], v[182:185], v[206:209], v[82:85]
	s_setprio 0
	s_barrier
	s_add_i32 s53, s61, s31
	v_lshl_add_u64 v[174:175], s[34:35], 0, v[148:149]
	s_mov_b32 m0, s53
	ds_read_b128 v[186:189], v180 offset:16384
	ds_read_b128 v[190:193], v180 offset:17408
	ds_read_b128 v[194:197], v180 offset:18432
	ds_read_b128 v[198:201], v180 offset:19456
	ds_read_b128 v[202:205], v180 offset:20480
	ds_read_b128 v[206:209], v180 offset:21504
	ds_read_b128 v[210:213], v180 offset:22528
	ds_read_b128 v[218:221], v180 offset:23552
	global_load_lds_dwordx4 v[174:175], off
	s_add_i32 m0, s53, 0x2000
	s_add_u32 s54, s34, 0x160000
	v_lshl_add_u64 v[214:215], s[34:35], 0, v[152:153]
	s_addc_u32 s55, s35, 0
	s_add_i32 s53, s70, s31
	global_load_lds_dwordx4 v[214:215], off
	v_lshl_add_u64 v[222:223], s[54:55], 0, v[148:149]
	s_mov_b32 m0, s53
	v_lshl_add_u64 v[224:225], s[40:41], 0, v[150:151]
	global_load_lds_dwordx4 v[222:223], off
	v_lshl_add_u64 v[222:223], s[54:55], 0, v[152:153]
	s_add_i32 m0, s53, 0x2000
	s_nop 0
	global_load_lds_dwordx4 v[222:223], off
	v_lshl_add_u64 v[222:223], s[40:41], 0, v[146:147]
	s_mov_b32 m0, s33
	s_nop 0
	global_load_lds_dwordx4 v[222:223], off
	s_mov_b32 m0, s46
	s_nop 0
	global_load_lds_dwordx4 v[224:225], off
	s_waitcnt vmcnt(8)
	s_waitcnt lgkmcnt(0)
	s_barrier
	s_setprio 1
	s_waitcnt lgkmcnt(0)
	v_mfma_f32_16x16x32_bf16 v[62:65], v[130:133], v[186:189], v[62:65]
	v_mfma_f32_16x16x32_bf16 v[42:45], v[138:141], v[194:197], v[42:45]
	v_mfma_f32_16x16x32_bf16 v[38:41], v[130:133], v[202:205], v[38:41]
	v_mfma_f32_16x16x32_bf16 v[10:13], v[138:141], v[210:213], v[10:13]
	v_mfma_f32_16x16x32_bf16 v[50:53], v[130:133], v[194:197], v[50:53]
	v_mfma_f32_16x16x32_bf16 v[58:61], v[138:141], v[186:189], v[58:61]
	v_mfma_f32_16x16x32_bf16 v[14:17], v[130:133], v[210:213], v[14:17]
	v_mfma_f32_16x16x32_bf16 v[34:37], v[138:141], v[202:205], v[34:37]
	v_mfma_f32_16x16x32_bf16 v[62:65], v[134:137], v[190:193], v[62:65]
	v_mfma_f32_16x16x32_bf16 v[42:45], v[142:145], v[198:201], v[42:45]
	v_mfma_f32_16x16x32_bf16 v[38:41], v[134:137], v[206:209], v[38:41]
	v_mfma_f32_16x16x32_bf16 v[10:13], v[142:145], v[218:221], v[10:13]
	v_mfma_f32_16x16x32_bf16 v[50:53], v[134:137], v[198:201], v[50:53]
	v_mfma_f32_16x16x32_bf16 v[58:61], v[142:145], v[190:193], v[58:61]
	v_mfma_f32_16x16x32_bf16 v[14:17], v[134:137], v[218:221], v[14:17]
	v_mfma_f32_16x16x32_bf16 v[34:37], v[142:145], v[206:209], v[34:37]
	s_setprio 0
	s_setprio 1
	v_mfma_f32_16x16x32_bf16 v[54:57], v[162:165], v[186:189], v[54:57]
	v_mfma_f32_16x16x32_bf16 v[26:29], v[170:173], v[194:197], v[26:29]
	v_mfma_f32_16x16x32_bf16 v[22:25], v[162:165], v[202:205], v[22:25]
	v_mfma_f32_16x16x32_bf16 v[2:5], v[170:173], v[210:213], v[2:5]
	v_mfma_f32_16x16x32_bf16 v[30:33], v[162:165], v[194:197], v[30:33]
	v_mfma_f32_16x16x32_bf16 v[46:49], v[170:173], v[186:189], v[46:49]
	v_mfma_f32_16x16x32_bf16 v[6:9], v[162:165], v[210:213], v[6:9]
	v_mfma_f32_16x16x32_bf16 v[18:21], v[170:173], v[202:205], v[18:21]
	v_mfma_f32_16x16x32_bf16 v[54:57], v[166:169], v[190:193], v[54:57]
	v_mfma_f32_16x16x32_bf16 v[26:29], v[182:185], v[198:201], v[26:29]
	v_mfma_f32_16x16x32_bf16 v[22:25], v[166:169], v[206:209], v[22:25]
	v_mfma_f32_16x16x32_bf16 v[2:5], v[182:185], v[218:221], v[2:5]
	v_mfma_f32_16x16x32_bf16 v[30:33], v[166:169], v[198:201], v[30:33]
	v_mfma_f32_16x16x32_bf16 v[46:49], v[182:185], v[190:193], v[46:49]
	v_mfma_f32_16x16x32_bf16 v[6:9], v[166:169], v[218:221], v[6:9]
	v_mfma_f32_16x16x32_bf16 v[18:21], v[182:185], v[206:209], v[18:21]
	s_setprio 0
	s_barrier
	s_add_i32 s53, 0, 0x18000
	s_add_i32 s54, 0, 0x1c000
	v_add_u32_e32 v142, s53, v176
	v_add_u32_e32 v181, s54, v176
	ds_read_b128 v[130:133], v142
	ds_read_b128 v[134:137], v142 offset:1024
	ds_read_b128 v[138:141], v142 offset:2048
	ds_read_b128 v[142:145], v142 offset:3072
	ds_read_b128 v[162:165], v181
	ds_read_b128 v[166:169], v181 offset:1024
	ds_read_b128 v[170:173], v181 offset:2048
	ds_read_b128 v[182:185], v181 offset:3072
	s_add_u32 s40, s40, 0x160000
	s_addc_u32 s41, s41, 0
	s_mov_b32 m0, s47
	v_lshl_add_u64 v[226:227], s[40:41], 0, v[146:147]
	ds_read_b128 v[186:189], v180 offset:32768
	ds_read_b128 v[190:193], v180 offset:33792
	ds_read_b128 v[194:197], v180 offset:34816
	ds_read_b128 v[198:201], v180 offset:35840
	ds_read_b128 v[202:205], v180 offset:36864
	ds_read_b128 v[206:209], v180 offset:37888
	ds_read_b128 v[210:213], v180 offset:38912
	ds_read_b128 v[218:221], v180 offset:39936
	global_load_lds_dwordx4 v[226:227], off
	v_lshl_add_u64 v[226:227], s[40:41], 0, v[150:151]
	s_mov_b32 m0, s56
	s_nop 0
	global_load_lds_dwordx4 v[226:227], off
	s_waitcnt vmcnt(8)
	s_waitcnt lgkmcnt(0)
	s_barrier
	s_setprio 1
	s_waitcnt lgkmcnt(0)
	v_mfma_f32_16x16x32_bf16 v[126:129], v[130:133], v[186:189], v[126:129]
	v_mfma_f32_16x16x32_bf16 v[106:109], v[138:141], v[194:197], v[106:109]
	v_mfma_f32_16x16x32_bf16 v[94:97], v[130:133], v[202:205], v[94:97]
	v_mfma_f32_16x16x32_bf16 v[74:77], v[138:141], v[210:213], v[74:77]
	v_mfma_f32_16x16x32_bf16 v[110:113], v[130:133], v[194:197], v[110:113]
	v_mfma_f32_16x16x32_bf16 v[122:125], v[138:141], v[186:189], v[122:125]
	v_mfma_f32_16x16x32_bf16 v[78:81], v[130:133], v[210:213], v[78:81]
	v_mfma_f32_16x16x32_bf16 v[90:93], v[138:141], v[202:205], v[90:93]
	v_mfma_f32_16x16x32_bf16 v[126:129], v[134:137], v[190:193], v[126:129]
	v_mfma_f32_16x16x32_bf16 v[106:109], v[142:145], v[198:201], v[106:109]
	v_mfma_f32_16x16x32_bf16 v[94:97], v[134:137], v[206:209], v[94:97]
	v_mfma_f32_16x16x32_bf16 v[74:77], v[142:145], v[218:221], v[74:77]
	v_mfma_f32_16x16x32_bf16 v[110:113], v[134:137], v[198:201], v[110:113]
	v_mfma_f32_16x16x32_bf16 v[122:125], v[142:145], v[190:193], v[122:125]
	v_mfma_f32_16x16x32_bf16 v[78:81], v[134:137], v[218:221], v[78:81]
	v_mfma_f32_16x16x32_bf16 v[90:93], v[142:145], v[206:209], v[90:93]
	s_setprio 0
	s_setprio 1
	v_mfma_f32_16x16x32_bf16 v[118:121], v[162:165], v[186:189], v[118:121]
	v_mfma_f32_16x16x32_bf16 v[98:101], v[170:173], v[194:197], v[98:101]
	v_mfma_f32_16x16x32_bf16 v[86:89], v[162:165], v[202:205], v[86:89]
	v_mfma_f32_16x16x32_bf16 v[66:69], v[170:173], v[210:213], v[66:69]
	v_mfma_f32_16x16x32_bf16 v[102:105], v[162:165], v[194:197], v[102:105]
	v_mfma_f32_16x16x32_bf16 v[114:117], v[170:173], v[186:189], v[114:117]
	v_mfma_f32_16x16x32_bf16 v[70:73], v[162:165], v[210:213], v[70:73]
	v_mfma_f32_16x16x32_bf16 v[82:85], v[170:173], v[202:205], v[82:85]
	v_mfma_f32_16x16x32_bf16 v[118:121], v[166:169], v[190:193], v[118:121]
	v_mfma_f32_16x16x32_bf16 v[98:101], v[182:185], v[198:201], v[98:101]
	v_mfma_f32_16x16x32_bf16 v[86:89], v[166:169], v[206:209], v[86:89]
	v_mfma_f32_16x16x32_bf16 v[66:69], v[182:185], v[218:221], v[66:69]
	v_mfma_f32_16x16x32_bf16 v[102:105], v[166:169], v[198:201], v[102:105]
	v_mfma_f32_16x16x32_bf16 v[114:117], v[182:185], v[190:193], v[114:117]
	v_mfma_f32_16x16x32_bf16 v[70:73], v[166:169], v[218:221], v[70:73]
	v_mfma_f32_16x16x32_bf16 v[82:85], v[182:185], v[206:209], v[82:85]
	s_setprio 0
	s_barrier
	s_add_i32 s40, s53, s31
	v_lshl_add_u64 v[174:175], v[174:175], 0, s[24:25]
	s_mov_b32 m0, s40
	ds_read_b128 v[186:189], v180 offset:49152
	ds_read_b128 v[190:193], v180 offset:50176
	ds_read_b128 v[194:197], v180 offset:51200
	ds_read_b128 v[198:201], v180 offset:52224
	ds_read_b128 v[202:205], v180 offset:53248
	ds_read_b128 v[206:209], v180 offset:54272
	ds_read_b128 v[210:213], v180 offset:55296
	ds_read_b128 v[218:221], v180 offset:56320
	global_load_lds_dwordx4 v[174:175], off
	s_add_i32 m0, s40, 0x2000
	s_add_u32 s34, s34, 0x160080
	v_lshl_add_u64 v[174:175], v[214:215], 0, s[24:25]
	s_addc_u32 s35, s35, 0
	s_add_i32 s40, s54, s31
	global_load_lds_dwordx4 v[174:175], off
	v_lshl_add_u64 v[174:175], s[34:35], 0, v[148:149]
	s_mov_b32 m0, s40
	s_nop 0
	global_load_lds_dwordx4 v[174:175], off
	v_lshl_add_u64 v[174:175], s[34:35], 0, v[152:153]
	s_add_i32 m0, s40, 0x2000
	s_nop 0
	global_load_lds_dwordx4 v[174:175], off
	v_lshl_add_u64 v[174:175], v[222:223], 0, s[24:25]
	s_mov_b32 m0, s58
	s_nop 0
	global_load_lds_dwordx4 v[174:175], off
	v_lshl_add_u64 v[174:175], v[224:225], 0, s[24:25]
	s_mov_b32 m0, s59
	s_nop 0
	global_load_lds_dwordx4 v[174:175], off
	s_waitcnt vmcnt(8)
	s_waitcnt lgkmcnt(0)
	s_barrier
	s_setprio 1
	s_waitcnt lgkmcnt(0)
	v_mfma_f32_16x16x32_bf16 v[62:65], v[130:133], v[186:189], v[62:65]
	v_mfma_f32_16x16x32_bf16 v[42:45], v[138:141], v[194:197], v[42:45]
	v_mfma_f32_16x16x32_bf16 v[38:41], v[130:133], v[202:205], v[38:41]
	v_mfma_f32_16x16x32_bf16 v[10:13], v[138:141], v[210:213], v[10:13]
	v_mfma_f32_16x16x32_bf16 v[50:53], v[130:133], v[194:197], v[50:53]
	v_mfma_f32_16x16x32_bf16 v[58:61], v[138:141], v[186:189], v[58:61]
	v_mfma_f32_16x16x32_bf16 v[14:17], v[130:133], v[210:213], v[14:17]
	v_mfma_f32_16x16x32_bf16 v[34:37], v[138:141], v[202:205], v[34:37]
	v_mfma_f32_16x16x32_bf16 v[62:65], v[134:137], v[190:193], v[62:65]
	v_mfma_f32_16x16x32_bf16 v[42:45], v[142:145], v[198:201], v[42:45]
	v_mfma_f32_16x16x32_bf16 v[38:41], v[134:137], v[206:209], v[38:41]
	v_mfma_f32_16x16x32_bf16 v[10:13], v[142:145], v[218:221], v[10:13]
	v_mfma_f32_16x16x32_bf16 v[50:53], v[134:137], v[198:201], v[50:53]
	v_mfma_f32_16x16x32_bf16 v[58:61], v[142:145], v[190:193], v[58:61]
	v_mfma_f32_16x16x32_bf16 v[14:17], v[134:137], v[218:221], v[14:17]
	v_mfma_f32_16x16x32_bf16 v[34:37], v[142:145], v[206:209], v[34:37]
	s_setprio 0
	s_setprio 1
	v_mfma_f32_16x16x32_bf16 v[54:57], v[162:165], v[186:189], v[54:57]
	v_mfma_f32_16x16x32_bf16 v[26:29], v[170:173], v[194:197], v[26:29]
	v_mfma_f32_16x16x32_bf16 v[22:25], v[162:165], v[202:205], v[22:25]
	v_mfma_f32_16x16x32_bf16 v[2:5], v[170:173], v[210:213], v[2:5]
	v_mfma_f32_16x16x32_bf16 v[30:33], v[162:165], v[194:197], v[30:33]
	v_mfma_f32_16x16x32_bf16 v[46:49], v[170:173], v[186:189], v[46:49]
	v_mfma_f32_16x16x32_bf16 v[6:9], v[162:165], v[210:213], v[6:9]
	v_mfma_f32_16x16x32_bf16 v[18:21], v[170:173], v[202:205], v[18:21]
	v_mfma_f32_16x16x32_bf16 v[54:57], v[166:169], v[190:193], v[54:57]
	v_mfma_f32_16x16x32_bf16 v[26:29], v[182:185], v[198:201], v[26:29]
	v_mfma_f32_16x16x32_bf16 v[22:25], v[166:169], v[206:209], v[22:25]
	v_mfma_f32_16x16x32_bf16 v[2:5], v[182:185], v[218:221], v[2:5]
	v_mfma_f32_16x16x32_bf16 v[30:33], v[166:169], v[198:201], v[30:33]
	v_mfma_f32_16x16x32_bf16 v[46:49], v[182:185], v[190:193], v[46:49]
	v_mfma_f32_16x16x32_bf16 v[6:9], v[166:169], v[218:221], v[6:9]
	v_mfma_f32_16x16x32_bf16 v[18:21], v[182:185], v[206:209], v[18:21]
	s_setprio 0
	s_barrier
	s_add_i32 s52, s52, 2
	s_add_u32 s38, s38, 0x100
	s_addc_u32 s39, s39, 0
	s_add_u32 s0, s0, 0x100
	s_addc_u32 s1, s1, 0
	s_cmpk_gt_u32 s52, 0x55
	s_cbranch_scc0 .LBB0_2089
	s_and_b64 vcc, exec, s[26:27]
	s_cbranch_vccz .LBB0_2092
	s_barrier

.LBB0_2218:
	ds_read_b128 v[146:149], v153
	ds_read_b128 v[156:159], v153 offset:1024
	ds_read_b128 v[160:163], v153 offset:2048
	ds_read_b128 v[164:167], v153 offset:3072
	ds_read_b128 v[168:171], v154
	ds_read_b128 v[172:175], v154 offset:1024
	ds_read_b128 v[176:179], v154 offset:2048
	ds_read_b128 v[180:183], v154 offset:3072
	s_add_u32 s34, s76, 0xfff80080
	s_addc_u32 s35, s77, -1
	s_cmp_eq_u32 s80, 28
	s_cselect_b32 s79, s0, s35
	s_cselect_b32 s78, s1, s34
	s_cselect_b32 s35, s27, s75
	s_cselect_b32 s34, s37, s52
	v_lshl_add_u64 v[218:219], s[76:77], 0, v[138:139]
	s_add_i32 m0, s47, 0xc000
	ds_read_b128 v[184:187], v155
	ds_read_b128 v[188:191], v155 offset:1024
	ds_read_b128 v[192:195], v155 offset:2048
	ds_read_b128 v[196:199], v155 offset:3072
	ds_read_b128 v[200:203], v155 offset:4096
	ds_read_b128 v[204:207], v155 offset:5120
	ds_read_b128 v[208:211], v155 offset:6144
	ds_read_b128 v[212:215], v155 offset:7168
	global_load_lds_dwordx4 v[218:219], off
	v_lshl_add_u64 v[218:219], s[76:77], 0, v[140:141]
	s_add_i32 m0, s47, 0xe000
	s_nop 0
	global_load_lds_dwordx4 v[218:219], off
	s_waitcnt vmcnt(8)
	s_waitcnt lgkmcnt(0)
	s_barrier
	s_setprio 1
	s_waitcnt lgkmcnt(0)
	v_mfma_f32_16x16x32_bf16 v[126:129], v[146:149], v[184:187], v[126:129]
	v_mfma_f32_16x16x32_bf16 v[102:105], v[160:163], v[192:195], v[102:105]
	v_mfma_f32_16x16x32_bf16 v[94:97], v[146:149], v[200:203], v[94:97]
	v_mfma_f32_16x16x32_bf16 v[70:73], v[160:163], v[208:211], v[70:73]
	v_mfma_f32_16x16x32_bf16 v[110:113], v[146:149], v[192:195], v[110:113]
	v_mfma_f32_16x16x32_bf16 v[118:121], v[160:163], v[184:187], v[118:121]
	v_mfma_f32_16x16x32_bf16 v[78:81], v[146:149], v[208:211], v[78:81]
	v_mfma_f32_16x16x32_bf16 v[86:89], v[160:163], v[200:203], v[86:89]
	v_mfma_f32_16x16x32_bf16 v[126:129], v[156:159], v[188:191], v[126:129]
	v_mfma_f32_16x16x32_bf16 v[102:105], v[164:167], v[196:199], v[102:105]
	v_mfma_f32_16x16x32_bf16 v[94:97], v[156:159], v[204:207], v[94:97]
	v_mfma_f32_16x16x32_bf16 v[70:73], v[164:167], v[212:215], v[70:73]
	v_mfma_f32_16x16x32_bf16 v[110:113], v[156:159], v[196:199], v[110:113]
	v_mfma_f32_16x16x32_bf16 v[118:121], v[164:167], v[188:191], v[118:121]
	v_mfma_f32_16x16x32_bf16 v[78:81], v[156:159], v[212:215], v[78:81]
	v_mfma_f32_16x16x32_bf16 v[86:89], v[164:167], v[204:207], v[86:89]
	s_setprio 0
	s_setprio 1
	v_mfma_f32_16x16x32_bf16 v[122:125], v[168:171], v[184:187], v[122:125]
	v_mfma_f32_16x16x32_bf16 v[98:101], v[176:179], v[192:195], v[98:101]
	v_mfma_f32_16x16x32_bf16 v[90:93], v[168:171], v[200:203], v[90:93]
	v_mfma_f32_16x16x32_bf16 v[66:69], v[176:179], v[208:211], v[66:69]
	v_mfma_f32_16x16x32_bf16 v[106:109], v[168:171], v[192:195], v[106:109]
	v_mfma_f32_16x16x32_bf16 v[114:117], v[176:179], v[184:187], v[114:117]
	v_mfma_f32_16x16x32_bf16 v[74:77], v[168:171], v[208:211], v[74:77]
	v_mfma_f32_16x16x32_bf16 v[82:85], v[176:179], v[200:203], v[82:85]
	v_mfma_f32_16x16x32_bf16 v[122:125], v[172:175], v[188:191], v[122:125]
	v_mfma_f32_16x16x32_bf16 v[98:101], v[180:183], v[196:199], v[98:101]
	v_mfma_f32_16x16x32_bf16 v[90:93], v[172:175], v[204:207], v[90:93]
	v_mfma_f32_16x16x32_bf16 v[66:69], v[180:183], v[212:215], v[66:69]
	v_mfma_f32_16x16x32_bf16 v[106:109], v[172:175], v[196:199], v[106:109]
	v_mfma_f32_16x16x32_bf16 v[114:117], v[180:183], v[188:191], v[114:117]
	v_mfma_f32_16x16x32_bf16 v[74:77], v[172:175], v[212:215], v[74:77]
	v_mfma_f32_16x16x32_bf16 v[82:85], v[180:183], v[204:207], v[82:85]
	s_setprio 0
	s_barrier
	s_add_i32 s53, s71, s30
	v_lshl_add_u64 v[218:219], s[34:35], 0, v[134:135]
	s_mov_b32 m0, s53
	ds_read_b128 v[184:187], v155 offset:16384
	ds_read_b128 v[188:191], v155 offset:17408
	ds_read_b128 v[192:195], v155 offset:18432
	ds_read_b128 v[196:199], v155 offset:19456
	ds_read_b128 v[200:203], v155 offset:20480
	ds_read_b128 v[204:207], v155 offset:21504
	ds_read_b128 v[208:211], v155 offset:22528
	ds_read_b128 v[212:215], v155 offset:23552
	global_load_lds_dwordx4 v[218:219], off
	s_add_i32 m0, s53, 0x2000
	s_add_u32 s54, s34, 0x80000
	v_lshl_add_u64 v[220:221], s[34:35], 0, v[130:131]
	s_addc_u32 s55, s35, 0
	s_add_i32 s53, s72, s30
	global_load_lds_dwordx4 v[220:221], off
	v_lshl_add_u64 v[222:223], s[54:55], 0, v[134:135]
	s_mov_b32 m0, s53
	v_lshl_add_u64 v[224:225], s[78:79], 0, v[132:133]
	global_load_lds_dwordx4 v[222:223], off
	v_lshl_add_u64 v[222:223], s[54:55], 0, v[130:131]
	s_add_i32 m0, s53, 0x2000
	s_nop 0
	global_load_lds_dwordx4 v[222:223], off
	v_lshl_add_u64 v[222:223], s[78:79], 0, v[136:137]
	s_mov_b32 m0, s47
	s_nop 0
	global_load_lds_dwordx4 v[222:223], off
	s_mov_b32 m0, s56
	s_nop 0
	global_load_lds_dwordx4 v[224:225], off
	s_waitcnt vmcnt(8)
	s_waitcnt lgkmcnt(0)
	s_barrier
	s_setprio 1
	s_waitcnt lgkmcnt(0)
	v_mfma_f32_16x16x32_bf16 v[62:65], v[146:149], v[184:187], v[62:65]
	v_mfma_f32_16x16x32_bf16 v[38:41], v[160:163], v[192:195], v[38:41]
	v_mfma_f32_16x16x32_bf16 v[30:33], v[146:149], v[200:203], v[30:33]
	v_mfma_f32_16x16x32_bf16 v[6:9], v[160:163], v[208:211], v[6:9]
	v_mfma_f32_16x16x32_bf16 v[46:49], v[146:149], v[192:195], v[46:49]
	v_mfma_f32_16x16x32_bf16 v[54:57], v[160:163], v[184:187], v[54:57]
	v_mfma_f32_16x16x32_bf16 v[14:17], v[146:149], v[208:211], v[14:17]
	v_mfma_f32_16x16x32_bf16 v[22:25], v[160:163], v[200:203], v[22:25]
	v_mfma_f32_16x16x32_bf16 v[62:65], v[156:159], v[188:191], v[62:65]
	v_mfma_f32_16x16x32_bf16 v[38:41], v[164:167], v[196:199], v[38:41]
	v_mfma_f32_16x16x32_bf16 v[30:33], v[156:159], v[204:207], v[30:33]
	v_mfma_f32_16x16x32_bf16 v[6:9], v[164:167], v[212:215], v[6:9]
	v_mfma_f32_16x16x32_bf16 v[46:49], v[156:159], v[196:199], v[46:49]
	v_mfma_f32_16x16x32_bf16 v[54:57], v[164:167], v[188:191], v[54:57]
	v_mfma_f32_16x16x32_bf16 v[14:17], v[156:159], v[212:215], v[14:17]
	v_mfma_f32_16x16x32_bf16 v[22:25], v[164:167], v[204:207], v[22:25]
	s_setprio 0
	s_setprio 1
	v_mfma_f32_16x16x32_bf16 v[58:61], v[168:171], v[184:187], v[58:61]
	v_mfma_f32_16x16x32_bf16 v[34:37], v[176:179], v[192:195], v[34:37]
	v_mfma_f32_16x16x32_bf16 v[26:29], v[168:171], v[200:203], v[26:29]
	v_mfma_f32_16x16x32_bf16 v[2:5], v[176:179], v[208:211], v[2:5]
	v_mfma_f32_16x16x32_bf16 v[42:45], v[168:171], v[192:195], v[42:45]
	v_mfma_f32_16x16x32_bf16 v[50:53], v[176:179], v[184:187], v[50:53]
	v_mfma_f32_16x16x32_bf16 v[10:13], v[168:171], v[208:211], v[10:13]
	v_mfma_f32_16x16x32_bf16 v[18:21], v[176:179], v[200:203], v[18:21]
	v_mfma_f32_16x16x32_bf16 v[58:61], v[172:175], v[188:191], v[58:61]
	v_mfma_f32_16x16x32_bf16 v[34:37], v[180:183], v[196:199], v[34:37]
	v_mfma_f32_16x16x32_bf16 v[26:29], v[172:175], v[204:207], v[26:29]
	v_mfma_f32_16x16x32_bf16 v[2:5], v[180:183], v[212:215], v[2:5]
	v_mfma_f32_16x16x32_bf16 v[42:45], v[172:175], v[196:199], v[42:45]
	v_mfma_f32_16x16x32_bf16 v[50:53], v[180:183], v[188:191], v[50:53]
	v_mfma_f32_16x16x32_bf16 v[10:13], v[172:175], v[212:215], v[10:13]
	v_mfma_f32_16x16x32_bf16 v[18:21], v[180:183], v[204:207], v[18:21]
	s_setprio 0
	s_barrier
	s_add_i32 s53, 0, 0x18000
	s_add_i32 s62, 0, 0x1c000
	v_add_u32_e32 v164, s53, v151
	v_add_u32_e32 v180, s62, v151
	ds_read_b128 v[146:149], v164
	ds_read_b128 v[156:159], v164 offset:1024
	ds_read_b128 v[160:163], v164 offset:2048
	ds_read_b128 v[164:167], v164 offset:3072
	ds_read_b128 v[168:171], v180
	ds_read_b128 v[172:175], v180 offset:1024
	ds_read_b128 v[176:179], v180 offset:2048
	ds_read_b128 v[180:183], v180 offset:3072
	s_add_u32 s54, s78, 0x80000
	s_addc_u32 s55, s79, 0
	s_mov_b32 m0, s57
	v_lshl_add_u64 v[226:227], s[54:55], 0, v[136:137]
	ds_read_b128 v[184:187], v155 offset:32768
	ds_read_b128 v[188:191], v155 offset:33792
	ds_read_b128 v[192:195], v155 offset:34816
	ds_read_b128 v[196:199], v155 offset:35840
	ds_read_b128 v[200:203], v155 offset:36864
	ds_read_b128 v[204:207], v155 offset:37888
	ds_read_b128 v[208:211], v155 offset:38912
	ds_read_b128 v[212:215], v155 offset:39936
	global_load_lds_dwordx4 v[226:227], off
	v_lshl_add_u64 v[226:227], s[54:55], 0, v[132:133]
	s_mov_b32 m0, s58
	s_nop 0
	global_load_lds_dwordx4 v[226:227], off
	s_waitcnt vmcnt(8)
	s_waitcnt lgkmcnt(0)
	s_barrier
	s_setprio 1
	s_waitcnt lgkmcnt(0)
	v_mfma_f32_16x16x32_bf16 v[126:129], v[146:149], v[184:187], v[126:129]
	v_mfma_f32_16x16x32_bf16 v[102:105], v[160:163], v[192:195], v[102:105]
	v_mfma_f32_16x16x32_bf16 v[94:97], v[146:149], v[200:203], v[94:97]
	v_mfma_f32_16x16x32_bf16 v[70:73], v[160:163], v[208:211], v[70:73]
	v_mfma_f32_16x16x32_bf16 v[110:113], v[146:149], v[192:195], v[110:113]
	v_mfma_f32_16x16x32_bf16 v[118:121], v[160:163], v[184:187], v[118:121]
	v_mfma_f32_16x16x32_bf16 v[78:81], v[146:149], v[208:211], v[78:81]
	v_mfma_f32_16x16x32_bf16 v[86:89], v[160:163], v[200:203], v[86:89]
	v_mfma_f32_16x16x32_bf16 v[126:129], v[156:159], v[188:191], v[126:129]
	v_mfma_f32_16x16x32_bf16 v[102:105], v[164:167], v[196:199], v[102:105]
	v_mfma_f32_16x16x32_bf16 v[94:97], v[156:159], v[204:207], v[94:97]
	v_mfma_f32_16x16x32_bf16 v[70:73], v[164:167], v[212:215], v[70:73]
	v_mfma_f32_16x16x32_bf16 v[110:113], v[156:159], v[196:199], v[110:113]
	v_mfma_f32_16x16x32_bf16 v[118:121], v[164:167], v[188:191], v[118:121]
	v_mfma_f32_16x16x32_bf16 v[78:81], v[156:159], v[212:215], v[78:81]
	v_mfma_f32_16x16x32_bf16 v[86:89], v[164:167], v[204:207], v[86:89]
	s_setprio 0
	s_setprio 1
	v_mfma_f32_16x16x32_bf16 v[122:125], v[168:171], v[184:187], v[122:125]
	v_mfma_f32_16x16x32_bf16 v[98:101], v[176:179], v[192:195], v[98:101]
	v_mfma_f32_16x16x32_bf16 v[90:93], v[168:171], v[200:203], v[90:93]
	v_mfma_f32_16x16x32_bf16 v[66:69], v[176:179], v[208:211], v[66:69]
	v_mfma_f32_16x16x32_bf16 v[106:109], v[168:171], v[192:195], v[106:109]
	v_mfma_f32_16x16x32_bf16 v[114:117], v[176:179], v[184:187], v[114:117]
	v_mfma_f32_16x16x32_bf16 v[74:77], v[168:171], v[208:211], v[74:77]
	v_mfma_f32_16x16x32_bf16 v[82:85], v[176:179], v[200:203], v[82:85]
	v_mfma_f32_16x16x32_bf16 v[122:125], v[172:175], v[188:191], v[122:125]
	v_mfma_f32_16x16x32_bf16 v[98:101], v[180:183], v[196:199], v[98:101]
	v_mfma_f32_16x16x32_bf16 v[90:93], v[172:175], v[204:207], v[90:93]
	v_mfma_f32_16x16x32_bf16 v[66:69], v[180:183], v[212:215], v[66:69]
	v_mfma_f32_16x16x32_bf16 v[106:109], v[172:175], v[196:199], v[106:109]
	v_mfma_f32_16x16x32_bf16 v[114:117], v[180:183], v[188:191], v[114:117]
	v_mfma_f32_16x16x32_bf16 v[74:77], v[172:175], v[212:215], v[74:77]
	v_mfma_f32_16x16x32_bf16 v[82:85], v[180:183], v[204:207], v[82:85]
	s_setprio 0
	s_barrier
	s_add_i32 s53, s53, s30
	v_lshl_add_u64 v[218:219], v[218:219], 0, s[8:9]
	s_mov_b32 m0, s53
	ds_read_b128 v[184:187], v155 offset:49152
	ds_read_b128 v[188:191], v155 offset:50176
	ds_read_b128 v[192:195], v155 offset:51200
	ds_read_b128 v[196:199], v155 offset:52224
	ds_read_b128 v[200:203], v155 offset:53248
	ds_read_b128 v[204:207], v155 offset:54272
	ds_read_b128 v[208:211], v155 offset:55296
	ds_read_b128 v[212:215], v155 offset:56320
	global_load_lds_dwordx4 v[218:219], off
	s_add_i32 m0, s53, 0x2000
	s_add_u32 s34, s34, 0x80080
	v_lshl_add_u64 v[218:219], v[220:221], 0, s[8:9]
	s_addc_u32 s35, s35, 0
	s_add_i32 s53, s62, s30
	global_load_lds_dwordx4 v[218:219], off
	v_lshl_add_u64 v[218:219], s[34:35], 0, v[134:135]
	s_mov_b32 m0, s53
	s_nop 0
	global_load_lds_dwordx4 v[218:219], off
	v_lshl_add_u64 v[218:219], s[34:35], 0, v[130:131]
	s_add_i32 m0, s53, 0x2000
	s_nop 0
	global_load_lds_dwordx4 v[218:219], off
	v_lshl_add_u64 v[218:219], v[222:223], 0, s[8:9]
	s_mov_b32 m0, s60
	s_nop 0
	global_load_lds_dwordx4 v[218:219], off
	v_lshl_add_u64 v[218:219], v[224:225], 0, s[8:9]
	s_mov_b32 m0, s61
	s_nop 0
	global_load_lds_dwordx4 v[218:219], off
	s_waitcnt vmcnt(8)
	s_waitcnt lgkmcnt(0)
	s_barrier
	s_setprio 1
	s_waitcnt lgkmcnt(0)
	v_mfma_f32_16x16x32_bf16 v[62:65], v[146:149], v[184:187], v[62:65]
	v_mfma_f32_16x16x32_bf16 v[38:41], v[160:163], v[192:195], v[38:41]
	v_mfma_f32_16x16x32_bf16 v[30:33], v[146:149], v[200:203], v[30:33]
	v_mfma_f32_16x16x32_bf16 v[6:9], v[160:163], v[208:211], v[6:9]
	v_mfma_f32_16x16x32_bf16 v[46:49], v[146:149], v[192:195], v[46:49]
	v_mfma_f32_16x16x32_bf16 v[54:57], v[160:163], v[184:187], v[54:57]
	v_mfma_f32_16x16x32_bf16 v[14:17], v[146:149], v[208:211], v[14:17]
	v_mfma_f32_16x16x32_bf16 v[22:25], v[160:163], v[200:203], v[22:25]
	v_mfma_f32_16x16x32_bf16 v[62:65], v[156:159], v[188:191], v[62:65]
	v_mfma_f32_16x16x32_bf16 v[38:41], v[164:167], v[196:199], v[38:41]
	v_mfma_f32_16x16x32_bf16 v[30:33], v[156:159], v[204:207], v[30:33]
	v_mfma_f32_16x16x32_bf16 v[6:9], v[164:167], v[212:215], v[6:9]
	v_mfma_f32_16x16x32_bf16 v[46:49], v[156:159], v[196:199], v[46:49]
	v_mfma_f32_16x16x32_bf16 v[54:57], v[164:167], v[188:191], v[54:57]
	v_mfma_f32_16x16x32_bf16 v[14:17], v[156:159], v[212:215], v[14:17]
	v_mfma_f32_16x16x32_bf16 v[22:25], v[164:167], v[204:207], v[22:25]
	s_setprio 0
	s_setprio 1
	v_mfma_f32_16x16x32_bf16 v[58:61], v[168:171], v[184:187], v[58:61]
	v_mfma_f32_16x16x32_bf16 v[34:37], v[176:179], v[192:195], v[34:37]
	v_mfma_f32_16x16x32_bf16 v[26:29], v[168:171], v[200:203], v[26:29]
	v_mfma_f32_16x16x32_bf16 v[2:5], v[176:179], v[208:211], v[2:5]
	v_mfma_f32_16x16x32_bf16 v[42:45], v[168:171], v[192:195], v[42:45]
	v_mfma_f32_16x16x32_bf16 v[50:53], v[176:179], v[184:187], v[50:53]
	v_mfma_f32_16x16x32_bf16 v[10:13], v[168:171], v[208:211], v[10:13]
	v_mfma_f32_16x16x32_bf16 v[18:21], v[176:179], v[200:203], v[18:21]
	v_mfma_f32_16x16x32_bf16 v[58:61], v[172:175], v[188:191], v[58:61]
	v_mfma_f32_16x16x32_bf16 v[34:37], v[180:183], v[196:199], v[34:37]
	v_mfma_f32_16x16x32_bf16 v[26:29], v[172:175], v[204:207], v[26:29]
	v_mfma_f32_16x16x32_bf16 v[2:5], v[180:183], v[212:215], v[2:5]
	v_mfma_f32_16x16x32_bf16 v[42:45], v[172:175], v[196:199], v[42:45]
	v_mfma_f32_16x16x32_bf16 v[50:53], v[180:183], v[188:191], v[50:53]
	v_mfma_f32_16x16x32_bf16 v[10:13], v[172:175], v[212:215], v[10:13]
	v_mfma_f32_16x16x32_bf16 v[18:21], v[180:183], v[204:207], v[18:21]
	s_setprio 0
	s_barrier
	s_add_i32 s80, s80, 2
	s_add_u32 s76, s76, 0x100
	s_addc_u32 s77, s77, 0
	s_add_u32 s52, s52, 0x100
	s_addc_u32 s75, s75, 0
	s_cmp_gt_u32 s80, 29
	s_cbranch_scc0 .LBB0_2218
	v_mov_b32_e32 v160, 0xbfb8aa3b
	s_and_b64 vcc, exec, s[24:25]
	s_cbranch_vccz .LBB0_2221
	s_barrier

.LBB0_2462:
	ds_read_b128 v[160:163], v155
	ds_read_b128 v[164:167], v155 offset:1024
	ds_read_b128 v[168:171], v155 offset:2048
	ds_read_b128 v[172:175], v155 offset:3072
	ds_read_b128 v[176:179], v156
	ds_read_b128 v[180:183], v156 offset:1024
	ds_read_b128 v[184:187], v156 offset:2048
	ds_read_b128 v[188:191], v156 offset:3072
	s_add_u32 s34, s76, 0xfff80080
	s_addc_u32 s35, s77, -1
	s_cmp_eq_u32 s74, 28
	s_cselect_b32 s89, s0, s35
	s_cselect_b32 s88, s1, s34
	s_cselect_b32 s35, s7, s52
	s_cselect_b32 s34, s9, s36
	v_lshl_add_u64 v[152:153], s[76:77], 0, v[144:145]
	s_add_i32 m0, s31, 0xc000
	ds_read_b128 v[192:195], v157
	ds_read_b128 v[196:199], v157 offset:1024
	ds_read_b128 v[200:203], v157 offset:2048
	ds_read_b128 v[204:207], v157 offset:3072
	ds_read_b128 v[208:211], v157 offset:4096
	ds_read_b128 v[212:215], v157 offset:5120
	ds_read_b128 v[218:221], v157 offset:6144
	ds_read_b128 v[222:225], v157 offset:7168
	global_load_lds_dwordx4 v[152:153], off
	v_lshl_add_u64 v[152:153], s[76:77], 0, v[146:147]
	s_add_i32 m0, s31, 0xe000
	s_nop 0
	global_load_lds_dwordx4 v[152:153], off
	s_waitcnt vmcnt(8)
	s_waitcnt lgkmcnt(0)
	s_barrier
	s_setprio 1
	s_waitcnt lgkmcnt(0)
	v_mfma_f32_16x16x32_bf16 v[126:129], v[160:163], v[192:195], v[126:129]
	v_mfma_f32_16x16x32_bf16 v[106:109], v[168:171], v[200:203], v[106:109]
	v_mfma_f32_16x16x32_bf16 v[94:97], v[160:163], v[208:211], v[94:97]
	v_mfma_f32_16x16x32_bf16 v[74:77], v[168:171], v[218:221], v[74:77]
	v_mfma_f32_16x16x32_bf16 v[110:113], v[160:163], v[200:203], v[110:113]
	v_mfma_f32_16x16x32_bf16 v[122:125], v[168:171], v[192:195], v[122:125]
	v_mfma_f32_16x16x32_bf16 v[78:81], v[160:163], v[218:221], v[78:81]
	v_mfma_f32_16x16x32_bf16 v[90:93], v[168:171], v[208:211], v[90:93]
	v_mfma_f32_16x16x32_bf16 v[126:129], v[164:167], v[196:199], v[126:129]
	v_mfma_f32_16x16x32_bf16 v[106:109], v[172:175], v[204:207], v[106:109]
	v_mfma_f32_16x16x32_bf16 v[94:97], v[164:167], v[212:215], v[94:97]
	v_mfma_f32_16x16x32_bf16 v[74:77], v[172:175], v[222:225], v[74:77]
	v_mfma_f32_16x16x32_bf16 v[110:113], v[164:167], v[204:207], v[110:113]
	v_mfma_f32_16x16x32_bf16 v[122:125], v[172:175], v[196:199], v[122:125]
	v_mfma_f32_16x16x32_bf16 v[78:81], v[164:167], v[222:225], v[78:81]
	v_mfma_f32_16x16x32_bf16 v[90:93], v[172:175], v[212:215], v[90:93]
	s_setprio 0
	s_setprio 1
	v_mfma_f32_16x16x32_bf16 v[118:121], v[176:179], v[192:195], v[118:121]
	v_mfma_f32_16x16x32_bf16 v[98:101], v[184:187], v[200:203], v[98:101]
	v_mfma_f32_16x16x32_bf16 v[86:89], v[176:179], v[208:211], v[86:89]
	v_mfma_f32_16x16x32_bf16 v[66:69], v[184:187], v[218:221], v[66:69]
	v_mfma_f32_16x16x32_bf16 v[102:105], v[176:179], v[200:203], v[102:105]
	v_mfma_f32_16x16x32_bf16 v[114:117], v[184:187], v[192:195], v[114:117]
	v_mfma_f32_16x16x32_bf16 v[70:73], v[176:179], v[218:221], v[70:73]
	v_mfma_f32_16x16x32_bf16 v[82:85], v[184:187], v[208:211], v[82:85]
	v_mfma_f32_16x16x32_bf16 v[118:121], v[180:183], v[196:199], v[118:121]
	v_mfma_f32_16x16x32_bf16 v[98:101], v[188:191], v[204:207], v[98:101]
	v_mfma_f32_16x16x32_bf16 v[86:89], v[180:183], v[212:215], v[86:89]
	v_mfma_f32_16x16x32_bf16 v[66:69], v[188:191], v[222:225], v[66:69]
	v_mfma_f32_16x16x32_bf16 v[102:105], v[180:183], v[204:207], v[102:105]
	v_mfma_f32_16x16x32_bf16 v[114:117], v[188:191], v[196:199], v[114:117]
	v_mfma_f32_16x16x32_bf16 v[70:73], v[180:183], v[222:225], v[70:73]
	v_mfma_f32_16x16x32_bf16 v[82:85], v[188:191], v[212:215], v[82:85]
	s_setprio 0
	s_barrier
	s_add_i32 s53, s71, s12
	v_lshl_add_u64 v[152:153], s[34:35], 0, v[132:133]
	s_mov_b32 m0, s53
	ds_read_b128 v[192:195], v157 offset:16384
	ds_read_b128 v[196:199], v157 offset:17408
	ds_read_b128 v[200:203], v157 offset:18432
	ds_read_b128 v[204:207], v157 offset:19456
	ds_read_b128 v[208:211], v157 offset:20480
	ds_read_b128 v[212:215], v157 offset:21504
	ds_read_b128 v[218:221], v157 offset:22528
	ds_read_b128 v[222:225], v157 offset:23552
	global_load_lds_dwordx4 v[152:153], off
	s_add_i32 m0, s53, 0x2000
	s_add_u32 s54, s34, 0x80000
	v_lshl_add_u64 v[226:227], s[34:35], 0, v[136:137]
	s_addc_u32 s55, s35, 0
	s_add_i32 s53, s72, s12
	global_load_lds_dwordx4 v[226:227], off
	v_lshl_add_u64 v[228:229], s[54:55], 0, v[132:133]
	s_mov_b32 m0, s53
	v_lshl_add_u64 v[230:231], s[88:89], 0, v[134:135]
	global_load_lds_dwordx4 v[228:229], off
	v_lshl_add_u64 v[228:229], s[54:55], 0, v[136:137]
	s_add_i32 m0, s53, 0x2000
	s_nop 0
	global_load_lds_dwordx4 v[228:229], off
	v_lshl_add_u64 v[228:229], s[88:89], 0, v[130:131]
	s_mov_b32 m0, s31
	s_nop 0
	global_load_lds_dwordx4 v[228:229], off
	s_mov_b32 m0, s33
	s_nop 0
	global_load_lds_dwordx4 v[230:231], off
	s_waitcnt vmcnt(8)
	s_waitcnt lgkmcnt(0)
	s_barrier
	s_setprio 1
	s_waitcnt lgkmcnt(0)
	v_mfma_f32_16x16x32_bf16 v[62:65], v[160:163], v[192:195], v[62:65]
	v_mfma_f32_16x16x32_bf16 v[42:45], v[168:171], v[200:203], v[42:45]
	v_mfma_f32_16x16x32_bf16 v[30:33], v[160:163], v[208:211], v[30:33]
	v_mfma_f32_16x16x32_bf16 v[10:13], v[168:171], v[218:221], v[10:13]
	v_mfma_f32_16x16x32_bf16 v[46:49], v[160:163], v[200:203], v[46:49]
	v_mfma_f32_16x16x32_bf16 v[58:61], v[168:171], v[192:195], v[58:61]
	v_mfma_f32_16x16x32_bf16 v[14:17], v[160:163], v[218:221], v[14:17]
	v_mfma_f32_16x16x32_bf16 v[26:29], v[168:171], v[208:211], v[26:29]
	v_mfma_f32_16x16x32_bf16 v[62:65], v[164:167], v[196:199], v[62:65]
	v_mfma_f32_16x16x32_bf16 v[42:45], v[172:175], v[204:207], v[42:45]
	v_mfma_f32_16x16x32_bf16 v[30:33], v[164:167], v[212:215], v[30:33]
	v_mfma_f32_16x16x32_bf16 v[10:13], v[172:175], v[222:225], v[10:13]
	v_mfma_f32_16x16x32_bf16 v[46:49], v[164:167], v[204:207], v[46:49]
	v_mfma_f32_16x16x32_bf16 v[58:61], v[172:175], v[196:199], v[58:61]
	v_mfma_f32_16x16x32_bf16 v[14:17], v[164:167], v[222:225], v[14:17]
	v_mfma_f32_16x16x32_bf16 v[26:29], v[172:175], v[212:215], v[26:29]
	s_setprio 0
	s_setprio 1
	v_mfma_f32_16x16x32_bf16 v[54:57], v[176:179], v[192:195], v[54:57]
	v_mfma_f32_16x16x32_bf16 v[34:37], v[184:187], v[200:203], v[34:37]
	v_mfma_f32_16x16x32_bf16 v[22:25], v[176:179], v[208:211], v[22:25]
	v_mfma_f32_16x16x32_bf16 v[2:5], v[184:187], v[218:221], v[2:5]
	v_mfma_f32_16x16x32_bf16 v[38:41], v[176:179], v[200:203], v[38:41]
	v_mfma_f32_16x16x32_bf16 v[50:53], v[184:187], v[192:195], v[50:53]
	v_mfma_f32_16x16x32_bf16 v[6:9], v[176:179], v[218:221], v[6:9]
	v_mfma_f32_16x16x32_bf16 v[18:21], v[184:187], v[208:211], v[18:21]
	v_mfma_f32_16x16x32_bf16 v[54:57], v[180:183], v[196:199], v[54:57]
	v_mfma_f32_16x16x32_bf16 v[34:37], v[188:191], v[204:207], v[34:37]
	v_mfma_f32_16x16x32_bf16 v[22:25], v[180:183], v[212:215], v[22:25]
	v_mfma_f32_16x16x32_bf16 v[2:5], v[188:191], v[222:225], v[2:5]
	v_mfma_f32_16x16x32_bf16 v[38:41], v[180:183], v[204:207], v[38:41]
	v_mfma_f32_16x16x32_bf16 v[50:53], v[188:191], v[196:199], v[50:53]
	v_mfma_f32_16x16x32_bf16 v[6:9], v[180:183], v[222:225], v[6:9]
	v_mfma_f32_16x16x32_bf16 v[18:21], v[188:191], v[212:215], v[18:21]
	s_setprio 0
	s_barrier
	s_add_i32 s53, 0, 0x18000
	v_add_u32_e32 v138, s53, v154
	s_add_i32 s62, 0, 0x1c000
	ds_read_b128 v[160:163], v138
	ds_read_b128 v[164:167], v138 offset:1024
	ds_read_b128 v[168:171], v138 offset:2048
	ds_read_b128 v[172:175], v138 offset:3072
	v_add_u32_e32 v138, s62, v154
	ds_read_b128 v[176:179], v138
	ds_read_b128 v[180:183], v138 offset:1024
	ds_read_b128 v[184:187], v138 offset:2048
	ds_read_b128 v[188:191], v138 offset:3072
	s_add_u32 s54, s88, 0x80000
	s_addc_u32 s55, s89, 0
	s_mov_b32 m0, s56
	v_lshl_add_u64 v[232:233], s[54:55], 0, v[130:131]
	ds_read_b128 v[192:195], v157 offset:32768
	ds_read_b128 v[196:199], v157 offset:33792
	ds_read_b128 v[200:203], v157 offset:34816
	ds_read_b128 v[204:207], v157 offset:35840
	ds_read_b128 v[208:211], v157 offset:36864
	ds_read_b128 v[212:215], v157 offset:37888
	ds_read_b128 v[218:221], v157 offset:38912
	ds_read_b128 v[222:225], v157 offset:39936
	global_load_lds_dwordx4 v[232:233], off
	v_lshl_add_u64 v[232:233], s[54:55], 0, v[134:135]
	s_mov_b32 m0, s57
	s_nop 0
	global_load_lds_dwordx4 v[232:233], off
	s_waitcnt vmcnt(8)
	s_waitcnt lgkmcnt(0)
	s_barrier
	s_setprio 1
	s_waitcnt lgkmcnt(0)
	v_mfma_f32_16x16x32_bf16 v[126:129], v[160:163], v[192:195], v[126:129]
	v_mfma_f32_16x16x32_bf16 v[106:109], v[168:171], v[200:203], v[106:109]
	v_mfma_f32_16x16x32_bf16 v[94:97], v[160:163], v[208:211], v[94:97]
	v_mfma_f32_16x16x32_bf16 v[74:77], v[168:171], v[218:221], v[74:77]
	v_mfma_f32_16x16x32_bf16 v[110:113], v[160:163], v[200:203], v[110:113]
	v_mfma_f32_16x16x32_bf16 v[122:125], v[168:171], v[192:195], v[122:125]
	v_mfma_f32_16x16x32_bf16 v[78:81], v[160:163], v[218:221], v[78:81]
	v_mfma_f32_16x16x32_bf16 v[90:93], v[168:171], v[208:211], v[90:93]
	v_mfma_f32_16x16x32_bf16 v[126:129], v[164:167], v[196:199], v[126:129]
	v_mfma_f32_16x16x32_bf16 v[106:109], v[172:175], v[204:207], v[106:109]
	v_mfma_f32_16x16x32_bf16 v[94:97], v[164:167], v[212:215], v[94:97]
	v_mfma_f32_16x16x32_bf16 v[74:77], v[172:175], v[222:225], v[74:77]
	v_mfma_f32_16x16x32_bf16 v[110:113], v[164:167], v[204:207], v[110:113]
	v_mfma_f32_16x16x32_bf16 v[122:125], v[172:175], v[196:199], v[122:125]
	v_mfma_f32_16x16x32_bf16 v[78:81], v[164:167], v[222:225], v[78:81]
	v_mfma_f32_16x16x32_bf16 v[90:93], v[172:175], v[212:215], v[90:93]
	s_setprio 0
	s_setprio 1
	v_mfma_f32_16x16x32_bf16 v[118:121], v[176:179], v[192:195], v[118:121]
	v_mfma_f32_16x16x32_bf16 v[98:101], v[184:187], v[200:203], v[98:101]
	v_mfma_f32_16x16x32_bf16 v[86:89], v[176:179], v[208:211], v[86:89]
	v_mfma_f32_16x16x32_bf16 v[66:69], v[184:187], v[218:221], v[66:69]
	v_mfma_f32_16x16x32_bf16 v[102:105], v[176:179], v[200:203], v[102:105]
	v_mfma_f32_16x16x32_bf16 v[114:117], v[184:187], v[192:195], v[114:117]
	v_mfma_f32_16x16x32_bf16 v[70:73], v[176:179], v[218:221], v[70:73]
	v_mfma_f32_16x16x32_bf16 v[82:85], v[184:187], v[208:211], v[82:85]
	v_mfma_f32_16x16x32_bf16 v[118:121], v[180:183], v[196:199], v[118:121]
	v_mfma_f32_16x16x32_bf16 v[98:101], v[188:191], v[204:207], v[98:101]
	v_mfma_f32_16x16x32_bf16 v[86:89], v[180:183], v[212:215], v[86:89]
	v_mfma_f32_16x16x32_bf16 v[66:69], v[188:191], v[222:225], v[66:69]
	v_mfma_f32_16x16x32_bf16 v[102:105], v[180:183], v[204:207], v[102:105]
	v_mfma_f32_16x16x32_bf16 v[114:117], v[188:191], v[196:199], v[114:117]
	v_mfma_f32_16x16x32_bf16 v[70:73], v[180:183], v[222:225], v[70:73]
	v_mfma_f32_16x16x32_bf16 v[82:85], v[188:191], v[212:215], v[82:85]
	s_setprio 0
	s_barrier
	s_add_i32 s53, s53, s12
	v_lshl_add_u64 v[152:153], v[152:153], 0, s[40:41]
	s_mov_b32 m0, s53
	ds_read_b128 v[192:195], v157 offset:49152
	ds_read_b128 v[196:199], v157 offset:50176
	ds_read_b128 v[200:203], v157 offset:51200
	ds_read_b128 v[204:207], v157 offset:52224
	ds_read_b128 v[208:211], v157 offset:53248
	ds_read_b128 v[212:215], v157 offset:54272
	ds_read_b128 v[218:221], v157 offset:55296
	ds_read_b128 v[222:225], v157 offset:56320
	global_load_lds_dwordx4 v[152:153], off
	s_add_i32 m0, s53, 0x2000
	s_add_u32 s34, s34, 0x80080
	v_lshl_add_u64 v[152:153], v[226:227], 0, s[40:41]
	s_addc_u32 s35, s35, 0
	s_add_i32 s53, s62, s12
	global_load_lds_dwordx4 v[152:153], off
	v_lshl_add_u64 v[152:153], s[34:35], 0, v[132:133]
	s_mov_b32 m0, s53
	s_nop 0
	global_load_lds_dwordx4 v[152:153], off
	v_lshl_add_u64 v[152:153], s[34:35], 0, v[136:137]
	s_add_i32 m0, s53, 0x2000
	s_nop 0
	global_load_lds_dwordx4 v[152:153], off
	v_lshl_add_u64 v[152:153], v[228:229], 0, s[40:41]
	s_mov_b32 m0, s59
	s_nop 0
	global_load_lds_dwordx4 v[152:153], off
	v_lshl_add_u64 v[152:153], v[230:231], 0, s[40:41]
	s_mov_b32 m0, s60
	s_nop 0
	global_load_lds_dwordx4 v[152:153], off
	s_waitcnt vmcnt(8)
	s_waitcnt lgkmcnt(0)
	s_barrier
	s_setprio 1
	s_waitcnt lgkmcnt(0)
	v_mfma_f32_16x16x32_bf16 v[62:65], v[160:163], v[192:195], v[62:65]
	v_mfma_f32_16x16x32_bf16 v[42:45], v[168:171], v[200:203], v[42:45]
	v_mfma_f32_16x16x32_bf16 v[30:33], v[160:163], v[208:211], v[30:33]
	v_mfma_f32_16x16x32_bf16 v[10:13], v[168:171], v[218:221], v[10:13]
	v_mfma_f32_16x16x32_bf16 v[46:49], v[160:163], v[200:203], v[46:49]
	v_mfma_f32_16x16x32_bf16 v[58:61], v[168:171], v[192:195], v[58:61]
	v_mfma_f32_16x16x32_bf16 v[14:17], v[160:163], v[218:221], v[14:17]
	v_mfma_f32_16x16x32_bf16 v[26:29], v[168:171], v[208:211], v[26:29]
	v_mfma_f32_16x16x32_bf16 v[62:65], v[164:167], v[196:199], v[62:65]
	v_mfma_f32_16x16x32_bf16 v[42:45], v[172:175], v[204:207], v[42:45]
	v_mfma_f32_16x16x32_bf16 v[30:33], v[164:167], v[212:215], v[30:33]
	v_mfma_f32_16x16x32_bf16 v[10:13], v[172:175], v[222:225], v[10:13]
	v_mfma_f32_16x16x32_bf16 v[46:49], v[164:167], v[204:207], v[46:49]
	v_mfma_f32_16x16x32_bf16 v[58:61], v[172:175], v[196:199], v[58:61]
	v_mfma_f32_16x16x32_bf16 v[14:17], v[164:167], v[222:225], v[14:17]
	v_mfma_f32_16x16x32_bf16 v[26:29], v[172:175], v[212:215], v[26:29]
	s_setprio 0
	s_setprio 1
	v_mfma_f32_16x16x32_bf16 v[54:57], v[176:179], v[192:195], v[54:57]
	v_mfma_f32_16x16x32_bf16 v[34:37], v[184:187], v[200:203], v[34:37]
	v_mfma_f32_16x16x32_bf16 v[22:25], v[176:179], v[208:211], v[22:25]
	v_mfma_f32_16x16x32_bf16 v[2:5], v[184:187], v[218:221], v[2:5]
	v_mfma_f32_16x16x32_bf16 v[38:41], v[176:179], v[200:203], v[38:41]
	v_mfma_f32_16x16x32_bf16 v[50:53], v[184:187], v[192:195], v[50:53]
	v_mfma_f32_16x16x32_bf16 v[6:9], v[176:179], v[218:221], v[6:9]
	v_mfma_f32_16x16x32_bf16 v[18:21], v[184:187], v[208:211], v[18:21]
	v_mfma_f32_16x16x32_bf16 v[54:57], v[180:183], v[196:199], v[54:57]
	v_mfma_f32_16x16x32_bf16 v[34:37], v[188:191], v[204:207], v[34:37]
	v_mfma_f32_16x16x32_bf16 v[22:25], v[180:183], v[212:215], v[22:25]
	v_mfma_f32_16x16x32_bf16 v[2:5], v[188:191], v[222:225], v[2:5]
	v_mfma_f32_16x16x32_bf16 v[38:41], v[180:183], v[204:207], v[38:41]
	v_mfma_f32_16x16x32_bf16 v[50:53], v[188:191], v[196:199], v[50:53]
	v_mfma_f32_16x16x32_bf16 v[6:9], v[180:183], v[222:225], v[6:9]
	v_mfma_f32_16x16x32_bf16 v[18:21], v[188:191], v[212:215], v[18:21]
	s_setprio 0
	s_barrier
	s_add_i32 s74, s74, 2
	s_add_u32 s76, s76, 0x100
	s_addc_u32 s77, s77, 0
	s_add_u32 s36, s36, 0x100
	s_addc_u32 s52, s52, 0
	s_cmp_gt_u32 s74, 29
	s_cbranch_scc0 .LBB0_2462
	s_and_b64 vcc, exec, s[46:47]
	s_cbranch_vccz .LBB0_2465
	s_barrier

.LBB0_2629:
	ds_read_b128 v[146:149], v165
	ds_read_b128 v[150:153], v165 offset:1024
	ds_read_b128 v[168:171], v165 offset:2048
	ds_read_b128 v[172:175], v165 offset:3072
	ds_read_b128 v[176:179], v166
	ds_read_b128 v[180:183], v166 offset:1024
	ds_read_b128 v[184:187], v166 offset:2048
	ds_read_b128 v[188:191], v166 offset:3072
	s_add_u32 s34, s74, 0xfffe0080
	s_addc_u32 s35, s75, -1
	s_cmp_eq_u32 s79, 4
	s_cselect_b32 s77, s0, s35
	s_cselect_b32 s76, s1, s34
	s_cselect_b32 s35, s27, s78
	s_cselect_b32 s34, s37, s52
	v_lshl_add_u64 v[226:227], s[74:75], 0, v[138:139]
	s_add_i32 m0, s33, 0xc000
	ds_read_b128 v[192:195], v167
	ds_read_b128 v[196:199], v167 offset:1024
	ds_read_b128 v[200:203], v167 offset:2048
	ds_read_b128 v[204:207], v167 offset:3072
	ds_read_b128 v[208:211], v167 offset:4096
	ds_read_b128 v[212:215], v167 offset:5120
	ds_read_b128 v[218:221], v167 offset:6144
	ds_read_b128 v[222:225], v167 offset:7168
	global_load_lds_dwordx4 v[226:227], off
	v_lshl_add_u64 v[226:227], s[74:75], 0, v[140:141]
	s_add_i32 m0, s33, 0xe000
	s_nop 0
	global_load_lds_dwordx4 v[226:227], off
	s_waitcnt vmcnt(8)
	s_waitcnt lgkmcnt(0)
	s_barrier
	s_setprio 1
	s_waitcnt lgkmcnt(0)
	v_mfma_f32_16x16x32_bf16 v[126:129], v[146:149], v[192:195], v[126:129]
	v_mfma_f32_16x16x32_bf16 v[106:109], v[168:171], v[200:203], v[106:109]
	v_mfma_f32_16x16x32_bf16 v[98:101], v[146:149], v[208:211], v[98:101]
	v_mfma_f32_16x16x32_bf16 v[74:77], v[168:171], v[218:221], v[74:77]
	v_mfma_f32_16x16x32_bf16 v[114:117], v[146:149], v[200:203], v[114:117]
	v_mfma_f32_16x16x32_bf16 v[122:125], v[168:171], v[192:195], v[122:125]
	v_mfma_f32_16x16x32_bf16 v[82:85], v[146:149], v[218:221], v[82:85]
	v_mfma_f32_16x16x32_bf16 v[90:93], v[168:171], v[208:211], v[90:93]
	v_mfma_f32_16x16x32_bf16 v[126:129], v[150:153], v[196:199], v[126:129]
	v_mfma_f32_16x16x32_bf16 v[106:109], v[172:175], v[204:207], v[106:109]
	v_mfma_f32_16x16x32_bf16 v[98:101], v[150:153], v[212:215], v[98:101]
	v_mfma_f32_16x16x32_bf16 v[74:77], v[172:175], v[222:225], v[74:77]
	v_mfma_f32_16x16x32_bf16 v[114:117], v[150:153], v[204:207], v[114:117]
	v_mfma_f32_16x16x32_bf16 v[122:125], v[172:175], v[196:199], v[122:125]
	v_mfma_f32_16x16x32_bf16 v[82:85], v[150:153], v[222:225], v[82:85]
	v_mfma_f32_16x16x32_bf16 v[90:93], v[172:175], v[212:215], v[90:93]
	s_setprio 0
	s_setprio 1
	v_mfma_f32_16x16x32_bf16 v[118:121], v[176:179], v[192:195], v[118:121]
	v_mfma_f32_16x16x32_bf16 v[94:97], v[184:187], v[200:203], v[94:97]
	v_mfma_f32_16x16x32_bf16 v[86:89], v[176:179], v[208:211], v[86:89]
	v_mfma_f32_16x16x32_bf16 v[66:69], v[184:187], v[218:221], v[66:69]
	v_mfma_f32_16x16x32_bf16 v[102:105], v[176:179], v[200:203], v[102:105]
	v_mfma_f32_16x16x32_bf16 v[110:113], v[184:187], v[192:195], v[110:113]
	v_mfma_f32_16x16x32_bf16 v[70:73], v[176:179], v[218:221], v[70:73]
	v_mfma_f32_16x16x32_bf16 v[78:81], v[184:187], v[208:211], v[78:81]
	v_mfma_f32_16x16x32_bf16 v[118:121], v[180:183], v[196:199], v[118:121]
	v_mfma_f32_16x16x32_bf16 v[94:97], v[188:191], v[204:207], v[94:97]
	v_mfma_f32_16x16x32_bf16 v[86:89], v[180:183], v[212:215], v[86:89]
	v_mfma_f32_16x16x32_bf16 v[66:69], v[188:191], v[222:225], v[66:69]
	v_mfma_f32_16x16x32_bf16 v[102:105], v[180:183], v[204:207], v[102:105]
	v_mfma_f32_16x16x32_bf16 v[110:113], v[188:191], v[196:199], v[110:113]
	v_mfma_f32_16x16x32_bf16 v[70:73], v[180:183], v[222:225], v[70:73]
	v_mfma_f32_16x16x32_bf16 v[78:81], v[188:191], v[212:215], v[78:81]
	s_setprio 0
	s_barrier
	s_add_i32 s53, s70, s12
	v_lshl_add_u64 v[226:227], s[34:35], 0, v[132:133]
	s_mov_b32 m0, s53
	ds_read_b128 v[192:195], v167 offset:16384
	ds_read_b128 v[196:199], v167 offset:17408
	ds_read_b128 v[200:203], v167 offset:18432
	ds_read_b128 v[204:207], v167 offset:19456
	ds_read_b128 v[208:211], v167 offset:20480
	ds_read_b128 v[212:215], v167 offset:21504
	ds_read_b128 v[218:221], v167 offset:22528
	ds_read_b128 v[222:225], v167 offset:23552
	global_load_lds_dwordx4 v[226:227], off
	s_add_i32 m0, s53, 0x2000
	s_add_u32 s54, s34, 0x20000
	v_lshl_add_u64 v[228:229], s[34:35], 0, v[136:137]
	s_addc_u32 s55, s35, 0
	s_add_i32 s53, s71, s12
	global_load_lds_dwordx4 v[228:229], off
	v_lshl_add_u64 v[230:231], s[54:55], 0, v[132:133]
	s_mov_b32 m0, s53
	v_lshl_add_u64 v[232:233], s[76:77], 0, v[134:135]
	global_load_lds_dwordx4 v[230:231], off
	v_lshl_add_u64 v[230:231], s[54:55], 0, v[136:137]
	s_add_i32 m0, s53, 0x2000
	s_nop 0
	global_load_lds_dwordx4 v[230:231], off
	v_lshl_add_u64 v[230:231], s[76:77], 0, v[130:131]
	s_mov_b32 m0, s33
	s_nop 0
	global_load_lds_dwordx4 v[230:231], off
	s_mov_b32 m0, s47
	s_nop 0
	global_load_lds_dwordx4 v[232:233], off
	s_waitcnt vmcnt(8)
	s_waitcnt lgkmcnt(0)
	s_barrier
	s_setprio 1
	s_waitcnt lgkmcnt(0)
	v_mfma_f32_16x16x32_bf16 v[62:65], v[146:149], v[192:195], v[62:65]
	v_mfma_f32_16x16x32_bf16 v[42:45], v[168:171], v[200:203], v[42:45]
	v_mfma_f32_16x16x32_bf16 v[34:37], v[146:149], v[208:211], v[34:37]
	v_mfma_f32_16x16x32_bf16 v[10:13], v[168:171], v[218:221], v[10:13]
	v_mfma_f32_16x16x32_bf16 v[50:53], v[146:149], v[200:203], v[50:53]
	v_mfma_f32_16x16x32_bf16 v[58:61], v[168:171], v[192:195], v[58:61]
	v_mfma_f32_16x16x32_bf16 v[18:21], v[146:149], v[218:221], v[18:21]
	v_mfma_f32_16x16x32_bf16 v[26:29], v[168:171], v[208:211], v[26:29]
	v_mfma_f32_16x16x32_bf16 v[62:65], v[150:153], v[196:199], v[62:65]
	v_mfma_f32_16x16x32_bf16 v[42:45], v[172:175], v[204:207], v[42:45]
	v_mfma_f32_16x16x32_bf16 v[34:37], v[150:153], v[212:215], v[34:37]
	v_mfma_f32_16x16x32_bf16 v[10:13], v[172:175], v[222:225], v[10:13]
	v_mfma_f32_16x16x32_bf16 v[50:53], v[150:153], v[204:207], v[50:53]
	v_mfma_f32_16x16x32_bf16 v[58:61], v[172:175], v[196:199], v[58:61]
	v_mfma_f32_16x16x32_bf16 v[18:21], v[150:153], v[222:225], v[18:21]
	v_mfma_f32_16x16x32_bf16 v[26:29], v[172:175], v[212:215], v[26:29]
	s_setprio 0
	s_setprio 1
	v_mfma_f32_16x16x32_bf16 v[54:57], v[176:179], v[192:195], v[54:57]
	v_mfma_f32_16x16x32_bf16 v[30:33], v[184:187], v[200:203], v[30:33]
	v_mfma_f32_16x16x32_bf16 v[22:25], v[176:179], v[208:211], v[22:25]
	v_mfma_f32_16x16x32_bf16 v[2:5], v[184:187], v[218:221], v[2:5]
	v_mfma_f32_16x16x32_bf16 v[38:41], v[176:179], v[200:203], v[38:41]
	v_mfma_f32_16x16x32_bf16 v[46:49], v[184:187], v[192:195], v[46:49]
	v_mfma_f32_16x16x32_bf16 v[6:9], v[176:179], v[218:221], v[6:9]
	v_mfma_f32_16x16x32_bf16 v[14:17], v[184:187], v[208:211], v[14:17]
	v_mfma_f32_16x16x32_bf16 v[54:57], v[180:183], v[196:199], v[54:57]
	v_mfma_f32_16x16x32_bf16 v[30:33], v[188:191], v[204:207], v[30:33]
	v_mfma_f32_16x16x32_bf16 v[22:25], v[180:183], v[212:215], v[22:25]
	v_mfma_f32_16x16x32_bf16 v[2:5], v[188:191], v[222:225], v[2:5]
	v_mfma_f32_16x16x32_bf16 v[38:41], v[180:183], v[204:207], v[38:41]
	v_mfma_f32_16x16x32_bf16 v[46:49], v[188:191], v[196:199], v[46:49]
	v_mfma_f32_16x16x32_bf16 v[6:9], v[180:183], v[222:225], v[6:9]
	v_mfma_f32_16x16x32_bf16 v[14:17], v[188:191], v[212:215], v[14:17]
	s_setprio 0
	s_barrier
	s_add_i32 s53, 0, 0x18000
	s_add_i32 s62, 0, 0x1c000
	v_add_u32_e32 v172, s53, v162
	v_add_u32_e32 v188, s62, v162
	ds_read_b128 v[146:149], v172
	ds_read_b128 v[150:153], v172 offset:1024
	ds_read_b128 v[168:171], v172 offset:2048
	ds_read_b128 v[172:175], v172 offset:3072
	ds_read_b128 v[176:179], v188
	ds_read_b128 v[180:183], v188 offset:1024
	ds_read_b128 v[184:187], v188 offset:2048
	ds_read_b128 v[188:191], v188 offset:3072
	s_add_u32 s54, s76, 0x20000
	s_addc_u32 s55, s77, 0
	s_mov_b32 m0, s56
	v_lshl_add_u64 v[234:235], s[54:55], 0, v[130:131]
	ds_read_b128 v[192:195], v167 offset:32768
	ds_read_b128 v[196:199], v167 offset:33792
	ds_read_b128 v[200:203], v167 offset:34816
	ds_read_b128 v[204:207], v167 offset:35840
	ds_read_b128 v[208:211], v167 offset:36864
	ds_read_b128 v[212:215], v167 offset:37888
	ds_read_b128 v[218:221], v167 offset:38912
	ds_read_b128 v[222:225], v167 offset:39936
	global_load_lds_dwordx4 v[234:235], off
	v_lshl_add_u64 v[234:235], s[54:55], 0, v[134:135]
	s_mov_b32 m0, s57
	s_nop 0
	global_load_lds_dwordx4 v[234:235], off
	s_waitcnt vmcnt(8)
	s_waitcnt lgkmcnt(0)
	s_barrier
	s_setprio 1
	s_waitcnt lgkmcnt(0)
	v_mfma_f32_16x16x32_bf16 v[126:129], v[146:149], v[192:195], v[126:129]
	v_mfma_f32_16x16x32_bf16 v[106:109], v[168:171], v[200:203], v[106:109]
	v_mfma_f32_16x16x32_bf16 v[98:101], v[146:149], v[208:211], v[98:101]
	v_mfma_f32_16x16x32_bf16 v[74:77], v[168:171], v[218:221], v[74:77]
	v_mfma_f32_16x16x32_bf16 v[114:117], v[146:149], v[200:203], v[114:117]
	v_mfma_f32_16x16x32_bf16 v[122:125], v[168:171], v[192:195], v[122:125]
	v_mfma_f32_16x16x32_bf16 v[82:85], v[146:149], v[218:221], v[82:85]
	v_mfma_f32_16x16x32_bf16 v[90:93], v[168:171], v[208:211], v[90:93]
	v_mfma_f32_16x16x32_bf16 v[126:129], v[150:153], v[196:199], v[126:129]
	v_mfma_f32_16x16x32_bf16 v[106:109], v[172:175], v[204:207], v[106:109]
	v_mfma_f32_16x16x32_bf16 v[98:101], v[150:153], v[212:215], v[98:101]
	v_mfma_f32_16x16x32_bf16 v[74:77], v[172:175], v[222:225], v[74:77]
	v_mfma_f32_16x16x32_bf16 v[114:117], v[150:153], v[204:207], v[114:117]
	v_mfma_f32_16x16x32_bf16 v[122:125], v[172:175], v[196:199], v[122:125]
	v_mfma_f32_16x16x32_bf16 v[82:85], v[150:153], v[222:225], v[82:85]
	v_mfma_f32_16x16x32_bf16 v[90:93], v[172:175], v[212:215], v[90:93]
	s_setprio 0
	s_setprio 1
	v_mfma_f32_16x16x32_bf16 v[118:121], v[176:179], v[192:195], v[118:121]
	v_mfma_f32_16x16x32_bf16 v[94:97], v[184:187], v[200:203], v[94:97]
	v_mfma_f32_16x16x32_bf16 v[86:89], v[176:179], v[208:211], v[86:89]
	v_mfma_f32_16x16x32_bf16 v[66:69], v[184:187], v[218:221], v[66:69]
	v_mfma_f32_16x16x32_bf16 v[102:105], v[176:179], v[200:203], v[102:105]
	v_mfma_f32_16x16x32_bf16 v[110:113], v[184:187], v[192:195], v[110:113]
	v_mfma_f32_16x16x32_bf16 v[70:73], v[176:179], v[218:221], v[70:73]
	v_mfma_f32_16x16x32_bf16 v[78:81], v[184:187], v[208:211], v[78:81]
	v_mfma_f32_16x16x32_bf16 v[118:121], v[180:183], v[196:199], v[118:121]
	v_mfma_f32_16x16x32_bf16 v[94:97], v[188:191], v[204:207], v[94:97]
	v_mfma_f32_16x16x32_bf16 v[86:89], v[180:183], v[212:215], v[86:89]
	v_mfma_f32_16x16x32_bf16 v[66:69], v[188:191], v[222:225], v[66:69]
	v_mfma_f32_16x16x32_bf16 v[102:105], v[180:183], v[204:207], v[102:105]
	v_mfma_f32_16x16x32_bf16 v[110:113], v[188:191], v[196:199], v[110:113]
	v_mfma_f32_16x16x32_bf16 v[70:73], v[180:183], v[222:225], v[70:73]
	v_mfma_f32_16x16x32_bf16 v[78:81], v[188:191], v[212:215], v[78:81]
	s_setprio 0
	s_barrier
	s_add_i32 s53, s53, s12
	v_lshl_add_u64 v[226:227], v[226:227], 0, s[8:9]
	s_mov_b32 m0, s53
	ds_read_b128 v[192:195], v167 offset:49152
	ds_read_b128 v[196:199], v167 offset:50176
	ds_read_b128 v[200:203], v167 offset:51200
	ds_read_b128 v[204:207], v167 offset:52224
	ds_read_b128 v[208:211], v167 offset:53248
	ds_read_b128 v[212:215], v167 offset:54272
	ds_read_b128 v[218:221], v167 offset:55296
	ds_read_b128 v[222:225], v167 offset:56320
	global_load_lds_dwordx4 v[226:227], off
	s_add_i32 m0, s53, 0x2000
	s_add_u32 s34, s34, 0x20080
	v_lshl_add_u64 v[226:227], v[228:229], 0, s[8:9]
	s_addc_u32 s35, s35, 0
	s_add_i32 s53, s62, s12
	global_load_lds_dwordx4 v[226:227], off
	v_lshl_add_u64 v[226:227], s[34:35], 0, v[132:133]
	s_mov_b32 m0, s53
	s_nop 0
	global_load_lds_dwordx4 v[226:227], off
	v_lshl_add_u64 v[226:227], s[34:35], 0, v[136:137]
	s_add_i32 m0, s53, 0x2000
	s_nop 0
	global_load_lds_dwordx4 v[226:227], off
	v_lshl_add_u64 v[226:227], v[230:231], 0, s[8:9]
	s_mov_b32 m0, s59
	s_nop 0
	global_load_lds_dwordx4 v[226:227], off
	v_lshl_add_u64 v[226:227], v[232:233], 0, s[8:9]
	s_mov_b32 m0, s60
	s_nop 0
	global_load_lds_dwordx4 v[226:227], off
	s_waitcnt vmcnt(8)
	s_waitcnt lgkmcnt(0)
	s_barrier
	s_setprio 1
	s_waitcnt lgkmcnt(0)
	v_mfma_f32_16x16x32_bf16 v[62:65], v[146:149], v[192:195], v[62:65]
	v_mfma_f32_16x16x32_bf16 v[42:45], v[168:171], v[200:203], v[42:45]
	v_mfma_f32_16x16x32_bf16 v[34:37], v[146:149], v[208:211], v[34:37]
	v_mfma_f32_16x16x32_bf16 v[10:13], v[168:171], v[218:221], v[10:13]
	v_mfma_f32_16x16x32_bf16 v[50:53], v[146:149], v[200:203], v[50:53]
	v_mfma_f32_16x16x32_bf16 v[58:61], v[168:171], v[192:195], v[58:61]
	v_mfma_f32_16x16x32_bf16 v[18:21], v[146:149], v[218:221], v[18:21]
	v_mfma_f32_16x16x32_bf16 v[26:29], v[168:171], v[208:211], v[26:29]
	v_mfma_f32_16x16x32_bf16 v[62:65], v[150:153], v[196:199], v[62:65]
	v_mfma_f32_16x16x32_bf16 v[42:45], v[172:175], v[204:207], v[42:45]
	v_mfma_f32_16x16x32_bf16 v[34:37], v[150:153], v[212:215], v[34:37]
	v_mfma_f32_16x16x32_bf16 v[10:13], v[172:175], v[222:225], v[10:13]
	v_mfma_f32_16x16x32_bf16 v[50:53], v[150:153], v[204:207], v[50:53]
	v_mfma_f32_16x16x32_bf16 v[58:61], v[172:175], v[196:199], v[58:61]
	v_mfma_f32_16x16x32_bf16 v[18:21], v[150:153], v[222:225], v[18:21]
	v_mfma_f32_16x16x32_bf16 v[26:29], v[172:175], v[212:215], v[26:29]
	s_setprio 0
	s_setprio 1
	v_mfma_f32_16x16x32_bf16 v[54:57], v[176:179], v[192:195], v[54:57]
	v_mfma_f32_16x16x32_bf16 v[30:33], v[184:187], v[200:203], v[30:33]
	v_mfma_f32_16x16x32_bf16 v[22:25], v[176:179], v[208:211], v[22:25]
	v_mfma_f32_16x16x32_bf16 v[2:5], v[184:187], v[218:221], v[2:5]
	v_mfma_f32_16x16x32_bf16 v[38:41], v[176:179], v[200:203], v[38:41]
	v_mfma_f32_16x16x32_bf16 v[46:49], v[184:187], v[192:195], v[46:49]
	v_mfma_f32_16x16x32_bf16 v[6:9], v[176:179], v[218:221], v[6:9]
	v_mfma_f32_16x16x32_bf16 v[14:17], v[184:187], v[208:211], v[14:17]
	v_mfma_f32_16x16x32_bf16 v[54:57], v[180:183], v[196:199], v[54:57]
	v_mfma_f32_16x16x32_bf16 v[30:33], v[188:191], v[204:207], v[30:33]
	v_mfma_f32_16x16x32_bf16 v[22:25], v[180:183], v[212:215], v[22:25]
	v_mfma_f32_16x16x32_bf16 v[2:5], v[188:191], v[222:225], v[2:5]
	v_mfma_f32_16x16x32_bf16 v[38:41], v[180:183], v[204:207], v[38:41]
	v_mfma_f32_16x16x32_bf16 v[46:49], v[188:191], v[196:199], v[46:49]
	v_mfma_f32_16x16x32_bf16 v[6:9], v[180:183], v[222:225], v[6:9]
	v_mfma_f32_16x16x32_bf16 v[14:17], v[188:191], v[212:215], v[14:17]
	s_setprio 0
	s_barrier
	s_add_i32 s79, s79, 2
	s_add_u32 s74, s74, 0x100
	s_addc_u32 s75, s75, 0
	s_add_u32 s52, s52, 0x100
	s_addc_u32 s78, s78, 0
	s_cmp_gt_u32 s79, 5
	s_cbranch_scc0 .LBB0_2629
	s_and_b64 vcc, exec, s[24:25]
	s_cbranch_vccz .LBB0_2632
	s_barrier

.LBB0_2659:
	ds_read_b128 v[146:149], v1
	ds_read_b128 v[160:163], v1 offset:1024
	ds_read_b128 v[164:167], v1 offset:2048
	ds_read_b128 v[168:171], v1 offset:3072
	ds_read_b128 v[172:175], v154
	ds_read_b128 v[176:179], v154 offset:1024
	ds_read_b128 v[180:183], v154 offset:2048
	ds_read_b128 v[184:187], v154 offset:3072
	s_add_u32 s34, s74, 0xfffe0080
	s_addc_u32 s35, s75, -1
	s_cmp_eq_u32 s72, 4
	s_cselect_b32 s77, s0, s35
	s_cselect_b32 s76, s1, s34
	s_cselect_b32 s35, s27, s71
	s_cselect_b32 s34, s37, s52
	v_lshl_add_u64 v[150:151], s[74:75], 0, v[138:139]
	s_add_i32 m0, s33, 0xc000
	ds_read_b128 v[188:191], v155
	ds_read_b128 v[192:195], v155 offset:1024
	ds_read_b128 v[196:199], v155 offset:2048
	ds_read_b128 v[200:203], v155 offset:3072
	ds_read_b128 v[204:207], v155 offset:4096
	ds_read_b128 v[208:211], v155 offset:5120
	ds_read_b128 v[212:215], v155 offset:6144
	ds_read_b128 v[218:221], v155 offset:7168
	global_load_lds_dwordx4 v[150:151], off
	v_lshl_add_u64 v[150:151], s[74:75], 0, v[140:141]
	s_add_i32 m0, s33, 0xe000
	s_nop 0
	global_load_lds_dwordx4 v[150:151], off
	s_waitcnt vmcnt(8)
	s_waitcnt lgkmcnt(0)
	s_barrier
	s_setprio 1
	s_waitcnt lgkmcnt(0)
	v_mfma_f32_16x16x32_bf16 v[126:129], v[146:149], v[188:191], v[126:129]
	v_mfma_f32_16x16x32_bf16 v[106:109], v[164:167], v[196:199], v[106:109]
	v_mfma_f32_16x16x32_bf16 v[94:97], v[146:149], v[204:207], v[94:97]
	v_mfma_f32_16x16x32_bf16 v[74:77], v[164:167], v[212:215], v[74:77]
	v_mfma_f32_16x16x32_bf16 v[110:113], v[146:149], v[196:199], v[110:113]
	v_mfma_f32_16x16x32_bf16 v[122:125], v[164:167], v[188:191], v[122:125]
	v_mfma_f32_16x16x32_bf16 v[78:81], v[146:149], v[212:215], v[78:81]
	v_mfma_f32_16x16x32_bf16 v[90:93], v[164:167], v[204:207], v[90:93]
	v_mfma_f32_16x16x32_bf16 v[126:129], v[160:163], v[192:195], v[126:129]
	v_mfma_f32_16x16x32_bf16 v[106:109], v[168:171], v[200:203], v[106:109]
	v_mfma_f32_16x16x32_bf16 v[94:97], v[160:163], v[208:211], v[94:97]
	v_mfma_f32_16x16x32_bf16 v[74:77], v[168:171], v[218:221], v[74:77]
	v_mfma_f32_16x16x32_bf16 v[110:113], v[160:163], v[200:203], v[110:113]
	v_mfma_f32_16x16x32_bf16 v[122:125], v[168:171], v[192:195], v[122:125]
	v_mfma_f32_16x16x32_bf16 v[78:81], v[160:163], v[218:221], v[78:81]
	v_mfma_f32_16x16x32_bf16 v[90:93], v[168:171], v[208:211], v[90:93]
	s_setprio 0
	s_setprio 1
	v_mfma_f32_16x16x32_bf16 v[118:121], v[172:175], v[188:191], v[118:121]
	v_mfma_f32_16x16x32_bf16 v[98:101], v[180:183], v[196:199], v[98:101]
	v_mfma_f32_16x16x32_bf16 v[86:89], v[172:175], v[204:207], v[86:89]
	v_mfma_f32_16x16x32_bf16 v[66:69], v[180:183], v[212:215], v[66:69]
	v_mfma_f32_16x16x32_bf16 v[102:105], v[172:175], v[196:199], v[102:105]
	v_mfma_f32_16x16x32_bf16 v[114:117], v[180:183], v[188:191], v[114:117]
	v_mfma_f32_16x16x32_bf16 v[70:73], v[172:175], v[212:215], v[70:73]
	v_mfma_f32_16x16x32_bf16 v[82:85], v[180:183], v[204:207], v[82:85]
	v_mfma_f32_16x16x32_bf16 v[118:121], v[176:179], v[192:195], v[118:121]
	v_mfma_f32_16x16x32_bf16 v[98:101], v[184:187], v[200:203], v[98:101]
	v_mfma_f32_16x16x32_bf16 v[86:89], v[176:179], v[208:211], v[86:89]
	v_mfma_f32_16x16x32_bf16 v[66:69], v[184:187], v[218:221], v[66:69]
	v_mfma_f32_16x16x32_bf16 v[102:105], v[176:179], v[200:203], v[102:105]
	v_mfma_f32_16x16x32_bf16 v[114:117], v[184:187], v[192:195], v[114:117]
	v_mfma_f32_16x16x32_bf16 v[70:73], v[176:179], v[218:221], v[70:73]
	v_mfma_f32_16x16x32_bf16 v[82:85], v[184:187], v[208:211], v[82:85]
	s_setprio 0
	s_barrier
	s_add_i32 s53, s60, s13
	v_lshl_add_u64 v[150:151], s[34:35], 0, v[132:133]
	s_mov_b32 m0, s53
	ds_read_b128 v[188:191], v155 offset:16384
	ds_read_b128 v[192:195], v155 offset:17408
	ds_read_b128 v[196:199], v155 offset:18432
	ds_read_b128 v[200:203], v155 offset:19456
	ds_read_b128 v[204:207], v155 offset:20480
	ds_read_b128 v[208:211], v155 offset:21504
	ds_read_b128 v[212:215], v155 offset:22528
	ds_read_b128 v[218:221], v155 offset:23552
	global_load_lds_dwordx4 v[150:151], off
	s_add_i32 m0, s53, 0x2000
	s_add_u32 s62, s34, 0x20000
	v_lshl_add_u64 v[222:223], s[34:35], 0, v[136:137]
	s_addc_u32 s63, s35, 0
	s_add_i32 s53, s61, s13
	global_load_lds_dwordx4 v[222:223], off
	v_lshl_add_u64 v[224:225], s[62:63], 0, v[132:133]
	s_mov_b32 m0, s53
	v_lshl_add_u64 v[226:227], s[76:77], 0, v[134:135]
	global_load_lds_dwordx4 v[224:225], off
	v_lshl_add_u64 v[224:225], s[62:63], 0, v[136:137]
	s_add_i32 m0, s53, 0x2000
	s_nop 0
	global_load_lds_dwordx4 v[224:225], off
	v_lshl_add_u64 v[224:225], s[76:77], 0, v[130:131]
	s_mov_b32 m0, s33
	s_nop 0
	global_load_lds_dwordx4 v[224:225], off
	s_mov_b32 m0, s47
	s_nop 0
	global_load_lds_dwordx4 v[226:227], off
	s_waitcnt vmcnt(8)
	s_waitcnt lgkmcnt(0)
	s_barrier
	s_setprio 1
	s_waitcnt lgkmcnt(0)
	v_mfma_f32_16x16x32_bf16 v[62:65], v[146:149], v[188:191], v[62:65]
	v_mfma_f32_16x16x32_bf16 v[42:45], v[164:167], v[196:199], v[42:45]
	v_mfma_f32_16x16x32_bf16 v[34:37], v[146:149], v[204:207], v[34:37]
	v_mfma_f32_16x16x32_bf16 v[10:13], v[164:167], v[212:215], v[10:13]
	v_mfma_f32_16x16x32_bf16 v[50:53], v[146:149], v[196:199], v[50:53]
	v_mfma_f32_16x16x32_bf16 v[58:61], v[164:167], v[188:191], v[58:61]
	v_mfma_f32_16x16x32_bf16 v[18:21], v[146:149], v[212:215], v[18:21]
	v_mfma_f32_16x16x32_bf16 v[26:29], v[164:167], v[204:207], v[26:29]
	v_mfma_f32_16x16x32_bf16 v[62:65], v[160:163], v[192:195], v[62:65]
	v_mfma_f32_16x16x32_bf16 v[42:45], v[168:171], v[200:203], v[42:45]
	v_mfma_f32_16x16x32_bf16 v[34:37], v[160:163], v[208:211], v[34:37]
	v_mfma_f32_16x16x32_bf16 v[10:13], v[168:171], v[218:221], v[10:13]
	v_mfma_f32_16x16x32_bf16 v[50:53], v[160:163], v[200:203], v[50:53]
	v_mfma_f32_16x16x32_bf16 v[58:61], v[168:171], v[192:195], v[58:61]
	v_mfma_f32_16x16x32_bf16 v[18:21], v[160:163], v[218:221], v[18:21]
	v_mfma_f32_16x16x32_bf16 v[26:29], v[168:171], v[208:211], v[26:29]
	s_setprio 0
	s_setprio 1
	v_mfma_f32_16x16x32_bf16 v[54:57], v[172:175], v[188:191], v[54:57]
	v_mfma_f32_16x16x32_bf16 v[30:33], v[180:183], v[196:199], v[30:33]
	v_mfma_f32_16x16x32_bf16 v[22:25], v[172:175], v[204:207], v[22:25]
	v_mfma_f32_16x16x32_bf16 v[2:5], v[180:183], v[212:215], v[2:5]
	v_mfma_f32_16x16x32_bf16 v[38:41], v[172:175], v[196:199], v[38:41]
	v_mfma_f32_16x16x32_bf16 v[46:49], v[180:183], v[188:191], v[46:49]
	v_mfma_f32_16x16x32_bf16 v[6:9], v[172:175], v[212:215], v[6:9]
	v_mfma_f32_16x16x32_bf16 v[14:17], v[180:183], v[204:207], v[14:17]
	v_mfma_f32_16x16x32_bf16 v[54:57], v[176:179], v[192:195], v[54:57]
	v_mfma_f32_16x16x32_bf16 v[30:33], v[184:187], v[200:203], v[30:33]
	v_mfma_f32_16x16x32_bf16 v[22:25], v[176:179], v[208:211], v[22:25]
	v_mfma_f32_16x16x32_bf16 v[2:5], v[184:187], v[218:221], v[2:5]
	v_mfma_f32_16x16x32_bf16 v[38:41], v[176:179], v[200:203], v[38:41]
	v_mfma_f32_16x16x32_bf16 v[46:49], v[184:187], v[192:195], v[46:49]
	v_mfma_f32_16x16x32_bf16 v[6:9], v[176:179], v[218:221], v[6:9]
	v_mfma_f32_16x16x32_bf16 v[14:17], v[184:187], v[208:211], v[14:17]
	s_setprio 0
	s_barrier
	s_add_i32 s53, 0, 0x18000
	v_add_u32_e32 v156, s53, v153
	s_add_i32 s66, 0, 0x1c000
	ds_read_b128 v[146:149], v156
	ds_read_b128 v[160:163], v156 offset:1024
	ds_read_b128 v[164:167], v156 offset:2048
	ds_read_b128 v[168:171], v156 offset:3072
	v_add_u32_e32 v156, s66, v153
	ds_read_b128 v[172:175], v156
	ds_read_b128 v[176:179], v156 offset:1024
	ds_read_b128 v[180:183], v156 offset:2048
	ds_read_b128 v[184:187], v156 offset:3072
	s_add_u32 s62, s76, 0x20000
	s_addc_u32 s63, s77, 0
	s_mov_b32 m0, s54
	v_lshl_add_u64 v[228:229], s[62:63], 0, v[130:131]
	ds_read_b128 v[188:191], v155 offset:32768
	ds_read_b128 v[192:195], v155 offset:33792
	ds_read_b128 v[196:199], v155 offset:34816
	ds_read_b128 v[200:203], v155 offset:35840
	ds_read_b128 v[204:207], v155 offset:36864
	ds_read_b128 v[208:211], v155 offset:37888
	ds_read_b128 v[212:215], v155 offset:38912
	ds_read_b128 v[218:221], v155 offset:39936
	global_load_lds_dwordx4 v[228:229], off
	v_lshl_add_u64 v[228:229], s[62:63], 0, v[134:135]
	s_mov_b32 m0, s55
	s_nop 0
	global_load_lds_dwordx4 v[228:229], off
	s_waitcnt vmcnt(8)
	s_waitcnt lgkmcnt(0)
	s_barrier
	s_setprio 1
	s_waitcnt lgkmcnt(0)
	v_mfma_f32_16x16x32_bf16 v[126:129], v[146:149], v[188:191], v[126:129]
	v_mfma_f32_16x16x32_bf16 v[106:109], v[164:167], v[196:199], v[106:109]
	v_mfma_f32_16x16x32_bf16 v[94:97], v[146:149], v[204:207], v[94:97]
	v_mfma_f32_16x16x32_bf16 v[74:77], v[164:167], v[212:215], v[74:77]
	v_mfma_f32_16x16x32_bf16 v[110:113], v[146:149], v[196:199], v[110:113]
	v_mfma_f32_16x16x32_bf16 v[122:125], v[164:167], v[188:191], v[122:125]
	v_mfma_f32_16x16x32_bf16 v[78:81], v[146:149], v[212:215], v[78:81]
	v_mfma_f32_16x16x32_bf16 v[90:93], v[164:167], v[204:207], v[90:93]
	v_mfma_f32_16x16x32_bf16 v[126:129], v[160:163], v[192:195], v[126:129]
	v_mfma_f32_16x16x32_bf16 v[106:109], v[168:171], v[200:203], v[106:109]
	v_mfma_f32_16x16x32_bf16 v[94:97], v[160:163], v[208:211], v[94:97]
	v_mfma_f32_16x16x32_bf16 v[74:77], v[168:171], v[218:221], v[74:77]
	v_mfma_f32_16x16x32_bf16 v[110:113], v[160:163], v[200:203], v[110:113]
	v_mfma_f32_16x16x32_bf16 v[122:125], v[168:171], v[192:195], v[122:125]
	v_mfma_f32_16x16x32_bf16 v[78:81], v[160:163], v[218:221], v[78:81]
	v_mfma_f32_16x16x32_bf16 v[90:93], v[168:171], v[208:211], v[90:93]
	s_setprio 0
	s_setprio 1
	v_mfma_f32_16x16x32_bf16 v[118:121], v[172:175], v[188:191], v[118:121]
	v_mfma_f32_16x16x32_bf16 v[98:101], v[180:183], v[196:199], v[98:101]
	v_mfma_f32_16x16x32_bf16 v[86:89], v[172:175], v[204:207], v[86:89]
	v_mfma_f32_16x16x32_bf16 v[66:69], v[180:183], v[212:215], v[66:69]
	v_mfma_f32_16x16x32_bf16 v[102:105], v[172:175], v[196:199], v[102:105]
	v_mfma_f32_16x16x32_bf16 v[114:117], v[180:183], v[188:191], v[114:117]
	v_mfma_f32_16x16x32_bf16 v[70:73], v[172:175], v[212:215], v[70:73]
	v_mfma_f32_16x16x32_bf16 v[82:85], v[180:183], v[204:207], v[82:85]
	v_mfma_f32_16x16x32_bf16 v[118:121], v[176:179], v[192:195], v[118:121]
	v_mfma_f32_16x16x32_bf16 v[98:101], v[184:187], v[200:203], v[98:101]
	v_mfma_f32_16x16x32_bf16 v[86:89], v[176:179], v[208:211], v[86:89]
	v_mfma_f32_16x16x32_bf16 v[66:69], v[184:187], v[218:221], v[66:69]
	v_mfma_f32_16x16x32_bf16 v[102:105], v[176:179], v[200:203], v[102:105]
	v_mfma_f32_16x16x32_bf16 v[114:117], v[184:187], v[192:195], v[114:117]
	v_mfma_f32_16x16x32_bf16 v[70:73], v[176:179], v[218:221], v[70:73]
	v_mfma_f32_16x16x32_bf16 v[82:85], v[184:187], v[208:211], v[82:85]
	s_setprio 0
	s_barrier
	s_add_i32 s53, s53, s13
	v_lshl_add_u64 v[150:151], v[150:151], 0, s[8:9]
	s_mov_b32 m0, s53
	ds_read_b128 v[188:191], v155 offset:49152
	ds_read_b128 v[192:195], v155 offset:50176
	ds_read_b128 v[196:199], v155 offset:51200
	ds_read_b128 v[200:203], v155 offset:52224
	ds_read_b128 v[204:207], v155 offset:53248
	ds_read_b128 v[208:211], v155 offset:54272
	ds_read_b128 v[212:215], v155 offset:55296
	ds_read_b128 v[218:221], v155 offset:56320
	global_load_lds_dwordx4 v[150:151], off
	s_add_i32 m0, s53, 0x2000
	s_add_u32 s34, s34, 0x20080
	v_lshl_add_u64 v[150:151], v[222:223], 0, s[8:9]
	s_addc_u32 s35, s35, 0
	s_add_i32 s53, s66, s13
	global_load_lds_dwordx4 v[150:151], off
	v_lshl_add_u64 v[150:151], s[34:35], 0, v[132:133]
	s_mov_b32 m0, s53
	s_nop 0
	global_load_lds_dwordx4 v[150:151], off
	v_lshl_add_u64 v[150:151], s[34:35], 0, v[136:137]
	s_add_i32 m0, s53, 0x2000
	s_nop 0
	global_load_lds_dwordx4 v[150:151], off
	v_lshl_add_u64 v[150:151], v[224:225], 0, s[8:9]
	s_mov_b32 m0, s57
	s_nop 0
	global_load_lds_dwordx4 v[150:151], off
	v_lshl_add_u64 v[150:151], v[226:227], 0, s[8:9]
	s_mov_b32 m0, s58
	s_nop 0
	global_load_lds_dwordx4 v[150:151], off
	s_waitcnt vmcnt(8)
	s_waitcnt lgkmcnt(0)
	s_barrier
	s_setprio 1
	s_waitcnt lgkmcnt(0)
	v_mfma_f32_16x16x32_bf16 v[62:65], v[146:149], v[188:191], v[62:65]
	v_mfma_f32_16x16x32_bf16 v[42:45], v[164:167], v[196:199], v[42:45]
	v_mfma_f32_16x16x32_bf16 v[34:37], v[146:149], v[204:207], v[34:37]
	v_mfma_f32_16x16x32_bf16 v[10:13], v[164:167], v[212:215], v[10:13]
	v_mfma_f32_16x16x32_bf16 v[50:53], v[146:149], v[196:199], v[50:53]
	v_mfma_f32_16x16x32_bf16 v[58:61], v[164:167], v[188:191], v[58:61]
	v_mfma_f32_16x16x32_bf16 v[18:21], v[146:149], v[212:215], v[18:21]
	v_mfma_f32_16x16x32_bf16 v[26:29], v[164:167], v[204:207], v[26:29]
	v_mfma_f32_16x16x32_bf16 v[62:65], v[160:163], v[192:195], v[62:65]
	v_mfma_f32_16x16x32_bf16 v[42:45], v[168:171], v[200:203], v[42:45]
	v_mfma_f32_16x16x32_bf16 v[34:37], v[160:163], v[208:211], v[34:37]
	v_mfma_f32_16x16x32_bf16 v[10:13], v[168:171], v[218:221], v[10:13]
	v_mfma_f32_16x16x32_bf16 v[50:53], v[160:163], v[200:203], v[50:53]
	v_mfma_f32_16x16x32_bf16 v[58:61], v[168:171], v[192:195], v[58:61]
	v_mfma_f32_16x16x32_bf16 v[18:21], v[160:163], v[218:221], v[18:21]
	v_mfma_f32_16x16x32_bf16 v[26:29], v[168:171], v[208:211], v[26:29]
	s_setprio 0
	s_setprio 1
	v_mfma_f32_16x16x32_bf16 v[54:57], v[172:175], v[188:191], v[54:57]
	v_mfma_f32_16x16x32_bf16 v[30:33], v[180:183], v[196:199], v[30:33]
	v_mfma_f32_16x16x32_bf16 v[22:25], v[172:175], v[204:207], v[22:25]
	v_mfma_f32_16x16x32_bf16 v[2:5], v[180:183], v[212:215], v[2:5]
	v_mfma_f32_16x16x32_bf16 v[38:41], v[172:175], v[196:199], v[38:41]
	v_mfma_f32_16x16x32_bf16 v[46:49], v[180:183], v[188:191], v[46:49]
	v_mfma_f32_16x16x32_bf16 v[6:9], v[172:175], v[212:215], v[6:9]
	v_mfma_f32_16x16x32_bf16 v[14:17], v[180:183], v[204:207], v[14:17]
	v_mfma_f32_16x16x32_bf16 v[54:57], v[176:179], v[192:195], v[54:57]
	v_mfma_f32_16x16x32_bf16 v[30:33], v[184:187], v[200:203], v[30:33]
	v_mfma_f32_16x16x32_bf16 v[22:25], v[176:179], v[208:211], v[22:25]
	v_mfma_f32_16x16x32_bf16 v[2:5], v[184:187], v[218:221], v[2:5]
	v_mfma_f32_16x16x32_bf16 v[38:41], v[176:179], v[200:203], v[38:41]
	v_mfma_f32_16x16x32_bf16 v[46:49], v[184:187], v[192:195], v[46:49]
	v_mfma_f32_16x16x32_bf16 v[6:9], v[176:179], v[218:221], v[6:9]
	v_mfma_f32_16x16x32_bf16 v[14:17], v[184:187], v[208:211], v[14:17]
	s_setprio 0
	s_barrier
	s_add_i32 s72, s72, 2
	s_add_u32 s74, s74, 0x100
	s_addc_u32 s75, s75, 0
	s_add_u32 s52, s52, 0x100
	s_addc_u32 s71, s71, 0
	s_cmp_gt_u32 s72, 5
	s_cbranch_scc0 .LBB0_2659
	s_and_b64 vcc, exec, s[24:25]
	s_cbranch_vccz .LBB0_2662
	s_barrier

.LBB0_2938:
	ds_read_b128 v[130:133], v174
	ds_read_b128 v[134:137], v174 offset:1024
	ds_read_b128 v[138:141], v174 offset:2048
	ds_read_b128 v[158:161], v174 offset:3072
	ds_read_b128 v[162:165], v175
	ds_read_b128 v[166:169], v175 offset:1024
	ds_read_b128 v[178:181], v175 offset:2048
	ds_read_b128 v[182:185], v175 offset:3072
	s_add_u32 s34, s46, 0xfff80080
	s_addc_u32 s35, s47, -1
	s_cmp_eq_u32 s72, 28
	s_cselect_b32 s69, s0, s35
	s_cselect_b32 s68, s1, s34
	s_cselect_b32 s35, s37, s71
	s_cselect_b32 s34, s39, s70
	v_lshl_add_u64 v[170:171], s[46:47], 0, v[150:151]
	s_add_i32 m0, s33, 0xc000
	ds_read_b128 v[186:189], v176
	ds_read_b128 v[190:193], v176 offset:1024
	ds_read_b128 v[194:197], v176 offset:2048
	ds_read_b128 v[198:201], v176 offset:3072
	ds_read_b128 v[202:205], v176 offset:4096
	ds_read_b128 v[206:209], v176 offset:5120
	ds_read_b128 v[210:213], v176 offset:6144
	ds_read_b128 v[218:221], v176 offset:7168
	global_load_lds_dwordx4 v[170:171], off
	v_lshl_add_u64 v[170:171], s[46:47], 0, v[152:153]
	s_add_i32 m0, s33, 0xe000
	s_nop 0
	global_load_lds_dwordx4 v[170:171], off
	s_waitcnt vmcnt(8)
	s_waitcnt lgkmcnt(0)
	s_barrier
	s_setprio 1
	s_waitcnt lgkmcnt(0)
	v_mfma_f32_16x16x32_bf16 v[126:129], v[130:133], v[186:189], v[126:129]
	v_mfma_f32_16x16x32_bf16 v[106:109], v[138:141], v[194:197], v[106:109]
	v_mfma_f32_16x16x32_bf16 v[94:97], v[130:133], v[202:205], v[94:97]
	v_mfma_f32_16x16x32_bf16 v[74:77], v[138:141], v[210:213], v[74:77]
	v_mfma_f32_16x16x32_bf16 v[110:113], v[130:133], v[194:197], v[110:113]
	v_mfma_f32_16x16x32_bf16 v[122:125], v[138:141], v[186:189], v[122:125]
	v_mfma_f32_16x16x32_bf16 v[78:81], v[130:133], v[210:213], v[78:81]
	v_mfma_f32_16x16x32_bf16 v[90:93], v[138:141], v[202:205], v[90:93]
	v_mfma_f32_16x16x32_bf16 v[126:129], v[134:137], v[190:193], v[126:129]
	v_mfma_f32_16x16x32_bf16 v[106:109], v[158:161], v[198:201], v[106:109]
	v_mfma_f32_16x16x32_bf16 v[94:97], v[134:137], v[206:209], v[94:97]
	v_mfma_f32_16x16x32_bf16 v[74:77], v[158:161], v[218:221], v[74:77]
	v_mfma_f32_16x16x32_bf16 v[110:113], v[134:137], v[198:201], v[110:113]
	v_mfma_f32_16x16x32_bf16 v[122:125], v[158:161], v[190:193], v[122:125]
	v_mfma_f32_16x16x32_bf16 v[78:81], v[134:137], v[218:221], v[78:81]
	v_mfma_f32_16x16x32_bf16 v[90:93], v[158:161], v[206:209], v[90:93]
	s_setprio 0
	s_setprio 1
	v_mfma_f32_16x16x32_bf16 v[118:121], v[162:165], v[186:189], v[118:121]
	v_mfma_f32_16x16x32_bf16 v[98:101], v[178:181], v[194:197], v[98:101]
	v_mfma_f32_16x16x32_bf16 v[86:89], v[162:165], v[202:205], v[86:89]
	v_mfma_f32_16x16x32_bf16 v[66:69], v[178:181], v[210:213], v[66:69]
	v_mfma_f32_16x16x32_bf16 v[102:105], v[162:165], v[194:197], v[102:105]
	v_mfma_f32_16x16x32_bf16 v[114:117], v[178:181], v[186:189], v[114:117]
	v_mfma_f32_16x16x32_bf16 v[70:73], v[162:165], v[210:213], v[70:73]
	v_mfma_f32_16x16x32_bf16 v[82:85], v[178:181], v[202:205], v[82:85]
	v_mfma_f32_16x16x32_bf16 v[118:121], v[166:169], v[190:193], v[118:121]
	v_mfma_f32_16x16x32_bf16 v[98:101], v[182:185], v[198:201], v[98:101]
	v_mfma_f32_16x16x32_bf16 v[86:89], v[166:169], v[206:209], v[86:89]
	v_mfma_f32_16x16x32_bf16 v[66:69], v[182:185], v[218:221], v[66:69]
	v_mfma_f32_16x16x32_bf16 v[102:105], v[166:169], v[198:201], v[102:105]
	v_mfma_f32_16x16x32_bf16 v[114:117], v[182:185], v[190:193], v[114:117]
	v_mfma_f32_16x16x32_bf16 v[70:73], v[166:169], v[218:221], v[70:73]
	v_mfma_f32_16x16x32_bf16 v[82:85], v[182:185], v[206:209], v[82:85]
	s_setprio 0
	s_barrier
	s_add_i32 s62, s58, s31
	v_lshl_add_u64 v[170:171], s[34:35], 0, v[144:145]
	s_mov_b32 m0, s62
	ds_read_b128 v[186:189], v176 offset:16384
	ds_read_b128 v[190:193], v176 offset:17408
	ds_read_b128 v[194:197], v176 offset:18432
	ds_read_b128 v[198:201], v176 offset:19456
	ds_read_b128 v[202:205], v176 offset:20480
	ds_read_b128 v[206:209], v176 offset:21504
	ds_read_b128 v[210:213], v176 offset:22528
	ds_read_b128 v[218:221], v176 offset:23552
	global_load_lds_dwordx4 v[170:171], off
	s_add_i32 m0, s62, 0x2000
	s_add_u32 s62, s34, 0x80000
	v_lshl_add_u64 v[214:215], s[34:35], 0, v[148:149]
	s_addc_u32 s63, s35, 0
	s_add_i32 s66, s59, s31
	global_load_lds_dwordx4 v[214:215], off
	v_lshl_add_u64 v[222:223], s[62:63], 0, v[144:145]
	s_mov_b32 m0, s66
	v_lshl_add_u64 v[224:225], s[68:69], 0, v[146:147]
	global_load_lds_dwordx4 v[222:223], off
	v_lshl_add_u64 v[222:223], s[62:63], 0, v[148:149]
	s_add_i32 m0, s66, 0x2000
	s_nop 0
	global_load_lds_dwordx4 v[222:223], off
	v_lshl_add_u64 v[222:223], s[68:69], 0, v[142:143]
	s_mov_b32 m0, s33
	s_nop 0
	global_load_lds_dwordx4 v[222:223], off
	s_mov_b32 m0, s45
	s_nop 0
	global_load_lds_dwordx4 v[224:225], off
	s_waitcnt vmcnt(8)
	s_waitcnt lgkmcnt(0)
	s_barrier
	s_setprio 1
	s_waitcnt lgkmcnt(0)
	v_mfma_f32_16x16x32_bf16 v[62:65], v[130:133], v[186:189], v[62:65]
	v_mfma_f32_16x16x32_bf16 v[42:45], v[138:141], v[194:197], v[42:45]
	v_mfma_f32_16x16x32_bf16 v[38:41], v[130:133], v[202:205], v[38:41]
	v_mfma_f32_16x16x32_bf16 v[10:13], v[138:141], v[210:213], v[10:13]
	v_mfma_f32_16x16x32_bf16 v[50:53], v[130:133], v[194:197], v[50:53]
	v_mfma_f32_16x16x32_bf16 v[58:61], v[138:141], v[186:189], v[58:61]
	v_mfma_f32_16x16x32_bf16 v[14:17], v[130:133], v[210:213], v[14:17]
	v_mfma_f32_16x16x32_bf16 v[34:37], v[138:141], v[202:205], v[34:37]
	v_mfma_f32_16x16x32_bf16 v[62:65], v[134:137], v[190:193], v[62:65]
	v_mfma_f32_16x16x32_bf16 v[42:45], v[158:161], v[198:201], v[42:45]
	v_mfma_f32_16x16x32_bf16 v[38:41], v[134:137], v[206:209], v[38:41]
	v_mfma_f32_16x16x32_bf16 v[10:13], v[158:161], v[218:221], v[10:13]
	v_mfma_f32_16x16x32_bf16 v[50:53], v[134:137], v[198:201], v[50:53]
	v_mfma_f32_16x16x32_bf16 v[58:61], v[158:161], v[190:193], v[58:61]
	v_mfma_f32_16x16x32_bf16 v[14:17], v[134:137], v[218:221], v[14:17]
	v_mfma_f32_16x16x32_bf16 v[34:37], v[158:161], v[206:209], v[34:37]
	s_setprio 0
	s_setprio 1
	v_mfma_f32_16x16x32_bf16 v[54:57], v[162:165], v[186:189], v[54:57]
	v_mfma_f32_16x16x32_bf16 v[26:29], v[178:181], v[194:197], v[26:29]
	v_mfma_f32_16x16x32_bf16 v[22:25], v[162:165], v[202:205], v[22:25]
	v_mfma_f32_16x16x32_bf16 v[2:5], v[178:181], v[210:213], v[2:5]
	v_mfma_f32_16x16x32_bf16 v[30:33], v[162:165], v[194:197], v[30:33]
	v_mfma_f32_16x16x32_bf16 v[46:49], v[178:181], v[186:189], v[46:49]
	v_mfma_f32_16x16x32_bf16 v[6:9], v[162:165], v[210:213], v[6:9]
	v_mfma_f32_16x16x32_bf16 v[18:21], v[178:181], v[202:205], v[18:21]
	v_mfma_f32_16x16x32_bf16 v[54:57], v[166:169], v[190:193], v[54:57]
	v_mfma_f32_16x16x32_bf16 v[26:29], v[182:185], v[198:201], v[26:29]
	v_mfma_f32_16x16x32_bf16 v[22:25], v[166:169], v[206:209], v[22:25]
	v_mfma_f32_16x16x32_bf16 v[2:5], v[182:185], v[218:221], v[2:5]
	v_mfma_f32_16x16x32_bf16 v[30:33], v[166:169], v[198:201], v[30:33]
	v_mfma_f32_16x16x32_bf16 v[46:49], v[182:185], v[190:193], v[46:49]
	v_mfma_f32_16x16x32_bf16 v[6:9], v[166:169], v[218:221], v[6:9]
	v_mfma_f32_16x16x32_bf16 v[18:21], v[182:185], v[206:209], v[18:21]
	s_setprio 0
	s_barrier
	s_add_i32 s66, 0, 0x18000
	s_add_i32 s67, 0, 0x1c000
	v_add_u32_e32 v158, s66, v172
	v_add_u32_e32 v177, s67, v172
	ds_read_b128 v[130:133], v158
	ds_read_b128 v[134:137], v158 offset:1024
	ds_read_b128 v[138:141], v158 offset:2048
	ds_read_b128 v[158:161], v158 offset:3072
	ds_read_b128 v[162:165], v177
	ds_read_b128 v[166:169], v177 offset:1024
	ds_read_b128 v[178:181], v177 offset:2048
	ds_read_b128 v[182:185], v177 offset:3072
	s_add_u32 s62, s68, 0x80000
	s_addc_u32 s63, s69, 0
	s_mov_b32 m0, s52
	v_lshl_add_u64 v[226:227], s[62:63], 0, v[142:143]
	ds_read_b128 v[186:189], v176 offset:32768
	ds_read_b128 v[190:193], v176 offset:33792
	ds_read_b128 v[194:197], v176 offset:34816
	ds_read_b128 v[198:201], v176 offset:35840
	ds_read_b128 v[202:205], v176 offset:36864
	ds_read_b128 v[206:209], v176 offset:37888
	ds_read_b128 v[210:213], v176 offset:38912
	ds_read_b128 v[218:221], v176 offset:39936
	global_load_lds_dwordx4 v[226:227], off
	v_lshl_add_u64 v[226:227], s[62:63], 0, v[146:147]
	s_mov_b32 m0, s53
	s_nop 0
	global_load_lds_dwordx4 v[226:227], off
	s_waitcnt vmcnt(8)
	s_waitcnt lgkmcnt(0)
	s_barrier
	s_setprio 1
	s_waitcnt lgkmcnt(0)
	v_mfma_f32_16x16x32_bf16 v[126:129], v[130:133], v[186:189], v[126:129]
	v_mfma_f32_16x16x32_bf16 v[106:109], v[138:141], v[194:197], v[106:109]
	v_mfma_f32_16x16x32_bf16 v[94:97], v[130:133], v[202:205], v[94:97]
	v_mfma_f32_16x16x32_bf16 v[74:77], v[138:141], v[210:213], v[74:77]
	v_mfma_f32_16x16x32_bf16 v[110:113], v[130:133], v[194:197], v[110:113]
	v_mfma_f32_16x16x32_bf16 v[122:125], v[138:141], v[186:189], v[122:125]
	v_mfma_f32_16x16x32_bf16 v[78:81], v[130:133], v[210:213], v[78:81]
	v_mfma_f32_16x16x32_bf16 v[90:93], v[138:141], v[202:205], v[90:93]
	v_mfma_f32_16x16x32_bf16 v[126:129], v[134:137], v[190:193], v[126:129]
	v_mfma_f32_16x16x32_bf16 v[106:109], v[158:161], v[198:201], v[106:109]
	v_mfma_f32_16x16x32_bf16 v[94:97], v[134:137], v[206:209], v[94:97]
	v_mfma_f32_16x16x32_bf16 v[74:77], v[158:161], v[218:221], v[74:77]
	v_mfma_f32_16x16x32_bf16 v[110:113], v[134:137], v[198:201], v[110:113]
	v_mfma_f32_16x16x32_bf16 v[122:125], v[158:161], v[190:193], v[122:125]
	v_mfma_f32_16x16x32_bf16 v[78:81], v[134:137], v[218:221], v[78:81]
	v_mfma_f32_16x16x32_bf16 v[90:93], v[158:161], v[206:209], v[90:93]
	s_setprio 0
	s_setprio 1
	v_mfma_f32_16x16x32_bf16 v[118:121], v[162:165], v[186:189], v[118:121]
	v_mfma_f32_16x16x32_bf16 v[98:101], v[178:181], v[194:197], v[98:101]
	v_mfma_f32_16x16x32_bf16 v[86:89], v[162:165], v[202:205], v[86:89]
	v_mfma_f32_16x16x32_bf16 v[66:69], v[178:181], v[210:213], v[66:69]
	v_mfma_f32_16x16x32_bf16 v[102:105], v[162:165], v[194:197], v[102:105]
	v_mfma_f32_16x16x32_bf16 v[114:117], v[178:181], v[186:189], v[114:117]
	v_mfma_f32_16x16x32_bf16 v[70:73], v[162:165], v[210:213], v[70:73]
	v_mfma_f32_16x16x32_bf16 v[82:85], v[178:181], v[202:205], v[82:85]
	v_mfma_f32_16x16x32_bf16 v[118:121], v[166:169], v[190:193], v[118:121]
	v_mfma_f32_16x16x32_bf16 v[98:101], v[182:185], v[198:201], v[98:101]
	v_mfma_f32_16x16x32_bf16 v[86:89], v[166:169], v[206:209], v[86:89]
	v_mfma_f32_16x16x32_bf16 v[66:69], v[182:185], v[218:221], v[66:69]
	v_mfma_f32_16x16x32_bf16 v[102:105], v[166:169], v[198:201], v[102:105]
	v_mfma_f32_16x16x32_bf16 v[114:117], v[182:185], v[190:193], v[114:117]
	v_mfma_f32_16x16x32_bf16 v[70:73], v[166:169], v[218:221], v[70:73]
	v_mfma_f32_16x16x32_bf16 v[82:85], v[182:185], v[206:209], v[82:85]
	s_setprio 0
	s_barrier
	s_add_i32 s62, s66, s31
	v_lshl_add_u64 v[170:171], v[170:171], 0, s[24:25]
	s_mov_b32 m0, s62
	ds_read_b128 v[186:189], v176 offset:49152
	ds_read_b128 v[190:193], v176 offset:50176
	ds_read_b128 v[194:197], v176 offset:51200
	ds_read_b128 v[198:201], v176 offset:52224
	ds_read_b128 v[202:205], v176 offset:53248
	ds_read_b128 v[206:209], v176 offset:54272
	ds_read_b128 v[210:213], v176 offset:55296
	ds_read_b128 v[218:221], v176 offset:56320
	global_load_lds_dwordx4 v[170:171], off
	s_add_i32 m0, s62, 0x2000
	s_add_u32 s34, s34, 0x80080
	v_lshl_add_u64 v[170:171], v[214:215], 0, s[24:25]
	s_addc_u32 s35, s35, 0
	s_add_i32 s62, s67, s31
	global_load_lds_dwordx4 v[170:171], off
	v_lshl_add_u64 v[170:171], s[34:35], 0, v[144:145]
	s_mov_b32 m0, s62
	s_nop 0
	global_load_lds_dwordx4 v[170:171], off
	v_lshl_add_u64 v[170:171], s[34:35], 0, v[148:149]
	s_add_i32 m0, s62, 0x2000
	s_nop 0
	global_load_lds_dwordx4 v[170:171], off
	v_lshl_add_u64 v[170:171], v[222:223], 0, s[24:25]
	s_mov_b32 m0, s55
	s_nop 0
	global_load_lds_dwordx4 v[170:171], off
	v_lshl_add_u64 v[170:171], v[224:225], 0, s[24:25]
	s_mov_b32 m0, s56
	s_nop 0
	global_load_lds_dwordx4 v[170:171], off
	s_waitcnt vmcnt(8)
	s_waitcnt lgkmcnt(0)
	s_barrier
	s_setprio 1
	s_waitcnt lgkmcnt(0)
	v_mfma_f32_16x16x32_bf16 v[62:65], v[130:133], v[186:189], v[62:65]
	v_mfma_f32_16x16x32_bf16 v[42:45], v[138:141], v[194:197], v[42:45]
	v_mfma_f32_16x16x32_bf16 v[38:41], v[130:133], v[202:205], v[38:41]
	v_mfma_f32_16x16x32_bf16 v[10:13], v[138:141], v[210:213], v[10:13]
	v_mfma_f32_16x16x32_bf16 v[50:53], v[130:133], v[194:197], v[50:53]
	v_mfma_f32_16x16x32_bf16 v[58:61], v[138:141], v[186:189], v[58:61]
	v_mfma_f32_16x16x32_bf16 v[14:17], v[130:133], v[210:213], v[14:17]
	v_mfma_f32_16x16x32_bf16 v[34:37], v[138:141], v[202:205], v[34:37]
	v_mfma_f32_16x16x32_bf16 v[62:65], v[134:137], v[190:193], v[62:65]
	v_mfma_f32_16x16x32_bf16 v[42:45], v[158:161], v[198:201], v[42:45]
	v_mfma_f32_16x16x32_bf16 v[38:41], v[134:137], v[206:209], v[38:41]
	v_mfma_f32_16x16x32_bf16 v[10:13], v[158:161], v[218:221], v[10:13]
	v_mfma_f32_16x16x32_bf16 v[50:53], v[134:137], v[198:201], v[50:53]
	v_mfma_f32_16x16x32_bf16 v[58:61], v[158:161], v[190:193], v[58:61]
	v_mfma_f32_16x16x32_bf16 v[14:17], v[134:137], v[218:221], v[14:17]
	v_mfma_f32_16x16x32_bf16 v[34:37], v[158:161], v[206:209], v[34:37]
	s_setprio 0
	s_setprio 1
	v_mfma_f32_16x16x32_bf16 v[54:57], v[162:165], v[186:189], v[54:57]
	v_mfma_f32_16x16x32_bf16 v[26:29], v[178:181], v[194:197], v[26:29]
	v_mfma_f32_16x16x32_bf16 v[22:25], v[162:165], v[202:205], v[22:25]
	v_mfma_f32_16x16x32_bf16 v[2:5], v[178:181], v[210:213], v[2:5]
	v_mfma_f32_16x16x32_bf16 v[30:33], v[162:165], v[194:197], v[30:33]
	v_mfma_f32_16x16x32_bf16 v[46:49], v[178:181], v[186:189], v[46:49]
	v_mfma_f32_16x16x32_bf16 v[6:9], v[162:165], v[210:213], v[6:9]
	v_mfma_f32_16x16x32_bf16 v[18:21], v[178:181], v[202:205], v[18:21]
	v_mfma_f32_16x16x32_bf16 v[54:57], v[166:169], v[190:193], v[54:57]
	v_mfma_f32_16x16x32_bf16 v[26:29], v[182:185], v[198:201], v[26:29]
	v_mfma_f32_16x16x32_bf16 v[22:25], v[166:169], v[206:209], v[22:25]
	v_mfma_f32_16x16x32_bf16 v[2:5], v[182:185], v[218:221], v[2:5]
	v_mfma_f32_16x16x32_bf16 v[30:33], v[166:169], v[198:201], v[30:33]
	v_mfma_f32_16x16x32_bf16 v[46:49], v[182:185], v[190:193], v[46:49]
	v_mfma_f32_16x16x32_bf16 v[6:9], v[166:169], v[218:221], v[6:9]
	v_mfma_f32_16x16x32_bf16 v[18:21], v[182:185], v[206:209], v[18:21]
	s_setprio 0
	s_barrier
	s_add_i32 s72, s72, 2
	s_add_u32 s46, s46, 0x100
	s_addc_u32 s47, s47, 0
	s_add_u32 s70, s70, 0x100
	s_addc_u32 s71, s71, 0
	s_cmp_gt_u32 s72, 29
	s_cbranch_scc0 .LBB0_2938
	s_and_b64 vcc, exec, s[26:27]
	s_cbranch_vccz .LBB0_2941
	s_barrier

.LBB0_3067:
	ds_read_b128 v[146:149], v153
	ds_read_b128 v[156:159], v153 offset:1024
	ds_read_b128 v[160:163], v153 offset:2048
	ds_read_b128 v[164:167], v153 offset:3072
	ds_read_b128 v[168:171], v154
	ds_read_b128 v[172:175], v154 offset:1024
	ds_read_b128 v[176:179], v154 offset:2048
	ds_read_b128 v[180:183], v154 offset:3072
	s_add_u32 s34, s44, 0xfff80080
	s_addc_u32 s35, s45, -1
	s_cmp_eq_u32 s71, 28
	s_cselect_b32 s47, s0, s35
	s_cselect_b32 s46, s1, s34
	s_cselect_b32 s35, s27, s70
	s_cselect_b32 s34, s37, s69
	v_lshl_add_u64 v[218:219], s[44:45], 0, v[138:139]
	s_add_i32 m0, s43, 0xc000
	ds_read_b128 v[184:187], v155
	ds_read_b128 v[188:191], v155 offset:1024
	ds_read_b128 v[192:195], v155 offset:2048
	ds_read_b128 v[196:199], v155 offset:3072
	ds_read_b128 v[200:203], v155 offset:4096
	ds_read_b128 v[204:207], v155 offset:5120
	ds_read_b128 v[208:211], v155 offset:6144
	ds_read_b128 v[212:215], v155 offset:7168
	global_load_lds_dwordx4 v[218:219], off
	v_lshl_add_u64 v[218:219], s[44:45], 0, v[140:141]
	s_add_i32 m0, s43, 0xe000
	s_nop 0
	global_load_lds_dwordx4 v[218:219], off
	s_waitcnt vmcnt(8)
	s_waitcnt lgkmcnt(0)
	s_barrier
	s_setprio 1
	s_waitcnt lgkmcnt(0)
	v_mfma_f32_16x16x32_bf16 v[126:129], v[146:149], v[184:187], v[126:129]
	v_mfma_f32_16x16x32_bf16 v[102:105], v[160:163], v[192:195], v[102:105]
	v_mfma_f32_16x16x32_bf16 v[94:97], v[146:149], v[200:203], v[94:97]
	v_mfma_f32_16x16x32_bf16 v[70:73], v[160:163], v[208:211], v[70:73]
	v_mfma_f32_16x16x32_bf16 v[110:113], v[146:149], v[192:195], v[110:113]
	v_mfma_f32_16x16x32_bf16 v[118:121], v[160:163], v[184:187], v[118:121]
	v_mfma_f32_16x16x32_bf16 v[78:81], v[146:149], v[208:211], v[78:81]
	v_mfma_f32_16x16x32_bf16 v[86:89], v[160:163], v[200:203], v[86:89]
	v_mfma_f32_16x16x32_bf16 v[126:129], v[156:159], v[188:191], v[126:129]
	v_mfma_f32_16x16x32_bf16 v[102:105], v[164:167], v[196:199], v[102:105]
	v_mfma_f32_16x16x32_bf16 v[94:97], v[156:159], v[204:207], v[94:97]
	v_mfma_f32_16x16x32_bf16 v[70:73], v[164:167], v[212:215], v[70:73]
	v_mfma_f32_16x16x32_bf16 v[110:113], v[156:159], v[196:199], v[110:113]
	v_mfma_f32_16x16x32_bf16 v[118:121], v[164:167], v[188:191], v[118:121]
	v_mfma_f32_16x16x32_bf16 v[78:81], v[156:159], v[212:215], v[78:81]
	v_mfma_f32_16x16x32_bf16 v[86:89], v[164:167], v[204:207], v[86:89]
	s_setprio 0
	s_setprio 1
	v_mfma_f32_16x16x32_bf16 v[122:125], v[168:171], v[184:187], v[122:125]
	v_mfma_f32_16x16x32_bf16 v[98:101], v[176:179], v[192:195], v[98:101]
	v_mfma_f32_16x16x32_bf16 v[90:93], v[168:171], v[200:203], v[90:93]
	v_mfma_f32_16x16x32_bf16 v[66:69], v[176:179], v[208:211], v[66:69]
	v_mfma_f32_16x16x32_bf16 v[106:109], v[168:171], v[192:195], v[106:109]
	v_mfma_f32_16x16x32_bf16 v[114:117], v[176:179], v[184:187], v[114:117]
	v_mfma_f32_16x16x32_bf16 v[74:77], v[168:171], v[208:211], v[74:77]
	v_mfma_f32_16x16x32_bf16 v[82:85], v[176:179], v[200:203], v[82:85]
	v_mfma_f32_16x16x32_bf16 v[122:125], v[172:175], v[188:191], v[122:125]
	v_mfma_f32_16x16x32_bf16 v[98:101], v[180:183], v[196:199], v[98:101]
	v_mfma_f32_16x16x32_bf16 v[90:93], v[172:175], v[204:207], v[90:93]
	v_mfma_f32_16x16x32_bf16 v[66:69], v[180:183], v[212:215], v[66:69]
	v_mfma_f32_16x16x32_bf16 v[106:109], v[172:175], v[196:199], v[106:109]
	v_mfma_f32_16x16x32_bf16 v[114:117], v[180:183], v[188:191], v[114:117]
	v_mfma_f32_16x16x32_bf16 v[74:77], v[172:175], v[212:215], v[74:77]
	v_mfma_f32_16x16x32_bf16 v[82:85], v[180:183], v[204:207], v[82:85]
	s_setprio 0
	s_barrier
	s_add_i32 s62, s59, s30
	v_lshl_add_u64 v[218:219], s[34:35], 0, v[134:135]
	s_mov_b32 m0, s62
	ds_read_b128 v[184:187], v155 offset:16384
	ds_read_b128 v[188:191], v155 offset:17408
	ds_read_b128 v[192:195], v155 offset:18432
	ds_read_b128 v[196:199], v155 offset:19456
	ds_read_b128 v[200:203], v155 offset:20480
	ds_read_b128 v[204:207], v155 offset:21504
	ds_read_b128 v[208:211], v155 offset:22528
	ds_read_b128 v[212:215], v155 offset:23552
	global_load_lds_dwordx4 v[218:219], off
	s_add_i32 m0, s62, 0x2000
	s_add_u32 s62, s34, 0x80000
	v_lshl_add_u64 v[220:221], s[34:35], 0, v[130:131]
	s_addc_u32 s63, s35, 0
	s_add_i32 s66, s60, s30
	global_load_lds_dwordx4 v[220:221], off
	v_lshl_add_u64 v[222:223], s[62:63], 0, v[134:135]
	s_mov_b32 m0, s66
	v_lshl_add_u64 v[224:225], s[46:47], 0, v[132:133]
	global_load_lds_dwordx4 v[222:223], off
	v_lshl_add_u64 v[222:223], s[62:63], 0, v[130:131]
	s_add_i32 m0, s66, 0x2000
	s_nop 0
	global_load_lds_dwordx4 v[222:223], off
	v_lshl_add_u64 v[222:223], s[46:47], 0, v[136:137]
	s_mov_b32 m0, s43
	s_nop 0
	global_load_lds_dwordx4 v[222:223], off
	s_mov_b32 m0, s52
	s_nop 0
	global_load_lds_dwordx4 v[224:225], off
	s_waitcnt vmcnt(8)
	s_waitcnt lgkmcnt(0)
	s_barrier
	s_setprio 1
	s_waitcnt lgkmcnt(0)
	v_mfma_f32_16x16x32_bf16 v[62:65], v[146:149], v[184:187], v[62:65]
	v_mfma_f32_16x16x32_bf16 v[38:41], v[160:163], v[192:195], v[38:41]
	v_mfma_f32_16x16x32_bf16 v[30:33], v[146:149], v[200:203], v[30:33]
	v_mfma_f32_16x16x32_bf16 v[6:9], v[160:163], v[208:211], v[6:9]
	v_mfma_f32_16x16x32_bf16 v[46:49], v[146:149], v[192:195], v[46:49]
	v_mfma_f32_16x16x32_bf16 v[54:57], v[160:163], v[184:187], v[54:57]
	v_mfma_f32_16x16x32_bf16 v[14:17], v[146:149], v[208:211], v[14:17]
	v_mfma_f32_16x16x32_bf16 v[22:25], v[160:163], v[200:203], v[22:25]
	v_mfma_f32_16x16x32_bf16 v[62:65], v[156:159], v[188:191], v[62:65]
	v_mfma_f32_16x16x32_bf16 v[38:41], v[164:167], v[196:199], v[38:41]
	v_mfma_f32_16x16x32_bf16 v[30:33], v[156:159], v[204:207], v[30:33]
	v_mfma_f32_16x16x32_bf16 v[6:9], v[164:167], v[212:215], v[6:9]
	v_mfma_f32_16x16x32_bf16 v[46:49], v[156:159], v[196:199], v[46:49]
	v_mfma_f32_16x16x32_bf16 v[54:57], v[164:167], v[188:191], v[54:57]
	v_mfma_f32_16x16x32_bf16 v[14:17], v[156:159], v[212:215], v[14:17]
	v_mfma_f32_16x16x32_bf16 v[22:25], v[164:167], v[204:207], v[22:25]
	s_setprio 0
	s_setprio 1
	v_mfma_f32_16x16x32_bf16 v[58:61], v[168:171], v[184:187], v[58:61]
	v_mfma_f32_16x16x32_bf16 v[34:37], v[176:179], v[192:195], v[34:37]
	v_mfma_f32_16x16x32_bf16 v[26:29], v[168:171], v[200:203], v[26:29]
	v_mfma_f32_16x16x32_bf16 v[2:5], v[176:179], v[208:211], v[2:5]
	v_mfma_f32_16x16x32_bf16 v[42:45], v[168:171], v[192:195], v[42:45]
	v_mfma_f32_16x16x32_bf16 v[50:53], v[176:179], v[184:187], v[50:53]
	v_mfma_f32_16x16x32_bf16 v[10:13], v[168:171], v[208:211], v[10:13]
	v_mfma_f32_16x16x32_bf16 v[18:21], v[176:179], v[200:203], v[18:21]
	v_mfma_f32_16x16x32_bf16 v[58:61], v[172:175], v[188:191], v[58:61]
	v_mfma_f32_16x16x32_bf16 v[34:37], v[180:183], v[196:199], v[34:37]
	v_mfma_f32_16x16x32_bf16 v[26:29], v[172:175], v[204:207], v[26:29]
	v_mfma_f32_16x16x32_bf16 v[2:5], v[180:183], v[212:215], v[2:5]
	v_mfma_f32_16x16x32_bf16 v[42:45], v[172:175], v[196:199], v[42:45]
	v_mfma_f32_16x16x32_bf16 v[50:53], v[180:183], v[188:191], v[50:53]
	v_mfma_f32_16x16x32_bf16 v[10:13], v[172:175], v[212:215], v[10:13]
	v_mfma_f32_16x16x32_bf16 v[18:21], v[180:183], v[204:207], v[18:21]
	s_setprio 0
	s_barrier
	s_add_i32 s62, 0, 0x18000
	s_add_i32 s63, 0, 0x1c000
	v_add_u32_e32 v164, s62, v151
	v_add_u32_e32 v180, s63, v151
	ds_read_b128 v[146:149], v164
	ds_read_b128 v[156:159], v164 offset:1024
	ds_read_b128 v[160:163], v164 offset:2048
	ds_read_b128 v[164:167], v164 offset:3072
	ds_read_b128 v[168:171], v180
	ds_read_b128 v[172:175], v180 offset:1024
	ds_read_b128 v[176:179], v180 offset:2048
	ds_read_b128 v[180:183], v180 offset:3072
	s_add_u32 s46, s46, 0x80000
	s_addc_u32 s47, s47, 0
	s_mov_b32 m0, s53
	v_lshl_add_u64 v[226:227], s[46:47], 0, v[136:137]
	ds_read_b128 v[184:187], v155 offset:32768
	ds_read_b128 v[188:191], v155 offset:33792
	ds_read_b128 v[192:195], v155 offset:34816
	ds_read_b128 v[196:199], v155 offset:35840
	ds_read_b128 v[200:203], v155 offset:36864
	ds_read_b128 v[204:207], v155 offset:37888
	ds_read_b128 v[208:211], v155 offset:38912
	ds_read_b128 v[212:215], v155 offset:39936
	global_load_lds_dwordx4 v[226:227], off
	v_lshl_add_u64 v[226:227], s[46:47], 0, v[132:133]
	s_mov_b32 m0, s54
	s_nop 0
	global_load_lds_dwordx4 v[226:227], off
	s_waitcnt vmcnt(8)
	s_waitcnt lgkmcnt(0)
	s_barrier
	s_setprio 1
	s_waitcnt lgkmcnt(0)
	v_mfma_f32_16x16x32_bf16 v[126:129], v[146:149], v[184:187], v[126:129]
	v_mfma_f32_16x16x32_bf16 v[102:105], v[160:163], v[192:195], v[102:105]
	v_mfma_f32_16x16x32_bf16 v[94:97], v[146:149], v[200:203], v[94:97]
	v_mfma_f32_16x16x32_bf16 v[70:73], v[160:163], v[208:211], v[70:73]
	v_mfma_f32_16x16x32_bf16 v[110:113], v[146:149], v[192:195], v[110:113]
	v_mfma_f32_16x16x32_bf16 v[118:121], v[160:163], v[184:187], v[118:121]
	v_mfma_f32_16x16x32_bf16 v[78:81], v[146:149], v[208:211], v[78:81]
	v_mfma_f32_16x16x32_bf16 v[86:89], v[160:163], v[200:203], v[86:89]
	v_mfma_f32_16x16x32_bf16 v[126:129], v[156:159], v[188:191], v[126:129]
	v_mfma_f32_16x16x32_bf16 v[102:105], v[164:167], v[196:199], v[102:105]
	v_mfma_f32_16x16x32_bf16 v[94:97], v[156:159], v[204:207], v[94:97]
	v_mfma_f32_16x16x32_bf16 v[70:73], v[164:167], v[212:215], v[70:73]
	v_mfma_f32_16x16x32_bf16 v[110:113], v[156:159], v[196:199], v[110:113]
	v_mfma_f32_16x16x32_bf16 v[118:121], v[164:167], v[188:191], v[118:121]
	v_mfma_f32_16x16x32_bf16 v[78:81], v[156:159], v[212:215], v[78:81]
	v_mfma_f32_16x16x32_bf16 v[86:89], v[164:167], v[204:207], v[86:89]
	s_setprio 0
	s_setprio 1
	v_mfma_f32_16x16x32_bf16 v[122:125], v[168:171], v[184:187], v[122:125]
	v_mfma_f32_16x16x32_bf16 v[98:101], v[176:179], v[192:195], v[98:101]
	v_mfma_f32_16x16x32_bf16 v[90:93], v[168:171], v[200:203], v[90:93]
	v_mfma_f32_16x16x32_bf16 v[66:69], v[176:179], v[208:211], v[66:69]
	v_mfma_f32_16x16x32_bf16 v[106:109], v[168:171], v[192:195], v[106:109]
	v_mfma_f32_16x16x32_bf16 v[114:117], v[176:179], v[184:187], v[114:117]
	v_mfma_f32_16x16x32_bf16 v[74:77], v[168:171], v[208:211], v[74:77]
	v_mfma_f32_16x16x32_bf16 v[82:85], v[176:179], v[200:203], v[82:85]
	v_mfma_f32_16x16x32_bf16 v[122:125], v[172:175], v[188:191], v[122:125]
	v_mfma_f32_16x16x32_bf16 v[98:101], v[180:183], v[196:199], v[98:101]
	v_mfma_f32_16x16x32_bf16 v[90:93], v[172:175], v[204:207], v[90:93]
	v_mfma_f32_16x16x32_bf16 v[66:69], v[180:183], v[212:215], v[66:69]
	v_mfma_f32_16x16x32_bf16 v[106:109], v[172:175], v[196:199], v[106:109]
	v_mfma_f32_16x16x32_bf16 v[114:117], v[180:183], v[188:191], v[114:117]
	v_mfma_f32_16x16x32_bf16 v[74:77], v[172:175], v[212:215], v[74:77]
	v_mfma_f32_16x16x32_bf16 v[82:85], v[180:183], v[204:207], v[82:85]
	s_setprio 0
	s_barrier
	s_add_i32 s46, s62, s30
	v_lshl_add_u64 v[218:219], v[218:219], 0, s[8:9]
	s_mov_b32 m0, s46
	ds_read_b128 v[184:187], v155 offset:49152
	ds_read_b128 v[188:191], v155 offset:50176
	ds_read_b128 v[192:195], v155 offset:51200
	ds_read_b128 v[196:199], v155 offset:52224
	ds_read_b128 v[200:203], v155 offset:53248
	ds_read_b128 v[204:207], v155 offset:54272
	ds_read_b128 v[208:211], v155 offset:55296
	ds_read_b128 v[212:215], v155 offset:56320
	global_load_lds_dwordx4 v[218:219], off
	s_add_i32 m0, s46, 0x2000
	s_add_u32 s34, s34, 0x80080
	v_lshl_add_u64 v[218:219], v[220:221], 0, s[8:9]
	s_addc_u32 s35, s35, 0
	s_add_i32 s46, s63, s30
	global_load_lds_dwordx4 v[218:219], off
	v_lshl_add_u64 v[218:219], s[34:35], 0, v[134:135]
	s_mov_b32 m0, s46
	s_nop 0
	global_load_lds_dwordx4 v[218:219], off
	v_lshl_add_u64 v[218:219], s[34:35], 0, v[130:131]
	s_add_i32 m0, s46, 0x2000
	s_nop 0
	global_load_lds_dwordx4 v[218:219], off
	v_lshl_add_u64 v[218:219], v[222:223], 0, s[8:9]
	s_mov_b32 m0, s56
	s_nop 0
	global_load_lds_dwordx4 v[218:219], off
	v_lshl_add_u64 v[218:219], v[224:225], 0, s[8:9]
	s_mov_b32 m0, s57
	s_nop 0
	global_load_lds_dwordx4 v[218:219], off
	s_waitcnt vmcnt(8)
	s_waitcnt lgkmcnt(0)
	s_barrier
	s_setprio 1
	s_waitcnt lgkmcnt(0)
	v_mfma_f32_16x16x32_bf16 v[62:65], v[146:149], v[184:187], v[62:65]
	v_mfma_f32_16x16x32_bf16 v[38:41], v[160:163], v[192:195], v[38:41]
	v_mfma_f32_16x16x32_bf16 v[30:33], v[146:149], v[200:203], v[30:33]
	v_mfma_f32_16x16x32_bf16 v[6:9], v[160:163], v[208:211], v[6:9]
	v_mfma_f32_16x16x32_bf16 v[46:49], v[146:149], v[192:195], v[46:49]
	v_mfma_f32_16x16x32_bf16 v[54:57], v[160:163], v[184:187], v[54:57]
	v_mfma_f32_16x16x32_bf16 v[14:17], v[146:149], v[208:211], v[14:17]
	v_mfma_f32_16x16x32_bf16 v[22:25], v[160:163], v[200:203], v[22:25]
	v_mfma_f32_16x16x32_bf16 v[62:65], v[156:159], v[188:191], v[62:65]
	v_mfma_f32_16x16x32_bf16 v[38:41], v[164:167], v[196:199], v[38:41]
	v_mfma_f32_16x16x32_bf16 v[30:33], v[156:159], v[204:207], v[30:33]
	v_mfma_f32_16x16x32_bf16 v[6:9], v[164:167], v[212:215], v[6:9]
	v_mfma_f32_16x16x32_bf16 v[46:49], v[156:159], v[196:199], v[46:49]
	v_mfma_f32_16x16x32_bf16 v[54:57], v[164:167], v[188:191], v[54:57]
	v_mfma_f32_16x16x32_bf16 v[14:17], v[156:159], v[212:215], v[14:17]
	v_mfma_f32_16x16x32_bf16 v[22:25], v[164:167], v[204:207], v[22:25]
	s_setprio 0
	s_setprio 1
	v_mfma_f32_16x16x32_bf16 v[58:61], v[168:171], v[184:187], v[58:61]
	v_mfma_f32_16x16x32_bf16 v[34:37], v[176:179], v[192:195], v[34:37]
	v_mfma_f32_16x16x32_bf16 v[26:29], v[168:171], v[200:203], v[26:29]
	v_mfma_f32_16x16x32_bf16 v[2:5], v[176:179], v[208:211], v[2:5]
	v_mfma_f32_16x16x32_bf16 v[42:45], v[168:171], v[192:195], v[42:45]
	v_mfma_f32_16x16x32_bf16 v[50:53], v[176:179], v[184:187], v[50:53]
	v_mfma_f32_16x16x32_bf16 v[10:13], v[168:171], v[208:211], v[10:13]
	v_mfma_f32_16x16x32_bf16 v[18:21], v[176:179], v[200:203], v[18:21]
	v_mfma_f32_16x16x32_bf16 v[58:61], v[172:175], v[188:191], v[58:61]
	v_mfma_f32_16x16x32_bf16 v[34:37], v[180:183], v[196:199], v[34:37]
	v_mfma_f32_16x16x32_bf16 v[26:29], v[172:175], v[204:207], v[26:29]
	v_mfma_f32_16x16x32_bf16 v[2:5], v[180:183], v[212:215], v[2:5]
	v_mfma_f32_16x16x32_bf16 v[42:45], v[172:175], v[196:199], v[42:45]
	v_mfma_f32_16x16x32_bf16 v[50:53], v[180:183], v[188:191], v[50:53]
	v_mfma_f32_16x16x32_bf16 v[10:13], v[172:175], v[212:215], v[10:13]
	v_mfma_f32_16x16x32_bf16 v[18:21], v[180:183], v[204:207], v[18:21]
	s_setprio 0
	s_barrier
	s_add_i32 s71, s71, 2
	s_add_u32 s44, s44, 0x100
	s_addc_u32 s45, s45, 0
	s_add_u32 s69, s69, 0x100
	s_addc_u32 s70, s70, 0
	s_cmp_gt_u32 s71, 29
	s_cbranch_scc0 .LBB0_3067
	v_mov_b32_e32 v160, 0xbfb8aa3b
	s_and_b64 vcc, exec, s[24:25]
	s_cbranch_vccz .LBB0_3070
	s_barrier

.LBB0_3180:
	ds_read_b128 v[130:133], v174
	ds_read_b128 v[134:137], v174 offset:1024
	ds_read_b128 v[138:141], v174 offset:2048
	ds_read_b128 v[158:161], v174 offset:3072
	ds_read_b128 v[162:165], v175
	ds_read_b128 v[166:169], v175 offset:1024
	ds_read_b128 v[178:181], v175 offset:2048
	ds_read_b128 v[182:185], v175 offset:3072
	s_add_u32 s34, s40, 0xffea0080
	s_addc_u32 s35, s41, -1
	s_cmpk_eq_i32 s60, 0x54
	s_cselect_b32 s43, s5, s35
	s_cselect_b32 s42, s4, s34
	s_cselect_b32 s35, s39, s1
	s_cselect_b32 s34, s38, s0
	v_lshl_add_u64 v[170:171], s[40:41], 0, v[150:151]
	s_add_i32 m0, s33, 0xc000
	ds_read_b128 v[186:189], v176
	ds_read_b128 v[190:193], v176 offset:1024
	ds_read_b128 v[194:197], v176 offset:2048
	ds_read_b128 v[198:201], v176 offset:3072
	ds_read_b128 v[202:205], v176 offset:4096
	ds_read_b128 v[206:209], v176 offset:5120
	ds_read_b128 v[210:213], v176 offset:6144
	ds_read_b128 v[218:221], v176 offset:7168
	global_load_lds_dwordx4 v[170:171], off
	v_lshl_add_u64 v[170:171], s[40:41], 0, v[152:153]
	s_add_i32 m0, s33, 0xe000
	s_nop 0
	global_load_lds_dwordx4 v[170:171], off
	s_waitcnt vmcnt(8)
	s_waitcnt lgkmcnt(0)
	s_barrier
	s_setprio 1
	s_waitcnt lgkmcnt(0)
	v_mfma_f32_16x16x32_bf16 v[126:129], v[130:133], v[186:189], v[126:129]
	v_mfma_f32_16x16x32_bf16 v[106:109], v[138:141], v[194:197], v[106:109]
	v_mfma_f32_16x16x32_bf16 v[94:97], v[130:133], v[202:205], v[94:97]
	v_mfma_f32_16x16x32_bf16 v[74:77], v[138:141], v[210:213], v[74:77]
	v_mfma_f32_16x16x32_bf16 v[110:113], v[130:133], v[194:197], v[110:113]
	v_mfma_f32_16x16x32_bf16 v[122:125], v[138:141], v[186:189], v[122:125]
	v_mfma_f32_16x16x32_bf16 v[78:81], v[130:133], v[210:213], v[78:81]
	v_mfma_f32_16x16x32_bf16 v[90:93], v[138:141], v[202:205], v[90:93]
	v_mfma_f32_16x16x32_bf16 v[126:129], v[134:137], v[190:193], v[126:129]
	v_mfma_f32_16x16x32_bf16 v[106:109], v[158:161], v[198:201], v[106:109]
	v_mfma_f32_16x16x32_bf16 v[94:97], v[134:137], v[206:209], v[94:97]
	v_mfma_f32_16x16x32_bf16 v[74:77], v[158:161], v[218:221], v[74:77]
	v_mfma_f32_16x16x32_bf16 v[110:113], v[134:137], v[198:201], v[110:113]
	v_mfma_f32_16x16x32_bf16 v[122:125], v[158:161], v[190:193], v[122:125]
	v_mfma_f32_16x16x32_bf16 v[78:81], v[134:137], v[218:221], v[78:81]
	v_mfma_f32_16x16x32_bf16 v[90:93], v[158:161], v[206:209], v[90:93]
	s_setprio 0
	s_setprio 1
	v_mfma_f32_16x16x32_bf16 v[118:121], v[162:165], v[186:189], v[118:121]
	v_mfma_f32_16x16x32_bf16 v[98:101], v[178:181], v[194:197], v[98:101]
	v_mfma_f32_16x16x32_bf16 v[86:89], v[162:165], v[202:205], v[86:89]
	v_mfma_f32_16x16x32_bf16 v[66:69], v[178:181], v[210:213], v[66:69]
	v_mfma_f32_16x16x32_bf16 v[102:105], v[162:165], v[194:197], v[102:105]
	v_mfma_f32_16x16x32_bf16 v[114:117], v[178:181], v[186:189], v[114:117]
	v_mfma_f32_16x16x32_bf16 v[70:73], v[162:165], v[210:213], v[70:73]
	v_mfma_f32_16x16x32_bf16 v[82:85], v[178:181], v[202:205], v[82:85]
	v_mfma_f32_16x16x32_bf16 v[118:121], v[166:169], v[190:193], v[118:121]
	v_mfma_f32_16x16x32_bf16 v[98:101], v[182:185], v[198:201], v[98:101]
	v_mfma_f32_16x16x32_bf16 v[86:89], v[166:169], v[206:209], v[86:89]
	v_mfma_f32_16x16x32_bf16 v[66:69], v[182:185], v[218:221], v[66:69]
	v_mfma_f32_16x16x32_bf16 v[102:105], v[166:169], v[198:201], v[102:105]
	v_mfma_f32_16x16x32_bf16 v[114:117], v[182:185], v[190:193], v[114:117]
	v_mfma_f32_16x16x32_bf16 v[70:73], v[166:169], v[218:221], v[70:73]
	v_mfma_f32_16x16x32_bf16 v[82:85], v[182:185], v[206:209], v[82:85]
	s_setprio 0
	s_barrier
	s_add_i32 s61, s53, s31
	v_lshl_add_u64 v[170:171], s[34:35], 0, v[144:145]
	s_mov_b32 m0, s61
	ds_read_b128 v[186:189], v176 offset:16384
	ds_read_b128 v[190:193], v176 offset:17408
	ds_read_b128 v[194:197], v176 offset:18432
	ds_read_b128 v[198:201], v176 offset:19456
	ds_read_b128 v[202:205], v176 offset:20480
	ds_read_b128 v[206:209], v176 offset:21504
	ds_read_b128 v[210:213], v176 offset:22528
	ds_read_b128 v[218:221], v176 offset:23552
	global_load_lds_dwordx4 v[170:171], off
	s_add_i32 m0, s61, 0x2000
	s_add_u32 s62, s34, 0x160000
	v_lshl_add_u64 v[214:215], s[34:35], 0, v[148:149]
	s_addc_u32 s63, s35, 0
	s_add_i32 s61, s54, s31
	global_load_lds_dwordx4 v[214:215], off
	v_lshl_add_u64 v[222:223], s[62:63], 0, v[144:145]
	s_mov_b32 m0, s61
	v_lshl_add_u64 v[224:225], s[42:43], 0, v[146:147]
	global_load_lds_dwordx4 v[222:223], off
	v_lshl_add_u64 v[222:223], s[62:63], 0, v[148:149]
	s_add_i32 m0, s61, 0x2000
	s_nop 0
	global_load_lds_dwordx4 v[222:223], off
	v_lshl_add_u64 v[222:223], s[42:43], 0, v[142:143]
	s_mov_b32 m0, s33
	s_nop 0
	global_load_lds_dwordx4 v[222:223], off
	s_mov_b32 m0, s44
	s_nop 0
	global_load_lds_dwordx4 v[224:225], off
	s_waitcnt vmcnt(8)
	s_waitcnt lgkmcnt(0)
	s_barrier
	s_setprio 1
	s_waitcnt lgkmcnt(0)
	v_mfma_f32_16x16x32_bf16 v[62:65], v[130:133], v[186:189], v[62:65]
	v_mfma_f32_16x16x32_bf16 v[42:45], v[138:141], v[194:197], v[42:45]
	v_mfma_f32_16x16x32_bf16 v[38:41], v[130:133], v[202:205], v[38:41]
	v_mfma_f32_16x16x32_bf16 v[10:13], v[138:141], v[210:213], v[10:13]
	v_mfma_f32_16x16x32_bf16 v[50:53], v[130:133], v[194:197], v[50:53]
	v_mfma_f32_16x16x32_bf16 v[58:61], v[138:141], v[186:189], v[58:61]
	v_mfma_f32_16x16x32_bf16 v[14:17], v[130:133], v[210:213], v[14:17]
	v_mfma_f32_16x16x32_bf16 v[34:37], v[138:141], v[202:205], v[34:37]
	v_mfma_f32_16x16x32_bf16 v[62:65], v[134:137], v[190:193], v[62:65]
	v_mfma_f32_16x16x32_bf16 v[42:45], v[158:161], v[198:201], v[42:45]
	v_mfma_f32_16x16x32_bf16 v[38:41], v[134:137], v[206:209], v[38:41]
	v_mfma_f32_16x16x32_bf16 v[10:13], v[158:161], v[218:221], v[10:13]
	v_mfma_f32_16x16x32_bf16 v[50:53], v[134:137], v[198:201], v[50:53]
	v_mfma_f32_16x16x32_bf16 v[58:61], v[158:161], v[190:193], v[58:61]
	v_mfma_f32_16x16x32_bf16 v[14:17], v[134:137], v[218:221], v[14:17]
	v_mfma_f32_16x16x32_bf16 v[34:37], v[158:161], v[206:209], v[34:37]
	s_setprio 0
	s_setprio 1
	v_mfma_f32_16x16x32_bf16 v[54:57], v[162:165], v[186:189], v[54:57]
	v_mfma_f32_16x16x32_bf16 v[26:29], v[178:181], v[194:197], v[26:29]
	v_mfma_f32_16x16x32_bf16 v[22:25], v[162:165], v[202:205], v[22:25]
	v_mfma_f32_16x16x32_bf16 v[2:5], v[178:181], v[210:213], v[2:5]
	v_mfma_f32_16x16x32_bf16 v[30:33], v[162:165], v[194:197], v[30:33]
	v_mfma_f32_16x16x32_bf16 v[46:49], v[178:181], v[186:189], v[46:49]
	v_mfma_f32_16x16x32_bf16 v[6:9], v[162:165], v[210:213], v[6:9]
	v_mfma_f32_16x16x32_bf16 v[18:21], v[178:181], v[202:205], v[18:21]
	v_mfma_f32_16x16x32_bf16 v[54:57], v[166:169], v[190:193], v[54:57]
	v_mfma_f32_16x16x32_bf16 v[26:29], v[182:185], v[198:201], v[26:29]
	v_mfma_f32_16x16x32_bf16 v[22:25], v[166:169], v[206:209], v[22:25]
	v_mfma_f32_16x16x32_bf16 v[2:5], v[182:185], v[218:221], v[2:5]
	v_mfma_f32_16x16x32_bf16 v[30:33], v[166:169], v[198:201], v[30:33]
	v_mfma_f32_16x16x32_bf16 v[46:49], v[182:185], v[190:193], v[46:49]
	v_mfma_f32_16x16x32_bf16 v[6:9], v[166:169], v[218:221], v[6:9]
	v_mfma_f32_16x16x32_bf16 v[18:21], v[182:185], v[206:209], v[18:21]
	s_setprio 0
	s_barrier
	s_add_i32 s61, 0, 0x18000
	s_add_i32 s62, 0, 0x1c000
	v_add_u32_e32 v158, s61, v172
	v_add_u32_e32 v177, s62, v172
	ds_read_b128 v[130:133], v158
	ds_read_b128 v[134:137], v158 offset:1024
	ds_read_b128 v[138:141], v158 offset:2048
	ds_read_b128 v[158:161], v158 offset:3072
	ds_read_b128 v[162:165], v177
	ds_read_b128 v[166:169], v177 offset:1024
	ds_read_b128 v[178:181], v177 offset:2048
	ds_read_b128 v[182:185], v177 offset:3072
	s_add_u32 s42, s42, 0x160000
	s_addc_u32 s43, s43, 0
	s_mov_b32 m0, s45
	v_lshl_add_u64 v[226:227], s[42:43], 0, v[142:143]
	ds_read_b128 v[186:189], v176 offset:32768
	ds_read_b128 v[190:193], v176 offset:33792
	ds_read_b128 v[194:197], v176 offset:34816
	ds_read_b128 v[198:201], v176 offset:35840
	ds_read_b128 v[202:205], v176 offset:36864
	ds_read_b128 v[206:209], v176 offset:37888
	ds_read_b128 v[210:213], v176 offset:38912
	ds_read_b128 v[218:221], v176 offset:39936
	global_load_lds_dwordx4 v[226:227], off
	v_lshl_add_u64 v[226:227], s[42:43], 0, v[146:147]
	s_mov_b32 m0, s46
	s_nop 0
	global_load_lds_dwordx4 v[226:227], off
	s_waitcnt vmcnt(8)
	s_waitcnt lgkmcnt(0)
	s_barrier
	s_setprio 1
	s_waitcnt lgkmcnt(0)
	v_mfma_f32_16x16x32_bf16 v[126:129], v[130:133], v[186:189], v[126:129]
	v_mfma_f32_16x16x32_bf16 v[106:109], v[138:141], v[194:197], v[106:109]
	v_mfma_f32_16x16x32_bf16 v[94:97], v[130:133], v[202:205], v[94:97]
	v_mfma_f32_16x16x32_bf16 v[74:77], v[138:141], v[210:213], v[74:77]
	v_mfma_f32_16x16x32_bf16 v[110:113], v[130:133], v[194:197], v[110:113]
	v_mfma_f32_16x16x32_bf16 v[122:125], v[138:141], v[186:189], v[122:125]
	v_mfma_f32_16x16x32_bf16 v[78:81], v[130:133], v[210:213], v[78:81]
	v_mfma_f32_16x16x32_bf16 v[90:93], v[138:141], v[202:205], v[90:93]
	v_mfma_f32_16x16x32_bf16 v[126:129], v[134:137], v[190:193], v[126:129]
	v_mfma_f32_16x16x32_bf16 v[106:109], v[158:161], v[198:201], v[106:109]
	v_mfma_f32_16x16x32_bf16 v[94:97], v[134:137], v[206:209], v[94:97]
	v_mfma_f32_16x16x32_bf16 v[74:77], v[158:161], v[218:221], v[74:77]
	v_mfma_f32_16x16x32_bf16 v[110:113], v[134:137], v[198:201], v[110:113]
	v_mfma_f32_16x16x32_bf16 v[122:125], v[158:161], v[190:193], v[122:125]
	v_mfma_f32_16x16x32_bf16 v[78:81], v[134:137], v[218:221], v[78:81]
	v_mfma_f32_16x16x32_bf16 v[90:93], v[158:161], v[206:209], v[90:93]
	s_setprio 0
	s_setprio 1
	v_mfma_f32_16x16x32_bf16 v[118:121], v[162:165], v[186:189], v[118:121]
	v_mfma_f32_16x16x32_bf16 v[98:101], v[178:181], v[194:197], v[98:101]
	v_mfma_f32_16x16x32_bf16 v[86:89], v[162:165], v[202:205], v[86:89]
	v_mfma_f32_16x16x32_bf16 v[66:69], v[178:181], v[210:213], v[66:69]
	v_mfma_f32_16x16x32_bf16 v[102:105], v[162:165], v[194:197], v[102:105]
	v_mfma_f32_16x16x32_bf16 v[114:117], v[178:181], v[186:189], v[114:117]
	v_mfma_f32_16x16x32_bf16 v[70:73], v[162:165], v[210:213], v[70:73]
	v_mfma_f32_16x16x32_bf16 v[82:85], v[178:181], v[202:205], v[82:85]
	v_mfma_f32_16x16x32_bf16 v[118:121], v[166:169], v[190:193], v[118:121]
	v_mfma_f32_16x16x32_bf16 v[98:101], v[182:185], v[198:201], v[98:101]
	v_mfma_f32_16x16x32_bf16 v[86:89], v[166:169], v[206:209], v[86:89]
	v_mfma_f32_16x16x32_bf16 v[66:69], v[182:185], v[218:221], v[66:69]
	v_mfma_f32_16x16x32_bf16 v[102:105], v[166:169], v[198:201], v[102:105]
	v_mfma_f32_16x16x32_bf16 v[114:117], v[182:185], v[190:193], v[114:117]
	v_mfma_f32_16x16x32_bf16 v[70:73], v[166:169], v[218:221], v[70:73]
	v_mfma_f32_16x16x32_bf16 v[82:85], v[182:185], v[206:209], v[82:85]
	s_setprio 0
	s_barrier
	s_add_i32 s42, s61, s31
	v_lshl_add_u64 v[170:171], v[170:171], 0, s[24:25]
	s_mov_b32 m0, s42
	ds_read_b128 v[186:189], v176 offset:49152
	ds_read_b128 v[190:193], v176 offset:50176
	ds_read_b128 v[194:197], v176 offset:51200
	ds_read_b128 v[198:201], v176 offset:52224
	ds_read_b128 v[202:205], v176 offset:53248
	ds_read_b128 v[206:209], v176 offset:54272
	ds_read_b128 v[210:213], v176 offset:55296
	ds_read_b128 v[218:221], v176 offset:56320
	global_load_lds_dwordx4 v[170:171], off
	s_add_i32 m0, s42, 0x2000
	s_add_u32 s34, s34, 0x160080
	v_lshl_add_u64 v[170:171], v[214:215], 0, s[24:25]
	s_addc_u32 s35, s35, 0
	s_add_i32 s42, s62, s31
	global_load_lds_dwordx4 v[170:171], off
	v_lshl_add_u64 v[170:171], s[34:35], 0, v[144:145]
	s_mov_b32 m0, s42
	s_nop 0
	global_load_lds_dwordx4 v[170:171], off
	v_lshl_add_u64 v[170:171], s[34:35], 0, v[148:149]
	s_add_i32 m0, s42, 0x2000
	s_nop 0
	global_load_lds_dwordx4 v[170:171], off
	v_lshl_add_u64 v[170:171], v[222:223], 0, s[24:25]
	s_mov_b32 m0, s48
	s_nop 0
	global_load_lds_dwordx4 v[170:171], off
	v_lshl_add_u64 v[170:171], v[224:225], 0, s[24:25]
	s_mov_b32 m0, s49
	s_nop 0
	global_load_lds_dwordx4 v[170:171], off
	s_waitcnt vmcnt(8)
	s_waitcnt lgkmcnt(0)
	s_barrier
	s_setprio 1
	s_waitcnt lgkmcnt(0)
	v_mfma_f32_16x16x32_bf16 v[62:65], v[130:133], v[186:189], v[62:65]
	v_mfma_f32_16x16x32_bf16 v[42:45], v[138:141], v[194:197], v[42:45]
	v_mfma_f32_16x16x32_bf16 v[38:41], v[130:133], v[202:205], v[38:41]
	v_mfma_f32_16x16x32_bf16 v[10:13], v[138:141], v[210:213], v[10:13]
	v_mfma_f32_16x16x32_bf16 v[50:53], v[130:133], v[194:197], v[50:53]
	v_mfma_f32_16x16x32_bf16 v[58:61], v[138:141], v[186:189], v[58:61]
	v_mfma_f32_16x16x32_bf16 v[14:17], v[130:133], v[210:213], v[14:17]
	v_mfma_f32_16x16x32_bf16 v[34:37], v[138:141], v[202:205], v[34:37]
	v_mfma_f32_16x16x32_bf16 v[62:65], v[134:137], v[190:193], v[62:65]
	v_mfma_f32_16x16x32_bf16 v[42:45], v[158:161], v[198:201], v[42:45]
	v_mfma_f32_16x16x32_bf16 v[38:41], v[134:137], v[206:209], v[38:41]
	v_mfma_f32_16x16x32_bf16 v[10:13], v[158:161], v[218:221], v[10:13]
	v_mfma_f32_16x16x32_bf16 v[50:53], v[134:137], v[198:201], v[50:53]
	v_mfma_f32_16x16x32_bf16 v[58:61], v[158:161], v[190:193], v[58:61]
	v_mfma_f32_16x16x32_bf16 v[14:17], v[134:137], v[218:221], v[14:17]
	v_mfma_f32_16x16x32_bf16 v[34:37], v[158:161], v[206:209], v[34:37]
	s_setprio 0
	s_setprio 1
	v_mfma_f32_16x16x32_bf16 v[54:57], v[162:165], v[186:189], v[54:57]
	v_mfma_f32_16x16x32_bf16 v[26:29], v[178:181], v[194:197], v[26:29]
	v_mfma_f32_16x16x32_bf16 v[22:25], v[162:165], v[202:205], v[22:25]
	v_mfma_f32_16x16x32_bf16 v[2:5], v[178:181], v[210:213], v[2:5]
	v_mfma_f32_16x16x32_bf16 v[30:33], v[162:165], v[194:197], v[30:33]
	v_mfma_f32_16x16x32_bf16 v[46:49], v[178:181], v[186:189], v[46:49]
	v_mfma_f32_16x16x32_bf16 v[6:9], v[162:165], v[210:213], v[6:9]
	v_mfma_f32_16x16x32_bf16 v[18:21], v[178:181], v[202:205], v[18:21]
	v_mfma_f32_16x16x32_bf16 v[54:57], v[166:169], v[190:193], v[54:57]
	v_mfma_f32_16x16x32_bf16 v[26:29], v[182:185], v[198:201], v[26:29]
	v_mfma_f32_16x16x32_bf16 v[22:25], v[166:169], v[206:209], v[22:25]
	v_mfma_f32_16x16x32_bf16 v[2:5], v[182:185], v[218:221], v[2:5]
	v_mfma_f32_16x16x32_bf16 v[30:33], v[166:169], v[198:201], v[30:33]
	v_mfma_f32_16x16x32_bf16 v[46:49], v[182:185], v[190:193], v[46:49]
	v_mfma_f32_16x16x32_bf16 v[6:9], v[166:169], v[218:221], v[6:9]
	v_mfma_f32_16x16x32_bf16 v[18:21], v[182:185], v[206:209], v[18:21]
	s_setprio 0
	s_barrier
	s_add_i32 s60, s60, 2
	s_add_u32 s40, s40, 0x100
	s_addc_u32 s41, s41, 0
	s_add_u32 s0, s0, 0x100
	s_addc_u32 s1, s1, 0
	s_cmpk_gt_u32 s60, 0x55
	s_cbranch_scc0 .LBB0_3180
	s_and_b64 vcc, exec, s[26:27]
	s_cbranch_vccz .LBB0_3183
	s_barrier

.LBB0_3309:
	ds_read_b128 v[146:149], v153
	ds_read_b128 v[156:159], v153 offset:1024
	ds_read_b128 v[160:163], v153 offset:2048
	ds_read_b128 v[164:167], v153 offset:3072
	ds_read_b128 v[168:171], v154
	ds_read_b128 v[172:175], v154 offset:1024
	ds_read_b128 v[176:179], v154 offset:2048
	ds_read_b128 v[180:183], v154 offset:3072
	s_add_u32 s34, s44, 0xfff80080
	s_addc_u32 s35, s45, -1
	s_cmp_eq_u32 s69, 28
	s_cselect_b32 s47, s0, s35
	s_cselect_b32 s46, s1, s34
	s_cselect_b32 s35, s27, s68
	s_cselect_b32 s34, s37, s61
	v_lshl_add_u64 v[218:219], s[44:45], 0, v[138:139]
	s_add_i32 m0, s43, 0xc000
	ds_read_b128 v[184:187], v155
	ds_read_b128 v[188:191], v155 offset:1024
	ds_read_b128 v[192:195], v155 offset:2048
	ds_read_b128 v[196:199], v155 offset:3072
	ds_read_b128 v[200:203], v155 offset:4096
	ds_read_b128 v[204:207], v155 offset:5120
	ds_read_b128 v[208:211], v155 offset:6144
	ds_read_b128 v[212:215], v155 offset:7168
	global_load_lds_dwordx4 v[218:219], off
	v_lshl_add_u64 v[218:219], s[44:45], 0, v[140:141]
	s_add_i32 m0, s43, 0xe000
	s_nop 0
	global_load_lds_dwordx4 v[218:219], off
	s_waitcnt vmcnt(8)
	s_waitcnt lgkmcnt(0)
	s_barrier
	s_setprio 1
	s_waitcnt lgkmcnt(0)
	v_mfma_f32_16x16x32_bf16 v[126:129], v[146:149], v[184:187], v[126:129]
	v_mfma_f32_16x16x32_bf16 v[102:105], v[160:163], v[192:195], v[102:105]
	v_mfma_f32_16x16x32_bf16 v[94:97], v[146:149], v[200:203], v[94:97]
	v_mfma_f32_16x16x32_bf16 v[70:73], v[160:163], v[208:211], v[70:73]
	v_mfma_f32_16x16x32_bf16 v[110:113], v[146:149], v[192:195], v[110:113]
	v_mfma_f32_16x16x32_bf16 v[118:121], v[160:163], v[184:187], v[118:121]
	v_mfma_f32_16x16x32_bf16 v[78:81], v[146:149], v[208:211], v[78:81]
	v_mfma_f32_16x16x32_bf16 v[86:89], v[160:163], v[200:203], v[86:89]
	v_mfma_f32_16x16x32_bf16 v[126:129], v[156:159], v[188:191], v[126:129]
	v_mfma_f32_16x16x32_bf16 v[102:105], v[164:167], v[196:199], v[102:105]
	v_mfma_f32_16x16x32_bf16 v[94:97], v[156:159], v[204:207], v[94:97]
	v_mfma_f32_16x16x32_bf16 v[70:73], v[164:167], v[212:215], v[70:73]
	v_mfma_f32_16x16x32_bf16 v[110:113], v[156:159], v[196:199], v[110:113]
	v_mfma_f32_16x16x32_bf16 v[118:121], v[164:167], v[188:191], v[118:121]
	v_mfma_f32_16x16x32_bf16 v[78:81], v[156:159], v[212:215], v[78:81]
	v_mfma_f32_16x16x32_bf16 v[86:89], v[164:167], v[204:207], v[86:89]
	s_setprio 0
	s_setprio 1
	v_mfma_f32_16x16x32_bf16 v[122:125], v[168:171], v[184:187], v[122:125]
	v_mfma_f32_16x16x32_bf16 v[98:101], v[176:179], v[192:195], v[98:101]
	v_mfma_f32_16x16x32_bf16 v[90:93], v[168:171], v[200:203], v[90:93]
	v_mfma_f32_16x16x32_bf16 v[66:69], v[176:179], v[208:211], v[66:69]
	v_mfma_f32_16x16x32_bf16 v[106:109], v[168:171], v[192:195], v[106:109]
	v_mfma_f32_16x16x32_bf16 v[114:117], v[176:179], v[184:187], v[114:117]
	v_mfma_f32_16x16x32_bf16 v[74:77], v[168:171], v[208:211], v[74:77]
	v_mfma_f32_16x16x32_bf16 v[82:85], v[176:179], v[200:203], v[82:85]
	v_mfma_f32_16x16x32_bf16 v[122:125], v[172:175], v[188:191], v[122:125]
	v_mfma_f32_16x16x32_bf16 v[98:101], v[180:183], v[196:199], v[98:101]
	v_mfma_f32_16x16x32_bf16 v[90:93], v[172:175], v[204:207], v[90:93]
	v_mfma_f32_16x16x32_bf16 v[66:69], v[180:183], v[212:215], v[66:69]
	v_mfma_f32_16x16x32_bf16 v[106:109], v[172:175], v[196:199], v[106:109]
	v_mfma_f32_16x16x32_bf16 v[114:117], v[180:183], v[188:191], v[114:117]
	v_mfma_f32_16x16x32_bf16 v[74:77], v[172:175], v[212:215], v[74:77]
	v_mfma_f32_16x16x32_bf16 v[82:85], v[180:183], v[204:207], v[82:85]
	s_setprio 0
	s_barrier
	s_add_i32 s62, s57, s30
	v_lshl_add_u64 v[218:219], s[34:35], 0, v[134:135]
	s_mov_b32 m0, s62
	ds_read_b128 v[184:187], v155 offset:16384
	ds_read_b128 v[188:191], v155 offset:17408
	ds_read_b128 v[192:195], v155 offset:18432
	ds_read_b128 v[196:199], v155 offset:19456
	ds_read_b128 v[200:203], v155 offset:20480
	ds_read_b128 v[204:207], v155 offset:21504
	ds_read_b128 v[208:211], v155 offset:22528
	ds_read_b128 v[212:215], v155 offset:23552
	global_load_lds_dwordx4 v[218:219], off
	s_add_i32 m0, s62, 0x2000
	s_add_u32 s62, s34, 0x80000
	v_lshl_add_u64 v[220:221], s[34:35], 0, v[130:131]
	s_addc_u32 s63, s35, 0
	s_add_i32 s66, s58, s30
	global_load_lds_dwordx4 v[220:221], off
	v_lshl_add_u64 v[222:223], s[62:63], 0, v[134:135]
	s_mov_b32 m0, s66
	v_lshl_add_u64 v[224:225], s[46:47], 0, v[132:133]
	global_load_lds_dwordx4 v[222:223], off
	v_lshl_add_u64 v[222:223], s[62:63], 0, v[130:131]
	s_add_i32 m0, s66, 0x2000
	s_nop 0
	global_load_lds_dwordx4 v[222:223], off
	v_lshl_add_u64 v[222:223], s[46:47], 0, v[136:137]
	s_mov_b32 m0, s43
	s_nop 0
	global_load_lds_dwordx4 v[222:223], off
	s_mov_b32 m0, s48
	s_nop 0
	global_load_lds_dwordx4 v[224:225], off
	s_waitcnt vmcnt(8)
	s_waitcnt lgkmcnt(0)
	s_barrier
	s_setprio 1
	s_waitcnt lgkmcnt(0)
	v_mfma_f32_16x16x32_bf16 v[62:65], v[146:149], v[184:187], v[62:65]
	v_mfma_f32_16x16x32_bf16 v[38:41], v[160:163], v[192:195], v[38:41]
	v_mfma_f32_16x16x32_bf16 v[30:33], v[146:149], v[200:203], v[30:33]
	v_mfma_f32_16x16x32_bf16 v[6:9], v[160:163], v[208:211], v[6:9]
	v_mfma_f32_16x16x32_bf16 v[46:49], v[146:149], v[192:195], v[46:49]
	v_mfma_f32_16x16x32_bf16 v[54:57], v[160:163], v[184:187], v[54:57]
	v_mfma_f32_16x16x32_bf16 v[14:17], v[146:149], v[208:211], v[14:17]
	v_mfma_f32_16x16x32_bf16 v[22:25], v[160:163], v[200:203], v[22:25]
	v_mfma_f32_16x16x32_bf16 v[62:65], v[156:159], v[188:191], v[62:65]
	v_mfma_f32_16x16x32_bf16 v[38:41], v[164:167], v[196:199], v[38:41]
	v_mfma_f32_16x16x32_bf16 v[30:33], v[156:159], v[204:207], v[30:33]
	v_mfma_f32_16x16x32_bf16 v[6:9], v[164:167], v[212:215], v[6:9]
	v_mfma_f32_16x16x32_bf16 v[46:49], v[156:159], v[196:199], v[46:49]
	v_mfma_f32_16x16x32_bf16 v[54:57], v[164:167], v[188:191], v[54:57]
	v_mfma_f32_16x16x32_bf16 v[14:17], v[156:159], v[212:215], v[14:17]
	v_mfma_f32_16x16x32_bf16 v[22:25], v[164:167], v[204:207], v[22:25]
	s_setprio 0
	s_setprio 1
	v_mfma_f32_16x16x32_bf16 v[58:61], v[168:171], v[184:187], v[58:61]
	v_mfma_f32_16x16x32_bf16 v[34:37], v[176:179], v[192:195], v[34:37]
	v_mfma_f32_16x16x32_bf16 v[26:29], v[168:171], v[200:203], v[26:29]
	v_mfma_f32_16x16x32_bf16 v[2:5], v[176:179], v[208:211], v[2:5]
	v_mfma_f32_16x16x32_bf16 v[42:45], v[168:171], v[192:195], v[42:45]
	v_mfma_f32_16x16x32_bf16 v[50:53], v[176:179], v[184:187], v[50:53]
	v_mfma_f32_16x16x32_bf16 v[10:13], v[168:171], v[208:211], v[10:13]
	v_mfma_f32_16x16x32_bf16 v[18:21], v[176:179], v[200:203], v[18:21]
	v_mfma_f32_16x16x32_bf16 v[58:61], v[172:175], v[188:191], v[58:61]
	v_mfma_f32_16x16x32_bf16 v[34:37], v[180:183], v[196:199], v[34:37]
	v_mfma_f32_16x16x32_bf16 v[26:29], v[172:175], v[204:207], v[26:29]
	v_mfma_f32_16x16x32_bf16 v[2:5], v[180:183], v[212:215], v[2:5]
	v_mfma_f32_16x16x32_bf16 v[42:45], v[172:175], v[196:199], v[42:45]
	v_mfma_f32_16x16x32_bf16 v[50:53], v[180:183], v[188:191], v[50:53]
	v_mfma_f32_16x16x32_bf16 v[10:13], v[172:175], v[212:215], v[10:13]
	v_mfma_f32_16x16x32_bf16 v[18:21], v[180:183], v[204:207], v[18:21]
	s_setprio 0
	s_barrier
	s_add_i32 s62, 0, 0x18000
	s_add_i32 s63, 0, 0x1c000
	v_add_u32_e32 v164, s62, v151
	v_add_u32_e32 v180, s63, v151
	ds_read_b128 v[146:149], v164
	ds_read_b128 v[156:159], v164 offset:1024
	ds_read_b128 v[160:163], v164 offset:2048
	ds_read_b128 v[164:167], v164 offset:3072
	ds_read_b128 v[168:171], v180
	ds_read_b128 v[172:175], v180 offset:1024
	ds_read_b128 v[176:179], v180 offset:2048
	ds_read_b128 v[180:183], v180 offset:3072
	s_add_u32 s46, s46, 0x80000
	s_addc_u32 s47, s47, 0
	s_mov_b32 m0, s49
	v_lshl_add_u64 v[226:227], s[46:47], 0, v[136:137]
	ds_read_b128 v[184:187], v155 offset:32768
	ds_read_b128 v[188:191], v155 offset:33792
	ds_read_b128 v[192:195], v155 offset:34816
	ds_read_b128 v[196:199], v155 offset:35840
	ds_read_b128 v[200:203], v155 offset:36864
	ds_read_b128 v[204:207], v155 offset:37888
	ds_read_b128 v[208:211], v155 offset:38912
	ds_read_b128 v[212:215], v155 offset:39936
	global_load_lds_dwordx4 v[226:227], off
	v_lshl_add_u64 v[226:227], s[46:47], 0, v[132:133]
	s_mov_b32 m0, s52
	s_nop 0
	global_load_lds_dwordx4 v[226:227], off
	s_waitcnt vmcnt(8)
	s_waitcnt lgkmcnt(0)
	s_barrier
	s_setprio 1
	s_waitcnt lgkmcnt(0)
	v_mfma_f32_16x16x32_bf16 v[126:129], v[146:149], v[184:187], v[126:129]
	v_mfma_f32_16x16x32_bf16 v[102:105], v[160:163], v[192:195], v[102:105]
	v_mfma_f32_16x16x32_bf16 v[94:97], v[146:149], v[200:203], v[94:97]
	v_mfma_f32_16x16x32_bf16 v[70:73], v[160:163], v[208:211], v[70:73]
	v_mfma_f32_16x16x32_bf16 v[110:113], v[146:149], v[192:195], v[110:113]
	v_mfma_f32_16x16x32_bf16 v[118:121], v[160:163], v[184:187], v[118:121]
	v_mfma_f32_16x16x32_bf16 v[78:81], v[146:149], v[208:211], v[78:81]
	v_mfma_f32_16x16x32_bf16 v[86:89], v[160:163], v[200:203], v[86:89]
	v_mfma_f32_16x16x32_bf16 v[126:129], v[156:159], v[188:191], v[126:129]
	v_mfma_f32_16x16x32_bf16 v[102:105], v[164:167], v[196:199], v[102:105]
	v_mfma_f32_16x16x32_bf16 v[94:97], v[156:159], v[204:207], v[94:97]
	v_mfma_f32_16x16x32_bf16 v[70:73], v[164:167], v[212:215], v[70:73]
	v_mfma_f32_16x16x32_bf16 v[110:113], v[156:159], v[196:199], v[110:113]
	v_mfma_f32_16x16x32_bf16 v[118:121], v[164:167], v[188:191], v[118:121]
	v_mfma_f32_16x16x32_bf16 v[78:81], v[156:159], v[212:215], v[78:81]
	v_mfma_f32_16x16x32_bf16 v[86:89], v[164:167], v[204:207], v[86:89]
	s_setprio 0
	s_setprio 1
	v_mfma_f32_16x16x32_bf16 v[122:125], v[168:171], v[184:187], v[122:125]
	v_mfma_f32_16x16x32_bf16 v[98:101], v[176:179], v[192:195], v[98:101]
	v_mfma_f32_16x16x32_bf16 v[90:93], v[168:171], v[200:203], v[90:93]
	v_mfma_f32_16x16x32_bf16 v[66:69], v[176:179], v[208:211], v[66:69]
	v_mfma_f32_16x16x32_bf16 v[106:109], v[168:171], v[192:195], v[106:109]
	v_mfma_f32_16x16x32_bf16 v[114:117], v[176:179], v[184:187], v[114:117]
	v_mfma_f32_16x16x32_bf16 v[74:77], v[168:171], v[208:211], v[74:77]
	v_mfma_f32_16x16x32_bf16 v[82:85], v[176:179], v[200:203], v[82:85]
	v_mfma_f32_16x16x32_bf16 v[122:125], v[172:175], v[188:191], v[122:125]
	v_mfma_f32_16x16x32_bf16 v[98:101], v[180:183], v[196:199], v[98:101]
	v_mfma_f32_16x16x32_bf16 v[90:93], v[172:175], v[204:207], v[90:93]
	v_mfma_f32_16x16x32_bf16 v[66:69], v[180:183], v[212:215], v[66:69]
	v_mfma_f32_16x16x32_bf16 v[106:109], v[172:175], v[196:199], v[106:109]
	v_mfma_f32_16x16x32_bf16 v[114:117], v[180:183], v[188:191], v[114:117]
	v_mfma_f32_16x16x32_bf16 v[74:77], v[172:175], v[212:215], v[74:77]
	v_mfma_f32_16x16x32_bf16 v[82:85], v[180:183], v[204:207], v[82:85]
	s_setprio 0
	s_barrier
	s_add_i32 s46, s62, s30
	v_lshl_add_u64 v[218:219], v[218:219], 0, s[8:9]
	s_mov_b32 m0, s46
	ds_read_b128 v[184:187], v155 offset:49152
	ds_read_b128 v[188:191], v155 offset:50176
	ds_read_b128 v[192:195], v155 offset:51200
	ds_read_b128 v[196:199], v155 offset:52224
	ds_read_b128 v[200:203], v155 offset:53248
	ds_read_b128 v[204:207], v155 offset:54272
	ds_read_b128 v[208:211], v155 offset:55296
	ds_read_b128 v[212:215], v155 offset:56320
	global_load_lds_dwordx4 v[218:219], off
	s_add_i32 m0, s46, 0x2000
	s_add_u32 s34, s34, 0x80080
	v_lshl_add_u64 v[218:219], v[220:221], 0, s[8:9]
	s_addc_u32 s35, s35, 0
	s_add_i32 s46, s63, s30
	global_load_lds_dwordx4 v[218:219], off
	v_lshl_add_u64 v[218:219], s[34:35], 0, v[134:135]
	s_mov_b32 m0, s46
	s_nop 0
	global_load_lds_dwordx4 v[218:219], off
	v_lshl_add_u64 v[218:219], s[34:35], 0, v[130:131]
	s_add_i32 m0, s46, 0x2000
	s_nop 0
	global_load_lds_dwordx4 v[218:219], off
	v_lshl_add_u64 v[218:219], v[222:223], 0, s[8:9]
	s_mov_b32 m0, s54
	s_nop 0
	global_load_lds_dwordx4 v[218:219], off
	v_lshl_add_u64 v[218:219], v[224:225], 0, s[8:9]
	s_mov_b32 m0, s55
	s_nop 0
	global_load_lds_dwordx4 v[218:219], off
	s_waitcnt vmcnt(8)
	s_waitcnt lgkmcnt(0)
	s_barrier
	s_setprio 1
	s_waitcnt lgkmcnt(0)
	v_mfma_f32_16x16x32_bf16 v[62:65], v[146:149], v[184:187], v[62:65]
	v_mfma_f32_16x16x32_bf16 v[38:41], v[160:163], v[192:195], v[38:41]
	v_mfma_f32_16x16x32_bf16 v[30:33], v[146:149], v[200:203], v[30:33]
	v_mfma_f32_16x16x32_bf16 v[6:9], v[160:163], v[208:211], v[6:9]
	v_mfma_f32_16x16x32_bf16 v[46:49], v[146:149], v[192:195], v[46:49]
	v_mfma_f32_16x16x32_bf16 v[54:57], v[160:163], v[184:187], v[54:57]
	v_mfma_f32_16x16x32_bf16 v[14:17], v[146:149], v[208:211], v[14:17]
	v_mfma_f32_16x16x32_bf16 v[22:25], v[160:163], v[200:203], v[22:25]
	v_mfma_f32_16x16x32_bf16 v[62:65], v[156:159], v[188:191], v[62:65]
	v_mfma_f32_16x16x32_bf16 v[38:41], v[164:167], v[196:199], v[38:41]
	v_mfma_f32_16x16x32_bf16 v[30:33], v[156:159], v[204:207], v[30:33]
	v_mfma_f32_16x16x32_bf16 v[6:9], v[164:167], v[212:215], v[6:9]
	v_mfma_f32_16x16x32_bf16 v[46:49], v[156:159], v[196:199], v[46:49]
	v_mfma_f32_16x16x32_bf16 v[54:57], v[164:167], v[188:191], v[54:57]
	v_mfma_f32_16x16x32_bf16 v[14:17], v[156:159], v[212:215], v[14:17]
	v_mfma_f32_16x16x32_bf16 v[22:25], v[164:167], v[204:207], v[22:25]
	s_setprio 0
	s_setprio 1
	v_mfma_f32_16x16x32_bf16 v[58:61], v[168:171], v[184:187], v[58:61]
	v_mfma_f32_16x16x32_bf16 v[34:37], v[176:179], v[192:195], v[34:37]
	v_mfma_f32_16x16x32_bf16 v[26:29], v[168:171], v[200:203], v[26:29]
	v_mfma_f32_16x16x32_bf16 v[2:5], v[176:179], v[208:211], v[2:5]
	v_mfma_f32_16x16x32_bf16 v[42:45], v[168:171], v[192:195], v[42:45]
	v_mfma_f32_16x16x32_bf16 v[50:53], v[176:179], v[184:187], v[50:53]
	v_mfma_f32_16x16x32_bf16 v[10:13], v[168:171], v[208:211], v[10:13]
	v_mfma_f32_16x16x32_bf16 v[18:21], v[176:179], v[200:203], v[18:21]
	v_mfma_f32_16x16x32_bf16 v[58:61], v[172:175], v[188:191], v[58:61]
	v_mfma_f32_16x16x32_bf16 v[34:37], v[180:183], v[196:199], v[34:37]
	v_mfma_f32_16x16x32_bf16 v[26:29], v[172:175], v[204:207], v[26:29]
	v_mfma_f32_16x16x32_bf16 v[2:5], v[180:183], v[212:215], v[2:5]
	v_mfma_f32_16x16x32_bf16 v[42:45], v[172:175], v[196:199], v[42:45]
	v_mfma_f32_16x16x32_bf16 v[50:53], v[180:183], v[188:191], v[50:53]
	v_mfma_f32_16x16x32_bf16 v[10:13], v[172:175], v[212:215], v[10:13]
	v_mfma_f32_16x16x32_bf16 v[18:21], v[180:183], v[204:207], v[18:21]
	s_setprio 0
	s_barrier
	s_add_i32 s69, s69, 2
	s_add_u32 s44, s44, 0x100
	s_addc_u32 s45, s45, 0
	s_add_u32 s61, s61, 0x100
	s_addc_u32 s68, s68, 0
	s_cmp_gt_u32 s69, 29
	s_cbranch_scc0 .LBB0_3309
	v_mov_b32_e32 v160, 0xbfb8aa3b
	s_and_b64 vcc, exec, s[24:25]
	s_cbranch_vccz .LBB0_3312
	s_barrier

.LBB0_3533:
	ds_read_b128 v[154:157], v151
	ds_read_b128 v[158:161], v151 offset:1024
	ds_read_b128 v[162:165], v151 offset:2048
	ds_read_b128 v[166:169], v151 offset:3072
	ds_read_b128 v[170:173], v152
	ds_read_b128 v[174:177], v152 offset:1024
	ds_read_b128 v[178:181], v152 offset:2048
	ds_read_b128 v[182:185], v152 offset:3072
	s_add_u32 s34, s44, 0xfff80080
	s_addc_u32 s35, s45, -1
	s_cmp_eq_u32 s68, 28
	s_cselect_b32 s47, s0, s35
	s_cselect_b32 s46, s1, s34
	s_cselect_b32 s35, s27, s61
	s_cselect_b32 s34, s37, s60
	v_lshl_add_u64 v[146:147], s[44:45], 0, v[138:139]
	s_add_i32 m0, s33, 0xc000
	ds_read_b128 v[186:189], v153
	ds_read_b128 v[190:193], v153 offset:1024
	ds_read_b128 v[194:197], v153 offset:2048
	ds_read_b128 v[198:201], v153 offset:3072
	ds_read_b128 v[202:205], v153 offset:4096
	ds_read_b128 v[206:209], v153 offset:5120
	ds_read_b128 v[210:213], v153 offset:6144
	ds_read_b128 v[218:221], v153 offset:7168
	global_load_lds_dwordx4 v[146:147], off
	v_lshl_add_u64 v[146:147], s[44:45], 0, v[140:141]
	s_add_i32 m0, s33, 0xe000
	s_nop 0
	global_load_lds_dwordx4 v[146:147], off
	s_waitcnt vmcnt(8)
	s_waitcnt lgkmcnt(0)
	s_barrier
	s_setprio 1
	s_waitcnt lgkmcnt(0)
	v_mfma_f32_16x16x32_bf16 v[126:129], v[154:157], v[186:189], v[126:129]
	v_mfma_f32_16x16x32_bf16 v[106:109], v[162:165], v[194:197], v[106:109]
	v_mfma_f32_16x16x32_bf16 v[98:101], v[154:157], v[202:205], v[98:101]
	v_mfma_f32_16x16x32_bf16 v[74:77], v[162:165], v[210:213], v[74:77]
	v_mfma_f32_16x16x32_bf16 v[114:117], v[154:157], v[194:197], v[114:117]
	v_mfma_f32_16x16x32_bf16 v[122:125], v[162:165], v[186:189], v[122:125]
	v_mfma_f32_16x16x32_bf16 v[82:85], v[154:157], v[210:213], v[82:85]
	v_mfma_f32_16x16x32_bf16 v[90:93], v[162:165], v[202:205], v[90:93]
	v_mfma_f32_16x16x32_bf16 v[126:129], v[158:161], v[190:193], v[126:129]
	v_mfma_f32_16x16x32_bf16 v[106:109], v[166:169], v[198:201], v[106:109]
	v_mfma_f32_16x16x32_bf16 v[98:101], v[158:161], v[206:209], v[98:101]
	v_mfma_f32_16x16x32_bf16 v[74:77], v[166:169], v[218:221], v[74:77]
	v_mfma_f32_16x16x32_bf16 v[114:117], v[158:161], v[198:201], v[114:117]
	v_mfma_f32_16x16x32_bf16 v[122:125], v[166:169], v[190:193], v[122:125]
	v_mfma_f32_16x16x32_bf16 v[82:85], v[158:161], v[218:221], v[82:85]
	v_mfma_f32_16x16x32_bf16 v[90:93], v[166:169], v[206:209], v[90:93]
	s_setprio 0
	s_setprio 1
	v_mfma_f32_16x16x32_bf16 v[118:121], v[170:173], v[186:189], v[118:121]
	v_mfma_f32_16x16x32_bf16 v[94:97], v[178:181], v[194:197], v[94:97]
	v_mfma_f32_16x16x32_bf16 v[86:89], v[170:173], v[202:205], v[86:89]
	v_mfma_f32_16x16x32_bf16 v[66:69], v[178:181], v[210:213], v[66:69]
	v_mfma_f32_16x16x32_bf16 v[102:105], v[170:173], v[194:197], v[102:105]
	v_mfma_f32_16x16x32_bf16 v[110:113], v[178:181], v[186:189], v[110:113]
	v_mfma_f32_16x16x32_bf16 v[70:73], v[170:173], v[210:213], v[70:73]
	v_mfma_f32_16x16x32_bf16 v[78:81], v[178:181], v[202:205], v[78:81]
	v_mfma_f32_16x16x32_bf16 v[118:121], v[174:177], v[190:193], v[118:121]
	v_mfma_f32_16x16x32_bf16 v[94:97], v[182:185], v[198:201], v[94:97]
	v_mfma_f32_16x16x32_bf16 v[86:89], v[174:177], v[206:209], v[86:89]
	v_mfma_f32_16x16x32_bf16 v[66:69], v[182:185], v[218:221], v[66:69]
	v_mfma_f32_16x16x32_bf16 v[102:105], v[174:177], v[198:201], v[102:105]
	v_mfma_f32_16x16x32_bf16 v[110:113], v[182:185], v[190:193], v[110:113]
	v_mfma_f32_16x16x32_bf16 v[70:73], v[174:177], v[218:221], v[70:73]
	v_mfma_f32_16x16x32_bf16 v[78:81], v[182:185], v[206:209], v[78:81]
	s_setprio 0
	s_barrier
	s_add_i32 s62, s56, s12
	v_lshl_add_u64 v[146:147], s[34:35], 0, v[134:135]
	s_mov_b32 m0, s62
	ds_read_b128 v[186:189], v153 offset:16384
	ds_read_b128 v[190:193], v153 offset:17408
	ds_read_b128 v[194:197], v153 offset:18432
	ds_read_b128 v[198:201], v153 offset:19456
	ds_read_b128 v[202:205], v153 offset:20480
	ds_read_b128 v[206:209], v153 offset:21504
	ds_read_b128 v[210:213], v153 offset:22528
	ds_read_b128 v[218:221], v153 offset:23552
	global_load_lds_dwordx4 v[146:147], off
	s_add_i32 m0, s62, 0x2000
	s_add_u32 s62, s34, 0x80000
	v_lshl_add_u64 v[214:215], s[34:35], 0, v[130:131]
	s_addc_u32 s63, s35, 0
	s_add_i32 s66, s57, s12
	global_load_lds_dwordx4 v[214:215], off
	v_lshl_add_u64 v[222:223], s[62:63], 0, v[134:135]
	s_mov_b32 m0, s66
	v_lshl_add_u64 v[224:225], s[46:47], 0, v[132:133]
	global_load_lds_dwordx4 v[222:223], off
	v_lshl_add_u64 v[222:223], s[62:63], 0, v[130:131]
	s_add_i32 m0, s66, 0x2000
	s_nop 0
	global_load_lds_dwordx4 v[222:223], off
	v_lshl_add_u64 v[222:223], s[46:47], 0, v[136:137]
	s_mov_b32 m0, s33
	s_nop 0
	global_load_lds_dwordx4 v[222:223], off
	s_mov_b32 m0, s43
	s_nop 0
	global_load_lds_dwordx4 v[224:225], off
	s_waitcnt vmcnt(8)
	s_waitcnt lgkmcnt(0)
	s_barrier
	s_setprio 1
	s_waitcnt lgkmcnt(0)
	v_mfma_f32_16x16x32_bf16 v[62:65], v[154:157], v[186:189], v[62:65]
	v_mfma_f32_16x16x32_bf16 v[42:45], v[162:165], v[194:197], v[42:45]
	v_mfma_f32_16x16x32_bf16 v[34:37], v[154:157], v[202:205], v[34:37]
	v_mfma_f32_16x16x32_bf16 v[10:13], v[162:165], v[210:213], v[10:13]
	v_mfma_f32_16x16x32_bf16 v[50:53], v[154:157], v[194:197], v[50:53]
	v_mfma_f32_16x16x32_bf16 v[58:61], v[162:165], v[186:189], v[58:61]
	v_mfma_f32_16x16x32_bf16 v[18:21], v[154:157], v[210:213], v[18:21]
	v_mfma_f32_16x16x32_bf16 v[26:29], v[162:165], v[202:205], v[26:29]
	v_mfma_f32_16x16x32_bf16 v[62:65], v[158:161], v[190:193], v[62:65]
	v_mfma_f32_16x16x32_bf16 v[42:45], v[166:169], v[198:201], v[42:45]
	v_mfma_f32_16x16x32_bf16 v[34:37], v[158:161], v[206:209], v[34:37]
	v_mfma_f32_16x16x32_bf16 v[10:13], v[166:169], v[218:221], v[10:13]
	v_mfma_f32_16x16x32_bf16 v[50:53], v[158:161], v[198:201], v[50:53]
	v_mfma_f32_16x16x32_bf16 v[58:61], v[166:169], v[190:193], v[58:61]
	v_mfma_f32_16x16x32_bf16 v[18:21], v[158:161], v[218:221], v[18:21]
	v_mfma_f32_16x16x32_bf16 v[26:29], v[166:169], v[206:209], v[26:29]
	s_setprio 0
	s_setprio 1
	v_mfma_f32_16x16x32_bf16 v[54:57], v[170:173], v[186:189], v[54:57]
	v_mfma_f32_16x16x32_bf16 v[30:33], v[178:181], v[194:197], v[30:33]
	v_mfma_f32_16x16x32_bf16 v[22:25], v[170:173], v[202:205], v[22:25]
	v_mfma_f32_16x16x32_bf16 v[2:5], v[178:181], v[210:213], v[2:5]
	v_mfma_f32_16x16x32_bf16 v[38:41], v[170:173], v[194:197], v[38:41]
	v_mfma_f32_16x16x32_bf16 v[46:49], v[178:181], v[186:189], v[46:49]
	v_mfma_f32_16x16x32_bf16 v[6:9], v[170:173], v[210:213], v[6:9]
	v_mfma_f32_16x16x32_bf16 v[14:17], v[178:181], v[202:205], v[14:17]
	v_mfma_f32_16x16x32_bf16 v[54:57], v[174:177], v[190:193], v[54:57]
	v_mfma_f32_16x16x32_bf16 v[30:33], v[182:185], v[198:201], v[30:33]
	v_mfma_f32_16x16x32_bf16 v[22:25], v[174:177], v[206:209], v[22:25]
	v_mfma_f32_16x16x32_bf16 v[2:5], v[182:185], v[218:221], v[2:5]
	v_mfma_f32_16x16x32_bf16 v[38:41], v[174:177], v[198:201], v[38:41]
	v_mfma_f32_16x16x32_bf16 v[46:49], v[182:185], v[190:193], v[46:49]
	v_mfma_f32_16x16x32_bf16 v[6:9], v[174:177], v[218:221], v[6:9]
	v_mfma_f32_16x16x32_bf16 v[14:17], v[182:185], v[206:209], v[14:17]
	s_setprio 0
	s_barrier
	s_add_i32 s62, 0, 0x18000
	s_add_i32 s63, 0, 0x1c000
	v_add_u32_e32 v166, s62, v149
	v_add_u32_e32 v182, s63, v149
	ds_read_b128 v[154:157], v166
	ds_read_b128 v[158:161], v166 offset:1024
	ds_read_b128 v[162:165], v166 offset:2048
	ds_read_b128 v[166:169], v166 offset:3072
	ds_read_b128 v[170:173], v182
	ds_read_b128 v[174:177], v182 offset:1024
	ds_read_b128 v[178:181], v182 offset:2048
	ds_read_b128 v[182:185], v182 offset:3072
	s_add_u32 s46, s46, 0x80000
	s_addc_u32 s47, s47, 0
	s_mov_b32 m0, s48
	v_lshl_add_u64 v[226:227], s[46:47], 0, v[136:137]
	ds_read_b128 v[186:189], v153 offset:32768
	ds_read_b128 v[190:193], v153 offset:33792
	ds_read_b128 v[194:197], v153 offset:34816
	ds_read_b128 v[198:201], v153 offset:35840
	ds_read_b128 v[202:205], v153 offset:36864
	ds_read_b128 v[206:209], v153 offset:37888
	ds_read_b128 v[210:213], v153 offset:38912
	ds_read_b128 v[218:221], v153 offset:39936
	global_load_lds_dwordx4 v[226:227], off
	v_lshl_add_u64 v[226:227], s[46:47], 0, v[132:133]
	s_mov_b32 m0, s49
	s_nop 0
	global_load_lds_dwordx4 v[226:227], off
	s_waitcnt vmcnt(8)
	s_waitcnt lgkmcnt(0)
	s_barrier
	s_setprio 1
	s_waitcnt lgkmcnt(0)
	v_mfma_f32_16x16x32_bf16 v[126:129], v[154:157], v[186:189], v[126:129]
	v_mfma_f32_16x16x32_bf16 v[106:109], v[162:165], v[194:197], v[106:109]
	v_mfma_f32_16x16x32_bf16 v[98:101], v[154:157], v[202:205], v[98:101]
	v_mfma_f32_16x16x32_bf16 v[74:77], v[162:165], v[210:213], v[74:77]
	v_mfma_f32_16x16x32_bf16 v[114:117], v[154:157], v[194:197], v[114:117]
	v_mfma_f32_16x16x32_bf16 v[122:125], v[162:165], v[186:189], v[122:125]
	v_mfma_f32_16x16x32_bf16 v[82:85], v[154:157], v[210:213], v[82:85]
	v_mfma_f32_16x16x32_bf16 v[90:93], v[162:165], v[202:205], v[90:93]
	v_mfma_f32_16x16x32_bf16 v[126:129], v[158:161], v[190:193], v[126:129]
	v_mfma_f32_16x16x32_bf16 v[106:109], v[166:169], v[198:201], v[106:109]
	v_mfma_f32_16x16x32_bf16 v[98:101], v[158:161], v[206:209], v[98:101]
	v_mfma_f32_16x16x32_bf16 v[74:77], v[166:169], v[218:221], v[74:77]
	v_mfma_f32_16x16x32_bf16 v[114:117], v[158:161], v[198:201], v[114:117]
	v_mfma_f32_16x16x32_bf16 v[122:125], v[166:169], v[190:193], v[122:125]
	v_mfma_f32_16x16x32_bf16 v[82:85], v[158:161], v[218:221], v[82:85]
	v_mfma_f32_16x16x32_bf16 v[90:93], v[166:169], v[206:209], v[90:93]
	s_setprio 0
	s_setprio 1
	v_mfma_f32_16x16x32_bf16 v[118:121], v[170:173], v[186:189], v[118:121]
	v_mfma_f32_16x16x32_bf16 v[94:97], v[178:181], v[194:197], v[94:97]
	v_mfma_f32_16x16x32_bf16 v[86:89], v[170:173], v[202:205], v[86:89]
	v_mfma_f32_16x16x32_bf16 v[66:69], v[178:181], v[210:213], v[66:69]
	v_mfma_f32_16x16x32_bf16 v[102:105], v[170:173], v[194:197], v[102:105]
	v_mfma_f32_16x16x32_bf16 v[110:113], v[178:181], v[186:189], v[110:113]
	v_mfma_f32_16x16x32_bf16 v[70:73], v[170:173], v[210:213], v[70:73]
	v_mfma_f32_16x16x32_bf16 v[78:81], v[178:181], v[202:205], v[78:81]
	v_mfma_f32_16x16x32_bf16 v[118:121], v[174:177], v[190:193], v[118:121]
	v_mfma_f32_16x16x32_bf16 v[94:97], v[182:185], v[198:201], v[94:97]
	v_mfma_f32_16x16x32_bf16 v[86:89], v[174:177], v[206:209], v[86:89]
	v_mfma_f32_16x16x32_bf16 v[66:69], v[182:185], v[218:221], v[66:69]
	v_mfma_f32_16x16x32_bf16 v[102:105], v[174:177], v[198:201], v[102:105]
	v_mfma_f32_16x16x32_bf16 v[110:113], v[182:185], v[190:193], v[110:113]
	v_mfma_f32_16x16x32_bf16 v[70:73], v[174:177], v[218:221], v[70:73]
	v_mfma_f32_16x16x32_bf16 v[78:81], v[182:185], v[206:209], v[78:81]
	s_setprio 0
	s_barrier
	s_add_i32 s46, s62, s12
	v_lshl_add_u64 v[146:147], v[146:147], 0, s[8:9]
	s_mov_b32 m0, s46
	ds_read_b128 v[186:189], v153 offset:49152
	ds_read_b128 v[190:193], v153 offset:50176
	ds_read_b128 v[194:197], v153 offset:51200
	ds_read_b128 v[198:201], v153 offset:52224
	ds_read_b128 v[202:205], v153 offset:53248
	ds_read_b128 v[206:209], v153 offset:54272
	ds_read_b128 v[210:213], v153 offset:55296
	ds_read_b128 v[218:221], v153 offset:56320
	global_load_lds_dwordx4 v[146:147], off
	s_add_i32 m0, s46, 0x2000
	s_add_u32 s34, s34, 0x80080
	v_lshl_add_u64 v[146:147], v[214:215], 0, s[8:9]
	s_addc_u32 s35, s35, 0
	s_add_i32 s46, s63, s12
	global_load_lds_dwordx4 v[146:147], off
	v_lshl_add_u64 v[146:147], s[34:35], 0, v[134:135]
	s_mov_b32 m0, s46
	s_nop 0
	global_load_lds_dwordx4 v[146:147], off
	v_lshl_add_u64 v[146:147], s[34:35], 0, v[130:131]
	s_add_i32 m0, s46, 0x2000
	s_nop 0
	global_load_lds_dwordx4 v[146:147], off
	v_lshl_add_u64 v[146:147], v[222:223], 0, s[8:9]
	s_mov_b32 m0, s53
	s_nop 0
	global_load_lds_dwordx4 v[146:147], off
	v_lshl_add_u64 v[146:147], v[224:225], 0, s[8:9]
	s_mov_b32 m0, s54
	s_nop 0
	global_load_lds_dwordx4 v[146:147], off
	s_waitcnt vmcnt(8)
	s_waitcnt lgkmcnt(0)
	s_barrier
	s_setprio 1
	s_waitcnt lgkmcnt(0)
	v_mfma_f32_16x16x32_bf16 v[62:65], v[154:157], v[186:189], v[62:65]
	v_mfma_f32_16x16x32_bf16 v[42:45], v[162:165], v[194:197], v[42:45]
	v_mfma_f32_16x16x32_bf16 v[34:37], v[154:157], v[202:205], v[34:37]
	v_mfma_f32_16x16x32_bf16 v[10:13], v[162:165], v[210:213], v[10:13]
	v_mfma_f32_16x16x32_bf16 v[50:53], v[154:157], v[194:197], v[50:53]
	v_mfma_f32_16x16x32_bf16 v[58:61], v[162:165], v[186:189], v[58:61]
	v_mfma_f32_16x16x32_bf16 v[18:21], v[154:157], v[210:213], v[18:21]
	v_mfma_f32_16x16x32_bf16 v[26:29], v[162:165], v[202:205], v[26:29]
	v_mfma_f32_16x16x32_bf16 v[62:65], v[158:161], v[190:193], v[62:65]
	v_mfma_f32_16x16x32_bf16 v[42:45], v[166:169], v[198:201], v[42:45]
	v_mfma_f32_16x16x32_bf16 v[34:37], v[158:161], v[206:209], v[34:37]
	v_mfma_f32_16x16x32_bf16 v[10:13], v[166:169], v[218:221], v[10:13]
	v_mfma_f32_16x16x32_bf16 v[50:53], v[158:161], v[198:201], v[50:53]
	v_mfma_f32_16x16x32_bf16 v[58:61], v[166:169], v[190:193], v[58:61]
	v_mfma_f32_16x16x32_bf16 v[18:21], v[158:161], v[218:221], v[18:21]
	v_mfma_f32_16x16x32_bf16 v[26:29], v[166:169], v[206:209], v[26:29]
	s_setprio 0
	s_setprio 1
	v_mfma_f32_16x16x32_bf16 v[54:57], v[170:173], v[186:189], v[54:57]
	v_mfma_f32_16x16x32_bf16 v[30:33], v[178:181], v[194:197], v[30:33]
	v_mfma_f32_16x16x32_bf16 v[22:25], v[170:173], v[202:205], v[22:25]
	v_mfma_f32_16x16x32_bf16 v[2:5], v[178:181], v[210:213], v[2:5]
	v_mfma_f32_16x16x32_bf16 v[38:41], v[170:173], v[194:197], v[38:41]
	v_mfma_f32_16x16x32_bf16 v[46:49], v[178:181], v[186:189], v[46:49]
	v_mfma_f32_16x16x32_bf16 v[6:9], v[170:173], v[210:213], v[6:9]
	v_mfma_f32_16x16x32_bf16 v[14:17], v[178:181], v[202:205], v[14:17]
	v_mfma_f32_16x16x32_bf16 v[54:57], v[174:177], v[190:193], v[54:57]
	v_mfma_f32_16x16x32_bf16 v[30:33], v[182:185], v[198:201], v[30:33]
	v_mfma_f32_16x16x32_bf16 v[22:25], v[174:177], v[206:209], v[22:25]
	v_mfma_f32_16x16x32_bf16 v[2:5], v[182:185], v[218:221], v[2:5]
	v_mfma_f32_16x16x32_bf16 v[38:41], v[174:177], v[198:201], v[38:41]
	v_mfma_f32_16x16x32_bf16 v[46:49], v[182:185], v[190:193], v[46:49]
	v_mfma_f32_16x16x32_bf16 v[6:9], v[174:177], v[218:221], v[6:9]
	v_mfma_f32_16x16x32_bf16 v[14:17], v[182:185], v[206:209], v[14:17]
	s_setprio 0
	s_barrier
	s_add_i32 s68, s68, 2
	s_add_u32 s44, s44, 0x100
	s_addc_u32 s45, s45, 0
	s_add_u32 s60, s60, 0x100
	s_addc_u32 s61, s61, 0
	s_cmp_gt_u32 s68, 29
	s_cbranch_scc0 .LBB0_3533
	s_and_b64 vcc, exec, s[24:25]
	s_cbranch_vccz .LBB0_3536
	s_barrier

.LBB0_3706:
	ds_read_b128 v[130:133], v174
	ds_read_b128 v[134:137], v174 offset:1024
	ds_read_b128 v[138:141], v174 offset:2048
	ds_read_b128 v[158:161], v174 offset:3072
	ds_read_b128 v[162:165], v175
	ds_read_b128 v[166:169], v175 offset:1024
	ds_read_b128 v[178:181], v175 offset:2048
	ds_read_b128 v[182:185], v175 offset:3072
	s_add_u32 s34, s42, 0xfff80080
	s_addc_u32 s35, s43, -1
	s_cmp_eq_u32 s60, 28
	s_cselect_b32 s45, s0, s35
	s_cselect_b32 s44, s1, s34
	s_cselect_b32 s35, s25, s59
	s_cselect_b32 s34, s27, s58
	v_lshl_add_u64 v[170:171], s[42:43], 0, v[150:151]
	s_add_i32 m0, s41, 0xc000
	ds_read_b128 v[186:189], v176
	ds_read_b128 v[190:193], v176 offset:1024
	ds_read_b128 v[194:197], v176 offset:2048
	ds_read_b128 v[198:201], v176 offset:3072
	ds_read_b128 v[202:205], v176 offset:4096
	ds_read_b128 v[206:209], v176 offset:5120
	ds_read_b128 v[210:213], v176 offset:6144
	ds_read_b128 v[218:221], v176 offset:7168
	global_load_lds_dwordx4 v[170:171], off
	v_lshl_add_u64 v[170:171], s[42:43], 0, v[152:153]
	s_add_i32 m0, s41, 0xe000
	s_nop 0
	global_load_lds_dwordx4 v[170:171], off
	s_waitcnt vmcnt(8)
	s_waitcnt lgkmcnt(0)
	s_barrier
	s_setprio 1
	s_waitcnt lgkmcnt(0)
	v_mfma_f32_16x16x32_bf16 v[126:129], v[130:133], v[186:189], v[126:129]
	v_mfma_f32_16x16x32_bf16 v[106:109], v[138:141], v[194:197], v[106:109]
	v_mfma_f32_16x16x32_bf16 v[94:97], v[130:133], v[202:205], v[94:97]
	v_mfma_f32_16x16x32_bf16 v[74:77], v[138:141], v[210:213], v[74:77]
	v_mfma_f32_16x16x32_bf16 v[110:113], v[130:133], v[194:197], v[110:113]
	v_mfma_f32_16x16x32_bf16 v[122:125], v[138:141], v[186:189], v[122:125]
	v_mfma_f32_16x16x32_bf16 v[78:81], v[130:133], v[210:213], v[78:81]
	v_mfma_f32_16x16x32_bf16 v[90:93], v[138:141], v[202:205], v[90:93]
	v_mfma_f32_16x16x32_bf16 v[126:129], v[134:137], v[190:193], v[126:129]
	v_mfma_f32_16x16x32_bf16 v[106:109], v[158:161], v[198:201], v[106:109]
	v_mfma_f32_16x16x32_bf16 v[94:97], v[134:137], v[206:209], v[94:97]
	v_mfma_f32_16x16x32_bf16 v[74:77], v[158:161], v[218:221], v[74:77]
	v_mfma_f32_16x16x32_bf16 v[110:113], v[134:137], v[198:201], v[110:113]
	v_mfma_f32_16x16x32_bf16 v[122:125], v[158:161], v[190:193], v[122:125]
	v_mfma_f32_16x16x32_bf16 v[78:81], v[134:137], v[218:221], v[78:81]
	v_mfma_f32_16x16x32_bf16 v[90:93], v[158:161], v[206:209], v[90:93]
	s_setprio 0
	s_setprio 1
	v_mfma_f32_16x16x32_bf16 v[118:121], v[162:165], v[186:189], v[118:121]
	v_mfma_f32_16x16x32_bf16 v[98:101], v[178:181], v[194:197], v[98:101]
	v_mfma_f32_16x16x32_bf16 v[86:89], v[162:165], v[202:205], v[86:89]
	v_mfma_f32_16x16x32_bf16 v[66:69], v[178:181], v[210:213], v[66:69]
	v_mfma_f32_16x16x32_bf16 v[102:105], v[162:165], v[194:197], v[102:105]
	v_mfma_f32_16x16x32_bf16 v[114:117], v[178:181], v[186:189], v[114:117]
	v_mfma_f32_16x16x32_bf16 v[70:73], v[162:165], v[210:213], v[70:73]
	v_mfma_f32_16x16x32_bf16 v[82:85], v[178:181], v[202:205], v[82:85]
	v_mfma_f32_16x16x32_bf16 v[118:121], v[166:169], v[190:193], v[118:121]
	v_mfma_f32_16x16x32_bf16 v[98:101], v[182:185], v[198:201], v[98:101]
	v_mfma_f32_16x16x32_bf16 v[86:89], v[166:169], v[206:209], v[86:89]
	v_mfma_f32_16x16x32_bf16 v[66:69], v[182:185], v[218:221], v[66:69]
	v_mfma_f32_16x16x32_bf16 v[102:105], v[166:169], v[198:201], v[102:105]
	v_mfma_f32_16x16x32_bf16 v[114:117], v[182:185], v[190:193], v[114:117]
	v_mfma_f32_16x16x32_bf16 v[70:73], v[166:169], v[218:221], v[70:73]
	v_mfma_f32_16x16x32_bf16 v[82:85], v[182:185], v[206:209], v[82:85]
	s_setprio 0
	s_barrier
	s_add_i32 s61, s54, s46
	v_lshl_add_u64 v[170:171], s[34:35], 0, v[144:145]
	s_mov_b32 m0, s61
	ds_read_b128 v[186:189], v176 offset:16384
	ds_read_b128 v[190:193], v176 offset:17408
	ds_read_b128 v[194:197], v176 offset:18432
	ds_read_b128 v[198:201], v176 offset:19456
	ds_read_b128 v[202:205], v176 offset:20480
	ds_read_b128 v[206:209], v176 offset:21504
	ds_read_b128 v[210:213], v176 offset:22528
	ds_read_b128 v[218:221], v176 offset:23552
	global_load_lds_dwordx4 v[170:171], off
	s_add_i32 m0, s61, 0x2000
	s_add_u32 s62, s34, 0x80000
	v_lshl_add_u64 v[214:215], s[34:35], 0, v[148:149]
	s_addc_u32 s63, s35, 0
	s_add_i32 s61, s55, s46
	global_load_lds_dwordx4 v[214:215], off
	v_lshl_add_u64 v[222:223], s[62:63], 0, v[144:145]
	s_mov_b32 m0, s61
	v_lshl_add_u64 v[224:225], s[44:45], 0, v[146:147]
	global_load_lds_dwordx4 v[222:223], off
	v_lshl_add_u64 v[222:223], s[62:63], 0, v[148:149]
	s_add_i32 m0, s61, 0x2000
	s_nop 0
	global_load_lds_dwordx4 v[222:223], off
	v_lshl_add_u64 v[222:223], s[44:45], 0, v[142:143]
	s_mov_b32 m0, s41
	s_nop 0
	global_load_lds_dwordx4 v[222:223], off
	s_mov_b32 m0, s47
	s_nop 0
	global_load_lds_dwordx4 v[224:225], off
	s_waitcnt vmcnt(8)
	s_waitcnt lgkmcnt(0)
	s_barrier
	s_setprio 1
	s_waitcnt lgkmcnt(0)
	v_mfma_f32_16x16x32_bf16 v[62:65], v[130:133], v[186:189], v[62:65]
	v_mfma_f32_16x16x32_bf16 v[42:45], v[138:141], v[194:197], v[42:45]
	v_mfma_f32_16x16x32_bf16 v[38:41], v[130:133], v[202:205], v[38:41]
	v_mfma_f32_16x16x32_bf16 v[10:13], v[138:141], v[210:213], v[10:13]
	v_mfma_f32_16x16x32_bf16 v[50:53], v[130:133], v[194:197], v[50:53]
	v_mfma_f32_16x16x32_bf16 v[58:61], v[138:141], v[186:189], v[58:61]
	v_mfma_f32_16x16x32_bf16 v[14:17], v[130:133], v[210:213], v[14:17]
	v_mfma_f32_16x16x32_bf16 v[34:37], v[138:141], v[202:205], v[34:37]
	v_mfma_f32_16x16x32_bf16 v[62:65], v[134:137], v[190:193], v[62:65]
	v_mfma_f32_16x16x32_bf16 v[42:45], v[158:161], v[198:201], v[42:45]
	v_mfma_f32_16x16x32_bf16 v[38:41], v[134:137], v[206:209], v[38:41]
	v_mfma_f32_16x16x32_bf16 v[10:13], v[158:161], v[218:221], v[10:13]
	v_mfma_f32_16x16x32_bf16 v[50:53], v[134:137], v[198:201], v[50:53]
	v_mfma_f32_16x16x32_bf16 v[58:61], v[158:161], v[190:193], v[58:61]
	v_mfma_f32_16x16x32_bf16 v[14:17], v[134:137], v[218:221], v[14:17]
	v_mfma_f32_16x16x32_bf16 v[34:37], v[158:161], v[206:209], v[34:37]
	s_setprio 0
	s_setprio 1
	v_mfma_f32_16x16x32_bf16 v[54:57], v[162:165], v[186:189], v[54:57]
	v_mfma_f32_16x16x32_bf16 v[26:29], v[178:181], v[194:197], v[26:29]
	v_mfma_f32_16x16x32_bf16 v[22:25], v[162:165], v[202:205], v[22:25]
	v_mfma_f32_16x16x32_bf16 v[2:5], v[178:181], v[210:213], v[2:5]
	v_mfma_f32_16x16x32_bf16 v[30:33], v[162:165], v[194:197], v[30:33]
	v_mfma_f32_16x16x32_bf16 v[46:49], v[178:181], v[186:189], v[46:49]
	v_mfma_f32_16x16x32_bf16 v[6:9], v[162:165], v[210:213], v[6:9]
	v_mfma_f32_16x16x32_bf16 v[18:21], v[178:181], v[202:205], v[18:21]
	v_mfma_f32_16x16x32_bf16 v[54:57], v[166:169], v[190:193], v[54:57]
	v_mfma_f32_16x16x32_bf16 v[26:29], v[182:185], v[198:201], v[26:29]
	v_mfma_f32_16x16x32_bf16 v[22:25], v[166:169], v[206:209], v[22:25]
	v_mfma_f32_16x16x32_bf16 v[2:5], v[182:185], v[218:221], v[2:5]
	v_mfma_f32_16x16x32_bf16 v[30:33], v[166:169], v[198:201], v[30:33]
	v_mfma_f32_16x16x32_bf16 v[46:49], v[182:185], v[190:193], v[46:49]
	v_mfma_f32_16x16x32_bf16 v[6:9], v[166:169], v[218:221], v[6:9]
	v_mfma_f32_16x16x32_bf16 v[18:21], v[182:185], v[206:209], v[18:21]
	s_setprio 0
	s_barrier
	s_add_i32 s61, 0, 0x18000
	s_add_i32 s62, 0, 0x1c000
	v_add_u32_e32 v158, s61, v172
	v_add_u32_e32 v177, s62, v172
	ds_read_b128 v[130:133], v158
	ds_read_b128 v[134:137], v158 offset:1024
	ds_read_b128 v[138:141], v158 offset:2048
	ds_read_b128 v[158:161], v158 offset:3072
	ds_read_b128 v[162:165], v177
	ds_read_b128 v[166:169], v177 offset:1024
	ds_read_b128 v[178:181], v177 offset:2048
	ds_read_b128 v[182:185], v177 offset:3072
	s_add_u32 s44, s44, 0x80000
	s_addc_u32 s45, s45, 0
	s_mov_b32 m0, s48
	v_lshl_add_u64 v[226:227], s[44:45], 0, v[142:143]
	ds_read_b128 v[186:189], v176 offset:32768
	ds_read_b128 v[190:193], v176 offset:33792
	ds_read_b128 v[194:197], v176 offset:34816
	ds_read_b128 v[198:201], v176 offset:35840
	ds_read_b128 v[202:205], v176 offset:36864
	ds_read_b128 v[206:209], v176 offset:37888
	ds_read_b128 v[210:213], v176 offset:38912
	ds_read_b128 v[218:221], v176 offset:39936
	global_load_lds_dwordx4 v[226:227], off
	v_lshl_add_u64 v[226:227], s[44:45], 0, v[146:147]
	s_mov_b32 m0, s49
	s_nop 0
	global_load_lds_dwordx4 v[226:227], off
	s_waitcnt vmcnt(8)
	s_waitcnt lgkmcnt(0)
	s_barrier
	s_setprio 1
	s_waitcnt lgkmcnt(0)
	v_mfma_f32_16x16x32_bf16 v[126:129], v[130:133], v[186:189], v[126:129]
	v_mfma_f32_16x16x32_bf16 v[106:109], v[138:141], v[194:197], v[106:109]
	v_mfma_f32_16x16x32_bf16 v[94:97], v[130:133], v[202:205], v[94:97]
	v_mfma_f32_16x16x32_bf16 v[74:77], v[138:141], v[210:213], v[74:77]
	v_mfma_f32_16x16x32_bf16 v[110:113], v[130:133], v[194:197], v[110:113]
	v_mfma_f32_16x16x32_bf16 v[122:125], v[138:141], v[186:189], v[122:125]
	v_mfma_f32_16x16x32_bf16 v[78:81], v[130:133], v[210:213], v[78:81]
	v_mfma_f32_16x16x32_bf16 v[90:93], v[138:141], v[202:205], v[90:93]
	v_mfma_f32_16x16x32_bf16 v[126:129], v[134:137], v[190:193], v[126:129]
	v_mfma_f32_16x16x32_bf16 v[106:109], v[158:161], v[198:201], v[106:109]
	v_mfma_f32_16x16x32_bf16 v[94:97], v[134:137], v[206:209], v[94:97]
	v_mfma_f32_16x16x32_bf16 v[74:77], v[158:161], v[218:221], v[74:77]
	v_mfma_f32_16x16x32_bf16 v[110:113], v[134:137], v[198:201], v[110:113]
	v_mfma_f32_16x16x32_bf16 v[122:125], v[158:161], v[190:193], v[122:125]
	v_mfma_f32_16x16x32_bf16 v[78:81], v[134:137], v[218:221], v[78:81]
	v_mfma_f32_16x16x32_bf16 v[90:93], v[158:161], v[206:209], v[90:93]
	s_setprio 0
	s_setprio 1
	v_mfma_f32_16x16x32_bf16 v[118:121], v[162:165], v[186:189], v[118:121]
	v_mfma_f32_16x16x32_bf16 v[98:101], v[178:181], v[194:197], v[98:101]
	v_mfma_f32_16x16x32_bf16 v[86:89], v[162:165], v[202:205], v[86:89]
	v_mfma_f32_16x16x32_bf16 v[66:69], v[178:181], v[210:213], v[66:69]
	v_mfma_f32_16x16x32_bf16 v[102:105], v[162:165], v[194:197], v[102:105]
	v_mfma_f32_16x16x32_bf16 v[114:117], v[178:181], v[186:189], v[114:117]
	v_mfma_f32_16x16x32_bf16 v[70:73], v[162:165], v[210:213], v[70:73]
	v_mfma_f32_16x16x32_bf16 v[82:85], v[178:181], v[202:205], v[82:85]
	v_mfma_f32_16x16x32_bf16 v[118:121], v[166:169], v[190:193], v[118:121]
	v_mfma_f32_16x16x32_bf16 v[98:101], v[182:185], v[198:201], v[98:101]
	v_mfma_f32_16x16x32_bf16 v[86:89], v[166:169], v[206:209], v[86:89]
	v_mfma_f32_16x16x32_bf16 v[66:69], v[182:185], v[218:221], v[66:69]
	v_mfma_f32_16x16x32_bf16 v[102:105], v[166:169], v[198:201], v[102:105]
	v_mfma_f32_16x16x32_bf16 v[114:117], v[182:185], v[190:193], v[114:117]
	v_mfma_f32_16x16x32_bf16 v[70:73], v[166:169], v[218:221], v[70:73]
	v_mfma_f32_16x16x32_bf16 v[82:85], v[182:185], v[206:209], v[82:85]
	s_setprio 0
	s_barrier
	s_add_i32 s44, s61, s46
	v_lshl_add_u64 v[170:171], v[170:171], 0, s[12:13]
	s_mov_b32 m0, s44
	ds_read_b128 v[186:189], v176 offset:49152
	ds_read_b128 v[190:193], v176 offset:50176
	ds_read_b128 v[194:197], v176 offset:51200
	ds_read_b128 v[198:201], v176 offset:52224
	ds_read_b128 v[202:205], v176 offset:53248
	ds_read_b128 v[206:209], v176 offset:54272
	ds_read_b128 v[210:213], v176 offset:55296
	ds_read_b128 v[218:221], v176 offset:56320
	global_load_lds_dwordx4 v[170:171], off
	s_add_i32 m0, s44, 0x2000
	s_add_u32 s34, s34, 0x80080
	v_lshl_add_u64 v[170:171], v[214:215], 0, s[12:13]
	s_addc_u32 s35, s35, 0
	s_add_i32 s44, s62, s46
	global_load_lds_dwordx4 v[170:171], off
	v_lshl_add_u64 v[170:171], s[34:35], 0, v[144:145]
	s_mov_b32 m0, s44
	s_nop 0
	global_load_lds_dwordx4 v[170:171], off
	v_lshl_add_u64 v[170:171], s[34:35], 0, v[148:149]
	s_add_i32 m0, s44, 0x2000
	s_nop 0
	global_load_lds_dwordx4 v[170:171], off
	v_lshl_add_u64 v[170:171], v[222:223], 0, s[12:13]
	s_mov_b32 m0, s51
	s_nop 0
	global_load_lds_dwordx4 v[170:171], off
	v_lshl_add_u64 v[170:171], v[224:225], 0, s[12:13]
	s_mov_b32 m0, s52
	s_nop 0
	global_load_lds_dwordx4 v[170:171], off
	s_waitcnt vmcnt(8)
	s_waitcnt lgkmcnt(0)
	s_barrier
	s_setprio 1
	s_waitcnt lgkmcnt(0)
	v_mfma_f32_16x16x32_bf16 v[62:65], v[130:133], v[186:189], v[62:65]
	v_mfma_f32_16x16x32_bf16 v[42:45], v[138:141], v[194:197], v[42:45]
	v_mfma_f32_16x16x32_bf16 v[38:41], v[130:133], v[202:205], v[38:41]
	v_mfma_f32_16x16x32_bf16 v[10:13], v[138:141], v[210:213], v[10:13]
	v_mfma_f32_16x16x32_bf16 v[50:53], v[130:133], v[194:197], v[50:53]
	v_mfma_f32_16x16x32_bf16 v[58:61], v[138:141], v[186:189], v[58:61]
	v_mfma_f32_16x16x32_bf16 v[14:17], v[130:133], v[210:213], v[14:17]
	v_mfma_f32_16x16x32_bf16 v[34:37], v[138:141], v[202:205], v[34:37]
	v_mfma_f32_16x16x32_bf16 v[62:65], v[134:137], v[190:193], v[62:65]
	v_mfma_f32_16x16x32_bf16 v[42:45], v[158:161], v[198:201], v[42:45]
	v_mfma_f32_16x16x32_bf16 v[38:41], v[134:137], v[206:209], v[38:41]
	v_mfma_f32_16x16x32_bf16 v[10:13], v[158:161], v[218:221], v[10:13]
	v_mfma_f32_16x16x32_bf16 v[50:53], v[134:137], v[198:201], v[50:53]
	v_mfma_f32_16x16x32_bf16 v[58:61], v[158:161], v[190:193], v[58:61]
	v_mfma_f32_16x16x32_bf16 v[14:17], v[134:137], v[218:221], v[14:17]
	v_mfma_f32_16x16x32_bf16 v[34:37], v[158:161], v[206:209], v[34:37]
	s_setprio 0
	s_setprio 1
	v_mfma_f32_16x16x32_bf16 v[54:57], v[162:165], v[186:189], v[54:57]
	v_mfma_f32_16x16x32_bf16 v[26:29], v[178:181], v[194:197], v[26:29]
	v_mfma_f32_16x16x32_bf16 v[22:25], v[162:165], v[202:205], v[22:25]
	v_mfma_f32_16x16x32_bf16 v[2:5], v[178:181], v[210:213], v[2:5]
	v_mfma_f32_16x16x32_bf16 v[30:33], v[162:165], v[194:197], v[30:33]
	v_mfma_f32_16x16x32_bf16 v[46:49], v[178:181], v[186:189], v[46:49]
	v_mfma_f32_16x16x32_bf16 v[6:9], v[162:165], v[210:213], v[6:9]
	v_mfma_f32_16x16x32_bf16 v[18:21], v[178:181], v[202:205], v[18:21]
	v_mfma_f32_16x16x32_bf16 v[54:57], v[166:169], v[190:193], v[54:57]
	v_mfma_f32_16x16x32_bf16 v[26:29], v[182:185], v[198:201], v[26:29]
	v_mfma_f32_16x16x32_bf16 v[22:25], v[166:169], v[206:209], v[22:25]
	v_mfma_f32_16x16x32_bf16 v[2:5], v[182:185], v[218:221], v[2:5]
	v_mfma_f32_16x16x32_bf16 v[30:33], v[166:169], v[198:201], v[30:33]
	v_mfma_f32_16x16x32_bf16 v[46:49], v[182:185], v[190:193], v[46:49]
	v_mfma_f32_16x16x32_bf16 v[6:9], v[166:169], v[218:221], v[6:9]
	v_mfma_f32_16x16x32_bf16 v[18:21], v[182:185], v[206:209], v[18:21]
	s_setprio 0
	s_barrier
	s_add_i32 s60, s60, 2
	s_add_u32 s42, s42, 0x100
	s_addc_u32 s43, s43, 0
	s_add_u32 s58, s58, 0x100
	s_addc_u32 s59, s59, 0
	s_cmp_gt_u32 s60, 29
	s_cbranch_scc0 .LBB0_3706
	s_and_b64 vcc, exec, s[14:15]
	s_cbranch_vccz .LBB0_3709
	s_barrier

.LBB0_3835:
	ds_read_b128 v[146:149], v153
	ds_read_b128 v[156:159], v153 offset:1024
	ds_read_b128 v[160:163], v153 offset:2048
	ds_read_b128 v[164:167], v153 offset:3072
	ds_read_b128 v[168:171], v154
	ds_read_b128 v[172:175], v154 offset:1024
	ds_read_b128 v[176:179], v154 offset:2048
	ds_read_b128 v[180:183], v154 offset:3072
	s_add_u32 s34, s38, 0xfff80080
	s_addc_u32 s35, s39, -1
	s_cmp_eq_u32 s57, 28
	s_cselect_b32 s41, s0, s35
	s_cselect_b32 s40, s1, s34
	s_cselect_b32 s35, s15, s56
	s_cselect_b32 s34, s17, s55
	v_lshl_add_u64 v[218:219], s[38:39], 0, v[138:139]
	s_add_i32 m0, s37, 0xc000
	ds_read_b128 v[184:187], v155
	ds_read_b128 v[188:191], v155 offset:1024
	ds_read_b128 v[192:195], v155 offset:2048
	ds_read_b128 v[196:199], v155 offset:3072
	ds_read_b128 v[200:203], v155 offset:4096
	ds_read_b128 v[204:207], v155 offset:5120
	ds_read_b128 v[208:211], v155 offset:6144
	ds_read_b128 v[212:215], v155 offset:7168
	global_load_lds_dwordx4 v[218:219], off
	v_lshl_add_u64 v[218:219], s[38:39], 0, v[140:141]
	s_add_i32 m0, s37, 0xe000
	s_nop 0
	global_load_lds_dwordx4 v[218:219], off
	s_waitcnt vmcnt(8)
	s_waitcnt lgkmcnt(0)
	s_barrier
	s_setprio 1
	s_waitcnt lgkmcnt(0)
	v_mfma_f32_16x16x32_bf16 v[126:129], v[146:149], v[184:187], v[126:129]
	v_mfma_f32_16x16x32_bf16 v[102:105], v[160:163], v[192:195], v[102:105]
	v_mfma_f32_16x16x32_bf16 v[94:97], v[146:149], v[200:203], v[94:97]
	v_mfma_f32_16x16x32_bf16 v[70:73], v[160:163], v[208:211], v[70:73]
	v_mfma_f32_16x16x32_bf16 v[110:113], v[146:149], v[192:195], v[110:113]
	v_mfma_f32_16x16x32_bf16 v[118:121], v[160:163], v[184:187], v[118:121]
	v_mfma_f32_16x16x32_bf16 v[78:81], v[146:149], v[208:211], v[78:81]
	v_mfma_f32_16x16x32_bf16 v[86:89], v[160:163], v[200:203], v[86:89]
	v_mfma_f32_16x16x32_bf16 v[126:129], v[156:159], v[188:191], v[126:129]
	v_mfma_f32_16x16x32_bf16 v[102:105], v[164:167], v[196:199], v[102:105]
	v_mfma_f32_16x16x32_bf16 v[94:97], v[156:159], v[204:207], v[94:97]
	v_mfma_f32_16x16x32_bf16 v[70:73], v[164:167], v[212:215], v[70:73]
	v_mfma_f32_16x16x32_bf16 v[110:113], v[156:159], v[196:199], v[110:113]
	v_mfma_f32_16x16x32_bf16 v[118:121], v[164:167], v[188:191], v[118:121]
	v_mfma_f32_16x16x32_bf16 v[78:81], v[156:159], v[212:215], v[78:81]
	v_mfma_f32_16x16x32_bf16 v[86:89], v[164:167], v[204:207], v[86:89]
	s_setprio 0
	s_setprio 1
	v_mfma_f32_16x16x32_bf16 v[122:125], v[168:171], v[184:187], v[122:125]
	v_mfma_f32_16x16x32_bf16 v[98:101], v[176:179], v[192:195], v[98:101]
	v_mfma_f32_16x16x32_bf16 v[90:93], v[168:171], v[200:203], v[90:93]
	v_mfma_f32_16x16x32_bf16 v[66:69], v[176:179], v[208:211], v[66:69]
	v_mfma_f32_16x16x32_bf16 v[106:109], v[168:171], v[192:195], v[106:109]
	v_mfma_f32_16x16x32_bf16 v[114:117], v[176:179], v[184:187], v[114:117]
	v_mfma_f32_16x16x32_bf16 v[74:77], v[168:171], v[208:211], v[74:77]
	v_mfma_f32_16x16x32_bf16 v[82:85], v[176:179], v[200:203], v[82:85]
	v_mfma_f32_16x16x32_bf16 v[122:125], v[172:175], v[188:191], v[122:125]
	v_mfma_f32_16x16x32_bf16 v[98:101], v[180:183], v[196:199], v[98:101]
	v_mfma_f32_16x16x32_bf16 v[90:93], v[172:175], v[204:207], v[90:93]
	v_mfma_f32_16x16x32_bf16 v[66:69], v[180:183], v[212:215], v[66:69]
	v_mfma_f32_16x16x32_bf16 v[106:109], v[172:175], v[196:199], v[106:109]
	v_mfma_f32_16x16x32_bf16 v[114:117], v[180:183], v[188:191], v[114:117]
	v_mfma_f32_16x16x32_bf16 v[74:77], v[172:175], v[212:215], v[74:77]
	v_mfma_f32_16x16x32_bf16 v[82:85], v[180:183], v[204:207], v[82:85]
	s_setprio 0
	s_barrier
	s_add_i32 s58, s51, s33
	v_lshl_add_u64 v[218:219], s[34:35], 0, v[134:135]
	s_mov_b32 m0, s58
	ds_read_b128 v[184:187], v155 offset:16384
	ds_read_b128 v[188:191], v155 offset:17408
	ds_read_b128 v[192:195], v155 offset:18432
	ds_read_b128 v[196:199], v155 offset:19456
	ds_read_b128 v[200:203], v155 offset:20480
	ds_read_b128 v[204:207], v155 offset:21504
	ds_read_b128 v[208:211], v155 offset:22528
	ds_read_b128 v[212:215], v155 offset:23552
	global_load_lds_dwordx4 v[218:219], off
	s_add_i32 m0, s58, 0x2000
	s_add_u32 s58, s34, 0x80000
	v_lshl_add_u64 v[220:221], s[34:35], 0, v[130:131]
	s_addc_u32 s59, s35, 0
	s_add_i32 s60, s52, s33
	global_load_lds_dwordx4 v[220:221], off
	v_lshl_add_u64 v[222:223], s[58:59], 0, v[134:135]
	s_mov_b32 m0, s60
	v_lshl_add_u64 v[224:225], s[40:41], 0, v[132:133]
	global_load_lds_dwordx4 v[222:223], off
	v_lshl_add_u64 v[222:223], s[58:59], 0, v[130:131]
	s_add_i32 m0, s60, 0x2000
	s_nop 0
	global_load_lds_dwordx4 v[222:223], off
	v_lshl_add_u64 v[222:223], s[40:41], 0, v[136:137]
	s_mov_b32 m0, s37
	s_nop 0
	global_load_lds_dwordx4 v[222:223], off
	s_mov_b32 m0, s44
	s_nop 0
	global_load_lds_dwordx4 v[224:225], off
	s_waitcnt vmcnt(8)
	s_waitcnt lgkmcnt(0)
	s_barrier
	s_setprio 1
	s_waitcnt lgkmcnt(0)
	v_mfma_f32_16x16x32_bf16 v[62:65], v[146:149], v[184:187], v[62:65]
	v_mfma_f32_16x16x32_bf16 v[38:41], v[160:163], v[192:195], v[38:41]
	v_mfma_f32_16x16x32_bf16 v[30:33], v[146:149], v[200:203], v[30:33]
	v_mfma_f32_16x16x32_bf16 v[6:9], v[160:163], v[208:211], v[6:9]
	v_mfma_f32_16x16x32_bf16 v[46:49], v[146:149], v[192:195], v[46:49]
	v_mfma_f32_16x16x32_bf16 v[54:57], v[160:163], v[184:187], v[54:57]
	v_mfma_f32_16x16x32_bf16 v[14:17], v[146:149], v[208:211], v[14:17]
	v_mfma_f32_16x16x32_bf16 v[22:25], v[160:163], v[200:203], v[22:25]
	v_mfma_f32_16x16x32_bf16 v[62:65], v[156:159], v[188:191], v[62:65]
	v_mfma_f32_16x16x32_bf16 v[38:41], v[164:167], v[196:199], v[38:41]
	v_mfma_f32_16x16x32_bf16 v[30:33], v[156:159], v[204:207], v[30:33]
	v_mfma_f32_16x16x32_bf16 v[6:9], v[164:167], v[212:215], v[6:9]
	v_mfma_f32_16x16x32_bf16 v[46:49], v[156:159], v[196:199], v[46:49]
	v_mfma_f32_16x16x32_bf16 v[54:57], v[164:167], v[188:191], v[54:57]
	v_mfma_f32_16x16x32_bf16 v[14:17], v[156:159], v[212:215], v[14:17]
	v_mfma_f32_16x16x32_bf16 v[22:25], v[164:167], v[204:207], v[22:25]
	s_setprio 0
	s_setprio 1
	v_mfma_f32_16x16x32_bf16 v[58:61], v[168:171], v[184:187], v[58:61]
	v_mfma_f32_16x16x32_bf16 v[34:37], v[176:179], v[192:195], v[34:37]
	v_mfma_f32_16x16x32_bf16 v[26:29], v[168:171], v[200:203], v[26:29]
	v_mfma_f32_16x16x32_bf16 v[2:5], v[176:179], v[208:211], v[2:5]
	v_mfma_f32_16x16x32_bf16 v[42:45], v[168:171], v[192:195], v[42:45]
	v_mfma_f32_16x16x32_bf16 v[50:53], v[176:179], v[184:187], v[50:53]
	v_mfma_f32_16x16x32_bf16 v[10:13], v[168:171], v[208:211], v[10:13]
	v_mfma_f32_16x16x32_bf16 v[18:21], v[176:179], v[200:203], v[18:21]
	v_mfma_f32_16x16x32_bf16 v[58:61], v[172:175], v[188:191], v[58:61]
	v_mfma_f32_16x16x32_bf16 v[34:37], v[180:183], v[196:199], v[34:37]
	v_mfma_f32_16x16x32_bf16 v[26:29], v[172:175], v[204:207], v[26:29]
	v_mfma_f32_16x16x32_bf16 v[2:5], v[180:183], v[212:215], v[2:5]
	v_mfma_f32_16x16x32_bf16 v[42:45], v[172:175], v[196:199], v[42:45]
	v_mfma_f32_16x16x32_bf16 v[50:53], v[180:183], v[188:191], v[50:53]
	v_mfma_f32_16x16x32_bf16 v[10:13], v[172:175], v[212:215], v[10:13]
	v_mfma_f32_16x16x32_bf16 v[18:21], v[180:183], v[204:207], v[18:21]
	s_setprio 0
	s_barrier
	s_add_i32 s58, 0, 0x18000
	s_add_i32 s59, 0, 0x1c000
	v_add_u32_e32 v164, s58, v151
	v_add_u32_e32 v180, s59, v151
	ds_read_b128 v[146:149], v164
	ds_read_b128 v[156:159], v164 offset:1024
	ds_read_b128 v[160:163], v164 offset:2048
	ds_read_b128 v[164:167], v164 offset:3072
	ds_read_b128 v[168:171], v180
	ds_read_b128 v[172:175], v180 offset:1024
	ds_read_b128 v[176:179], v180 offset:2048
	ds_read_b128 v[180:183], v180 offset:3072
	s_add_u32 s40, s40, 0x80000
	s_addc_u32 s41, s41, 0
	s_mov_b32 m0, s45
	v_lshl_add_u64 v[226:227], s[40:41], 0, v[136:137]
	ds_read_b128 v[184:187], v155 offset:32768
	ds_read_b128 v[188:191], v155 offset:33792
	ds_read_b128 v[192:195], v155 offset:34816
	ds_read_b128 v[196:199], v155 offset:35840
	ds_read_b128 v[200:203], v155 offset:36864
	ds_read_b128 v[204:207], v155 offset:37888
	ds_read_b128 v[208:211], v155 offset:38912
	ds_read_b128 v[212:215], v155 offset:39936
	global_load_lds_dwordx4 v[226:227], off
	v_lshl_add_u64 v[226:227], s[40:41], 0, v[132:133]
	s_mov_b32 m0, s46
	s_nop 0
	global_load_lds_dwordx4 v[226:227], off
	s_waitcnt vmcnt(8)
	s_waitcnt lgkmcnt(0)
	s_barrier
	s_setprio 1
	s_waitcnt lgkmcnt(0)
	v_mfma_f32_16x16x32_bf16 v[126:129], v[146:149], v[184:187], v[126:129]
	v_mfma_f32_16x16x32_bf16 v[102:105], v[160:163], v[192:195], v[102:105]
	v_mfma_f32_16x16x32_bf16 v[94:97], v[146:149], v[200:203], v[94:97]
	v_mfma_f32_16x16x32_bf16 v[70:73], v[160:163], v[208:211], v[70:73]
	v_mfma_f32_16x16x32_bf16 v[110:113], v[146:149], v[192:195], v[110:113]
	v_mfma_f32_16x16x32_bf16 v[118:121], v[160:163], v[184:187], v[118:121]
	v_mfma_f32_16x16x32_bf16 v[78:81], v[146:149], v[208:211], v[78:81]
	v_mfma_f32_16x16x32_bf16 v[86:89], v[160:163], v[200:203], v[86:89]
	v_mfma_f32_16x16x32_bf16 v[126:129], v[156:159], v[188:191], v[126:129]
	v_mfma_f32_16x16x32_bf16 v[102:105], v[164:167], v[196:199], v[102:105]
	v_mfma_f32_16x16x32_bf16 v[94:97], v[156:159], v[204:207], v[94:97]
	v_mfma_f32_16x16x32_bf16 v[70:73], v[164:167], v[212:215], v[70:73]
	v_mfma_f32_16x16x32_bf16 v[110:113], v[156:159], v[196:199], v[110:113]
	v_mfma_f32_16x16x32_bf16 v[118:121], v[164:167], v[188:191], v[118:121]
	v_mfma_f32_16x16x32_bf16 v[78:81], v[156:159], v[212:215], v[78:81]
	v_mfma_f32_16x16x32_bf16 v[86:89], v[164:167], v[204:207], v[86:89]
	s_setprio 0
	s_setprio 1
	v_mfma_f32_16x16x32_bf16 v[122:125], v[168:171], v[184:187], v[122:125]
	v_mfma_f32_16x16x32_bf16 v[98:101], v[176:179], v[192:195], v[98:101]
	v_mfma_f32_16x16x32_bf16 v[90:93], v[168:171], v[200:203], v[90:93]
	v_mfma_f32_16x16x32_bf16 v[66:69], v[176:179], v[208:211], v[66:69]
	v_mfma_f32_16x16x32_bf16 v[106:109], v[168:171], v[192:195], v[106:109]
	v_mfma_f32_16x16x32_bf16 v[114:117], v[176:179], v[184:187], v[114:117]
	v_mfma_f32_16x16x32_bf16 v[74:77], v[168:171], v[208:211], v[74:77]
	v_mfma_f32_16x16x32_bf16 v[82:85], v[176:179], v[200:203], v[82:85]
	v_mfma_f32_16x16x32_bf16 v[122:125], v[172:175], v[188:191], v[122:125]
	v_mfma_f32_16x16x32_bf16 v[98:101], v[180:183], v[196:199], v[98:101]
	v_mfma_f32_16x16x32_bf16 v[90:93], v[172:175], v[204:207], v[90:93]
	v_mfma_f32_16x16x32_bf16 v[66:69], v[180:183], v[212:215], v[66:69]
	v_mfma_f32_16x16x32_bf16 v[106:109], v[172:175], v[196:199], v[106:109]
	v_mfma_f32_16x16x32_bf16 v[114:117], v[180:183], v[188:191], v[114:117]
	v_mfma_f32_16x16x32_bf16 v[74:77], v[172:175], v[212:215], v[74:77]
	v_mfma_f32_16x16x32_bf16 v[82:85], v[180:183], v[204:207], v[82:85]
	s_setprio 0
	s_barrier
	s_add_i32 s40, s58, s33
	v_lshl_add_u64 v[218:219], v[218:219], 0, s[8:9]
	s_mov_b32 m0, s40
	ds_read_b128 v[184:187], v155 offset:49152
	ds_read_b128 v[188:191], v155 offset:50176
	ds_read_b128 v[192:195], v155 offset:51200
	ds_read_b128 v[196:199], v155 offset:52224
	ds_read_b128 v[200:203], v155 offset:53248
	ds_read_b128 v[204:207], v155 offset:54272
	ds_read_b128 v[208:211], v155 offset:55296
	ds_read_b128 v[212:215], v155 offset:56320
	global_load_lds_dwordx4 v[218:219], off
	s_add_i32 m0, s40, 0x2000
	s_add_u32 s34, s34, 0x80080
	v_lshl_add_u64 v[218:219], v[220:221], 0, s[8:9]
	s_addc_u32 s35, s35, 0
	s_add_i32 s40, s59, s33
	global_load_lds_dwordx4 v[218:219], off
	v_lshl_add_u64 v[218:219], s[34:35], 0, v[134:135]
	s_mov_b32 m0, s40
	s_nop 0
	global_load_lds_dwordx4 v[218:219], off
	v_lshl_add_u64 v[218:219], s[34:35], 0, v[130:131]
	s_add_i32 m0, s40, 0x2000
	s_nop 0
	global_load_lds_dwordx4 v[218:219], off
	v_lshl_add_u64 v[218:219], v[222:223], 0, s[8:9]
	s_mov_b32 m0, s48
	s_nop 0
	global_load_lds_dwordx4 v[218:219], off
	v_lshl_add_u64 v[218:219], v[224:225], 0, s[8:9]
	s_mov_b32 m0, s49
	s_nop 0
	global_load_lds_dwordx4 v[218:219], off
	s_waitcnt vmcnt(8)
	s_waitcnt lgkmcnt(0)
	s_barrier
	s_setprio 1
	s_waitcnt lgkmcnt(0)
	v_mfma_f32_16x16x32_bf16 v[62:65], v[146:149], v[184:187], v[62:65]
	v_mfma_f32_16x16x32_bf16 v[38:41], v[160:163], v[192:195], v[38:41]
	v_mfma_f32_16x16x32_bf16 v[30:33], v[146:149], v[200:203], v[30:33]
	v_mfma_f32_16x16x32_bf16 v[6:9], v[160:163], v[208:211], v[6:9]
	v_mfma_f32_16x16x32_bf16 v[46:49], v[146:149], v[192:195], v[46:49]
	v_mfma_f32_16x16x32_bf16 v[54:57], v[160:163], v[184:187], v[54:57]
	v_mfma_f32_16x16x32_bf16 v[14:17], v[146:149], v[208:211], v[14:17]
	v_mfma_f32_16x16x32_bf16 v[22:25], v[160:163], v[200:203], v[22:25]
	v_mfma_f32_16x16x32_bf16 v[62:65], v[156:159], v[188:191], v[62:65]
	v_mfma_f32_16x16x32_bf16 v[38:41], v[164:167], v[196:199], v[38:41]
	v_mfma_f32_16x16x32_bf16 v[30:33], v[156:159], v[204:207], v[30:33]
	v_mfma_f32_16x16x32_bf16 v[6:9], v[164:167], v[212:215], v[6:9]
	v_mfma_f32_16x16x32_bf16 v[46:49], v[156:159], v[196:199], v[46:49]
	v_mfma_f32_16x16x32_bf16 v[54:57], v[164:167], v[188:191], v[54:57]
	v_mfma_f32_16x16x32_bf16 v[14:17], v[156:159], v[212:215], v[14:17]
	v_mfma_f32_16x16x32_bf16 v[22:25], v[164:167], v[204:207], v[22:25]
	s_setprio 0
	s_setprio 1
	v_mfma_f32_16x16x32_bf16 v[58:61], v[168:171], v[184:187], v[58:61]
	v_mfma_f32_16x16x32_bf16 v[34:37], v[176:179], v[192:195], v[34:37]
	v_mfma_f32_16x16x32_bf16 v[26:29], v[168:171], v[200:203], v[26:29]
	v_mfma_f32_16x16x32_bf16 v[2:5], v[176:179], v[208:211], v[2:5]
	v_mfma_f32_16x16x32_bf16 v[42:45], v[168:171], v[192:195], v[42:45]
	v_mfma_f32_16x16x32_bf16 v[50:53], v[176:179], v[184:187], v[50:53]
	v_mfma_f32_16x16x32_bf16 v[10:13], v[168:171], v[208:211], v[10:13]
	v_mfma_f32_16x16x32_bf16 v[18:21], v[176:179], v[200:203], v[18:21]
	v_mfma_f32_16x16x32_bf16 v[58:61], v[172:175], v[188:191], v[58:61]
	v_mfma_f32_16x16x32_bf16 v[34:37], v[180:183], v[196:199], v[34:37]
	v_mfma_f32_16x16x32_bf16 v[26:29], v[172:175], v[204:207], v[26:29]
	v_mfma_f32_16x16x32_bf16 v[2:5], v[180:183], v[212:215], v[2:5]
	v_mfma_f32_16x16x32_bf16 v[42:45], v[172:175], v[196:199], v[42:45]
	v_mfma_f32_16x16x32_bf16 v[50:53], v[180:183], v[188:191], v[50:53]
	v_mfma_f32_16x16x32_bf16 v[10:13], v[172:175], v[212:215], v[10:13]
	v_mfma_f32_16x16x32_bf16 v[18:21], v[180:183], v[204:207], v[18:21]
	s_setprio 0
	s_barrier
	s_add_i32 s57, s57, 2
	s_add_u32 s38, s38, 0x100
	s_addc_u32 s39, s39, 0
	s_add_u32 s55, s55, 0x100
	s_addc_u32 s56, s56, 0
	s_cmp_gt_u32 s57, 29
	s_cbranch_scc0 .LBB0_3835
	v_mov_b32_e32 v160, 0xbfb8aa3b
	s_and_b64 vcc, exec, s[12:13]
	s_cbranch_vccz .LBB0_3838
	s_barrier

.LBB0_3930:
	ds_read_b128 v[144:147], v155
	ds_read_b128 v[148:151], v155 offset:1024
	ds_read_b128 v[158:161], v155 offset:2048
	ds_read_b128 v[162:165], v155 offset:3072
	ds_read_b128 v[166:169], v156
	ds_read_b128 v[170:173], v156 offset:1024
	ds_read_b128 v[174:177], v156 offset:2048
	ds_read_b128 v[178:181], v156 offset:3072
	s_add_u32 s20, s18, 0xffea0080
	s_addc_u32 s21, s19, -1
	s_cmpk_eq_i32 s45, 0x54
	s_cselect_b32 s23, s5, s21
	s_cselect_b32 s22, s4, s20
	s_cselect_b32 s21, s17, s1
	s_cselect_b32 s20, s16, s0
	v_lshl_add_u64 v[214:215], s[18:19], 0, v[136:137]
	s_add_i32 m0, s30, 0xc000
	ds_read_b128 v[182:185], v157
	ds_read_b128 v[186:189], v157 offset:1024
	ds_read_b128 v[190:193], v157 offset:2048
	ds_read_b128 v[194:197], v157 offset:3072
	ds_read_b128 v[198:201], v157 offset:4096
	ds_read_b128 v[202:205], v157 offset:5120
	ds_read_b128 v[206:209], v157 offset:6144
	ds_read_b128 v[210:213], v157 offset:7168
	global_load_lds_dwordx4 v[214:215], off
	v_lshl_add_u64 v[214:215], s[18:19], 0, v[138:139]
	s_add_i32 m0, s30, 0xe000
	s_nop 0
	global_load_lds_dwordx4 v[214:215], off
	s_waitcnt vmcnt(8)
	s_waitcnt lgkmcnt(0)
	s_barrier
	s_setprio 1
	s_waitcnt lgkmcnt(0)
	v_mfma_f32_16x16x32_bf16 v[124:127], v[144:147], v[182:185], v[124:127]
	v_mfma_f32_16x16x32_bf16 v[112:115], v[158:161], v[190:193], v[112:115]
	v_mfma_f32_16x16x32_bf16 v[92:95], v[144:147], v[198:201], v[92:95]
	v_mfma_f32_16x16x32_bf16 v[80:83], v[158:161], v[206:209], v[80:83]
	v_mfma_f32_16x16x32_bf16 v[116:119], v[144:147], v[190:193], v[116:119]
	v_mfma_f32_16x16x32_bf16 v[120:123], v[158:161], v[182:185], v[120:123]
	v_mfma_f32_16x16x32_bf16 v[84:87], v[144:147], v[206:209], v[84:87]
	v_mfma_f32_16x16x32_bf16 v[88:91], v[158:161], v[198:201], v[88:91]
	v_mfma_f32_16x16x32_bf16 v[124:127], v[148:151], v[186:189], v[124:127]
	v_mfma_f32_16x16x32_bf16 v[112:115], v[162:165], v[194:197], v[112:115]
	v_mfma_f32_16x16x32_bf16 v[92:95], v[148:151], v[202:205], v[92:95]
	v_mfma_f32_16x16x32_bf16 v[80:83], v[162:165], v[210:213], v[80:83]
	v_mfma_f32_16x16x32_bf16 v[116:119], v[148:151], v[194:197], v[116:119]
	v_mfma_f32_16x16x32_bf16 v[120:123], v[162:165], v[186:189], v[120:123]
	v_mfma_f32_16x16x32_bf16 v[84:87], v[148:151], v[210:213], v[84:87]
	v_mfma_f32_16x16x32_bf16 v[88:91], v[162:165], v[202:205], v[88:91]
	s_setprio 0
	s_setprio 1
	v_mfma_f32_16x16x32_bf16 v[108:111], v[166:169], v[182:185], v[108:111]
	v_mfma_f32_16x16x32_bf16 v[96:99], v[174:177], v[190:193], v[96:99]
	v_mfma_f32_16x16x32_bf16 v[76:79], v[166:169], v[198:201], v[76:79]
	v_mfma_f32_16x16x32_bf16 v[64:67], v[174:177], v[206:209], v[64:67]
	v_mfma_f32_16x16x32_bf16 v[100:103], v[166:169], v[190:193], v[100:103]
	v_mfma_f32_16x16x32_bf16 v[104:107], v[174:177], v[182:185], v[104:107]
	v_mfma_f32_16x16x32_bf16 v[68:71], v[166:169], v[206:209], v[68:71]
	v_mfma_f32_16x16x32_bf16 v[72:75], v[174:177], v[198:201], v[72:75]
	v_mfma_f32_16x16x32_bf16 v[108:111], v[170:173], v[186:189], v[108:111]
	v_mfma_f32_16x16x32_bf16 v[96:99], v[178:181], v[194:197], v[96:99]
	v_mfma_f32_16x16x32_bf16 v[76:79], v[170:173], v[202:205], v[76:79]
	v_mfma_f32_16x16x32_bf16 v[64:67], v[178:181], v[210:213], v[64:67]
	v_mfma_f32_16x16x32_bf16 v[100:103], v[170:173], v[194:197], v[100:103]
	v_mfma_f32_16x16x32_bf16 v[104:107], v[178:181], v[186:189], v[104:107]
	v_mfma_f32_16x16x32_bf16 v[68:71], v[170:173], v[210:213], v[68:71]
	v_mfma_f32_16x16x32_bf16 v[72:75], v[178:181], v[202:205], v[72:75]
	s_setprio 0
	s_barrier
	s_add_i32 s46, s39, s27
	v_lshl_add_u64 v[214:215], s[20:21], 0, v[130:131]
	s_mov_b32 m0, s46
	ds_read_b128 v[182:185], v157 offset:16384
	ds_read_b128 v[186:189], v157 offset:17408
	ds_read_b128 v[190:193], v157 offset:18432
	ds_read_b128 v[194:197], v157 offset:19456
	ds_read_b128 v[198:201], v157 offset:20480
	ds_read_b128 v[202:205], v157 offset:21504
	ds_read_b128 v[206:209], v157 offset:22528
	ds_read_b128 v[210:213], v157 offset:23552
	global_load_lds_dwordx4 v[214:215], off
	s_add_i32 m0, s46, 0x2000
	s_add_u32 s46, s20, 0x160000
	v_lshl_add_u64 v[216:217], s[20:21], 0, v[134:135]
	s_addc_u32 s47, s21, 0
	s_add_i32 s48, s40, s27
	global_load_lds_dwordx4 v[216:217], off
	v_lshl_add_u64 v[218:219], s[46:47], 0, v[130:131]
	s_mov_b32 m0, s48
	v_lshl_add_u64 v[220:221], s[22:23], 0, v[132:133]
	global_load_lds_dwordx4 v[218:219], off
	v_lshl_add_u64 v[218:219], s[46:47], 0, v[134:135]
	s_add_i32 m0, s48, 0x2000
	s_nop 0
	global_load_lds_dwordx4 v[218:219], off
	v_lshl_add_u64 v[218:219], s[22:23], 0, v[128:129]
	s_mov_b32 m0, s30
	s_nop 0
	global_load_lds_dwordx4 v[218:219], off
	s_mov_b32 m0, s31
	s_nop 0
	global_load_lds_dwordx4 v[220:221], off
	s_waitcnt vmcnt(8)
	s_waitcnt lgkmcnt(0)
	s_barrier
	s_setprio 1
	s_waitcnt lgkmcnt(0)
	v_mfma_f32_16x16x32_bf16 v[60:63], v[144:147], v[182:185], v[60:63]
	v_mfma_f32_16x16x32_bf16 v[48:51], v[158:161], v[190:193], v[48:51]
	v_mfma_f32_16x16x32_bf16 v[28:31], v[144:147], v[198:201], v[28:31]
	v_mfma_f32_16x16x32_bf16 v[16:19], v[158:161], v[206:209], v[16:19]
	v_mfma_f32_16x16x32_bf16 v[52:55], v[144:147], v[190:193], v[52:55]
	v_mfma_f32_16x16x32_bf16 v[56:59], v[158:161], v[182:185], v[56:59]
	v_mfma_f32_16x16x32_bf16 v[20:23], v[144:147], v[206:209], v[20:23]
	v_mfma_f32_16x16x32_bf16 v[24:27], v[158:161], v[198:201], v[24:27]
	v_mfma_f32_16x16x32_bf16 v[60:63], v[148:151], v[186:189], v[60:63]
	v_mfma_f32_16x16x32_bf16 v[48:51], v[162:165], v[194:197], v[48:51]
	v_mfma_f32_16x16x32_bf16 v[28:31], v[148:151], v[202:205], v[28:31]
	v_mfma_f32_16x16x32_bf16 v[16:19], v[162:165], v[210:213], v[16:19]
	v_mfma_f32_16x16x32_bf16 v[52:55], v[148:151], v[194:197], v[52:55]
	v_mfma_f32_16x16x32_bf16 v[56:59], v[162:165], v[186:189], v[56:59]
	v_mfma_f32_16x16x32_bf16 v[20:23], v[148:151], v[210:213], v[20:23]
	v_mfma_f32_16x16x32_bf16 v[24:27], v[162:165], v[202:205], v[24:27]
	s_setprio 0
	s_setprio 1
	v_mfma_f32_16x16x32_bf16 v[44:47], v[166:169], v[182:185], v[44:47]
	v_mfma_f32_16x16x32_bf16 v[32:35], v[174:177], v[190:193], v[32:35]
	v_mfma_f32_16x16x32_bf16 v[12:15], v[166:169], v[198:201], v[12:15]
	v_mfma_f32_16x16x32_bf16 v[0:3], v[174:177], v[206:209], v[0:3]
	v_mfma_f32_16x16x32_bf16 v[36:39], v[166:169], v[190:193], v[36:39]
	v_mfma_f32_16x16x32_bf16 v[40:43], v[174:177], v[182:185], v[40:43]
	v_mfma_f32_16x16x32_bf16 v[4:7], v[166:169], v[206:209], v[4:7]
	v_mfma_f32_16x16x32_bf16 v[8:11], v[174:177], v[198:201], v[8:11]
	v_mfma_f32_16x16x32_bf16 v[44:47], v[170:173], v[186:189], v[44:47]
	v_mfma_f32_16x16x32_bf16 v[32:35], v[178:181], v[194:197], v[32:35]
	v_mfma_f32_16x16x32_bf16 v[12:15], v[170:173], v[202:205], v[12:15]
	v_mfma_f32_16x16x32_bf16 v[0:3], v[178:181], v[210:213], v[0:3]
	v_mfma_f32_16x16x32_bf16 v[36:39], v[170:173], v[194:197], v[36:39]
	v_mfma_f32_16x16x32_bf16 v[40:43], v[178:181], v[186:189], v[40:43]
	v_mfma_f32_16x16x32_bf16 v[4:7], v[170:173], v[210:213], v[4:7]
	v_mfma_f32_16x16x32_bf16 v[8:11], v[178:181], v[202:205], v[8:11]
	s_setprio 0
	s_barrier
	s_add_i32 s46, 0, 0x18000
	s_add_i32 s47, 0, 0x1c000
	v_add_u32_e32 v162, s46, v153
	v_add_u32_e32 v178, s47, v153
	ds_read_b128 v[144:147], v162
	ds_read_b128 v[148:151], v162 offset:1024
	ds_read_b128 v[158:161], v162 offset:2048
	ds_read_b128 v[162:165], v162 offset:3072
	ds_read_b128 v[166:169], v178
	ds_read_b128 v[170:173], v178 offset:1024
	ds_read_b128 v[174:177], v178 offset:2048
	ds_read_b128 v[178:181], v178 offset:3072
	s_add_u32 s22, s22, 0x160000
	s_addc_u32 s23, s23, 0
	s_mov_b32 m0, s33
	v_lshl_add_u64 v[222:223], s[22:23], 0, v[128:129]
	ds_read_b128 v[182:185], v157 offset:32768
	ds_read_b128 v[186:189], v157 offset:33792
	ds_read_b128 v[190:193], v157 offset:34816
	ds_read_b128 v[194:197], v157 offset:35840
	ds_read_b128 v[198:201], v157 offset:36864
	ds_read_b128 v[202:205], v157 offset:37888
	ds_read_b128 v[206:209], v157 offset:38912
	ds_read_b128 v[210:213], v157 offset:39936
	global_load_lds_dwordx4 v[222:223], off
	v_lshl_add_u64 v[222:223], s[22:23], 0, v[132:133]
	s_mov_b32 m0, s34
	s_nop 0
	global_load_lds_dwordx4 v[222:223], off
	s_waitcnt vmcnt(8)
	s_waitcnt lgkmcnt(0)
	s_barrier
	s_setprio 1
	s_waitcnt lgkmcnt(0)
	v_mfma_f32_16x16x32_bf16 v[124:127], v[144:147], v[182:185], v[124:127]
	v_mfma_f32_16x16x32_bf16 v[112:115], v[158:161], v[190:193], v[112:115]
	v_mfma_f32_16x16x32_bf16 v[92:95], v[144:147], v[198:201], v[92:95]
	v_mfma_f32_16x16x32_bf16 v[80:83], v[158:161], v[206:209], v[80:83]
	v_mfma_f32_16x16x32_bf16 v[116:119], v[144:147], v[190:193], v[116:119]
	v_mfma_f32_16x16x32_bf16 v[120:123], v[158:161], v[182:185], v[120:123]
	v_mfma_f32_16x16x32_bf16 v[84:87], v[144:147], v[206:209], v[84:87]
	v_mfma_f32_16x16x32_bf16 v[88:91], v[158:161], v[198:201], v[88:91]
	v_mfma_f32_16x16x32_bf16 v[124:127], v[148:151], v[186:189], v[124:127]
	v_mfma_f32_16x16x32_bf16 v[112:115], v[162:165], v[194:197], v[112:115]
	v_mfma_f32_16x16x32_bf16 v[92:95], v[148:151], v[202:205], v[92:95]
	v_mfma_f32_16x16x32_bf16 v[80:83], v[162:165], v[210:213], v[80:83]
	v_mfma_f32_16x16x32_bf16 v[116:119], v[148:151], v[194:197], v[116:119]
	v_mfma_f32_16x16x32_bf16 v[120:123], v[162:165], v[186:189], v[120:123]
	v_mfma_f32_16x16x32_bf16 v[84:87], v[148:151], v[210:213], v[84:87]
	v_mfma_f32_16x16x32_bf16 v[88:91], v[162:165], v[202:205], v[88:91]
	s_setprio 0
	s_setprio 1
	v_mfma_f32_16x16x32_bf16 v[108:111], v[166:169], v[182:185], v[108:111]
	v_mfma_f32_16x16x32_bf16 v[96:99], v[174:177], v[190:193], v[96:99]
	v_mfma_f32_16x16x32_bf16 v[76:79], v[166:169], v[198:201], v[76:79]
	v_mfma_f32_16x16x32_bf16 v[64:67], v[174:177], v[206:209], v[64:67]
	v_mfma_f32_16x16x32_bf16 v[100:103], v[166:169], v[190:193], v[100:103]
	v_mfma_f32_16x16x32_bf16 v[104:107], v[174:177], v[182:185], v[104:107]
	v_mfma_f32_16x16x32_bf16 v[68:71], v[166:169], v[206:209], v[68:71]
	v_mfma_f32_16x16x32_bf16 v[72:75], v[174:177], v[198:201], v[72:75]
	v_mfma_f32_16x16x32_bf16 v[108:111], v[170:173], v[186:189], v[108:111]
	v_mfma_f32_16x16x32_bf16 v[96:99], v[178:181], v[194:197], v[96:99]
	v_mfma_f32_16x16x32_bf16 v[76:79], v[170:173], v[202:205], v[76:79]
	v_mfma_f32_16x16x32_bf16 v[64:67], v[178:181], v[210:213], v[64:67]
	v_mfma_f32_16x16x32_bf16 v[100:103], v[170:173], v[194:197], v[100:103]
	v_mfma_f32_16x16x32_bf16 v[104:107], v[178:181], v[186:189], v[104:107]
	v_mfma_f32_16x16x32_bf16 v[68:71], v[170:173], v[210:213], v[68:71]
	v_mfma_f32_16x16x32_bf16 v[72:75], v[178:181], v[202:205], v[72:75]
	s_setprio 0
	s_barrier
	s_add_i32 s22, s46, s27
	v_lshl_add_u64 v[214:215], v[214:215], 0, s[12:13]
	s_mov_b32 m0, s22
	ds_read_b128 v[182:185], v157 offset:49152
	ds_read_b128 v[186:189], v157 offset:50176
	ds_read_b128 v[190:193], v157 offset:51200
	ds_read_b128 v[194:197], v157 offset:52224
	ds_read_b128 v[198:201], v157 offset:53248
	ds_read_b128 v[202:205], v157 offset:54272
	ds_read_b128 v[206:209], v157 offset:55296
	ds_read_b128 v[210:213], v157 offset:56320
	global_load_lds_dwordx4 v[214:215], off
	s_add_i32 m0, s22, 0x2000
	s_add_u32 s20, s20, 0x160080
	v_lshl_add_u64 v[214:215], v[216:217], 0, s[12:13]
	s_addc_u32 s21, s21, 0
	s_add_i32 s22, s47, s27
	global_load_lds_dwordx4 v[214:215], off
	v_lshl_add_u64 v[214:215], s[20:21], 0, v[130:131]
	s_mov_b32 m0, s22
	s_nop 0
	global_load_lds_dwordx4 v[214:215], off
	v_lshl_add_u64 v[214:215], s[20:21], 0, v[134:135]
	s_add_i32 m0, s22, 0x2000
	s_nop 0
	global_load_lds_dwordx4 v[214:215], off
	v_lshl_add_u64 v[214:215], v[218:219], 0, s[12:13]
	s_mov_b32 m0, s36
	s_nop 0
	global_load_lds_dwordx4 v[214:215], off
	v_lshl_add_u64 v[214:215], v[220:221], 0, s[12:13]
	s_mov_b32 m0, s37
	s_nop 0
	global_load_lds_dwordx4 v[214:215], off
	s_waitcnt vmcnt(8)
	s_waitcnt lgkmcnt(0)
	s_barrier
	s_setprio 1
	s_waitcnt lgkmcnt(0)
	v_mfma_f32_16x16x32_bf16 v[60:63], v[144:147], v[182:185], v[60:63]
	v_mfma_f32_16x16x32_bf16 v[48:51], v[158:161], v[190:193], v[48:51]
	v_mfma_f32_16x16x32_bf16 v[28:31], v[144:147], v[198:201], v[28:31]
	v_mfma_f32_16x16x32_bf16 v[16:19], v[158:161], v[206:209], v[16:19]
	v_mfma_f32_16x16x32_bf16 v[52:55], v[144:147], v[190:193], v[52:55]
	v_mfma_f32_16x16x32_bf16 v[56:59], v[158:161], v[182:185], v[56:59]
	v_mfma_f32_16x16x32_bf16 v[20:23], v[144:147], v[206:209], v[20:23]
	v_mfma_f32_16x16x32_bf16 v[24:27], v[158:161], v[198:201], v[24:27]
	v_mfma_f32_16x16x32_bf16 v[60:63], v[148:151], v[186:189], v[60:63]
	v_mfma_f32_16x16x32_bf16 v[48:51], v[162:165], v[194:197], v[48:51]
	v_mfma_f32_16x16x32_bf16 v[28:31], v[148:151], v[202:205], v[28:31]
	v_mfma_f32_16x16x32_bf16 v[16:19], v[162:165], v[210:213], v[16:19]
	v_mfma_f32_16x16x32_bf16 v[52:55], v[148:151], v[194:197], v[52:55]
	v_mfma_f32_16x16x32_bf16 v[56:59], v[162:165], v[186:189], v[56:59]
	v_mfma_f32_16x16x32_bf16 v[20:23], v[148:151], v[210:213], v[20:23]
	v_mfma_f32_16x16x32_bf16 v[24:27], v[162:165], v[202:205], v[24:27]
	s_setprio 0
	s_setprio 1
	v_mfma_f32_16x16x32_bf16 v[44:47], v[166:169], v[182:185], v[44:47]
	v_mfma_f32_16x16x32_bf16 v[32:35], v[174:177], v[190:193], v[32:35]
	v_mfma_f32_16x16x32_bf16 v[12:15], v[166:169], v[198:201], v[12:15]
	v_mfma_f32_16x16x32_bf16 v[0:3], v[174:177], v[206:209], v[0:3]
	v_mfma_f32_16x16x32_bf16 v[36:39], v[166:169], v[190:193], v[36:39]
	v_mfma_f32_16x16x32_bf16 v[40:43], v[174:177], v[182:185], v[40:43]
	v_mfma_f32_16x16x32_bf16 v[4:7], v[166:169], v[206:209], v[4:7]
	v_mfma_f32_16x16x32_bf16 v[8:11], v[174:177], v[198:201], v[8:11]
	v_mfma_f32_16x16x32_bf16 v[44:47], v[170:173], v[186:189], v[44:47]
	v_mfma_f32_16x16x32_bf16 v[32:35], v[178:181], v[194:197], v[32:35]
	v_mfma_f32_16x16x32_bf16 v[12:15], v[170:173], v[202:205], v[12:15]
	v_mfma_f32_16x16x32_bf16 v[0:3], v[178:181], v[210:213], v[0:3]
	v_mfma_f32_16x16x32_bf16 v[36:39], v[170:173], v[194:197], v[36:39]
	v_mfma_f32_16x16x32_bf16 v[40:43], v[178:181], v[186:189], v[40:43]
	v_mfma_f32_16x16x32_bf16 v[4:7], v[170:173], v[210:213], v[4:7]
	v_mfma_f32_16x16x32_bf16 v[8:11], v[178:181], v[202:205], v[8:11]
	s_setprio 0
	s_barrier
	s_add_i32 s45, s45, 2
	s_add_u32 s18, s18, 0x100
	s_addc_u32 s19, s19, 0
	s_add_u32 s0, s0, 0x100
	s_addc_u32 s1, s1, 0
	s_cmpk_gt_u32 s45, 0x55
	s_cbranch_scc0 .LBB0_3930
	s_and_b64 vcc, exec, s[14:15]
	s_cbranch_vccz .LBB0_3933
	s_barrier
